# K-loop MFMA segments: priority raise before the opening barrier, duplicate lgkmcnt(0) removed, priority drop after the closing barrier
# speedup vs baseline: 1.0227x; 1.0135x over previous
.LBB0_74:
	s_ashr_i32 s27, s26, 31
	s_lshl_b64 s[28:29], s[26:27], 19
	s_add_u32 s28, s3, s28
	s_addc_u32 s29, s35, s29
	s_and_b64 s[30:31], s[4:5], exec
	s_cselect_b32 s27, s29, s49
	s_cselect_b32 s68, s28, s48
	s_ashr_i32 s23, s22, 31
	s_lshl_b64 s[30:31], s[22:23], 19
	s_add_u32 s30, s50, s30
	s_addc_u32 s31, s51, s31
	s_and_b64 s[70:71], s[4:5], exec
	s_cselect_b32 s69, s31, s47
	s_cselect_b32 s70, s30, s46
	s_lshl_b32 s23, s44, 8
	v_add_u32_e32 v0, s23, v148
	s_add_u32 s71, s46, 0x100
	v_ashrrev_i32_e32 v1, 31, v0
	s_addc_u32 s74, s47, 0
	v_lshl_add_u64 v[144:145], v[0:1], 4, s[12:13]
	s_add_u32 s44, s48, 0x40080
	s_addc_u32 s45, s49, 0
	s_mov_b32 s75, -2
	s_mov_b64 s[46:47], 0
	s_cmp_eq_u32 s59, 1
	s_cbranch_scc1 .Lfa_0
	v_add_u32_e32 v153, s64, v147
	ds_read_b128 v[160:163], v153
	v_xor_b32_e32 v253, 64, v153
	ds_read_b128 v[164:167], v253
	ds_read_b128 v[168:171], v153 offset:2048
	ds_read_b128 v[172:175], v253 offset:2048
	v_add_u32_e32 v153, s65, v147
	ds_read_b128 v[176:179], v153
	v_xor_b32_e32 v253, 64, v153
	ds_read_b128 v[180:183], v253
	ds_read_b128 v[186:189], v153 offset:2048
	ds_read_b128 v[190:193], v253 offset:2048
	s_add_u32 s48, s44, 0xfffc0080
	s_addc_u32 s49, s45, -1
	s_and_b64 s[46:47], s[46:47], exec
	s_cselect_b32 s49, s27, s49
	s_cselect_b32 s48, s68, s48
	s_cselect_b32 s47, s69, s74
	s_cselect_b32 s46, s70, s71
	v_lshl_add_u64 v[154:155], s[44:45], 0, v[138:139]
	s_add_i32 m0, s55, 0xc000
	ds_read_b128 v[194:197], v150
	v_xor_b32_e32 v253, 64, v150
	ds_read_b128 v[198:201], v253
	ds_read_b128 v[202:205], v150 offset:2048
	ds_read_b128 v[206:209], v253 offset:2048
	ds_read_b128 v[210:213], v150 offset:4096
	ds_read_b128 v[214:217], v253 offset:4096
	ds_read_b128 v[218:221], v150 offset:6144
	ds_read_b128 v[222:225], v253 offset:6144
	global_load_lds_dwordx4 v[154:155], off
	v_lshl_add_u64 v[154:155], s[44:45], 0, v[136:137]
	s_add_i32 m0, s55, 0xe000
	s_nop 0
	global_load_lds_dwordx4 v[154:155], off
	s_waitcnt vmcnt(16)
	s_waitcnt lgkmcnt(0)
	s_setprio 1
	s_barrier
	v_mfma_f32_16x16x32_bf16 v[124:127], v[160:163], v[194:197], 0
	v_mfma_f32_16x16x32_bf16 v[116:119], v[168:171], v[194:197], 0
	v_mfma_f32_16x16x32_bf16 v[108:111], v[160:163], v[202:205], 0
	v_mfma_f32_16x16x32_bf16 v[100:103], v[168:171], v[202:205], 0
	v_mfma_f32_16x16x32_bf16 v[92:95], v[160:163], v[210:213], 0
	v_mfma_f32_16x16x32_bf16 v[84:87], v[168:171], v[210:213], 0
	v_mfma_f32_16x16x32_bf16 v[76:79], v[160:163], v[218:221], 0
	v_mfma_f32_16x16x32_bf16 v[68:71], v[168:171], v[218:221], 0
	v_mfma_f32_16x16x32_bf16 v[124:127], v[164:167], v[198:201], v[124:127]
	v_mfma_f32_16x16x32_bf16 v[116:119], v[172:175], v[198:201], v[116:119]
	v_mfma_f32_16x16x32_bf16 v[108:111], v[164:167], v[206:209], v[108:111]
	v_mfma_f32_16x16x32_bf16 v[100:103], v[172:175], v[206:209], v[100:103]
	v_mfma_f32_16x16x32_bf16 v[92:95], v[164:167], v[214:217], v[92:95]
	v_mfma_f32_16x16x32_bf16 v[84:87], v[172:175], v[214:217], v[84:87]
	v_mfma_f32_16x16x32_bf16 v[76:79], v[164:167], v[222:225], v[76:79]
	v_mfma_f32_16x16x32_bf16 v[68:71], v[172:175], v[222:225], v[68:71]
	s_setprio 0
	s_setprio 1
	v_mfma_f32_16x16x32_bf16 v[120:123], v[176:179], v[194:197], 0
	v_mfma_f32_16x16x32_bf16 v[112:115], v[186:189], v[194:197], 0
	v_mfma_f32_16x16x32_bf16 v[104:107], v[176:179], v[202:205], 0
	v_mfma_f32_16x16x32_bf16 v[96:99], v[186:189], v[202:205], 0
	v_mfma_f32_16x16x32_bf16 v[88:91], v[176:179], v[210:213], 0
	v_mfma_f32_16x16x32_bf16 v[80:83], v[186:189], v[210:213], 0
	v_mfma_f32_16x16x32_bf16 v[72:75], v[176:179], v[218:221], 0
	v_mfma_f32_16x16x32_bf16 v[64:67], v[186:189], v[218:221], 0
	v_mfma_f32_16x16x32_bf16 v[120:123], v[180:183], v[198:201], v[120:123]
	v_mfma_f32_16x16x32_bf16 v[112:115], v[190:193], v[198:201], v[112:115]
	v_mfma_f32_16x16x32_bf16 v[104:107], v[180:183], v[206:209], v[104:107]
	v_mfma_f32_16x16x32_bf16 v[96:99], v[190:193], v[206:209], v[96:99]
	v_mfma_f32_16x16x32_bf16 v[88:91], v[180:183], v[214:217], v[88:91]
	v_mfma_f32_16x16x32_bf16 v[80:83], v[190:193], v[214:217], v[80:83]
	v_mfma_f32_16x16x32_bf16 v[72:75], v[180:183], v[222:225], v[72:75]
	v_mfma_f32_16x16x32_bf16 v[64:67], v[190:193], v[222:225], v[64:67]
	s_barrier
	s_setprio 0
	s_add_i32 s76, s64, s52
	v_lshl_add_u64 v[154:155], s[46:47], 0, v[132:133]
	s_mov_b32 m0, s76
	ds_read_b128 v[194:197], v150 offset:16384
	v_xor_b32_e32 v253, 64, v150
	ds_read_b128 v[198:201], v253 offset:16384
	ds_read_b128 v[202:205], v150 offset:18432
	ds_read_b128 v[206:209], v253 offset:18432
	ds_read_b128 v[210:213], v150 offset:20480
	ds_read_b128 v[214:217], v253 offset:20480
	ds_read_b128 v[218:221], v150 offset:22528
	ds_read_b128 v[222:225], v253 offset:22528
	global_load_lds_dwordx4 v[154:155], off
	s_add_i32 m0, s76, 0x2000
	s_add_u32 s76, s46, 0x40000
	v_lshl_add_u64 v[226:227], s[46:47], 0, v[128:129]
	s_addc_u32 s77, s47, 0
	s_add_i32 s78, s65, s52
	global_load_lds_dwordx4 v[226:227], off
	v_lshl_add_u64 v[228:229], s[76:77], 0, v[132:133]
	s_mov_b32 m0, s78
	v_lshl_add_u64 v[230:231], s[48:49], 0, v[130:131]
	global_load_lds_dwordx4 v[228:229], off
	v_lshl_add_u64 v[228:229], s[76:77], 0, v[128:129]
	s_add_i32 m0, s78, 0x2000
	s_nop 0
	global_load_lds_dwordx4 v[228:229], off
	v_lshl_add_u64 v[228:229], s[48:49], 0, v[134:135]
	s_mov_b32 m0, s55
	s_nop 0
	global_load_lds_dwordx4 v[228:229], off
	s_mov_b32 m0, s56
	s_nop 0
	global_load_lds_dwordx4 v[230:231], off
	s_waitcnt vmcnt(16)
	s_waitcnt lgkmcnt(0)
	s_setprio 1
	s_barrier
	v_mfma_f32_16x16x32_bf16 v[60:63], v[160:163], v[194:197], 0
	v_mfma_f32_16x16x32_bf16 v[52:55], v[168:171], v[194:197], 0
	v_mfma_f32_16x16x32_bf16 v[44:47], v[160:163], v[202:205], 0
	v_mfma_f32_16x16x32_bf16 v[36:39], v[168:171], v[202:205], 0
	v_mfma_f32_16x16x32_bf16 v[28:31], v[160:163], v[210:213], 0
	v_mfma_f32_16x16x32_bf16 v[20:23], v[168:171], v[210:213], 0
	v_mfma_f32_16x16x32_bf16 v[12:15], v[160:163], v[218:221], 0
	v_mfma_f32_16x16x32_bf16 v[4:7], v[168:171], v[218:221], 0
	v_mfma_f32_16x16x32_bf16 v[60:63], v[164:167], v[198:201], v[60:63]
	v_mfma_f32_16x16x32_bf16 v[52:55], v[172:175], v[198:201], v[52:55]
	v_mfma_f32_16x16x32_bf16 v[44:47], v[164:167], v[206:209], v[44:47]
	v_mfma_f32_16x16x32_bf16 v[36:39], v[172:175], v[206:209], v[36:39]
	v_mfma_f32_16x16x32_bf16 v[28:31], v[164:167], v[214:217], v[28:31]
	v_mfma_f32_16x16x32_bf16 v[20:23], v[172:175], v[214:217], v[20:23]
	v_mfma_f32_16x16x32_bf16 v[12:15], v[164:167], v[222:225], v[12:15]
	v_mfma_f32_16x16x32_bf16 v[4:7], v[172:175], v[222:225], v[4:7]
	s_setprio 0
	s_setprio 1
	v_mfma_f32_16x16x32_bf16 v[56:59], v[176:179], v[194:197], 0
	v_mfma_f32_16x16x32_bf16 v[48:51], v[186:189], v[194:197], 0
	v_mfma_f32_16x16x32_bf16 v[40:43], v[176:179], v[202:205], 0
	v_mfma_f32_16x16x32_bf16 v[32:35], v[186:189], v[202:205], 0
	v_mfma_f32_16x16x32_bf16 v[24:27], v[176:179], v[210:213], 0
	v_mfma_f32_16x16x32_bf16 v[16:19], v[186:189], v[210:213], 0
	v_mfma_f32_16x16x32_bf16 v[8:11], v[176:179], v[218:221], 0
	v_mfma_f32_16x16x32_bf16 v[0:3], v[186:189], v[218:221], 0
	v_mfma_f32_16x16x32_bf16 v[56:59], v[180:183], v[198:201], v[56:59]
	v_mfma_f32_16x16x32_bf16 v[48:51], v[190:193], v[198:201], v[48:51]
	v_mfma_f32_16x16x32_bf16 v[40:43], v[180:183], v[206:209], v[40:43]
	v_mfma_f32_16x16x32_bf16 v[32:35], v[190:193], v[206:209], v[32:35]
	v_mfma_f32_16x16x32_bf16 v[24:27], v[180:183], v[214:217], v[24:27]
	v_mfma_f32_16x16x32_bf16 v[16:19], v[190:193], v[214:217], v[16:19]
	v_mfma_f32_16x16x32_bf16 v[8:11], v[180:183], v[222:225], v[8:11]
	v_mfma_f32_16x16x32_bf16 v[0:3], v[190:193], v[222:225], v[0:3]
	s_barrier
	s_setprio 0
	s_add_i32 s76, 0, 0x18000
	v_add_u32_e32 v153, s76, v147
	s_add_i32 s77, 0, 0x1c000
	ds_read_b128 v[160:163], v153
	v_xor_b32_e32 v253, 64, v153
	ds_read_b128 v[164:167], v253
	ds_read_b128 v[168:171], v153 offset:2048
	ds_read_b128 v[172:175], v253 offset:2048
	v_add_u32_e32 v153, s77, v147
	ds_read_b128 v[176:179], v153
	v_xor_b32_e32 v253, 64, v153
	ds_read_b128 v[180:183], v253
	ds_read_b128 v[186:189], v153 offset:2048
	ds_read_b128 v[190:193], v253 offset:2048
	s_add_u32 s48, s48, 0x40000
	s_addc_u32 s49, s49, 0
	s_mov_b32 m0, s57
	v_lshl_add_u64 v[232:233], s[48:49], 0, v[134:135]
	ds_read_b128 v[194:197], v150 offset:32768
	v_xor_b32_e32 v253, 64, v150
	ds_read_b128 v[198:201], v253 offset:32768
	ds_read_b128 v[202:205], v150 offset:34816
	ds_read_b128 v[206:209], v253 offset:34816
	ds_read_b128 v[210:213], v150 offset:36864
	ds_read_b128 v[214:217], v253 offset:36864
	ds_read_b128 v[218:221], v150 offset:38912
	ds_read_b128 v[222:225], v253 offset:38912
	global_load_lds_dwordx4 v[232:233], off
	v_lshl_add_u64 v[232:233], s[48:49], 0, v[130:131]
	s_mov_b32 m0, s58
	s_nop 0
	global_load_lds_dwordx4 v[232:233], off
	s_waitcnt vmcnt(8)
	s_waitcnt lgkmcnt(0)
	s_setprio 1
	s_barrier
	v_mfma_f32_16x16x32_bf16 v[124:127], v[160:163], v[194:197], v[124:127]
	v_mfma_f32_16x16x32_bf16 v[124:127], v[164:167], v[198:201], v[124:127]
	v_mfma_f32_16x16x32_bf16 v[116:119], v[172:175], v[198:201], v[116:119]
	v_mfma_f32_16x16x32_bf16 v[116:119], v[168:171], v[194:197], v[116:119]
	v_mfma_f32_16x16x32_bf16 v[100:103], v[168:171], v[202:205], v[100:103]
	v_mfma_f32_16x16x32_bf16 v[100:103], v[172:175], v[206:209], v[100:103]
	v_mfma_f32_16x16x32_bf16 v[108:111], v[164:167], v[206:209], v[108:111]
	v_mfma_f32_16x16x32_bf16 v[108:111], v[160:163], v[202:205], v[108:111]
	v_mfma_f32_16x16x32_bf16 v[92:95], v[160:163], v[210:213], v[92:95]
	v_mfma_f32_16x16x32_bf16 v[92:95], v[164:167], v[214:217], v[92:95]
	v_mfma_f32_16x16x32_bf16 v[84:87], v[172:175], v[214:217], v[84:87]
	v_mfma_f32_16x16x32_bf16 v[84:87], v[168:171], v[210:213], v[84:87]
	v_mfma_f32_16x16x32_bf16 v[68:71], v[168:171], v[218:221], v[68:71]
	v_mfma_f32_16x16x32_bf16 v[68:71], v[172:175], v[222:225], v[68:71]
	v_mfma_f32_16x16x32_bf16 v[76:79], v[164:167], v[222:225], v[76:79]
	v_mfma_f32_16x16x32_bf16 v[76:79], v[160:163], v[218:221], v[76:79]
	s_setprio 0
	s_setprio 1
	v_mfma_f32_16x16x32_bf16 v[120:123], v[176:179], v[194:197], v[120:123]
	v_mfma_f32_16x16x32_bf16 v[120:123], v[180:183], v[198:201], v[120:123]
	v_mfma_f32_16x16x32_bf16 v[112:115], v[190:193], v[198:201], v[112:115]
	v_mfma_f32_16x16x32_bf16 v[112:115], v[186:189], v[194:197], v[112:115]
	v_mfma_f32_16x16x32_bf16 v[96:99], v[186:189], v[202:205], v[96:99]
	v_mfma_f32_16x16x32_bf16 v[96:99], v[190:193], v[206:209], v[96:99]
	v_mfma_f32_16x16x32_bf16 v[104:107], v[180:183], v[206:209], v[104:107]
	v_mfma_f32_16x16x32_bf16 v[104:107], v[176:179], v[202:205], v[104:107]
	v_mfma_f32_16x16x32_bf16 v[88:91], v[176:179], v[210:213], v[88:91]
	v_mfma_f32_16x16x32_bf16 v[88:91], v[180:183], v[214:217], v[88:91]
	v_mfma_f32_16x16x32_bf16 v[80:83], v[190:193], v[214:217], v[80:83]
	v_mfma_f32_16x16x32_bf16 v[80:83], v[186:189], v[210:213], v[80:83]
	v_mfma_f32_16x16x32_bf16 v[64:67], v[186:189], v[218:221], v[64:67]
	v_mfma_f32_16x16x32_bf16 v[64:67], v[190:193], v[222:225], v[64:67]
	v_mfma_f32_16x16x32_bf16 v[72:75], v[180:183], v[222:225], v[72:75]
	v_mfma_f32_16x16x32_bf16 v[72:75], v[176:179], v[218:221], v[72:75]
	s_barrier
	s_setprio 0
	s_add_i32 s48, s76, s52
	v_lshl_add_u64 v[154:155], v[154:155], 0, s[14:15]
	s_mov_b32 m0, s48
	ds_read_b128 v[194:197], v150 offset:49152
	v_xor_b32_e32 v253, 64, v150
	ds_read_b128 v[198:201], v253 offset:49152
	ds_read_b128 v[202:205], v150 offset:51200
	ds_read_b128 v[206:209], v253 offset:51200
	ds_read_b128 v[210:213], v150 offset:53248
	ds_read_b128 v[214:217], v253 offset:53248
	ds_read_b128 v[218:221], v150 offset:55296
	ds_read_b128 v[222:225], v253 offset:55296
	global_load_lds_dwordx4 v[154:155], off
	s_add_i32 m0, s48, 0x2000
	s_add_u32 s46, s46, 0x40080
	v_lshl_add_u64 v[154:155], v[226:227], 0, s[14:15]
	s_addc_u32 s47, s47, 0
	s_add_i32 s48, s77, s52
	global_load_lds_dwordx4 v[154:155], off
	v_lshl_add_u64 v[154:155], s[46:47], 0, v[132:133]
	s_mov_b32 m0, s48
	s_nop 0
	global_load_lds_dwordx4 v[154:155], off
	v_lshl_add_u64 v[154:155], s[46:47], 0, v[128:129]
	s_add_i32 m0, s48, 0x2000
	s_nop 0
	global_load_lds_dwordx4 v[154:155], off
	v_lshl_add_u64 v[154:155], v[228:229], 0, s[14:15]
	s_mov_b32 m0, s60
	s_nop 0
	global_load_lds_dwordx4 v[154:155], off
	v_lshl_add_u64 v[154:155], v[230:231], 0, s[14:15]
	s_mov_b32 m0, s61
	s_nop 0
	global_load_lds_dwordx4 v[154:155], off
	s_waitcnt vmcnt(8)
	s_waitcnt lgkmcnt(0)
	s_setprio 1
	s_barrier
	v_mfma_f32_16x16x32_bf16 v[60:63], v[160:163], v[194:197], v[60:63]
	v_mfma_f32_16x16x32_bf16 v[60:63], v[164:167], v[198:201], v[60:63]
	v_mfma_f32_16x16x32_bf16 v[52:55], v[172:175], v[198:201], v[52:55]
	v_mfma_f32_16x16x32_bf16 v[52:55], v[168:171], v[194:197], v[52:55]
	v_mfma_f32_16x16x32_bf16 v[36:39], v[168:171], v[202:205], v[36:39]
	v_mfma_f32_16x16x32_bf16 v[36:39], v[172:175], v[206:209], v[36:39]
	v_mfma_f32_16x16x32_bf16 v[44:47], v[164:167], v[206:209], v[44:47]
	v_mfma_f32_16x16x32_bf16 v[44:47], v[160:163], v[202:205], v[44:47]
	v_mfma_f32_16x16x32_bf16 v[28:31], v[160:163], v[210:213], v[28:31]
	v_mfma_f32_16x16x32_bf16 v[28:31], v[164:167], v[214:217], v[28:31]
	v_mfma_f32_16x16x32_bf16 v[20:23], v[172:175], v[214:217], v[20:23]
	v_mfma_f32_16x16x32_bf16 v[20:23], v[168:171], v[210:213], v[20:23]
	v_mfma_f32_16x16x32_bf16 v[4:7], v[168:171], v[218:221], v[4:7]
	v_mfma_f32_16x16x32_bf16 v[4:7], v[172:175], v[222:225], v[4:7]
	v_mfma_f32_16x16x32_bf16 v[12:15], v[164:167], v[222:225], v[12:15]
	v_mfma_f32_16x16x32_bf16 v[12:15], v[160:163], v[218:221], v[12:15]
	s_setprio 0
	s_setprio 1
	v_mfma_f32_16x16x32_bf16 v[56:59], v[176:179], v[194:197], v[56:59]
	v_mfma_f32_16x16x32_bf16 v[56:59], v[180:183], v[198:201], v[56:59]
	v_mfma_f32_16x16x32_bf16 v[48:51], v[190:193], v[198:201], v[48:51]
	v_mfma_f32_16x16x32_bf16 v[48:51], v[186:189], v[194:197], v[48:51]
	v_mfma_f32_16x16x32_bf16 v[32:35], v[186:189], v[202:205], v[32:35]
	v_mfma_f32_16x16x32_bf16 v[32:35], v[190:193], v[206:209], v[32:35]
	v_mfma_f32_16x16x32_bf16 v[40:43], v[180:183], v[206:209], v[40:43]
	v_mfma_f32_16x16x32_bf16 v[40:43], v[176:179], v[202:205], v[40:43]
	v_mfma_f32_16x16x32_bf16 v[24:27], v[176:179], v[210:213], v[24:27]
	v_mfma_f32_16x16x32_bf16 v[24:27], v[180:183], v[214:217], v[24:27]
	v_mfma_f32_16x16x32_bf16 v[16:19], v[190:193], v[214:217], v[16:19]
	v_mfma_f32_16x16x32_bf16 v[16:19], v[186:189], v[210:213], v[16:19]
	v_mfma_f32_16x16x32_bf16 v[0:3], v[186:189], v[218:221], v[0:3]
	v_mfma_f32_16x16x32_bf16 v[0:3], v[190:193], v[222:225], v[0:3]
	v_mfma_f32_16x16x32_bf16 v[8:11], v[180:183], v[222:225], v[8:11]
	v_mfma_f32_16x16x32_bf16 v[8:11], v[176:179], v[218:221], v[8:11]
	s_barrier
	s_setprio 0
	s_add_i32 s75, s75, 2
	s_add_u32 s71, s71, 0x100
	s_addc_u32 s74, s74, 0
	s_add_u32 s44, s44, 0x100
	s_addc_u32 s45, s45, 0
	s_branch .LBB0_76
.Lfa_0:
	v_add_u32_e32 v153, s64, v147
	ds_read_b128 v[160:163], v153
	v_xor_b32_e32 v253, 64, v153
	ds_read_b128 v[164:167], v253
	ds_read_b128 v[168:171], v153 offset:2048
	ds_read_b128 v[172:175], v253 offset:2048
	v_add_u32_e32 v153, s65, v147
	ds_read_b128 v[176:179], v153
	v_xor_b32_e32 v253, 64, v153
	ds_read_b128 v[180:183], v253
	ds_read_b128 v[186:189], v153 offset:2048
	ds_read_b128 v[190:193], v253 offset:2048
	s_add_u32 s48, s44, 0xfffc0080
	s_addc_u32 s49, s45, -1
	s_and_b64 s[46:47], s[46:47], exec
	s_cselect_b32 s49, s27, s49
	s_cselect_b32 s48, s68, s48
	s_cselect_b32 s47, s69, s74
	s_cselect_b32 s46, s70, s71
	v_lshl_add_u64 v[154:155], s[44:45], 0, v[138:139]
	s_add_i32 m0, s55, 0xc000
	ds_read_b128 v[194:197], v150
	v_xor_b32_e32 v253, 64, v150
	ds_read_b128 v[198:201], v253
	ds_read_b128 v[202:205], v150 offset:2048
	ds_read_b128 v[206:209], v253 offset:2048
	ds_read_b128 v[210:213], v150 offset:4096
	ds_read_b128 v[214:217], v253 offset:4096
	ds_read_b128 v[218:221], v150 offset:6144
	ds_read_b128 v[222:225], v253 offset:6144
	global_load_lds_dwordx4 v[154:155], off
	v_lshl_add_u64 v[154:155], s[44:45], 0, v[136:137]
	s_add_i32 m0, s55, 0xe000
	s_nop 0
	global_load_lds_dwordx4 v[154:155], off
	s_waitcnt vmcnt(8)
	s_waitcnt lgkmcnt(0)
	s_setprio 1
	s_barrier
	v_mfma_f32_16x16x32_bf16 v[124:127], v[160:163], v[194:197], 0
	v_mfma_f32_16x16x32_bf16 v[116:119], v[168:171], v[194:197], 0
	v_mfma_f32_16x16x32_bf16 v[108:111], v[160:163], v[202:205], 0
	v_mfma_f32_16x16x32_bf16 v[100:103], v[168:171], v[202:205], 0
	v_mfma_f32_16x16x32_bf16 v[92:95], v[160:163], v[210:213], 0
	v_mfma_f32_16x16x32_bf16 v[84:87], v[168:171], v[210:213], 0
	v_mfma_f32_16x16x32_bf16 v[76:79], v[160:163], v[218:221], 0
	v_mfma_f32_16x16x32_bf16 v[68:71], v[168:171], v[218:221], 0
	v_mfma_f32_16x16x32_bf16 v[124:127], v[164:167], v[198:201], v[124:127]
	v_mfma_f32_16x16x32_bf16 v[116:119], v[172:175], v[198:201], v[116:119]
	v_mfma_f32_16x16x32_bf16 v[108:111], v[164:167], v[206:209], v[108:111]
	v_mfma_f32_16x16x32_bf16 v[100:103], v[172:175], v[206:209], v[100:103]
	v_mfma_f32_16x16x32_bf16 v[92:95], v[164:167], v[214:217], v[92:95]
	v_mfma_f32_16x16x32_bf16 v[84:87], v[172:175], v[214:217], v[84:87]
	v_mfma_f32_16x16x32_bf16 v[76:79], v[164:167], v[222:225], v[76:79]
	v_mfma_f32_16x16x32_bf16 v[68:71], v[172:175], v[222:225], v[68:71]
	s_setprio 0
	s_setprio 1
	v_mfma_f32_16x16x32_bf16 v[120:123], v[176:179], v[194:197], 0
	v_mfma_f32_16x16x32_bf16 v[112:115], v[186:189], v[194:197], 0
	v_mfma_f32_16x16x32_bf16 v[104:107], v[176:179], v[202:205], 0
	v_mfma_f32_16x16x32_bf16 v[96:99], v[186:189], v[202:205], 0
	v_mfma_f32_16x16x32_bf16 v[88:91], v[176:179], v[210:213], 0
	v_mfma_f32_16x16x32_bf16 v[80:83], v[186:189], v[210:213], 0
	v_mfma_f32_16x16x32_bf16 v[72:75], v[176:179], v[218:221], 0
	v_mfma_f32_16x16x32_bf16 v[64:67], v[186:189], v[218:221], 0
	v_mfma_f32_16x16x32_bf16 v[120:123], v[180:183], v[198:201], v[120:123]
	v_mfma_f32_16x16x32_bf16 v[112:115], v[190:193], v[198:201], v[112:115]
	v_mfma_f32_16x16x32_bf16 v[104:107], v[180:183], v[206:209], v[104:107]
	v_mfma_f32_16x16x32_bf16 v[96:99], v[190:193], v[206:209], v[96:99]
	v_mfma_f32_16x16x32_bf16 v[88:91], v[180:183], v[214:217], v[88:91]
	v_mfma_f32_16x16x32_bf16 v[80:83], v[190:193], v[214:217], v[80:83]
	v_mfma_f32_16x16x32_bf16 v[72:75], v[180:183], v[222:225], v[72:75]
	v_mfma_f32_16x16x32_bf16 v[64:67], v[190:193], v[222:225], v[64:67]
	s_barrier
	s_setprio 0
	s_add_i32 s76, s64, s52
	v_lshl_add_u64 v[154:155], s[46:47], 0, v[132:133]
	s_mov_b32 m0, s76
	ds_read_b128 v[194:197], v150 offset:16384
	v_xor_b32_e32 v253, 64, v150
	ds_read_b128 v[198:201], v253 offset:16384
	ds_read_b128 v[202:205], v150 offset:18432
	ds_read_b128 v[206:209], v253 offset:18432
	ds_read_b128 v[210:213], v150 offset:20480
	ds_read_b128 v[214:217], v253 offset:20480
	ds_read_b128 v[218:221], v150 offset:22528
	ds_read_b128 v[222:225], v253 offset:22528
	global_load_lds_dwordx4 v[154:155], off
	s_add_i32 m0, s76, 0x2000
	s_add_u32 s76, s46, 0x40000
	v_lshl_add_u64 v[226:227], s[46:47], 0, v[128:129]
	s_addc_u32 s77, s47, 0
	s_add_i32 s78, s65, s52
	global_load_lds_dwordx4 v[226:227], off
	v_lshl_add_u64 v[228:229], s[76:77], 0, v[132:133]
	s_mov_b32 m0, s78
	v_lshl_add_u64 v[230:231], s[48:49], 0, v[130:131]
	global_load_lds_dwordx4 v[228:229], off
	v_lshl_add_u64 v[228:229], s[76:77], 0, v[128:129]
	s_add_i32 m0, s78, 0x2000
	s_nop 0
	global_load_lds_dwordx4 v[228:229], off
	v_lshl_add_u64 v[228:229], s[48:49], 0, v[134:135]
	s_mov_b32 m0, s55
	s_nop 0
	global_load_lds_dwordx4 v[228:229], off
	s_mov_b32 m0, s56
	s_nop 0
	global_load_lds_dwordx4 v[230:231], off
	s_waitcnt vmcnt(8)
	s_waitcnt lgkmcnt(0)
	s_setprio 1
	s_barrier
	v_mfma_f32_16x16x32_bf16 v[60:63], v[160:163], v[194:197], 0
	v_mfma_f32_16x16x32_bf16 v[52:55], v[168:171], v[194:197], 0
	v_mfma_f32_16x16x32_bf16 v[44:47], v[160:163], v[202:205], 0
	v_mfma_f32_16x16x32_bf16 v[36:39], v[168:171], v[202:205], 0
	v_mfma_f32_16x16x32_bf16 v[28:31], v[160:163], v[210:213], 0
	v_mfma_f32_16x16x32_bf16 v[20:23], v[168:171], v[210:213], 0
	v_mfma_f32_16x16x32_bf16 v[12:15], v[160:163], v[218:221], 0
	v_mfma_f32_16x16x32_bf16 v[4:7], v[168:171], v[218:221], 0
	v_mfma_f32_16x16x32_bf16 v[60:63], v[164:167], v[198:201], v[60:63]
	v_mfma_f32_16x16x32_bf16 v[52:55], v[172:175], v[198:201], v[52:55]
	v_mfma_f32_16x16x32_bf16 v[44:47], v[164:167], v[206:209], v[44:47]
	v_mfma_f32_16x16x32_bf16 v[36:39], v[172:175], v[206:209], v[36:39]
	v_mfma_f32_16x16x32_bf16 v[28:31], v[164:167], v[214:217], v[28:31]
	v_mfma_f32_16x16x32_bf16 v[20:23], v[172:175], v[214:217], v[20:23]
	v_mfma_f32_16x16x32_bf16 v[12:15], v[164:167], v[222:225], v[12:15]
	v_mfma_f32_16x16x32_bf16 v[4:7], v[172:175], v[222:225], v[4:7]
	s_setprio 0
	s_setprio 1
	v_mfma_f32_16x16x32_bf16 v[56:59], v[176:179], v[194:197], 0
	v_mfma_f32_16x16x32_bf16 v[48:51], v[186:189], v[194:197], 0
	v_mfma_f32_16x16x32_bf16 v[40:43], v[176:179], v[202:205], 0
	v_mfma_f32_16x16x32_bf16 v[32:35], v[186:189], v[202:205], 0
	v_mfma_f32_16x16x32_bf16 v[24:27], v[176:179], v[210:213], 0
	v_mfma_f32_16x16x32_bf16 v[16:19], v[186:189], v[210:213], 0
	v_mfma_f32_16x16x32_bf16 v[8:11], v[176:179], v[218:221], 0
	v_mfma_f32_16x16x32_bf16 v[0:3], v[186:189], v[218:221], 0
	v_mfma_f32_16x16x32_bf16 v[56:59], v[180:183], v[198:201], v[56:59]
	v_mfma_f32_16x16x32_bf16 v[48:51], v[190:193], v[198:201], v[48:51]
	v_mfma_f32_16x16x32_bf16 v[40:43], v[180:183], v[206:209], v[40:43]
	v_mfma_f32_16x16x32_bf16 v[32:35], v[190:193], v[206:209], v[32:35]
	v_mfma_f32_16x16x32_bf16 v[24:27], v[180:183], v[214:217], v[24:27]
	v_mfma_f32_16x16x32_bf16 v[16:19], v[190:193], v[214:217], v[16:19]
	v_mfma_f32_16x16x32_bf16 v[8:11], v[180:183], v[222:225], v[8:11]
	v_mfma_f32_16x16x32_bf16 v[0:3], v[190:193], v[222:225], v[0:3]
	s_barrier
	s_setprio 0
	s_add_i32 s76, 0, 0x18000
	v_add_u32_e32 v153, s76, v147
	s_add_i32 s77, 0, 0x1c000
	ds_read_b128 v[160:163], v153
	v_xor_b32_e32 v253, 64, v153
	ds_read_b128 v[164:167], v253
	ds_read_b128 v[168:171], v153 offset:2048
	ds_read_b128 v[172:175], v253 offset:2048
	v_add_u32_e32 v153, s77, v147
	ds_read_b128 v[176:179], v153
	v_xor_b32_e32 v253, 64, v153
	ds_read_b128 v[180:183], v253
	ds_read_b128 v[186:189], v153 offset:2048
	ds_read_b128 v[190:193], v253 offset:2048
	s_add_u32 s48, s48, 0x40000
	s_addc_u32 s49, s49, 0
	s_mov_b32 m0, s57
	v_lshl_add_u64 v[232:233], s[48:49], 0, v[134:135]
	ds_read_b128 v[194:197], v150 offset:32768
	v_xor_b32_e32 v253, 64, v150
	ds_read_b128 v[198:201], v253 offset:32768
	ds_read_b128 v[202:205], v150 offset:34816
	ds_read_b128 v[206:209], v253 offset:34816
	ds_read_b128 v[210:213], v150 offset:36864
	ds_read_b128 v[214:217], v253 offset:36864
	ds_read_b128 v[218:221], v150 offset:38912
	ds_read_b128 v[222:225], v253 offset:38912
	global_load_lds_dwordx4 v[232:233], off
	v_lshl_add_u64 v[232:233], s[48:49], 0, v[130:131]
	s_mov_b32 m0, s58
	s_nop 0
	global_load_lds_dwordx4 v[232:233], off
	s_waitcnt vmcnt(8)
	s_waitcnt lgkmcnt(0)
	s_setprio 1
	s_barrier
	v_mfma_f32_16x16x32_bf16 v[124:127], v[160:163], v[194:197], v[124:127]
	v_mfma_f32_16x16x32_bf16 v[124:127], v[164:167], v[198:201], v[124:127]
	v_mfma_f32_16x16x32_bf16 v[116:119], v[172:175], v[198:201], v[116:119]
	v_mfma_f32_16x16x32_bf16 v[116:119], v[168:171], v[194:197], v[116:119]
	v_mfma_f32_16x16x32_bf16 v[100:103], v[168:171], v[202:205], v[100:103]
	v_mfma_f32_16x16x32_bf16 v[100:103], v[172:175], v[206:209], v[100:103]
	v_mfma_f32_16x16x32_bf16 v[108:111], v[164:167], v[206:209], v[108:111]
	v_mfma_f32_16x16x32_bf16 v[108:111], v[160:163], v[202:205], v[108:111]
	v_mfma_f32_16x16x32_bf16 v[92:95], v[160:163], v[210:213], v[92:95]
	v_mfma_f32_16x16x32_bf16 v[92:95], v[164:167], v[214:217], v[92:95]
	v_mfma_f32_16x16x32_bf16 v[84:87], v[172:175], v[214:217], v[84:87]
	v_mfma_f32_16x16x32_bf16 v[84:87], v[168:171], v[210:213], v[84:87]
	v_mfma_f32_16x16x32_bf16 v[68:71], v[168:171], v[218:221], v[68:71]
	v_mfma_f32_16x16x32_bf16 v[68:71], v[172:175], v[222:225], v[68:71]
	v_mfma_f32_16x16x32_bf16 v[76:79], v[164:167], v[222:225], v[76:79]
	v_mfma_f32_16x16x32_bf16 v[76:79], v[160:163], v[218:221], v[76:79]
	s_setprio 0
	s_setprio 1
	v_mfma_f32_16x16x32_bf16 v[120:123], v[176:179], v[194:197], v[120:123]
	v_mfma_f32_16x16x32_bf16 v[120:123], v[180:183], v[198:201], v[120:123]
	v_mfma_f32_16x16x32_bf16 v[112:115], v[190:193], v[198:201], v[112:115]
	v_mfma_f32_16x16x32_bf16 v[112:115], v[186:189], v[194:197], v[112:115]
	v_mfma_f32_16x16x32_bf16 v[96:99], v[186:189], v[202:205], v[96:99]
	v_mfma_f32_16x16x32_bf16 v[96:99], v[190:193], v[206:209], v[96:99]
	v_mfma_f32_16x16x32_bf16 v[104:107], v[180:183], v[206:209], v[104:107]
	v_mfma_f32_16x16x32_bf16 v[104:107], v[176:179], v[202:205], v[104:107]
	v_mfma_f32_16x16x32_bf16 v[88:91], v[176:179], v[210:213], v[88:91]
	v_mfma_f32_16x16x32_bf16 v[88:91], v[180:183], v[214:217], v[88:91]
	v_mfma_f32_16x16x32_bf16 v[80:83], v[190:193], v[214:217], v[80:83]
	v_mfma_f32_16x16x32_bf16 v[80:83], v[186:189], v[210:213], v[80:83]
	v_mfma_f32_16x16x32_bf16 v[64:67], v[186:189], v[218:221], v[64:67]
	v_mfma_f32_16x16x32_bf16 v[64:67], v[190:193], v[222:225], v[64:67]
	v_mfma_f32_16x16x32_bf16 v[72:75], v[180:183], v[222:225], v[72:75]
	v_mfma_f32_16x16x32_bf16 v[72:75], v[176:179], v[218:221], v[72:75]
	s_barrier
	s_setprio 0
	s_add_i32 s48, s76, s52
	v_lshl_add_u64 v[154:155], v[154:155], 0, s[14:15]
	s_mov_b32 m0, s48
	ds_read_b128 v[194:197], v150 offset:49152
	v_xor_b32_e32 v253, 64, v150
	ds_read_b128 v[198:201], v253 offset:49152
	ds_read_b128 v[202:205], v150 offset:51200
	ds_read_b128 v[206:209], v253 offset:51200
	ds_read_b128 v[210:213], v150 offset:53248
	ds_read_b128 v[214:217], v253 offset:53248
	ds_read_b128 v[218:221], v150 offset:55296
	ds_read_b128 v[222:225], v253 offset:55296
	global_load_lds_dwordx4 v[154:155], off
	s_add_i32 m0, s48, 0x2000
	s_add_u32 s46, s46, 0x40080
	v_lshl_add_u64 v[154:155], v[226:227], 0, s[14:15]
	s_addc_u32 s47, s47, 0
	s_add_i32 s48, s77, s52
	global_load_lds_dwordx4 v[154:155], off
	v_lshl_add_u64 v[154:155], s[46:47], 0, v[132:133]
	s_mov_b32 m0, s48
	s_nop 0
	global_load_lds_dwordx4 v[154:155], off
	v_lshl_add_u64 v[154:155], s[46:47], 0, v[128:129]
	s_add_i32 m0, s48, 0x2000
	s_nop 0
	global_load_lds_dwordx4 v[154:155], off
	v_lshl_add_u64 v[154:155], v[228:229], 0, s[14:15]
	s_mov_b32 m0, s60
	s_nop 0
	global_load_lds_dwordx4 v[154:155], off
	v_lshl_add_u64 v[154:155], v[230:231], 0, s[14:15]
	s_mov_b32 m0, s61
	s_nop 0
	global_load_lds_dwordx4 v[154:155], off
	s_waitcnt vmcnt(8)
	s_waitcnt lgkmcnt(0)
	s_setprio 1
	s_barrier
	v_mfma_f32_16x16x32_bf16 v[60:63], v[160:163], v[194:197], v[60:63]
	v_mfma_f32_16x16x32_bf16 v[60:63], v[164:167], v[198:201], v[60:63]
	v_mfma_f32_16x16x32_bf16 v[52:55], v[172:175], v[198:201], v[52:55]
	v_mfma_f32_16x16x32_bf16 v[52:55], v[168:171], v[194:197], v[52:55]
	v_mfma_f32_16x16x32_bf16 v[36:39], v[168:171], v[202:205], v[36:39]
	v_mfma_f32_16x16x32_bf16 v[36:39], v[172:175], v[206:209], v[36:39]
	v_mfma_f32_16x16x32_bf16 v[44:47], v[164:167], v[206:209], v[44:47]
	v_mfma_f32_16x16x32_bf16 v[44:47], v[160:163], v[202:205], v[44:47]
	v_mfma_f32_16x16x32_bf16 v[28:31], v[160:163], v[210:213], v[28:31]
	v_mfma_f32_16x16x32_bf16 v[28:31], v[164:167], v[214:217], v[28:31]
	v_mfma_f32_16x16x32_bf16 v[20:23], v[172:175], v[214:217], v[20:23]
	v_mfma_f32_16x16x32_bf16 v[20:23], v[168:171], v[210:213], v[20:23]
	v_mfma_f32_16x16x32_bf16 v[4:7], v[168:171], v[218:221], v[4:7]
	v_mfma_f32_16x16x32_bf16 v[4:7], v[172:175], v[222:225], v[4:7]
	v_mfma_f32_16x16x32_bf16 v[12:15], v[164:167], v[222:225], v[12:15]
	v_mfma_f32_16x16x32_bf16 v[12:15], v[160:163], v[218:221], v[12:15]
	s_setprio 0
	s_setprio 1
	v_mfma_f32_16x16x32_bf16 v[56:59], v[176:179], v[194:197], v[56:59]
	v_mfma_f32_16x16x32_bf16 v[56:59], v[180:183], v[198:201], v[56:59]
	v_mfma_f32_16x16x32_bf16 v[48:51], v[190:193], v[198:201], v[48:51]
	v_mfma_f32_16x16x32_bf16 v[48:51], v[186:189], v[194:197], v[48:51]
	v_mfma_f32_16x16x32_bf16 v[32:35], v[186:189], v[202:205], v[32:35]
	v_mfma_f32_16x16x32_bf16 v[32:35], v[190:193], v[206:209], v[32:35]
	v_mfma_f32_16x16x32_bf16 v[40:43], v[180:183], v[206:209], v[40:43]
	v_mfma_f32_16x16x32_bf16 v[40:43], v[176:179], v[202:205], v[40:43]
	v_mfma_f32_16x16x32_bf16 v[24:27], v[176:179], v[210:213], v[24:27]
	v_mfma_f32_16x16x32_bf16 v[24:27], v[180:183], v[214:217], v[24:27]
	v_mfma_f32_16x16x32_bf16 v[16:19], v[190:193], v[214:217], v[16:19]
	v_mfma_f32_16x16x32_bf16 v[16:19], v[186:189], v[210:213], v[16:19]
	v_mfma_f32_16x16x32_bf16 v[0:3], v[186:189], v[218:221], v[0:3]
	v_mfma_f32_16x16x32_bf16 v[0:3], v[190:193], v[222:225], v[0:3]
	v_mfma_f32_16x16x32_bf16 v[8:11], v[180:183], v[222:225], v[8:11]
	v_mfma_f32_16x16x32_bf16 v[8:11], v[176:179], v[218:221], v[8:11]
	s_barrier
	s_setprio 0
	s_add_i32 s75, s75, 2
	s_add_u32 s71, s71, 0x100
	s_addc_u32 s74, s74, 0
	s_add_u32 s44, s44, 0x100
	s_addc_u32 s45, s45, 0
	s_branch .LBB0_76
.LBB0_75:
	v_add_u32_e32 v153, s64, v147
	ds_read_b128 v[160:163], v153
	v_xor_b32_e32 v253, 64, v153
	ds_read_b128 v[164:167], v253
	ds_read_b128 v[168:171], v153 offset:2048
	ds_read_b128 v[172:175], v253 offset:2048
	v_add_u32_e32 v153, s65, v147
	ds_read_b128 v[176:179], v153
	v_xor_b32_e32 v253, 64, v153
	ds_read_b128 v[180:183], v253
	ds_read_b128 v[186:189], v153 offset:2048
	ds_read_b128 v[190:193], v253 offset:2048
	s_add_u32 s48, s44, 0xfffc0080
	s_addc_u32 s49, s45, -1
	s_and_b64 s[46:47], s[46:47], exec
	s_cselect_b32 s49, s27, s49
	s_cselect_b32 s48, s68, s48
	s_cselect_b32 s47, s69, s74
	s_cselect_b32 s46, s70, s71
	v_lshl_add_u64 v[154:155], s[44:45], 0, v[138:139]
	s_add_i32 m0, s55, 0xc000
	ds_read_b128 v[194:197], v150
	v_xor_b32_e32 v253, 64, v150
	ds_read_b128 v[198:201], v253
	ds_read_b128 v[202:205], v150 offset:2048
	ds_read_b128 v[206:209], v253 offset:2048
	ds_read_b128 v[210:213], v150 offset:4096
	ds_read_b128 v[214:217], v253 offset:4096
	ds_read_b128 v[218:221], v150 offset:6144
	ds_read_b128 v[222:225], v253 offset:6144
	global_load_lds_dwordx4 v[154:155], off
	v_lshl_add_u64 v[154:155], s[44:45], 0, v[136:137]
	s_add_i32 m0, s55, 0xe000
	s_nop 0
	global_load_lds_dwordx4 v[154:155], off
	s_waitcnt vmcnt(8)
	s_waitcnt lgkmcnt(0)
	s_setprio 1
	s_barrier
	v_mfma_f32_16x16x32_bf16 v[124:127], v[160:163], v[194:197], v[124:127]
	v_mfma_f32_16x16x32_bf16 v[124:127], v[164:167], v[198:201], v[124:127]
	v_mfma_f32_16x16x32_bf16 v[116:119], v[172:175], v[198:201], v[116:119]
	v_mfma_f32_16x16x32_bf16 v[116:119], v[168:171], v[194:197], v[116:119]
	v_mfma_f32_16x16x32_bf16 v[100:103], v[168:171], v[202:205], v[100:103]
	v_mfma_f32_16x16x32_bf16 v[100:103], v[172:175], v[206:209], v[100:103]
	v_mfma_f32_16x16x32_bf16 v[108:111], v[164:167], v[206:209], v[108:111]
	v_mfma_f32_16x16x32_bf16 v[108:111], v[160:163], v[202:205], v[108:111]
	v_mfma_f32_16x16x32_bf16 v[92:95], v[160:163], v[210:213], v[92:95]
	v_mfma_f32_16x16x32_bf16 v[92:95], v[164:167], v[214:217], v[92:95]
	v_mfma_f32_16x16x32_bf16 v[84:87], v[172:175], v[214:217], v[84:87]
	v_mfma_f32_16x16x32_bf16 v[84:87], v[168:171], v[210:213], v[84:87]
	v_mfma_f32_16x16x32_bf16 v[68:71], v[168:171], v[218:221], v[68:71]
	v_mfma_f32_16x16x32_bf16 v[68:71], v[172:175], v[222:225], v[68:71]
	v_mfma_f32_16x16x32_bf16 v[76:79], v[164:167], v[222:225], v[76:79]
	v_mfma_f32_16x16x32_bf16 v[76:79], v[160:163], v[218:221], v[76:79]
	s_setprio 0
	s_setprio 1
	v_mfma_f32_16x16x32_bf16 v[120:123], v[176:179], v[194:197], v[120:123]
	v_mfma_f32_16x16x32_bf16 v[120:123], v[180:183], v[198:201], v[120:123]
	v_mfma_f32_16x16x32_bf16 v[112:115], v[190:193], v[198:201], v[112:115]
	v_mfma_f32_16x16x32_bf16 v[112:115], v[186:189], v[194:197], v[112:115]
	v_mfma_f32_16x16x32_bf16 v[96:99], v[186:189], v[202:205], v[96:99]
	v_mfma_f32_16x16x32_bf16 v[96:99], v[190:193], v[206:209], v[96:99]
	v_mfma_f32_16x16x32_bf16 v[104:107], v[180:183], v[206:209], v[104:107]
	v_mfma_f32_16x16x32_bf16 v[104:107], v[176:179], v[202:205], v[104:107]
	v_mfma_f32_16x16x32_bf16 v[88:91], v[176:179], v[210:213], v[88:91]
	v_mfma_f32_16x16x32_bf16 v[88:91], v[180:183], v[214:217], v[88:91]
	v_mfma_f32_16x16x32_bf16 v[80:83], v[190:193], v[214:217], v[80:83]
	v_mfma_f32_16x16x32_bf16 v[80:83], v[186:189], v[210:213], v[80:83]
	v_mfma_f32_16x16x32_bf16 v[64:67], v[186:189], v[218:221], v[64:67]
	v_mfma_f32_16x16x32_bf16 v[64:67], v[190:193], v[222:225], v[64:67]
	v_mfma_f32_16x16x32_bf16 v[72:75], v[180:183], v[222:225], v[72:75]
	v_mfma_f32_16x16x32_bf16 v[72:75], v[176:179], v[218:221], v[72:75]
	s_barrier
	s_setprio 0
	s_add_i32 s76, s64, s52
	v_lshl_add_u64 v[154:155], s[46:47], 0, v[132:133]
	s_mov_b32 m0, s76
	ds_read_b128 v[194:197], v150 offset:16384
	v_xor_b32_e32 v253, 64, v150
	ds_read_b128 v[198:201], v253 offset:16384
	ds_read_b128 v[202:205], v150 offset:18432
	ds_read_b128 v[206:209], v253 offset:18432
	ds_read_b128 v[210:213], v150 offset:20480
	ds_read_b128 v[214:217], v253 offset:20480
	ds_read_b128 v[218:221], v150 offset:22528
	ds_read_b128 v[222:225], v253 offset:22528
	global_load_lds_dwordx4 v[154:155], off
	s_add_i32 m0, s76, 0x2000
	s_add_u32 s76, s46, 0x40000
	v_lshl_add_u64 v[226:227], s[46:47], 0, v[128:129]
	s_addc_u32 s77, s47, 0
	s_add_i32 s78, s65, s52
	global_load_lds_dwordx4 v[226:227], off
	v_lshl_add_u64 v[228:229], s[76:77], 0, v[132:133]
	s_mov_b32 m0, s78
	v_lshl_add_u64 v[230:231], s[48:49], 0, v[130:131]
	global_load_lds_dwordx4 v[228:229], off
	v_lshl_add_u64 v[228:229], s[76:77], 0, v[128:129]
	s_add_i32 m0, s78, 0x2000
	s_nop 0
	global_load_lds_dwordx4 v[228:229], off
	v_lshl_add_u64 v[228:229], s[48:49], 0, v[134:135]
	s_mov_b32 m0, s55
	s_nop 0
	global_load_lds_dwordx4 v[228:229], off
	s_mov_b32 m0, s56
	s_nop 0
	global_load_lds_dwordx4 v[230:231], off
	s_waitcnt vmcnt(8)
	s_waitcnt lgkmcnt(0)
	s_setprio 1
	s_barrier
	v_mfma_f32_16x16x32_bf16 v[60:63], v[160:163], v[194:197], v[60:63]
	v_mfma_f32_16x16x32_bf16 v[60:63], v[164:167], v[198:201], v[60:63]
	v_mfma_f32_16x16x32_bf16 v[52:55], v[172:175], v[198:201], v[52:55]
	v_mfma_f32_16x16x32_bf16 v[52:55], v[168:171], v[194:197], v[52:55]
	v_mfma_f32_16x16x32_bf16 v[36:39], v[168:171], v[202:205], v[36:39]
	v_mfma_f32_16x16x32_bf16 v[36:39], v[172:175], v[206:209], v[36:39]
	v_mfma_f32_16x16x32_bf16 v[44:47], v[164:167], v[206:209], v[44:47]
	v_mfma_f32_16x16x32_bf16 v[44:47], v[160:163], v[202:205], v[44:47]
	v_mfma_f32_16x16x32_bf16 v[28:31], v[160:163], v[210:213], v[28:31]
	v_mfma_f32_16x16x32_bf16 v[28:31], v[164:167], v[214:217], v[28:31]
	v_mfma_f32_16x16x32_bf16 v[20:23], v[172:175], v[214:217], v[20:23]
	v_mfma_f32_16x16x32_bf16 v[20:23], v[168:171], v[210:213], v[20:23]
	v_mfma_f32_16x16x32_bf16 v[4:7], v[168:171], v[218:221], v[4:7]
	v_mfma_f32_16x16x32_bf16 v[4:7], v[172:175], v[222:225], v[4:7]
	v_mfma_f32_16x16x32_bf16 v[12:15], v[164:167], v[222:225], v[12:15]
	v_mfma_f32_16x16x32_bf16 v[12:15], v[160:163], v[218:221], v[12:15]
	s_setprio 0
	s_setprio 1
	v_mfma_f32_16x16x32_bf16 v[56:59], v[176:179], v[194:197], v[56:59]
	v_mfma_f32_16x16x32_bf16 v[56:59], v[180:183], v[198:201], v[56:59]
	v_mfma_f32_16x16x32_bf16 v[48:51], v[190:193], v[198:201], v[48:51]
	v_mfma_f32_16x16x32_bf16 v[48:51], v[186:189], v[194:197], v[48:51]
	v_mfma_f32_16x16x32_bf16 v[32:35], v[186:189], v[202:205], v[32:35]
	v_mfma_f32_16x16x32_bf16 v[32:35], v[190:193], v[206:209], v[32:35]
	v_mfma_f32_16x16x32_bf16 v[40:43], v[180:183], v[206:209], v[40:43]
	v_mfma_f32_16x16x32_bf16 v[40:43], v[176:179], v[202:205], v[40:43]
	v_mfma_f32_16x16x32_bf16 v[24:27], v[176:179], v[210:213], v[24:27]
	v_mfma_f32_16x16x32_bf16 v[24:27], v[180:183], v[214:217], v[24:27]
	v_mfma_f32_16x16x32_bf16 v[16:19], v[190:193], v[214:217], v[16:19]
	v_mfma_f32_16x16x32_bf16 v[16:19], v[186:189], v[210:213], v[16:19]
	v_mfma_f32_16x16x32_bf16 v[0:3], v[186:189], v[218:221], v[0:3]
	v_mfma_f32_16x16x32_bf16 v[0:3], v[190:193], v[222:225], v[0:3]
	v_mfma_f32_16x16x32_bf16 v[8:11], v[180:183], v[222:225], v[8:11]
	v_mfma_f32_16x16x32_bf16 v[8:11], v[176:179], v[218:221], v[8:11]
	s_barrier
	s_setprio 0
	s_add_i32 s76, 0, 0x18000
	v_add_u32_e32 v153, s76, v147
	s_add_i32 s77, 0, 0x1c000
	ds_read_b128 v[160:163], v153
	v_xor_b32_e32 v253, 64, v153
	ds_read_b128 v[164:167], v253
	ds_read_b128 v[168:171], v153 offset:2048
	ds_read_b128 v[172:175], v253 offset:2048
	v_add_u32_e32 v153, s77, v147
	ds_read_b128 v[176:179], v153
	v_xor_b32_e32 v253, 64, v153
	ds_read_b128 v[180:183], v253
	ds_read_b128 v[186:189], v153 offset:2048
	ds_read_b128 v[190:193], v253 offset:2048
	s_add_u32 s48, s48, 0x40000
	s_addc_u32 s49, s49, 0
	s_mov_b32 m0, s57
	v_lshl_add_u64 v[232:233], s[48:49], 0, v[134:135]
	ds_read_b128 v[194:197], v150 offset:32768
	v_xor_b32_e32 v253, 64, v150
	ds_read_b128 v[198:201], v253 offset:32768
	ds_read_b128 v[202:205], v150 offset:34816
	ds_read_b128 v[206:209], v253 offset:34816
	ds_read_b128 v[210:213], v150 offset:36864
	ds_read_b128 v[214:217], v253 offset:36864
	ds_read_b128 v[218:221], v150 offset:38912
	ds_read_b128 v[222:225], v253 offset:38912
	global_load_lds_dwordx4 v[232:233], off
	v_lshl_add_u64 v[232:233], s[48:49], 0, v[130:131]
	s_mov_b32 m0, s58
	s_nop 0
	global_load_lds_dwordx4 v[232:233], off
	s_waitcnt vmcnt(8)
	s_waitcnt lgkmcnt(0)
	s_setprio 1
	s_barrier
	v_mfma_f32_16x16x32_bf16 v[124:127], v[160:163], v[194:197], v[124:127]
	v_mfma_f32_16x16x32_bf16 v[124:127], v[164:167], v[198:201], v[124:127]
	v_mfma_f32_16x16x32_bf16 v[116:119], v[172:175], v[198:201], v[116:119]
	v_mfma_f32_16x16x32_bf16 v[116:119], v[168:171], v[194:197], v[116:119]
	v_mfma_f32_16x16x32_bf16 v[100:103], v[168:171], v[202:205], v[100:103]
	v_mfma_f32_16x16x32_bf16 v[100:103], v[172:175], v[206:209], v[100:103]
	v_mfma_f32_16x16x32_bf16 v[108:111], v[164:167], v[206:209], v[108:111]
	v_mfma_f32_16x16x32_bf16 v[108:111], v[160:163], v[202:205], v[108:111]
	v_mfma_f32_16x16x32_bf16 v[92:95], v[160:163], v[210:213], v[92:95]
	v_mfma_f32_16x16x32_bf16 v[92:95], v[164:167], v[214:217], v[92:95]
	v_mfma_f32_16x16x32_bf16 v[84:87], v[172:175], v[214:217], v[84:87]
	v_mfma_f32_16x16x32_bf16 v[84:87], v[168:171], v[210:213], v[84:87]
	v_mfma_f32_16x16x32_bf16 v[68:71], v[168:171], v[218:221], v[68:71]
	v_mfma_f32_16x16x32_bf16 v[68:71], v[172:175], v[222:225], v[68:71]
	v_mfma_f32_16x16x32_bf16 v[76:79], v[164:167], v[222:225], v[76:79]
	v_mfma_f32_16x16x32_bf16 v[76:79], v[160:163], v[218:221], v[76:79]
	s_setprio 0
	s_setprio 1
	v_mfma_f32_16x16x32_bf16 v[120:123], v[176:179], v[194:197], v[120:123]
	v_mfma_f32_16x16x32_bf16 v[120:123], v[180:183], v[198:201], v[120:123]
	v_mfma_f32_16x16x32_bf16 v[112:115], v[190:193], v[198:201], v[112:115]
	v_mfma_f32_16x16x32_bf16 v[112:115], v[186:189], v[194:197], v[112:115]
	v_mfma_f32_16x16x32_bf16 v[96:99], v[186:189], v[202:205], v[96:99]
	v_mfma_f32_16x16x32_bf16 v[96:99], v[190:193], v[206:209], v[96:99]
	v_mfma_f32_16x16x32_bf16 v[104:107], v[180:183], v[206:209], v[104:107]
	v_mfma_f32_16x16x32_bf16 v[104:107], v[176:179], v[202:205], v[104:107]
	v_mfma_f32_16x16x32_bf16 v[88:91], v[176:179], v[210:213], v[88:91]
	v_mfma_f32_16x16x32_bf16 v[88:91], v[180:183], v[214:217], v[88:91]
	v_mfma_f32_16x16x32_bf16 v[80:83], v[190:193], v[214:217], v[80:83]
	v_mfma_f32_16x16x32_bf16 v[80:83], v[186:189], v[210:213], v[80:83]
	v_mfma_f32_16x16x32_bf16 v[64:67], v[186:189], v[218:221], v[64:67]
	v_mfma_f32_16x16x32_bf16 v[64:67], v[190:193], v[222:225], v[64:67]
	v_mfma_f32_16x16x32_bf16 v[72:75], v[180:183], v[222:225], v[72:75]
	v_mfma_f32_16x16x32_bf16 v[72:75], v[176:179], v[218:221], v[72:75]
	s_barrier
	s_setprio 0
	s_add_i32 s48, s76, s52
	v_lshl_add_u64 v[154:155], v[154:155], 0, s[14:15]
	s_mov_b32 m0, s48
	ds_read_b128 v[194:197], v150 offset:49152
	v_xor_b32_e32 v253, 64, v150
	ds_read_b128 v[198:201], v253 offset:49152
	ds_read_b128 v[202:205], v150 offset:51200
	ds_read_b128 v[206:209], v253 offset:51200
	ds_read_b128 v[210:213], v150 offset:53248
	ds_read_b128 v[214:217], v253 offset:53248
	ds_read_b128 v[218:221], v150 offset:55296
	ds_read_b128 v[222:225], v253 offset:55296
	global_load_lds_dwordx4 v[154:155], off
	s_add_i32 m0, s48, 0x2000
	s_add_u32 s46, s46, 0x40080
	v_lshl_add_u64 v[154:155], v[226:227], 0, s[14:15]
	s_addc_u32 s47, s47, 0
	s_add_i32 s48, s77, s52
	global_load_lds_dwordx4 v[154:155], off
	v_lshl_add_u64 v[154:155], s[46:47], 0, v[132:133]
	s_mov_b32 m0, s48
	s_nop 0
	global_load_lds_dwordx4 v[154:155], off
	v_lshl_add_u64 v[154:155], s[46:47], 0, v[128:129]
	s_add_i32 m0, s48, 0x2000
	s_nop 0
	global_load_lds_dwordx4 v[154:155], off
	v_lshl_add_u64 v[154:155], v[228:229], 0, s[14:15]
	s_mov_b32 m0, s60
	s_nop 0
	global_load_lds_dwordx4 v[154:155], off
	v_lshl_add_u64 v[154:155], v[230:231], 0, s[14:15]
	s_mov_b32 m0, s61
	s_nop 0
	global_load_lds_dwordx4 v[154:155], off
	s_waitcnt vmcnt(8)
	s_waitcnt lgkmcnt(0)
	s_setprio 1
	s_barrier
	v_mfma_f32_16x16x32_bf16 v[60:63], v[160:163], v[194:197], v[60:63]
	v_mfma_f32_16x16x32_bf16 v[60:63], v[164:167], v[198:201], v[60:63]
	v_mfma_f32_16x16x32_bf16 v[52:55], v[172:175], v[198:201], v[52:55]
	v_mfma_f32_16x16x32_bf16 v[52:55], v[168:171], v[194:197], v[52:55]
	v_mfma_f32_16x16x32_bf16 v[36:39], v[168:171], v[202:205], v[36:39]
	v_mfma_f32_16x16x32_bf16 v[36:39], v[172:175], v[206:209], v[36:39]
	v_mfma_f32_16x16x32_bf16 v[44:47], v[164:167], v[206:209], v[44:47]
	v_mfma_f32_16x16x32_bf16 v[44:47], v[160:163], v[202:205], v[44:47]
	v_mfma_f32_16x16x32_bf16 v[28:31], v[160:163], v[210:213], v[28:31]
	v_mfma_f32_16x16x32_bf16 v[28:31], v[164:167], v[214:217], v[28:31]
	v_mfma_f32_16x16x32_bf16 v[20:23], v[172:175], v[214:217], v[20:23]
	v_mfma_f32_16x16x32_bf16 v[20:23], v[168:171], v[210:213], v[20:23]
	v_mfma_f32_16x16x32_bf16 v[4:7], v[168:171], v[218:221], v[4:7]
	v_mfma_f32_16x16x32_bf16 v[4:7], v[172:175], v[222:225], v[4:7]
	v_mfma_f32_16x16x32_bf16 v[12:15], v[164:167], v[222:225], v[12:15]
	v_mfma_f32_16x16x32_bf16 v[12:15], v[160:163], v[218:221], v[12:15]
	s_setprio 0
	s_setprio 1
	v_mfma_f32_16x16x32_bf16 v[56:59], v[176:179], v[194:197], v[56:59]
	v_mfma_f32_16x16x32_bf16 v[56:59], v[180:183], v[198:201], v[56:59]
	v_mfma_f32_16x16x32_bf16 v[48:51], v[190:193], v[198:201], v[48:51]
	v_mfma_f32_16x16x32_bf16 v[48:51], v[186:189], v[194:197], v[48:51]
	v_mfma_f32_16x16x32_bf16 v[32:35], v[186:189], v[202:205], v[32:35]
	v_mfma_f32_16x16x32_bf16 v[32:35], v[190:193], v[206:209], v[32:35]
	v_mfma_f32_16x16x32_bf16 v[40:43], v[180:183], v[206:209], v[40:43]
	v_mfma_f32_16x16x32_bf16 v[40:43], v[176:179], v[202:205], v[40:43]
	v_mfma_f32_16x16x32_bf16 v[24:27], v[176:179], v[210:213], v[24:27]
	v_mfma_f32_16x16x32_bf16 v[24:27], v[180:183], v[214:217], v[24:27]
	v_mfma_f32_16x16x32_bf16 v[16:19], v[190:193], v[214:217], v[16:19]
	v_mfma_f32_16x16x32_bf16 v[16:19], v[186:189], v[210:213], v[16:19]
	v_mfma_f32_16x16x32_bf16 v[0:3], v[186:189], v[218:221], v[0:3]
	v_mfma_f32_16x16x32_bf16 v[0:3], v[190:193], v[222:225], v[0:3]
	v_mfma_f32_16x16x32_bf16 v[8:11], v[180:183], v[222:225], v[8:11]
	v_mfma_f32_16x16x32_bf16 v[8:11], v[176:179], v[218:221], v[8:11]
	s_barrier
	s_setprio 0
	s_add_i32 s75, s75, 2
	s_add_u32 s71, s71, 0x100
	s_addc_u32 s74, s74, 0
	s_add_u32 s44, s44, 0x100
	s_addc_u32 s45, s45, 0
	s_cmp_gt_u32 s75, 13
	s_cbranch_scc1 .LBB0_78

.Llast_0:
	v_add_u32_e32 v153, s64, v147
	ds_read_b128 v[160:163], v153
	v_xor_b32_e32 v253, 64, v153
	ds_read_b128 v[164:167], v253
	ds_read_b128 v[168:171], v153 offset:2048
	ds_read_b128 v[172:175], v253 offset:2048
	v_add_u32_e32 v153, s65, v147
	ds_read_b128 v[176:179], v153
	v_xor_b32_e32 v253, 64, v153
	ds_read_b128 v[180:183], v253
	ds_read_b128 v[186:189], v153 offset:2048
	ds_read_b128 v[190:193], v253 offset:2048
	s_add_u32 s48, s44, 0xfffc0080
	s_addc_u32 s49, s45, -1
	s_and_b64 s[46:47], s[46:47], exec
	s_cselect_b32 s49, s27, s49
	s_cselect_b32 s48, s68, s48
	s_cselect_b32 s47, s69, s74
	s_cselect_b32 s46, s70, s71
	v_lshl_add_u64 v[154:155], s[44:45], 0, v[138:139]
	s_add_i32 m0, s55, 0xc000
	ds_read_b128 v[194:197], v150
	v_xor_b32_e32 v253, 64, v150
	ds_read_b128 v[198:201], v253
	ds_read_b128 v[202:205], v150 offset:2048
	ds_read_b128 v[206:209], v253 offset:2048
	ds_read_b128 v[210:213], v150 offset:4096
	ds_read_b128 v[214:217], v253 offset:4096
	ds_read_b128 v[218:221], v150 offset:6144
	ds_read_b128 v[222:225], v253 offset:6144
	global_load_lds_dwordx4 v[154:155], off
	v_lshl_add_u64 v[154:155], s[44:45], 0, v[136:137]
	s_add_i32 m0, s55, 0xe000
	s_nop 0
	global_load_lds_dwordx4 v[154:155], off
	s_waitcnt vmcnt(8)
	s_waitcnt lgkmcnt(0)
	s_setprio 1
	s_barrier
	v_mfma_f32_16x16x32_bf16 v[124:127], v[160:163], v[194:197], v[124:127]
	v_mfma_f32_16x16x32_bf16 v[124:127], v[164:167], v[198:201], v[124:127]
	v_mfma_f32_16x16x32_bf16 v[116:119], v[172:175], v[198:201], v[116:119]
	v_mfma_f32_16x16x32_bf16 v[116:119], v[168:171], v[194:197], v[116:119]
	v_mfma_f32_16x16x32_bf16 v[100:103], v[168:171], v[202:205], v[100:103]
	v_mfma_f32_16x16x32_bf16 v[100:103], v[172:175], v[206:209], v[100:103]
	v_mfma_f32_16x16x32_bf16 v[108:111], v[164:167], v[206:209], v[108:111]
	v_mfma_f32_16x16x32_bf16 v[108:111], v[160:163], v[202:205], v[108:111]
	v_mfma_f32_16x16x32_bf16 v[92:95], v[160:163], v[210:213], v[92:95]
	v_mfma_f32_16x16x32_bf16 v[92:95], v[164:167], v[214:217], v[92:95]
	v_mfma_f32_16x16x32_bf16 v[84:87], v[172:175], v[214:217], v[84:87]
	v_mfma_f32_16x16x32_bf16 v[84:87], v[168:171], v[210:213], v[84:87]
	v_mfma_f32_16x16x32_bf16 v[68:71], v[168:171], v[218:221], v[68:71]
	v_mfma_f32_16x16x32_bf16 v[68:71], v[172:175], v[222:225], v[68:71]
	v_mfma_f32_16x16x32_bf16 v[76:79], v[164:167], v[222:225], v[76:79]
	v_mfma_f32_16x16x32_bf16 v[76:79], v[160:163], v[218:221], v[76:79]
	s_setprio 0
	s_setprio 1
	v_mfma_f32_16x16x32_bf16 v[120:123], v[176:179], v[194:197], v[120:123]
	v_mfma_f32_16x16x32_bf16 v[120:123], v[180:183], v[198:201], v[120:123]
	v_mfma_f32_16x16x32_bf16 v[112:115], v[190:193], v[198:201], v[112:115]
	v_mfma_f32_16x16x32_bf16 v[112:115], v[186:189], v[194:197], v[112:115]
	v_mfma_f32_16x16x32_bf16 v[96:99], v[186:189], v[202:205], v[96:99]
	v_mfma_f32_16x16x32_bf16 v[96:99], v[190:193], v[206:209], v[96:99]
	v_mfma_f32_16x16x32_bf16 v[104:107], v[180:183], v[206:209], v[104:107]
	v_mfma_f32_16x16x32_bf16 v[104:107], v[176:179], v[202:205], v[104:107]
	v_mfma_f32_16x16x32_bf16 v[88:91], v[176:179], v[210:213], v[88:91]
	v_mfma_f32_16x16x32_bf16 v[88:91], v[180:183], v[214:217], v[88:91]
	v_mfma_f32_16x16x32_bf16 v[80:83], v[190:193], v[214:217], v[80:83]
	v_mfma_f32_16x16x32_bf16 v[80:83], v[186:189], v[210:213], v[80:83]
	v_mfma_f32_16x16x32_bf16 v[64:67], v[186:189], v[218:221], v[64:67]
	v_mfma_f32_16x16x32_bf16 v[64:67], v[190:193], v[222:225], v[64:67]
	v_mfma_f32_16x16x32_bf16 v[72:75], v[180:183], v[222:225], v[72:75]
	v_mfma_f32_16x16x32_bf16 v[72:75], v[176:179], v[218:221], v[72:75]
	s_barrier
	s_setprio 0
	s_add_i32 s76, s64, s52
	v_lshl_add_u64 v[154:155], s[46:47], 0, v[132:133]
	s_mov_b32 m0, s76
	ds_read_b128 v[194:197], v150 offset:16384
	v_xor_b32_e32 v253, 64, v150
	ds_read_b128 v[198:201], v253 offset:16384
	ds_read_b128 v[202:205], v150 offset:18432
	ds_read_b128 v[206:209], v253 offset:18432
	ds_read_b128 v[210:213], v150 offset:20480
	ds_read_b128 v[214:217], v253 offset:20480
	ds_read_b128 v[218:221], v150 offset:22528
	ds_read_b128 v[222:225], v253 offset:22528
	global_load_lds_dwordx4 v[154:155], off
	s_add_i32 m0, s76, 0x2000
	s_add_u32 s76, s46, 0x40000
	v_lshl_add_u64 v[226:227], s[46:47], 0, v[128:129]
	s_addc_u32 s77, s47, 0
	s_add_i32 s78, s65, s52
	global_load_lds_dwordx4 v[226:227], off
	v_lshl_add_u64 v[228:229], s[76:77], 0, v[132:133]
	s_mov_b32 m0, s78
	v_lshl_add_u64 v[230:231], s[48:49], 0, v[130:131]
	global_load_lds_dwordx4 v[228:229], off
	v_lshl_add_u64 v[228:229], s[76:77], 0, v[128:129]
	s_add_i32 m0, s78, 0x2000
	s_nop 0
	global_load_lds_dwordx4 v[228:229], off
	v_lshl_add_u64 v[228:229], s[48:49], 0, v[134:135]
	s_mov_b32 m0, s55
	s_nop 0
	global_load_lds_dwordx4 v[228:229], off
	s_mov_b32 m0, s56
	s_nop 0
	global_load_lds_dwordx4 v[230:231], off
	s_waitcnt vmcnt(8)
	s_waitcnt lgkmcnt(0)
	s_setprio 1
	s_barrier
	v_mfma_f32_16x16x32_bf16 v[60:63], v[160:163], v[194:197], v[60:63]
	v_mfma_f32_16x16x32_bf16 v[60:63], v[164:167], v[198:201], v[60:63]
	v_mfma_f32_16x16x32_bf16 v[52:55], v[172:175], v[198:201], v[52:55]
	v_mfma_f32_16x16x32_bf16 v[52:55], v[168:171], v[194:197], v[52:55]
	v_mfma_f32_16x16x32_bf16 v[36:39], v[168:171], v[202:205], v[36:39]
	v_mfma_f32_16x16x32_bf16 v[36:39], v[172:175], v[206:209], v[36:39]
	v_mfma_f32_16x16x32_bf16 v[44:47], v[164:167], v[206:209], v[44:47]
	v_mfma_f32_16x16x32_bf16 v[44:47], v[160:163], v[202:205], v[44:47]
	v_mfma_f32_16x16x32_bf16 v[28:31], v[160:163], v[210:213], v[28:31]
	v_mfma_f32_16x16x32_bf16 v[28:31], v[164:167], v[214:217], v[28:31]
	v_mfma_f32_16x16x32_bf16 v[20:23], v[172:175], v[214:217], v[20:23]
	v_mfma_f32_16x16x32_bf16 v[20:23], v[168:171], v[210:213], v[20:23]
	v_mfma_f32_16x16x32_bf16 v[4:7], v[168:171], v[218:221], v[4:7]
	v_mfma_f32_16x16x32_bf16 v[4:7], v[172:175], v[222:225], v[4:7]
	v_mfma_f32_16x16x32_bf16 v[12:15], v[164:167], v[222:225], v[12:15]
	v_mfma_f32_16x16x32_bf16 v[12:15], v[160:163], v[218:221], v[12:15]
	s_setprio 0
	s_setprio 1
	v_mfma_f32_16x16x32_bf16 v[56:59], v[176:179], v[194:197], v[56:59]
	v_mfma_f32_16x16x32_bf16 v[56:59], v[180:183], v[198:201], v[56:59]
	v_mfma_f32_16x16x32_bf16 v[48:51], v[190:193], v[198:201], v[48:51]
	v_mfma_f32_16x16x32_bf16 v[48:51], v[186:189], v[194:197], v[48:51]
	v_mfma_f32_16x16x32_bf16 v[32:35], v[186:189], v[202:205], v[32:35]
	v_mfma_f32_16x16x32_bf16 v[32:35], v[190:193], v[206:209], v[32:35]
	v_mfma_f32_16x16x32_bf16 v[40:43], v[180:183], v[206:209], v[40:43]
	v_mfma_f32_16x16x32_bf16 v[40:43], v[176:179], v[202:205], v[40:43]
	v_mfma_f32_16x16x32_bf16 v[24:27], v[176:179], v[210:213], v[24:27]
	v_mfma_f32_16x16x32_bf16 v[24:27], v[180:183], v[214:217], v[24:27]
	v_mfma_f32_16x16x32_bf16 v[16:19], v[190:193], v[214:217], v[16:19]
	v_mfma_f32_16x16x32_bf16 v[16:19], v[186:189], v[210:213], v[16:19]
	v_mfma_f32_16x16x32_bf16 v[0:3], v[186:189], v[218:221], v[0:3]
	v_mfma_f32_16x16x32_bf16 v[0:3], v[190:193], v[222:225], v[0:3]
	v_mfma_f32_16x16x32_bf16 v[8:11], v[180:183], v[222:225], v[8:11]
	v_mfma_f32_16x16x32_bf16 v[8:11], v[176:179], v[218:221], v[8:11]
	s_barrier
	s_setprio 0
	s_add_i32 s76, 0, 0x18000
	v_add_u32_e32 v153, s76, v147
	s_add_i32 s77, 0, 0x1c000
	ds_read_b128 v[160:163], v153
	v_xor_b32_e32 v253, 64, v153
	ds_read_b128 v[164:167], v253
	ds_read_b128 v[168:171], v153 offset:2048
	ds_read_b128 v[172:175], v253 offset:2048
	v_add_u32_e32 v153, s77, v147
	ds_read_b128 v[176:179], v153
	v_xor_b32_e32 v253, 64, v153
	ds_read_b128 v[180:183], v253
	ds_read_b128 v[186:189], v153 offset:2048
	ds_read_b128 v[190:193], v253 offset:2048
	s_add_u32 s48, s48, 0x40000
	s_addc_u32 s49, s49, 0
	s_mov_b32 m0, s57
	v_lshl_add_u64 v[232:233], s[48:49], 0, v[134:135]
	ds_read_b128 v[194:197], v150 offset:32768
	v_xor_b32_e32 v253, 64, v150
	ds_read_b128 v[198:201], v253 offset:32768
	ds_read_b128 v[202:205], v150 offset:34816
	ds_read_b128 v[206:209], v253 offset:34816
	ds_read_b128 v[210:213], v150 offset:36864
	ds_read_b128 v[214:217], v253 offset:36864
	ds_read_b128 v[218:221], v150 offset:38912
	ds_read_b128 v[222:225], v253 offset:38912
	global_load_lds_dwordx4 v[232:233], off
	v_lshl_add_u64 v[232:233], s[48:49], 0, v[130:131]
	s_mov_b32 m0, s58
	s_nop 0
	global_load_lds_dwordx4 v[232:233], off
	s_waitcnt vmcnt(8)
	s_waitcnt lgkmcnt(0)
	s_setprio 1
	s_barrier
	v_mfma_f32_16x16x32_bf16 v[124:127], v[160:163], v[194:197], v[124:127]
	v_mfma_f32_16x16x32_bf16 v[124:127], v[164:167], v[198:201], v[124:127]
	v_mfma_f32_16x16x32_bf16 v[116:119], v[172:175], v[198:201], v[116:119]
	v_mfma_f32_16x16x32_bf16 v[116:119], v[168:171], v[194:197], v[116:119]
	v_mfma_f32_16x16x32_bf16 v[100:103], v[168:171], v[202:205], v[100:103]
	v_mfma_f32_16x16x32_bf16 v[100:103], v[172:175], v[206:209], v[100:103]
	v_mfma_f32_16x16x32_bf16 v[108:111], v[164:167], v[206:209], v[108:111]
	v_mfma_f32_16x16x32_bf16 v[108:111], v[160:163], v[202:205], v[108:111]
	v_mfma_f32_16x16x32_bf16 v[92:95], v[160:163], v[210:213], v[92:95]
	v_mfma_f32_16x16x32_bf16 v[92:95], v[164:167], v[214:217], v[92:95]
	v_mfma_f32_16x16x32_bf16 v[84:87], v[172:175], v[214:217], v[84:87]
	v_mfma_f32_16x16x32_bf16 v[84:87], v[168:171], v[210:213], v[84:87]
	v_mfma_f32_16x16x32_bf16 v[68:71], v[168:171], v[218:221], v[68:71]
	v_mfma_f32_16x16x32_bf16 v[68:71], v[172:175], v[222:225], v[68:71]
	v_mfma_f32_16x16x32_bf16 v[76:79], v[164:167], v[222:225], v[76:79]
	v_mfma_f32_16x16x32_bf16 v[76:79], v[160:163], v[218:221], v[76:79]
	s_setprio 0
	s_setprio 1
	v_mfma_f32_16x16x32_bf16 v[120:123], v[176:179], v[194:197], v[120:123]
	v_mfma_f32_16x16x32_bf16 v[120:123], v[180:183], v[198:201], v[120:123]
	v_mfma_f32_16x16x32_bf16 v[112:115], v[190:193], v[198:201], v[112:115]
	v_mfma_f32_16x16x32_bf16 v[112:115], v[186:189], v[194:197], v[112:115]
	v_mfma_f32_16x16x32_bf16 v[96:99], v[186:189], v[202:205], v[96:99]
	v_mfma_f32_16x16x32_bf16 v[96:99], v[190:193], v[206:209], v[96:99]
	v_mfma_f32_16x16x32_bf16 v[104:107], v[180:183], v[206:209], v[104:107]
	v_mfma_f32_16x16x32_bf16 v[104:107], v[176:179], v[202:205], v[104:107]
	v_mfma_f32_16x16x32_bf16 v[88:91], v[176:179], v[210:213], v[88:91]
	v_mfma_f32_16x16x32_bf16 v[88:91], v[180:183], v[214:217], v[88:91]
	v_mfma_f32_16x16x32_bf16 v[80:83], v[190:193], v[214:217], v[80:83]
	v_mfma_f32_16x16x32_bf16 v[80:83], v[186:189], v[210:213], v[80:83]
	v_mfma_f32_16x16x32_bf16 v[64:67], v[186:189], v[218:221], v[64:67]
	v_mfma_f32_16x16x32_bf16 v[64:67], v[190:193], v[222:225], v[64:67]
	v_mfma_f32_16x16x32_bf16 v[72:75], v[180:183], v[222:225], v[72:75]
	v_mfma_f32_16x16x32_bf16 v[72:75], v[176:179], v[218:221], v[72:75]
	s_barrier
	s_setprio 0
	v_add_u32_e32 v234, 0x21000, v151
	ds_read_b128 v[236:239], v234
	ds_read_b128 v[240:243], v234 offset:256
	ds_read_b128 v[244:247], v234 offset:512
	ds_read_b128 v[248:251], v234 offset:768
	v_add_u32_e32 v235, s23, v146
	v_mul_u32_u24_e32 v235, 0x1600, v235
	v_lshl_or_b32 v234, s67, 7, v149
	v_lshl_add_u32 v235, v234, 1, v235
	s_add_i32 s48, s76, s52
	v_lshl_add_u64 v[154:155], v[154:155], 0, s[14:15]
	s_mov_b32 m0, s48
	ds_read_b128 v[194:197], v150 offset:49152
	v_xor_b32_e32 v253, 64, v150
	ds_read_b128 v[198:201], v253 offset:49152
	ds_read_b128 v[202:205], v150 offset:51200
	ds_read_b128 v[206:209], v253 offset:51200
	ds_read_b128 v[210:213], v150 offset:53248
	ds_read_b128 v[214:217], v253 offset:53248
	ds_read_b128 v[218:221], v150 offset:55296
	ds_read_b128 v[222:225], v253 offset:55296
	global_load_lds_dwordx4 v[154:155], off
	s_add_i32 m0, s48, 0x2000
	s_add_u32 s46, s46, 0x40080
	v_lshl_add_u64 v[154:155], v[226:227], 0, s[14:15]
	s_addc_u32 s47, s47, 0
	s_add_i32 s48, s77, s52
	global_load_lds_dwordx4 v[154:155], off
	v_lshl_add_u64 v[154:155], s[46:47], 0, v[132:133]
	s_mov_b32 m0, s48
	s_nop 0
	global_load_lds_dwordx4 v[154:155], off
	v_lshl_add_u64 v[154:155], s[46:47], 0, v[128:129]
	s_add_i32 m0, s48, 0x2000
	s_nop 0
	global_load_lds_dwordx4 v[154:155], off
	v_lshl_add_u64 v[154:155], v[228:229], 0, s[14:15]
	s_mov_b32 m0, s60
	s_nop 0
	global_load_lds_dwordx4 v[154:155], off
	v_lshl_add_u64 v[154:155], v[230:231], 0, s[14:15]
	s_mov_b32 m0, s61
	s_nop 0
	global_load_lds_dwordx4 v[154:155], off
	s_waitcnt lgkmcnt(8)
	v_add_f32_e32 v236, v236, v237
	v_add_f32_e32 v238, v238, v239
	v_add_f32_e32 v240, v240, v241
	v_add_f32_e32 v242, v242, v243
	v_add_f32_e32 v244, v244, v245
	v_add_f32_e32 v246, v246, v247
	v_add_f32_e32 v248, v248, v249
	v_add_f32_e32 v250, v250, v251
	v_add_f32_e32 v236, v236, v238
	v_add_f32_e32 v240, v240, v242
	v_add_f32_e32 v244, v244, v246
	v_add_f32_e32 v248, v248, v250
	v_fmamk_f32 v236, v236, 0x3a800000, v152
	v_fmamk_f32 v240, v240, 0x3a800000, v152
	v_fmamk_f32 v244, v244, 0x3a800000, v152
	v_fmamk_f32 v248, v248, 0x3a800000, v152
	v_rsq_f32_e32 v236, v236
	v_rsq_f32_e32 v240, v240
	v_rsq_f32_e32 v244, v244
	v_rsq_f32_e32 v248, v248
	v_mul_f32_e32 v252, 0xbfb8aa3b, v236
	v_mul_f32_e32 v254, v236, v236
	v_rcp_f32_e32 v254, v254
	v_pk_mul_f32 v[120:121], v[124:125], v[120:121]
	v_pk_mul_f32 v[122:123], v[126:127], v[122:123]
	v_pk_mul_f32 v[112:113], v[116:117], v[112:113]
	v_pk_mul_f32 v[114:115], v[118:119], v[114:115]
	v_pk_mul_f32 v[124:125], v[124:125], v[252:253] op_sel_hi:[1,0]
	v_pk_mul_f32 v[126:127], v[126:127], v[252:253] op_sel_hi:[1,0]
	v_pk_mul_f32 v[116:117], v[116:117], v[252:253] op_sel_hi:[1,0]
	v_pk_mul_f32 v[118:119], v[118:119], v[252:253] op_sel_hi:[1,0]
	v_exp_f32_e32 v124, v124
	v_exp_f32_e32 v125, v125
	v_exp_f32_e32 v126, v126
	v_exp_f32_e32 v127, v127
	v_exp_f32_e32 v116, v116
	v_exp_f32_e32 v117, v117
	v_exp_f32_e32 v118, v118
	v_exp_f32_e32 v119, v119
	v_pk_fma_f32 v[124:125], v[124:125], v[254:255], v[254:255] op_sel_hi:[1,0,0]
	v_pk_fma_f32 v[126:127], v[126:127], v[254:255], v[254:255] op_sel_hi:[1,0,0]
	v_pk_fma_f32 v[116:117], v[116:117], v[254:255], v[254:255] op_sel_hi:[1,0,0]
	v_pk_fma_f32 v[118:119], v[118:119], v[254:255], v[254:255] op_sel_hi:[1,0,0]
	v_rcp_f32_e32 v124, v124
	v_rcp_f32_e32 v125, v125
	v_rcp_f32_e32 v126, v126
	v_rcp_f32_e32 v127, v127
	v_rcp_f32_e32 v116, v116
	v_rcp_f32_e32 v117, v117
	v_rcp_f32_e32 v118, v118
	v_rcp_f32_e32 v119, v119
	v_pk_mul_f32 v[120:121], v[120:121], v[124:125]
	v_pk_mul_f32 v[122:123], v[122:123], v[126:127]
	v_pk_mul_f32 v[112:113], v[112:113], v[116:117]
	v_pk_mul_f32 v[114:115], v[114:115], v[118:119]
	v_cvt_pk_bf16_f32 v120, v120, v121
	v_cvt_pk_bf16_f32 v121, v122, v123
	v_cvt_pk_bf16_f32 v122, v112, v113
	v_cvt_pk_bf16_f32 v123, v114, v115
	global_store_dwordx4 v235, v[120:123], s[10:11]
	v_add_u32_e32 v234, 0x16000, v235
	v_mul_f32_e32 v252, 0xbfb8aa3b, v240
	v_mul_f32_e32 v254, v240, v240
	v_rcp_f32_e32 v254, v254
	v_pk_mul_f32 v[104:105], v[108:109], v[104:105]
	v_pk_mul_f32 v[106:107], v[110:111], v[106:107]
	v_pk_mul_f32 v[96:97], v[100:101], v[96:97]
	v_pk_mul_f32 v[98:99], v[102:103], v[98:99]
	v_pk_mul_f32 v[108:109], v[108:109], v[252:253] op_sel_hi:[1,0]
	v_pk_mul_f32 v[110:111], v[110:111], v[252:253] op_sel_hi:[1,0]
	v_pk_mul_f32 v[100:101], v[100:101], v[252:253] op_sel_hi:[1,0]
	v_pk_mul_f32 v[102:103], v[102:103], v[252:253] op_sel_hi:[1,0]
	v_exp_f32_e32 v108, v108
	v_exp_f32_e32 v109, v109
	v_exp_f32_e32 v110, v110
	v_exp_f32_e32 v111, v111
	v_exp_f32_e32 v100, v100
	v_exp_f32_e32 v101, v101
	v_exp_f32_e32 v102, v102
	v_exp_f32_e32 v103, v103
	v_pk_fma_f32 v[108:109], v[108:109], v[254:255], v[254:255] op_sel_hi:[1,0,0]
	v_pk_fma_f32 v[110:111], v[110:111], v[254:255], v[254:255] op_sel_hi:[1,0,0]
	v_pk_fma_f32 v[100:101], v[100:101], v[254:255], v[254:255] op_sel_hi:[1,0,0]
	v_pk_fma_f32 v[102:103], v[102:103], v[254:255], v[254:255] op_sel_hi:[1,0,0]
	v_rcp_f32_e32 v108, v108
	v_rcp_f32_e32 v109, v109
	v_rcp_f32_e32 v110, v110
	v_rcp_f32_e32 v111, v111
	v_rcp_f32_e32 v100, v100
	v_rcp_f32_e32 v101, v101
	v_rcp_f32_e32 v102, v102
	v_rcp_f32_e32 v103, v103
	v_pk_mul_f32 v[104:105], v[104:105], v[108:109]
	v_pk_mul_f32 v[106:107], v[106:107], v[110:111]
	v_pk_mul_f32 v[96:97], v[96:97], v[100:101]
	v_pk_mul_f32 v[98:99], v[98:99], v[102:103]
	v_cvt_pk_bf16_f32 v104, v104, v105
	v_cvt_pk_bf16_f32 v105, v106, v107
	v_cvt_pk_bf16_f32 v106, v96, v97
	v_cvt_pk_bf16_f32 v107, v98, v99
	global_store_dwordx4 v234, v[104:107], s[10:11]
	v_add_u32_e32 v235, 0x16000, v234
	v_mul_f32_e32 v252, 0xbfb8aa3b, v244
	v_mul_f32_e32 v254, v244, v244
	v_rcp_f32_e32 v254, v254
	v_pk_mul_f32 v[88:89], v[92:93], v[88:89]
	v_pk_mul_f32 v[90:91], v[94:95], v[90:91]
	v_pk_mul_f32 v[80:81], v[84:85], v[80:81]
	v_pk_mul_f32 v[82:83], v[86:87], v[82:83]
	v_pk_mul_f32 v[92:93], v[92:93], v[252:253] op_sel_hi:[1,0]
	v_pk_mul_f32 v[94:95], v[94:95], v[252:253] op_sel_hi:[1,0]
	v_pk_mul_f32 v[84:85], v[84:85], v[252:253] op_sel_hi:[1,0]
	v_pk_mul_f32 v[86:87], v[86:87], v[252:253] op_sel_hi:[1,0]
	v_exp_f32_e32 v92, v92
	v_exp_f32_e32 v93, v93
	v_exp_f32_e32 v94, v94
	v_exp_f32_e32 v95, v95
	v_exp_f32_e32 v84, v84
	v_exp_f32_e32 v85, v85
	v_exp_f32_e32 v86, v86
	v_exp_f32_e32 v87, v87
	v_pk_fma_f32 v[92:93], v[92:93], v[254:255], v[254:255] op_sel_hi:[1,0,0]
	v_pk_fma_f32 v[94:95], v[94:95], v[254:255], v[254:255] op_sel_hi:[1,0,0]
	v_pk_fma_f32 v[84:85], v[84:85], v[254:255], v[254:255] op_sel_hi:[1,0,0]
	v_pk_fma_f32 v[86:87], v[86:87], v[254:255], v[254:255] op_sel_hi:[1,0,0]
	v_rcp_f32_e32 v92, v92
	v_rcp_f32_e32 v93, v93
	v_rcp_f32_e32 v94, v94
	v_rcp_f32_e32 v95, v95
	v_rcp_f32_e32 v84, v84
	v_rcp_f32_e32 v85, v85
	v_rcp_f32_e32 v86, v86
	v_rcp_f32_e32 v87, v87
	v_pk_mul_f32 v[88:89], v[88:89], v[92:93]
	v_pk_mul_f32 v[90:91], v[90:91], v[94:95]
	v_pk_mul_f32 v[80:81], v[80:81], v[84:85]
	v_pk_mul_f32 v[82:83], v[82:83], v[86:87]
	v_cvt_pk_bf16_f32 v88, v88, v89
	v_cvt_pk_bf16_f32 v89, v90, v91
	v_cvt_pk_bf16_f32 v90, v80, v81
	v_cvt_pk_bf16_f32 v91, v82, v83
	global_store_dwordx4 v235, v[88:91], s[10:11]
	v_add_u32_e32 v234, 0x16000, v235
	v_mul_f32_e32 v252, 0xbfb8aa3b, v248
	v_mul_f32_e32 v254, v248, v248
	v_rcp_f32_e32 v254, v254
	v_pk_mul_f32 v[72:73], v[76:77], v[72:73]
	v_pk_mul_f32 v[74:75], v[78:79], v[74:75]
	v_pk_mul_f32 v[64:65], v[68:69], v[64:65]
	v_pk_mul_f32 v[66:67], v[70:71], v[66:67]
	v_pk_mul_f32 v[76:77], v[76:77], v[252:253] op_sel_hi:[1,0]
	v_pk_mul_f32 v[78:79], v[78:79], v[252:253] op_sel_hi:[1,0]
	v_pk_mul_f32 v[68:69], v[68:69], v[252:253] op_sel_hi:[1,0]
	v_pk_mul_f32 v[70:71], v[70:71], v[252:253] op_sel_hi:[1,0]
	v_exp_f32_e32 v76, v76
	v_exp_f32_e32 v77, v77
	v_exp_f32_e32 v78, v78
	v_exp_f32_e32 v79, v79
	v_exp_f32_e32 v68, v68
	v_exp_f32_e32 v69, v69
	v_exp_f32_e32 v70, v70
	v_exp_f32_e32 v71, v71
	v_pk_fma_f32 v[76:77], v[76:77], v[254:255], v[254:255] op_sel_hi:[1,0,0]
	v_pk_fma_f32 v[78:79], v[78:79], v[254:255], v[254:255] op_sel_hi:[1,0,0]
	v_pk_fma_f32 v[68:69], v[68:69], v[254:255], v[254:255] op_sel_hi:[1,0,0]
	v_pk_fma_f32 v[70:71], v[70:71], v[254:255], v[254:255] op_sel_hi:[1,0,0]
	v_rcp_f32_e32 v76, v76
	v_rcp_f32_e32 v77, v77
	v_rcp_f32_e32 v78, v78
	v_rcp_f32_e32 v79, v79
	v_rcp_f32_e32 v68, v68
	v_rcp_f32_e32 v69, v69
	v_rcp_f32_e32 v70, v70
	v_rcp_f32_e32 v71, v71
	v_pk_mul_f32 v[72:73], v[72:73], v[76:77]
	v_pk_mul_f32 v[74:75], v[74:75], v[78:79]
	v_pk_mul_f32 v[64:65], v[64:65], v[68:69]
	v_pk_mul_f32 v[66:67], v[66:67], v[70:71]
	v_cvt_pk_bf16_f32 v72, v72, v73
	v_cvt_pk_bf16_f32 v73, v74, v75
	v_cvt_pk_bf16_f32 v74, v64, v65
	v_cvt_pk_bf16_f32 v75, v66, v67
	global_store_dwordx4 v234, v[72:75], s[10:11]
	s_waitcnt vmcnt(12)
	s_waitcnt lgkmcnt(0)
	s_setprio 1
	s_barrier
	v_mfma_f32_16x16x32_bf16 v[60:63], v[160:163], v[194:197], v[60:63]
	v_mfma_f32_16x16x32_bf16 v[60:63], v[164:167], v[198:201], v[60:63]
	v_mfma_f32_16x16x32_bf16 v[52:55], v[172:175], v[198:201], v[52:55]
	v_mfma_f32_16x16x32_bf16 v[52:55], v[168:171], v[194:197], v[52:55]
	v_mfma_f32_16x16x32_bf16 v[36:39], v[168:171], v[202:205], v[36:39]
	v_mfma_f32_16x16x32_bf16 v[36:39], v[172:175], v[206:209], v[36:39]
	v_mfma_f32_16x16x32_bf16 v[44:47], v[164:167], v[206:209], v[44:47]
	v_mfma_f32_16x16x32_bf16 v[44:47], v[160:163], v[202:205], v[44:47]
	v_mfma_f32_16x16x32_bf16 v[28:31], v[160:163], v[210:213], v[28:31]
	v_mfma_f32_16x16x32_bf16 v[28:31], v[164:167], v[214:217], v[28:31]
	v_mfma_f32_16x16x32_bf16 v[20:23], v[172:175], v[214:217], v[20:23]
	v_mfma_f32_16x16x32_bf16 v[20:23], v[168:171], v[210:213], v[20:23]
	v_mfma_f32_16x16x32_bf16 v[4:7], v[168:171], v[218:221], v[4:7]
	v_mfma_f32_16x16x32_bf16 v[4:7], v[172:175], v[222:225], v[4:7]
	v_mfma_f32_16x16x32_bf16 v[12:15], v[164:167], v[222:225], v[12:15]
	v_mfma_f32_16x16x32_bf16 v[12:15], v[160:163], v[218:221], v[12:15]
	s_setprio 0
	s_setprio 1
	v_mfma_f32_16x16x32_bf16 v[56:59], v[176:179], v[194:197], v[56:59]
	v_mfma_f32_16x16x32_bf16 v[56:59], v[180:183], v[198:201], v[56:59]
	v_mfma_f32_16x16x32_bf16 v[48:51], v[190:193], v[198:201], v[48:51]
	v_mfma_f32_16x16x32_bf16 v[48:51], v[186:189], v[194:197], v[48:51]
	v_mfma_f32_16x16x32_bf16 v[32:35], v[186:189], v[202:205], v[32:35]
	v_mfma_f32_16x16x32_bf16 v[32:35], v[190:193], v[206:209], v[32:35]
	v_mfma_f32_16x16x32_bf16 v[40:43], v[180:183], v[206:209], v[40:43]
	v_mfma_f32_16x16x32_bf16 v[40:43], v[176:179], v[202:205], v[40:43]
	v_mfma_f32_16x16x32_bf16 v[24:27], v[176:179], v[210:213], v[24:27]
	v_mfma_f32_16x16x32_bf16 v[24:27], v[180:183], v[214:217], v[24:27]
	v_mfma_f32_16x16x32_bf16 v[16:19], v[190:193], v[214:217], v[16:19]
	v_mfma_f32_16x16x32_bf16 v[16:19], v[186:189], v[210:213], v[16:19]
	v_mfma_f32_16x16x32_bf16 v[0:3], v[186:189], v[218:221], v[0:3]
	v_mfma_f32_16x16x32_bf16 v[0:3], v[190:193], v[222:225], v[0:3]
	v_mfma_f32_16x16x32_bf16 v[8:11], v[180:183], v[222:225], v[8:11]
	v_mfma_f32_16x16x32_bf16 v[8:11], v[176:179], v[218:221], v[8:11]
	s_barrier
	s_setprio 0
	s_add_i32 s75, s75, 2
	s_add_u32 s71, s71, 0x100
	s_addc_u32 s74, s74, 0
	s_add_u32 s44, s44, 0x100
	s_addc_u32 s45, s45, 0

.LBB0_158:
	s_add_u32 s81, s56, 0x100
	s_addc_u32 s82, s57, 0
	s_mov_b32 s83, -2
	s_waitcnt lgkmcnt(0)
	s_cmp_eq_u32 s70, 1
	s_cbranch_scc1 .Lfa_1
	ds_read_b128 v[128:131], v189
	v_xor_b32_e32 v253, 64, v189
	ds_read_b128 v[132:135], v253
	ds_read_b128 v[136:139], v189 offset:2048
	ds_read_b128 v[140:143], v253 offset:2048
	ds_read_b128 v[144:147], v190
	v_xor_b32_e32 v253, 64, v190
	ds_read_b128 v[148:151], v253
	ds_read_b128 v[172:175], v190 offset:2048
	ds_read_b128 v[176:179], v253 offset:2048
	s_add_u32 s56, s54, 0x100
	s_addc_u32 s57, s55, 0
	s_cmp_eq_u32 s83, 40
	s_cselect_b32 s61, s15, s57
	s_cselect_b32 s60, s14, s56
	s_cselect_b32 s59, s53, s82
	s_cselect_b32 s58, s52, s81
	v_lshl_add_u64 v[222:223], s[54:55], 0, v[166:167]
	s_add_i32 m0, s66, 0xc000
	ds_read_b128 v[180:183], v191
	v_xor_b32_e32 v253, 64, v191
	ds_read_b128 v[194:197], v253
	ds_read_b128 v[198:201], v191 offset:2048
	ds_read_b128 v[202:205], v253 offset:2048
	ds_read_b128 v[206:209], v191 offset:4096
	ds_read_b128 v[210:213], v253 offset:4096
	ds_read_b128 v[214:217], v191 offset:6144
	ds_read_b128 v[218:221], v253 offset:6144
	global_load_lds_dwordx4 v[222:223], off
	v_lshl_add_u64 v[222:223], s[54:55], 0, v[164:165]
	s_add_i32 m0, s66, 0xe000
	s_nop 0
	global_load_lds_dwordx4 v[222:223], off
	s_waitcnt vmcnt(24)
	s_waitcnt lgkmcnt(0)
	s_setprio 1
	s_barrier
	v_mfma_f32_16x16x32_bf16 v[124:127], v[128:131], v[180:183], 0
	v_mfma_f32_16x16x32_bf16 v[120:123], v[136:139], v[180:183], 0
	v_mfma_f32_16x16x32_bf16 v[108:111], v[128:131], v[198:201], 0
	v_mfma_f32_16x16x32_bf16 v[104:107], v[136:139], v[198:201], 0
	v_mfma_f32_16x16x32_bf16 v[92:95], v[128:131], v[206:209], 0
	v_mfma_f32_16x16x32_bf16 v[88:91], v[136:139], v[206:209], 0
	v_mfma_f32_16x16x32_bf16 v[76:79], v[128:131], v[214:217], 0
	v_mfma_f32_16x16x32_bf16 v[72:75], v[136:139], v[214:217], 0
	v_mfma_f32_16x16x32_bf16 v[124:127], v[132:135], v[194:197], v[124:127]
	v_mfma_f32_16x16x32_bf16 v[120:123], v[140:143], v[194:197], v[120:123]
	v_mfma_f32_16x16x32_bf16 v[108:111], v[132:135], v[202:205], v[108:111]
	v_mfma_f32_16x16x32_bf16 v[104:107], v[140:143], v[202:205], v[104:107]
	v_mfma_f32_16x16x32_bf16 v[92:95], v[132:135], v[210:213], v[92:95]
	v_mfma_f32_16x16x32_bf16 v[88:91], v[140:143], v[210:213], v[88:91]
	v_mfma_f32_16x16x32_bf16 v[76:79], v[132:135], v[218:221], v[76:79]
	v_mfma_f32_16x16x32_bf16 v[72:75], v[140:143], v[218:221], v[72:75]
	s_setprio 0
	s_setprio 1
	v_mfma_f32_16x16x32_bf16 v[116:119], v[144:147], v[180:183], 0
	v_mfma_f32_16x16x32_bf16 v[112:115], v[172:175], v[180:183], 0
	v_mfma_f32_16x16x32_bf16 v[100:103], v[144:147], v[198:201], 0
	v_mfma_f32_16x16x32_bf16 v[96:99], v[172:175], v[198:201], 0
	v_mfma_f32_16x16x32_bf16 v[84:87], v[144:147], v[206:209], 0
	v_mfma_f32_16x16x32_bf16 v[80:83], v[172:175], v[206:209], 0
	v_mfma_f32_16x16x32_bf16 v[68:71], v[144:147], v[214:217], 0
	v_mfma_f32_16x16x32_bf16 v[64:67], v[172:175], v[214:217], 0
	v_mfma_f32_16x16x32_bf16 v[116:119], v[148:151], v[194:197], v[116:119]
	v_mfma_f32_16x16x32_bf16 v[112:115], v[176:179], v[194:197], v[112:115]
	v_mfma_f32_16x16x32_bf16 v[100:103], v[148:151], v[202:205], v[100:103]
	v_mfma_f32_16x16x32_bf16 v[96:99], v[176:179], v[202:205], v[96:99]
	v_mfma_f32_16x16x32_bf16 v[84:87], v[148:151], v[210:213], v[84:87]
	v_mfma_f32_16x16x32_bf16 v[80:83], v[176:179], v[210:213], v[80:83]
	v_mfma_f32_16x16x32_bf16 v[68:71], v[148:151], v[218:221], v[68:71]
	v_mfma_f32_16x16x32_bf16 v[64:67], v[176:179], v[218:221], v[64:67]
	s_barrier
	s_setprio 0
	s_add_i32 s54, s77, s65
	v_lshl_add_u64 v[222:223], s[58:59], 0, v[154:155]
	s_mov_b32 m0, s54
	ds_read_b128 v[180:183], v191 offset:16384
	v_xor_b32_e32 v253, 64, v191
	ds_read_b128 v[194:197], v253 offset:16384
	ds_read_b128 v[198:201], v191 offset:18432
	ds_read_b128 v[202:205], v253 offset:18432
	ds_read_b128 v[206:209], v191 offset:20480
	ds_read_b128 v[210:213], v253 offset:20480
	ds_read_b128 v[214:217], v191 offset:22528
	ds_read_b128 v[218:221], v253 offset:22528
	global_load_lds_dwordx4 v[222:223], off
	s_add_i32 m0, s54, 0x2000
	s_add_u32 s54, s58, 0xb0000
	v_lshl_add_u64 v[224:225], s[58:59], 0, v[162:163]
	s_addc_u32 s55, s59, 0
	s_add_i32 s84, s78, s65
	global_load_lds_dwordx4 v[224:225], off
	v_lshl_add_u64 v[226:227], s[54:55], 0, v[154:155]
	s_mov_b32 m0, s84
	v_lshl_add_u64 v[228:229], s[60:61], 0, v[160:161]
	global_load_lds_dwordx4 v[226:227], off
	v_lshl_add_u64 v[226:227], s[54:55], 0, v[162:163]
	s_add_i32 m0, s84, 0x2000
	s_nop 0
	global_load_lds_dwordx4 v[226:227], off
	v_lshl_add_u64 v[226:227], s[60:61], 0, v[152:153]
	s_mov_b32 m0, s66
	s_nop 0
	global_load_lds_dwordx4 v[226:227], off
	s_mov_b32 m0, s67
	s_nop 0
	global_load_lds_dwordx4 v[228:229], off
	s_waitcnt vmcnt(24)
	s_waitcnt lgkmcnt(0)
	s_setprio 1
	s_barrier
	v_mfma_f32_16x16x32_bf16 v[60:63], v[128:131], v[180:183], 0
	v_mfma_f32_16x16x32_bf16 v[56:59], v[136:139], v[180:183], 0
	v_mfma_f32_16x16x32_bf16 v[44:47], v[128:131], v[198:201], 0
	v_mfma_f32_16x16x32_bf16 v[40:43], v[136:139], v[198:201], 0
	v_mfma_f32_16x16x32_bf16 v[28:31], v[128:131], v[206:209], 0
	v_mfma_f32_16x16x32_bf16 v[24:27], v[136:139], v[206:209], 0
	v_mfma_f32_16x16x32_bf16 v[12:15], v[128:131], v[214:217], 0
	v_mfma_f32_16x16x32_bf16 v[8:11], v[136:139], v[214:217], 0
	v_mfma_f32_16x16x32_bf16 v[60:63], v[132:135], v[194:197], v[60:63]
	v_mfma_f32_16x16x32_bf16 v[56:59], v[140:143], v[194:197], v[56:59]
	v_mfma_f32_16x16x32_bf16 v[44:47], v[132:135], v[202:205], v[44:47]
	v_mfma_f32_16x16x32_bf16 v[40:43], v[140:143], v[202:205], v[40:43]
	v_mfma_f32_16x16x32_bf16 v[28:31], v[132:135], v[210:213], v[28:31]
	v_mfma_f32_16x16x32_bf16 v[24:27], v[140:143], v[210:213], v[24:27]
	v_mfma_f32_16x16x32_bf16 v[12:15], v[132:135], v[218:221], v[12:15]
	v_mfma_f32_16x16x32_bf16 v[8:11], v[140:143], v[218:221], v[8:11]
	s_setprio 0
	s_setprio 1
	v_mfma_f32_16x16x32_bf16 v[52:55], v[144:147], v[180:183], 0
	v_mfma_f32_16x16x32_bf16 v[48:51], v[172:175], v[180:183], 0
	v_mfma_f32_16x16x32_bf16 v[36:39], v[144:147], v[198:201], 0
	v_mfma_f32_16x16x32_bf16 v[32:35], v[172:175], v[198:201], 0
	v_mfma_f32_16x16x32_bf16 v[20:23], v[144:147], v[206:209], 0
	v_mfma_f32_16x16x32_bf16 v[16:19], v[172:175], v[206:209], 0
	v_mfma_f32_16x16x32_bf16 v[4:7], v[144:147], v[214:217], 0
	v_mfma_f32_16x16x32_bf16 v[0:3], v[172:175], v[214:217], 0
	v_mfma_f32_16x16x32_bf16 v[52:55], v[148:151], v[194:197], v[52:55]
	v_mfma_f32_16x16x32_bf16 v[48:51], v[176:179], v[194:197], v[48:51]
	v_mfma_f32_16x16x32_bf16 v[36:39], v[148:151], v[202:205], v[36:39]
	v_mfma_f32_16x16x32_bf16 v[32:35], v[176:179], v[202:205], v[32:35]
	v_mfma_f32_16x16x32_bf16 v[20:23], v[148:151], v[210:213], v[20:23]
	v_mfma_f32_16x16x32_bf16 v[16:19], v[176:179], v[210:213], v[16:19]
	v_mfma_f32_16x16x32_bf16 v[4:7], v[148:151], v[218:221], v[4:7]
	v_mfma_f32_16x16x32_bf16 v[0:3], v[176:179], v[218:221], v[0:3]
	s_barrier
	s_setprio 0
	s_add_i32 s84, 0, 0x18000
	s_add_i32 s85, 0, 0x1c000
	v_add_u32_e32 v140, s84, v186
	v_add_u32_e32 v176, s85, v186
	ds_read_b128 v[128:131], v140
	v_xor_b32_e32 v253, 64, v140
	ds_read_b128 v[132:135], v253
	ds_read_b128 v[136:139], v140 offset:2048
	ds_read_b128 v[140:143], v253 offset:2048
	ds_read_b128 v[144:147], v176
	v_xor_b32_e32 v253, 64, v176
	ds_read_b128 v[148:151], v253
	ds_read_b128 v[172:175], v176 offset:2048
	ds_read_b128 v[176:179], v253 offset:2048
	s_add_u32 s54, s60, 0xb0000
	s_addc_u32 s55, s61, 0
	s_mov_b32 m0, s68
	v_lshl_add_u64 v[230:231], s[54:55], 0, v[152:153]
	ds_read_b128 v[180:183], v191 offset:32768
	v_xor_b32_e32 v253, 64, v191
	ds_read_b128 v[194:197], v253 offset:32768
	ds_read_b128 v[198:201], v191 offset:34816
	ds_read_b128 v[202:205], v253 offset:34816
	ds_read_b128 v[206:209], v191 offset:36864
	ds_read_b128 v[210:213], v253 offset:36864
	ds_read_b128 v[214:217], v191 offset:38912
	ds_read_b128 v[218:221], v253 offset:38912
	global_load_lds_dwordx4 v[230:231], off
	v_lshl_add_u64 v[230:231], s[54:55], 0, v[160:161]
	s_mov_b32 m0, s69
	s_nop 0
	global_load_lds_dwordx4 v[230:231], off
	s_waitcnt vmcnt(8)
	s_waitcnt lgkmcnt(0)
	s_setprio 1
	s_barrier
	v_mfma_f32_16x16x32_bf16 v[124:127], v[128:131], v[180:183], v[124:127]
	v_mfma_f32_16x16x32_bf16 v[124:127], v[132:135], v[194:197], v[124:127]
	v_mfma_f32_16x16x32_bf16 v[120:123], v[140:143], v[194:197], v[120:123]
	v_mfma_f32_16x16x32_bf16 v[120:123], v[136:139], v[180:183], v[120:123]
	v_mfma_f32_16x16x32_bf16 v[104:107], v[136:139], v[198:201], v[104:107]
	v_mfma_f32_16x16x32_bf16 v[104:107], v[140:143], v[202:205], v[104:107]
	v_mfma_f32_16x16x32_bf16 v[108:111], v[132:135], v[202:205], v[108:111]
	v_mfma_f32_16x16x32_bf16 v[108:111], v[128:131], v[198:201], v[108:111]
	v_mfma_f32_16x16x32_bf16 v[92:95], v[128:131], v[206:209], v[92:95]
	v_mfma_f32_16x16x32_bf16 v[92:95], v[132:135], v[210:213], v[92:95]
	v_mfma_f32_16x16x32_bf16 v[88:91], v[140:143], v[210:213], v[88:91]
	v_mfma_f32_16x16x32_bf16 v[88:91], v[136:139], v[206:209], v[88:91]
	v_mfma_f32_16x16x32_bf16 v[72:75], v[136:139], v[214:217], v[72:75]
	v_mfma_f32_16x16x32_bf16 v[72:75], v[140:143], v[218:221], v[72:75]
	v_mfma_f32_16x16x32_bf16 v[76:79], v[132:135], v[218:221], v[76:79]
	v_mfma_f32_16x16x32_bf16 v[76:79], v[128:131], v[214:217], v[76:79]
	s_setprio 0
	s_setprio 1
	v_mfma_f32_16x16x32_bf16 v[116:119], v[144:147], v[180:183], v[116:119]
	v_mfma_f32_16x16x32_bf16 v[116:119], v[148:151], v[194:197], v[116:119]
	v_mfma_f32_16x16x32_bf16 v[112:115], v[176:179], v[194:197], v[112:115]
	v_mfma_f32_16x16x32_bf16 v[112:115], v[172:175], v[180:183], v[112:115]
	v_mfma_f32_16x16x32_bf16 v[96:99], v[172:175], v[198:201], v[96:99]
	v_mfma_f32_16x16x32_bf16 v[96:99], v[176:179], v[202:205], v[96:99]
	v_mfma_f32_16x16x32_bf16 v[100:103], v[148:151], v[202:205], v[100:103]
	v_mfma_f32_16x16x32_bf16 v[100:103], v[144:147], v[198:201], v[100:103]
	v_mfma_f32_16x16x32_bf16 v[84:87], v[144:147], v[206:209], v[84:87]
	v_mfma_f32_16x16x32_bf16 v[84:87], v[148:151], v[210:213], v[84:87]
	v_mfma_f32_16x16x32_bf16 v[80:83], v[176:179], v[210:213], v[80:83]
	v_mfma_f32_16x16x32_bf16 v[80:83], v[172:175], v[206:209], v[80:83]
	v_mfma_f32_16x16x32_bf16 v[64:67], v[172:175], v[214:217], v[64:67]
	v_mfma_f32_16x16x32_bf16 v[64:67], v[176:179], v[218:221], v[64:67]
	v_mfma_f32_16x16x32_bf16 v[68:71], v[148:151], v[218:221], v[68:71]
	v_mfma_f32_16x16x32_bf16 v[68:71], v[144:147], v[214:217], v[68:71]
	s_barrier
	s_setprio 0
	s_add_i32 s54, s84, s65
	v_lshl_add_u64 v[222:223], v[222:223], 0, s[28:29]
	s_mov_b32 m0, s54
	ds_read_b128 v[180:183], v191 offset:49152
	v_xor_b32_e32 v253, 64, v191
	ds_read_b128 v[194:197], v253 offset:49152
	ds_read_b128 v[198:201], v191 offset:51200
	ds_read_b128 v[202:205], v253 offset:51200
	ds_read_b128 v[206:209], v191 offset:53248
	ds_read_b128 v[210:213], v253 offset:53248
	ds_read_b128 v[214:217], v191 offset:55296
	ds_read_b128 v[218:221], v253 offset:55296
	global_load_lds_dwordx4 v[222:223], off
	s_add_i32 m0, s54, 0x2000
	s_add_u32 s54, s58, 0xb0080
	v_lshl_add_u64 v[222:223], v[224:225], 0, s[28:29]
	s_addc_u32 s55, s59, 0
	s_add_i32 s58, s85, s65
	global_load_lds_dwordx4 v[222:223], off
	v_lshl_add_u64 v[222:223], s[54:55], 0, v[154:155]
	s_mov_b32 m0, s58
	s_nop 0
	global_load_lds_dwordx4 v[222:223], off
	v_lshl_add_u64 v[222:223], s[54:55], 0, v[162:163]
	s_add_i32 m0, s58, 0x2000
	s_nop 0
	global_load_lds_dwordx4 v[222:223], off
	v_lshl_add_u64 v[222:223], v[226:227], 0, s[28:29]
	s_mov_b32 m0, s3
	s_nop 0
	global_load_lds_dwordx4 v[222:223], off
	v_lshl_add_u64 v[222:223], v[228:229], 0, s[28:29]
	s_mov_b32 m0, s71
	s_nop 0
	global_load_lds_dwordx4 v[222:223], off
	s_waitcnt vmcnt(8)
	s_waitcnt lgkmcnt(0)
	s_setprio 1
	s_barrier
	v_mfma_f32_16x16x32_bf16 v[60:63], v[128:131], v[180:183], v[60:63]
	v_mfma_f32_16x16x32_bf16 v[60:63], v[132:135], v[194:197], v[60:63]
	v_mfma_f32_16x16x32_bf16 v[56:59], v[140:143], v[194:197], v[56:59]
	v_mfma_f32_16x16x32_bf16 v[56:59], v[136:139], v[180:183], v[56:59]
	v_mfma_f32_16x16x32_bf16 v[40:43], v[136:139], v[198:201], v[40:43]
	v_mfma_f32_16x16x32_bf16 v[40:43], v[140:143], v[202:205], v[40:43]
	v_mfma_f32_16x16x32_bf16 v[44:47], v[132:135], v[202:205], v[44:47]
	v_mfma_f32_16x16x32_bf16 v[44:47], v[128:131], v[198:201], v[44:47]
	v_mfma_f32_16x16x32_bf16 v[28:31], v[128:131], v[206:209], v[28:31]
	v_mfma_f32_16x16x32_bf16 v[28:31], v[132:135], v[210:213], v[28:31]
	v_mfma_f32_16x16x32_bf16 v[24:27], v[140:143], v[210:213], v[24:27]
	v_mfma_f32_16x16x32_bf16 v[24:27], v[136:139], v[206:209], v[24:27]
	v_mfma_f32_16x16x32_bf16 v[8:11], v[136:139], v[214:217], v[8:11]
	v_mfma_f32_16x16x32_bf16 v[8:11], v[140:143], v[218:221], v[8:11]
	v_mfma_f32_16x16x32_bf16 v[12:15], v[132:135], v[218:221], v[12:15]
	v_mfma_f32_16x16x32_bf16 v[12:15], v[128:131], v[214:217], v[12:15]
	s_setprio 0
	s_setprio 1
	v_mfma_f32_16x16x32_bf16 v[52:55], v[144:147], v[180:183], v[52:55]
	v_mfma_f32_16x16x32_bf16 v[52:55], v[148:151], v[194:197], v[52:55]
	v_mfma_f32_16x16x32_bf16 v[48:51], v[176:179], v[194:197], v[48:51]
	v_mfma_f32_16x16x32_bf16 v[48:51], v[172:175], v[180:183], v[48:51]
	v_mfma_f32_16x16x32_bf16 v[32:35], v[172:175], v[198:201], v[32:35]
	v_mfma_f32_16x16x32_bf16 v[32:35], v[176:179], v[202:205], v[32:35]
	v_mfma_f32_16x16x32_bf16 v[36:39], v[148:151], v[202:205], v[36:39]
	v_mfma_f32_16x16x32_bf16 v[36:39], v[144:147], v[198:201], v[36:39]
	v_mfma_f32_16x16x32_bf16 v[20:23], v[144:147], v[206:209], v[20:23]
	v_mfma_f32_16x16x32_bf16 v[20:23], v[148:151], v[210:213], v[20:23]
	v_mfma_f32_16x16x32_bf16 v[16:19], v[176:179], v[210:213], v[16:19]
	v_mfma_f32_16x16x32_bf16 v[16:19], v[172:175], v[206:209], v[16:19]
	v_mfma_f32_16x16x32_bf16 v[0:3], v[172:175], v[214:217], v[0:3]
	v_mfma_f32_16x16x32_bf16 v[0:3], v[176:179], v[218:221], v[0:3]
	v_mfma_f32_16x16x32_bf16 v[4:7], v[148:151], v[218:221], v[4:7]
	v_mfma_f32_16x16x32_bf16 v[4:7], v[144:147], v[214:217], v[4:7]
	s_barrier
	s_setprio 0
	s_add_i32 s83, s83, 2
	s_add_u32 s81, s81, 0x100
	s_addc_u32 s82, s82, 0
	s_cmp_gt_u32 s83, 41
	s_mov_b64 s[54:55], s[56:57]
	s_branch .LBB0_159
.Lfa_1:
	ds_read_b128 v[128:131], v189
	v_xor_b32_e32 v253, 64, v189
	ds_read_b128 v[132:135], v253
	ds_read_b128 v[136:139], v189 offset:2048
	ds_read_b128 v[140:143], v253 offset:2048
	ds_read_b128 v[144:147], v190
	v_xor_b32_e32 v253, 64, v190
	ds_read_b128 v[148:151], v253
	ds_read_b128 v[172:175], v190 offset:2048
	ds_read_b128 v[176:179], v253 offset:2048
	s_add_u32 s56, s54, 0x100
	s_addc_u32 s57, s55, 0
	s_cmp_eq_u32 s83, 40
	s_cselect_b32 s61, s15, s57
	s_cselect_b32 s60, s14, s56
	s_cselect_b32 s59, s53, s82
	s_cselect_b32 s58, s52, s81
	v_lshl_add_u64 v[222:223], s[54:55], 0, v[166:167]
	s_add_i32 m0, s66, 0xc000
	ds_read_b128 v[180:183], v191
	v_xor_b32_e32 v253, 64, v191
	ds_read_b128 v[194:197], v253
	ds_read_b128 v[198:201], v191 offset:2048
	ds_read_b128 v[202:205], v253 offset:2048
	ds_read_b128 v[206:209], v191 offset:4096
	ds_read_b128 v[210:213], v253 offset:4096
	ds_read_b128 v[214:217], v191 offset:6144
	ds_read_b128 v[218:221], v253 offset:6144
	global_load_lds_dwordx4 v[222:223], off
	v_lshl_add_u64 v[222:223], s[54:55], 0, v[164:165]
	s_add_i32 m0, s66, 0xe000
	s_nop 0
	global_load_lds_dwordx4 v[222:223], off
	s_waitcnt vmcnt(8)
	s_waitcnt lgkmcnt(0)
	s_setprio 1
	s_barrier
	v_mfma_f32_16x16x32_bf16 v[124:127], v[128:131], v[180:183], 0
	v_mfma_f32_16x16x32_bf16 v[120:123], v[136:139], v[180:183], 0
	v_mfma_f32_16x16x32_bf16 v[108:111], v[128:131], v[198:201], 0
	v_mfma_f32_16x16x32_bf16 v[104:107], v[136:139], v[198:201], 0
	v_mfma_f32_16x16x32_bf16 v[92:95], v[128:131], v[206:209], 0
	v_mfma_f32_16x16x32_bf16 v[88:91], v[136:139], v[206:209], 0
	v_mfma_f32_16x16x32_bf16 v[76:79], v[128:131], v[214:217], 0
	v_mfma_f32_16x16x32_bf16 v[72:75], v[136:139], v[214:217], 0
	v_mfma_f32_16x16x32_bf16 v[124:127], v[132:135], v[194:197], v[124:127]
	v_mfma_f32_16x16x32_bf16 v[120:123], v[140:143], v[194:197], v[120:123]
	v_mfma_f32_16x16x32_bf16 v[108:111], v[132:135], v[202:205], v[108:111]
	v_mfma_f32_16x16x32_bf16 v[104:107], v[140:143], v[202:205], v[104:107]
	v_mfma_f32_16x16x32_bf16 v[92:95], v[132:135], v[210:213], v[92:95]
	v_mfma_f32_16x16x32_bf16 v[88:91], v[140:143], v[210:213], v[88:91]
	v_mfma_f32_16x16x32_bf16 v[76:79], v[132:135], v[218:221], v[76:79]
	v_mfma_f32_16x16x32_bf16 v[72:75], v[140:143], v[218:221], v[72:75]
	s_setprio 0
	s_setprio 1
	v_mfma_f32_16x16x32_bf16 v[116:119], v[144:147], v[180:183], 0
	v_mfma_f32_16x16x32_bf16 v[112:115], v[172:175], v[180:183], 0
	v_mfma_f32_16x16x32_bf16 v[100:103], v[144:147], v[198:201], 0
	v_mfma_f32_16x16x32_bf16 v[96:99], v[172:175], v[198:201], 0
	v_mfma_f32_16x16x32_bf16 v[84:87], v[144:147], v[206:209], 0
	v_mfma_f32_16x16x32_bf16 v[80:83], v[172:175], v[206:209], 0
	v_mfma_f32_16x16x32_bf16 v[68:71], v[144:147], v[214:217], 0
	v_mfma_f32_16x16x32_bf16 v[64:67], v[172:175], v[214:217], 0
	v_mfma_f32_16x16x32_bf16 v[116:119], v[148:151], v[194:197], v[116:119]
	v_mfma_f32_16x16x32_bf16 v[112:115], v[176:179], v[194:197], v[112:115]
	v_mfma_f32_16x16x32_bf16 v[100:103], v[148:151], v[202:205], v[100:103]
	v_mfma_f32_16x16x32_bf16 v[96:99], v[176:179], v[202:205], v[96:99]
	v_mfma_f32_16x16x32_bf16 v[84:87], v[148:151], v[210:213], v[84:87]
	v_mfma_f32_16x16x32_bf16 v[80:83], v[176:179], v[210:213], v[80:83]
	v_mfma_f32_16x16x32_bf16 v[68:71], v[148:151], v[218:221], v[68:71]
	v_mfma_f32_16x16x32_bf16 v[64:67], v[176:179], v[218:221], v[64:67]
	s_barrier
	s_setprio 0
	s_add_i32 s54, s77, s65
	v_lshl_add_u64 v[222:223], s[58:59], 0, v[154:155]
	s_mov_b32 m0, s54
	ds_read_b128 v[180:183], v191 offset:16384
	v_xor_b32_e32 v253, 64, v191
	ds_read_b128 v[194:197], v253 offset:16384
	ds_read_b128 v[198:201], v191 offset:18432
	ds_read_b128 v[202:205], v253 offset:18432
	ds_read_b128 v[206:209], v191 offset:20480
	ds_read_b128 v[210:213], v253 offset:20480
	ds_read_b128 v[214:217], v191 offset:22528
	ds_read_b128 v[218:221], v253 offset:22528
	global_load_lds_dwordx4 v[222:223], off
	s_add_i32 m0, s54, 0x2000
	s_add_u32 s54, s58, 0xb0000
	v_lshl_add_u64 v[224:225], s[58:59], 0, v[162:163]
	s_addc_u32 s55, s59, 0
	s_add_i32 s84, s78, s65
	global_load_lds_dwordx4 v[224:225], off
	v_lshl_add_u64 v[226:227], s[54:55], 0, v[154:155]
	s_mov_b32 m0, s84
	v_lshl_add_u64 v[228:229], s[60:61], 0, v[160:161]
	global_load_lds_dwordx4 v[226:227], off
	v_lshl_add_u64 v[226:227], s[54:55], 0, v[162:163]
	s_add_i32 m0, s84, 0x2000
	s_nop 0
	global_load_lds_dwordx4 v[226:227], off
	v_lshl_add_u64 v[226:227], s[60:61], 0, v[152:153]
	s_mov_b32 m0, s66
	s_nop 0
	global_load_lds_dwordx4 v[226:227], off
	s_mov_b32 m0, s67
	s_nop 0
	global_load_lds_dwordx4 v[228:229], off
	s_waitcnt vmcnt(8)
	s_waitcnt lgkmcnt(0)
	s_setprio 1
	s_barrier
	v_mfma_f32_16x16x32_bf16 v[60:63], v[128:131], v[180:183], 0
	v_mfma_f32_16x16x32_bf16 v[56:59], v[136:139], v[180:183], 0
	v_mfma_f32_16x16x32_bf16 v[44:47], v[128:131], v[198:201], 0
	v_mfma_f32_16x16x32_bf16 v[40:43], v[136:139], v[198:201], 0
	v_mfma_f32_16x16x32_bf16 v[28:31], v[128:131], v[206:209], 0
	v_mfma_f32_16x16x32_bf16 v[24:27], v[136:139], v[206:209], 0
	v_mfma_f32_16x16x32_bf16 v[12:15], v[128:131], v[214:217], 0
	v_mfma_f32_16x16x32_bf16 v[8:11], v[136:139], v[214:217], 0
	v_mfma_f32_16x16x32_bf16 v[60:63], v[132:135], v[194:197], v[60:63]
	v_mfma_f32_16x16x32_bf16 v[56:59], v[140:143], v[194:197], v[56:59]
	v_mfma_f32_16x16x32_bf16 v[44:47], v[132:135], v[202:205], v[44:47]
	v_mfma_f32_16x16x32_bf16 v[40:43], v[140:143], v[202:205], v[40:43]
	v_mfma_f32_16x16x32_bf16 v[28:31], v[132:135], v[210:213], v[28:31]
	v_mfma_f32_16x16x32_bf16 v[24:27], v[140:143], v[210:213], v[24:27]
	v_mfma_f32_16x16x32_bf16 v[12:15], v[132:135], v[218:221], v[12:15]
	v_mfma_f32_16x16x32_bf16 v[8:11], v[140:143], v[218:221], v[8:11]
	s_setprio 0
	s_setprio 1
	v_mfma_f32_16x16x32_bf16 v[52:55], v[144:147], v[180:183], 0
	v_mfma_f32_16x16x32_bf16 v[48:51], v[172:175], v[180:183], 0
	v_mfma_f32_16x16x32_bf16 v[36:39], v[144:147], v[198:201], 0
	v_mfma_f32_16x16x32_bf16 v[32:35], v[172:175], v[198:201], 0
	v_mfma_f32_16x16x32_bf16 v[20:23], v[144:147], v[206:209], 0
	v_mfma_f32_16x16x32_bf16 v[16:19], v[172:175], v[206:209], 0
	v_mfma_f32_16x16x32_bf16 v[4:7], v[144:147], v[214:217], 0
	v_mfma_f32_16x16x32_bf16 v[0:3], v[172:175], v[214:217], 0
	v_mfma_f32_16x16x32_bf16 v[52:55], v[148:151], v[194:197], v[52:55]
	v_mfma_f32_16x16x32_bf16 v[48:51], v[176:179], v[194:197], v[48:51]
	v_mfma_f32_16x16x32_bf16 v[36:39], v[148:151], v[202:205], v[36:39]
	v_mfma_f32_16x16x32_bf16 v[32:35], v[176:179], v[202:205], v[32:35]
	v_mfma_f32_16x16x32_bf16 v[20:23], v[148:151], v[210:213], v[20:23]
	v_mfma_f32_16x16x32_bf16 v[16:19], v[176:179], v[210:213], v[16:19]
	v_mfma_f32_16x16x32_bf16 v[4:7], v[148:151], v[218:221], v[4:7]
	v_mfma_f32_16x16x32_bf16 v[0:3], v[176:179], v[218:221], v[0:3]
	s_barrier
	s_setprio 0
	s_add_i32 s84, 0, 0x18000
	s_add_i32 s85, 0, 0x1c000
	v_add_u32_e32 v140, s84, v186
	v_add_u32_e32 v176, s85, v186
	ds_read_b128 v[128:131], v140
	v_xor_b32_e32 v253, 64, v140
	ds_read_b128 v[132:135], v253
	ds_read_b128 v[136:139], v140 offset:2048
	ds_read_b128 v[140:143], v253 offset:2048
	ds_read_b128 v[144:147], v176
	v_xor_b32_e32 v253, 64, v176
	ds_read_b128 v[148:151], v253
	ds_read_b128 v[172:175], v176 offset:2048
	ds_read_b128 v[176:179], v253 offset:2048
	s_add_u32 s54, s60, 0xb0000
	s_addc_u32 s55, s61, 0
	s_mov_b32 m0, s68
	v_lshl_add_u64 v[230:231], s[54:55], 0, v[152:153]
	ds_read_b128 v[180:183], v191 offset:32768
	v_xor_b32_e32 v253, 64, v191
	ds_read_b128 v[194:197], v253 offset:32768
	ds_read_b128 v[198:201], v191 offset:34816
	ds_read_b128 v[202:205], v253 offset:34816
	ds_read_b128 v[206:209], v191 offset:36864
	ds_read_b128 v[210:213], v253 offset:36864
	ds_read_b128 v[214:217], v191 offset:38912
	ds_read_b128 v[218:221], v253 offset:38912
	global_load_lds_dwordx4 v[230:231], off
	v_lshl_add_u64 v[230:231], s[54:55], 0, v[160:161]
	s_mov_b32 m0, s69
	s_nop 0
	global_load_lds_dwordx4 v[230:231], off
	s_waitcnt vmcnt(8)
	s_waitcnt lgkmcnt(0)
	s_setprio 1
	s_barrier
	v_mfma_f32_16x16x32_bf16 v[124:127], v[128:131], v[180:183], v[124:127]
	v_mfma_f32_16x16x32_bf16 v[124:127], v[132:135], v[194:197], v[124:127]
	v_mfma_f32_16x16x32_bf16 v[120:123], v[140:143], v[194:197], v[120:123]
	v_mfma_f32_16x16x32_bf16 v[120:123], v[136:139], v[180:183], v[120:123]
	v_mfma_f32_16x16x32_bf16 v[104:107], v[136:139], v[198:201], v[104:107]
	v_mfma_f32_16x16x32_bf16 v[104:107], v[140:143], v[202:205], v[104:107]
	v_mfma_f32_16x16x32_bf16 v[108:111], v[132:135], v[202:205], v[108:111]
	v_mfma_f32_16x16x32_bf16 v[108:111], v[128:131], v[198:201], v[108:111]
	v_mfma_f32_16x16x32_bf16 v[92:95], v[128:131], v[206:209], v[92:95]
	v_mfma_f32_16x16x32_bf16 v[92:95], v[132:135], v[210:213], v[92:95]
	v_mfma_f32_16x16x32_bf16 v[88:91], v[140:143], v[210:213], v[88:91]
	v_mfma_f32_16x16x32_bf16 v[88:91], v[136:139], v[206:209], v[88:91]
	v_mfma_f32_16x16x32_bf16 v[72:75], v[136:139], v[214:217], v[72:75]
	v_mfma_f32_16x16x32_bf16 v[72:75], v[140:143], v[218:221], v[72:75]
	v_mfma_f32_16x16x32_bf16 v[76:79], v[132:135], v[218:221], v[76:79]
	v_mfma_f32_16x16x32_bf16 v[76:79], v[128:131], v[214:217], v[76:79]
	s_setprio 0
	s_setprio 1
	v_mfma_f32_16x16x32_bf16 v[116:119], v[144:147], v[180:183], v[116:119]
	v_mfma_f32_16x16x32_bf16 v[116:119], v[148:151], v[194:197], v[116:119]
	v_mfma_f32_16x16x32_bf16 v[112:115], v[176:179], v[194:197], v[112:115]
	v_mfma_f32_16x16x32_bf16 v[112:115], v[172:175], v[180:183], v[112:115]
	v_mfma_f32_16x16x32_bf16 v[96:99], v[172:175], v[198:201], v[96:99]
	v_mfma_f32_16x16x32_bf16 v[96:99], v[176:179], v[202:205], v[96:99]
	v_mfma_f32_16x16x32_bf16 v[100:103], v[148:151], v[202:205], v[100:103]
	v_mfma_f32_16x16x32_bf16 v[100:103], v[144:147], v[198:201], v[100:103]
	v_mfma_f32_16x16x32_bf16 v[84:87], v[144:147], v[206:209], v[84:87]
	v_mfma_f32_16x16x32_bf16 v[84:87], v[148:151], v[210:213], v[84:87]
	v_mfma_f32_16x16x32_bf16 v[80:83], v[176:179], v[210:213], v[80:83]
	v_mfma_f32_16x16x32_bf16 v[80:83], v[172:175], v[206:209], v[80:83]
	v_mfma_f32_16x16x32_bf16 v[64:67], v[172:175], v[214:217], v[64:67]
	v_mfma_f32_16x16x32_bf16 v[64:67], v[176:179], v[218:221], v[64:67]
	v_mfma_f32_16x16x32_bf16 v[68:71], v[148:151], v[218:221], v[68:71]
	v_mfma_f32_16x16x32_bf16 v[68:71], v[144:147], v[214:217], v[68:71]
	s_barrier
	s_setprio 0
	s_add_i32 s54, s84, s65
	v_lshl_add_u64 v[222:223], v[222:223], 0, s[28:29]
	s_mov_b32 m0, s54
	ds_read_b128 v[180:183], v191 offset:49152
	v_xor_b32_e32 v253, 64, v191
	ds_read_b128 v[194:197], v253 offset:49152
	ds_read_b128 v[198:201], v191 offset:51200
	ds_read_b128 v[202:205], v253 offset:51200
	ds_read_b128 v[206:209], v191 offset:53248
	ds_read_b128 v[210:213], v253 offset:53248
	ds_read_b128 v[214:217], v191 offset:55296
	ds_read_b128 v[218:221], v253 offset:55296
	global_load_lds_dwordx4 v[222:223], off
	s_add_i32 m0, s54, 0x2000
	s_add_u32 s54, s58, 0xb0080
	v_lshl_add_u64 v[222:223], v[224:225], 0, s[28:29]
	s_addc_u32 s55, s59, 0
	s_add_i32 s58, s85, s65
	global_load_lds_dwordx4 v[222:223], off
	v_lshl_add_u64 v[222:223], s[54:55], 0, v[154:155]
	s_mov_b32 m0, s58
	s_nop 0
	global_load_lds_dwordx4 v[222:223], off
	v_lshl_add_u64 v[222:223], s[54:55], 0, v[162:163]
	s_add_i32 m0, s58, 0x2000
	s_nop 0
	global_load_lds_dwordx4 v[222:223], off
	v_lshl_add_u64 v[222:223], v[226:227], 0, s[28:29]
	s_mov_b32 m0, s3
	s_nop 0
	global_load_lds_dwordx4 v[222:223], off
	v_lshl_add_u64 v[222:223], v[228:229], 0, s[28:29]
	s_mov_b32 m0, s71
	s_nop 0
	global_load_lds_dwordx4 v[222:223], off
	s_waitcnt vmcnt(8)
	s_waitcnt lgkmcnt(0)
	s_setprio 1
	s_barrier
	v_mfma_f32_16x16x32_bf16 v[60:63], v[128:131], v[180:183], v[60:63]
	v_mfma_f32_16x16x32_bf16 v[60:63], v[132:135], v[194:197], v[60:63]
	v_mfma_f32_16x16x32_bf16 v[56:59], v[140:143], v[194:197], v[56:59]
	v_mfma_f32_16x16x32_bf16 v[56:59], v[136:139], v[180:183], v[56:59]
	v_mfma_f32_16x16x32_bf16 v[40:43], v[136:139], v[198:201], v[40:43]
	v_mfma_f32_16x16x32_bf16 v[40:43], v[140:143], v[202:205], v[40:43]
	v_mfma_f32_16x16x32_bf16 v[44:47], v[132:135], v[202:205], v[44:47]
	v_mfma_f32_16x16x32_bf16 v[44:47], v[128:131], v[198:201], v[44:47]
	v_mfma_f32_16x16x32_bf16 v[28:31], v[128:131], v[206:209], v[28:31]
	v_mfma_f32_16x16x32_bf16 v[28:31], v[132:135], v[210:213], v[28:31]
	v_mfma_f32_16x16x32_bf16 v[24:27], v[140:143], v[210:213], v[24:27]
	v_mfma_f32_16x16x32_bf16 v[24:27], v[136:139], v[206:209], v[24:27]
	v_mfma_f32_16x16x32_bf16 v[8:11], v[136:139], v[214:217], v[8:11]
	v_mfma_f32_16x16x32_bf16 v[8:11], v[140:143], v[218:221], v[8:11]
	v_mfma_f32_16x16x32_bf16 v[12:15], v[132:135], v[218:221], v[12:15]
	v_mfma_f32_16x16x32_bf16 v[12:15], v[128:131], v[214:217], v[12:15]
	s_setprio 0
	s_setprio 1
	v_mfma_f32_16x16x32_bf16 v[52:55], v[144:147], v[180:183], v[52:55]
	v_mfma_f32_16x16x32_bf16 v[52:55], v[148:151], v[194:197], v[52:55]
	v_mfma_f32_16x16x32_bf16 v[48:51], v[176:179], v[194:197], v[48:51]
	v_mfma_f32_16x16x32_bf16 v[48:51], v[172:175], v[180:183], v[48:51]
	v_mfma_f32_16x16x32_bf16 v[32:35], v[172:175], v[198:201], v[32:35]
	v_mfma_f32_16x16x32_bf16 v[32:35], v[176:179], v[202:205], v[32:35]
	v_mfma_f32_16x16x32_bf16 v[36:39], v[148:151], v[202:205], v[36:39]
	v_mfma_f32_16x16x32_bf16 v[36:39], v[144:147], v[198:201], v[36:39]
	v_mfma_f32_16x16x32_bf16 v[20:23], v[144:147], v[206:209], v[20:23]
	v_mfma_f32_16x16x32_bf16 v[20:23], v[148:151], v[210:213], v[20:23]
	v_mfma_f32_16x16x32_bf16 v[16:19], v[176:179], v[210:213], v[16:19]
	v_mfma_f32_16x16x32_bf16 v[16:19], v[172:175], v[206:209], v[16:19]
	v_mfma_f32_16x16x32_bf16 v[0:3], v[172:175], v[214:217], v[0:3]
	v_mfma_f32_16x16x32_bf16 v[0:3], v[176:179], v[218:221], v[0:3]
	v_mfma_f32_16x16x32_bf16 v[4:7], v[148:151], v[218:221], v[4:7]
	v_mfma_f32_16x16x32_bf16 v[4:7], v[144:147], v[214:217], v[4:7]
	s_barrier
	s_setprio 0
	s_add_i32 s83, s83, 2
	s_add_u32 s81, s81, 0x100
	s_addc_u32 s82, s82, 0
	s_cmp_gt_u32 s83, 41
	s_mov_b64 s[54:55], s[56:57]
.LBB0_159:
	ds_read_b128 v[128:131], v189
	v_xor_b32_e32 v253, 64, v189
	ds_read_b128 v[132:135], v253
	ds_read_b128 v[136:139], v189 offset:2048
	ds_read_b128 v[140:143], v253 offset:2048
	ds_read_b128 v[144:147], v190
	v_xor_b32_e32 v253, 64, v190
	ds_read_b128 v[148:151], v253
	ds_read_b128 v[172:175], v190 offset:2048
	ds_read_b128 v[176:179], v253 offset:2048
	s_add_u32 s56, s54, 0x100
	s_addc_u32 s57, s55, 0
	s_cmp_eq_u32 s83, 40
	s_cselect_b32 s61, s15, s57
	s_cselect_b32 s60, s14, s56
	s_cselect_b32 s59, s53, s82
	s_cselect_b32 s58, s52, s81
	v_lshl_add_u64 v[222:223], s[54:55], 0, v[166:167]
	s_add_i32 m0, s66, 0xc000
	ds_read_b128 v[180:183], v191
	v_xor_b32_e32 v253, 64, v191
	ds_read_b128 v[194:197], v253
	ds_read_b128 v[198:201], v191 offset:2048
	ds_read_b128 v[202:205], v253 offset:2048
	ds_read_b128 v[206:209], v191 offset:4096
	ds_read_b128 v[210:213], v253 offset:4096
	ds_read_b128 v[214:217], v191 offset:6144
	ds_read_b128 v[218:221], v253 offset:6144
	global_load_lds_dwordx4 v[222:223], off
	v_lshl_add_u64 v[222:223], s[54:55], 0, v[164:165]
	s_add_i32 m0, s66, 0xe000
	s_nop 0
	global_load_lds_dwordx4 v[222:223], off
	s_waitcnt vmcnt(8)
	s_waitcnt lgkmcnt(0)
	s_setprio 1
	s_barrier
	v_mfma_f32_16x16x32_bf16 v[124:127], v[128:131], v[180:183], v[124:127]
	v_mfma_f32_16x16x32_bf16 v[124:127], v[132:135], v[194:197], v[124:127]
	v_mfma_f32_16x16x32_bf16 v[120:123], v[140:143], v[194:197], v[120:123]
	v_mfma_f32_16x16x32_bf16 v[120:123], v[136:139], v[180:183], v[120:123]
	v_mfma_f32_16x16x32_bf16 v[104:107], v[136:139], v[198:201], v[104:107]
	v_mfma_f32_16x16x32_bf16 v[104:107], v[140:143], v[202:205], v[104:107]
	v_mfma_f32_16x16x32_bf16 v[108:111], v[132:135], v[202:205], v[108:111]
	v_mfma_f32_16x16x32_bf16 v[108:111], v[128:131], v[198:201], v[108:111]
	v_mfma_f32_16x16x32_bf16 v[92:95], v[128:131], v[206:209], v[92:95]
	v_mfma_f32_16x16x32_bf16 v[92:95], v[132:135], v[210:213], v[92:95]
	v_mfma_f32_16x16x32_bf16 v[88:91], v[140:143], v[210:213], v[88:91]
	v_mfma_f32_16x16x32_bf16 v[88:91], v[136:139], v[206:209], v[88:91]
	v_mfma_f32_16x16x32_bf16 v[72:75], v[136:139], v[214:217], v[72:75]
	v_mfma_f32_16x16x32_bf16 v[72:75], v[140:143], v[218:221], v[72:75]
	v_mfma_f32_16x16x32_bf16 v[76:79], v[132:135], v[218:221], v[76:79]
	v_mfma_f32_16x16x32_bf16 v[76:79], v[128:131], v[214:217], v[76:79]
	s_setprio 0
	s_setprio 1
	v_mfma_f32_16x16x32_bf16 v[116:119], v[144:147], v[180:183], v[116:119]
	v_mfma_f32_16x16x32_bf16 v[116:119], v[148:151], v[194:197], v[116:119]
	v_mfma_f32_16x16x32_bf16 v[112:115], v[176:179], v[194:197], v[112:115]
	v_mfma_f32_16x16x32_bf16 v[112:115], v[172:175], v[180:183], v[112:115]
	v_mfma_f32_16x16x32_bf16 v[96:99], v[172:175], v[198:201], v[96:99]
	v_mfma_f32_16x16x32_bf16 v[96:99], v[176:179], v[202:205], v[96:99]
	v_mfma_f32_16x16x32_bf16 v[100:103], v[148:151], v[202:205], v[100:103]
	v_mfma_f32_16x16x32_bf16 v[100:103], v[144:147], v[198:201], v[100:103]
	v_mfma_f32_16x16x32_bf16 v[84:87], v[144:147], v[206:209], v[84:87]
	v_mfma_f32_16x16x32_bf16 v[84:87], v[148:151], v[210:213], v[84:87]
	v_mfma_f32_16x16x32_bf16 v[80:83], v[176:179], v[210:213], v[80:83]
	v_mfma_f32_16x16x32_bf16 v[80:83], v[172:175], v[206:209], v[80:83]
	v_mfma_f32_16x16x32_bf16 v[64:67], v[172:175], v[214:217], v[64:67]
	v_mfma_f32_16x16x32_bf16 v[64:67], v[176:179], v[218:221], v[64:67]
	v_mfma_f32_16x16x32_bf16 v[68:71], v[148:151], v[218:221], v[68:71]
	v_mfma_f32_16x16x32_bf16 v[68:71], v[144:147], v[214:217], v[68:71]
	s_barrier
	s_setprio 0
	s_add_i32 s54, s77, s65
	v_lshl_add_u64 v[222:223], s[58:59], 0, v[154:155]
	s_mov_b32 m0, s54
	ds_read_b128 v[180:183], v191 offset:16384
	v_xor_b32_e32 v253, 64, v191
	ds_read_b128 v[194:197], v253 offset:16384
	ds_read_b128 v[198:201], v191 offset:18432
	ds_read_b128 v[202:205], v253 offset:18432
	ds_read_b128 v[206:209], v191 offset:20480
	ds_read_b128 v[210:213], v253 offset:20480
	ds_read_b128 v[214:217], v191 offset:22528
	ds_read_b128 v[218:221], v253 offset:22528
	global_load_lds_dwordx4 v[222:223], off
	s_add_i32 m0, s54, 0x2000
	s_add_u32 s54, s58, 0xb0000
	v_lshl_add_u64 v[224:225], s[58:59], 0, v[162:163]
	s_addc_u32 s55, s59, 0
	s_add_i32 s84, s78, s65
	global_load_lds_dwordx4 v[224:225], off
	v_lshl_add_u64 v[226:227], s[54:55], 0, v[154:155]
	s_mov_b32 m0, s84
	v_lshl_add_u64 v[228:229], s[60:61], 0, v[160:161]
	global_load_lds_dwordx4 v[226:227], off
	v_lshl_add_u64 v[226:227], s[54:55], 0, v[162:163]
	s_add_i32 m0, s84, 0x2000
	s_nop 0
	global_load_lds_dwordx4 v[226:227], off
	v_lshl_add_u64 v[226:227], s[60:61], 0, v[152:153]
	s_mov_b32 m0, s66
	s_nop 0
	global_load_lds_dwordx4 v[226:227], off
	s_mov_b32 m0, s67
	s_nop 0
	global_load_lds_dwordx4 v[228:229], off
	s_waitcnt vmcnt(8)
	s_waitcnt lgkmcnt(0)
	s_setprio 1
	s_barrier
	v_mfma_f32_16x16x32_bf16 v[60:63], v[128:131], v[180:183], v[60:63]
	v_mfma_f32_16x16x32_bf16 v[60:63], v[132:135], v[194:197], v[60:63]
	v_mfma_f32_16x16x32_bf16 v[56:59], v[140:143], v[194:197], v[56:59]
	v_mfma_f32_16x16x32_bf16 v[56:59], v[136:139], v[180:183], v[56:59]
	v_mfma_f32_16x16x32_bf16 v[40:43], v[136:139], v[198:201], v[40:43]
	v_mfma_f32_16x16x32_bf16 v[40:43], v[140:143], v[202:205], v[40:43]
	v_mfma_f32_16x16x32_bf16 v[44:47], v[132:135], v[202:205], v[44:47]
	v_mfma_f32_16x16x32_bf16 v[44:47], v[128:131], v[198:201], v[44:47]
	v_mfma_f32_16x16x32_bf16 v[28:31], v[128:131], v[206:209], v[28:31]
	v_mfma_f32_16x16x32_bf16 v[28:31], v[132:135], v[210:213], v[28:31]
	v_mfma_f32_16x16x32_bf16 v[24:27], v[140:143], v[210:213], v[24:27]
	v_mfma_f32_16x16x32_bf16 v[24:27], v[136:139], v[206:209], v[24:27]
	v_mfma_f32_16x16x32_bf16 v[8:11], v[136:139], v[214:217], v[8:11]
	v_mfma_f32_16x16x32_bf16 v[8:11], v[140:143], v[218:221], v[8:11]
	v_mfma_f32_16x16x32_bf16 v[12:15], v[132:135], v[218:221], v[12:15]
	v_mfma_f32_16x16x32_bf16 v[12:15], v[128:131], v[214:217], v[12:15]
	s_setprio 0
	s_setprio 1
	v_mfma_f32_16x16x32_bf16 v[52:55], v[144:147], v[180:183], v[52:55]
	v_mfma_f32_16x16x32_bf16 v[52:55], v[148:151], v[194:197], v[52:55]
	v_mfma_f32_16x16x32_bf16 v[48:51], v[176:179], v[194:197], v[48:51]
	v_mfma_f32_16x16x32_bf16 v[48:51], v[172:175], v[180:183], v[48:51]
	v_mfma_f32_16x16x32_bf16 v[32:35], v[172:175], v[198:201], v[32:35]
	v_mfma_f32_16x16x32_bf16 v[32:35], v[176:179], v[202:205], v[32:35]
	v_mfma_f32_16x16x32_bf16 v[36:39], v[148:151], v[202:205], v[36:39]
	v_mfma_f32_16x16x32_bf16 v[36:39], v[144:147], v[198:201], v[36:39]
	v_mfma_f32_16x16x32_bf16 v[20:23], v[144:147], v[206:209], v[20:23]
	v_mfma_f32_16x16x32_bf16 v[20:23], v[148:151], v[210:213], v[20:23]
	v_mfma_f32_16x16x32_bf16 v[16:19], v[176:179], v[210:213], v[16:19]
	v_mfma_f32_16x16x32_bf16 v[16:19], v[172:175], v[206:209], v[16:19]
	v_mfma_f32_16x16x32_bf16 v[0:3], v[172:175], v[214:217], v[0:3]
	v_mfma_f32_16x16x32_bf16 v[0:3], v[176:179], v[218:221], v[0:3]
	v_mfma_f32_16x16x32_bf16 v[4:7], v[148:151], v[218:221], v[4:7]
	v_mfma_f32_16x16x32_bf16 v[4:7], v[144:147], v[214:217], v[4:7]
	s_barrier
	s_setprio 0
	s_add_i32 s84, 0, 0x18000
	s_add_i32 s85, 0, 0x1c000
	v_add_u32_e32 v140, s84, v186
	v_add_u32_e32 v176, s85, v186
	ds_read_b128 v[128:131], v140
	v_xor_b32_e32 v253, 64, v140
	ds_read_b128 v[132:135], v253
	ds_read_b128 v[136:139], v140 offset:2048
	ds_read_b128 v[140:143], v253 offset:2048
	ds_read_b128 v[144:147], v176
	v_xor_b32_e32 v253, 64, v176
	ds_read_b128 v[148:151], v253
	ds_read_b128 v[172:175], v176 offset:2048
	ds_read_b128 v[176:179], v253 offset:2048
	s_add_u32 s54, s60, 0xb0000
	s_addc_u32 s55, s61, 0
	s_mov_b32 m0, s68
	v_lshl_add_u64 v[230:231], s[54:55], 0, v[152:153]
	ds_read_b128 v[180:183], v191 offset:32768
	v_xor_b32_e32 v253, 64, v191
	ds_read_b128 v[194:197], v253 offset:32768
	ds_read_b128 v[198:201], v191 offset:34816
	ds_read_b128 v[202:205], v253 offset:34816
	ds_read_b128 v[206:209], v191 offset:36864
	ds_read_b128 v[210:213], v253 offset:36864
	ds_read_b128 v[214:217], v191 offset:38912
	ds_read_b128 v[218:221], v253 offset:38912
	global_load_lds_dwordx4 v[230:231], off
	v_lshl_add_u64 v[230:231], s[54:55], 0, v[160:161]
	s_mov_b32 m0, s69
	s_nop 0
	global_load_lds_dwordx4 v[230:231], off
	s_waitcnt vmcnt(8)
	s_waitcnt lgkmcnt(0)
	s_setprio 1
	s_barrier
	v_mfma_f32_16x16x32_bf16 v[124:127], v[128:131], v[180:183], v[124:127]
	v_mfma_f32_16x16x32_bf16 v[124:127], v[132:135], v[194:197], v[124:127]
	v_mfma_f32_16x16x32_bf16 v[120:123], v[140:143], v[194:197], v[120:123]
	v_mfma_f32_16x16x32_bf16 v[120:123], v[136:139], v[180:183], v[120:123]
	v_mfma_f32_16x16x32_bf16 v[104:107], v[136:139], v[198:201], v[104:107]
	v_mfma_f32_16x16x32_bf16 v[104:107], v[140:143], v[202:205], v[104:107]
	v_mfma_f32_16x16x32_bf16 v[108:111], v[132:135], v[202:205], v[108:111]
	v_mfma_f32_16x16x32_bf16 v[108:111], v[128:131], v[198:201], v[108:111]
	v_mfma_f32_16x16x32_bf16 v[92:95], v[128:131], v[206:209], v[92:95]
	v_mfma_f32_16x16x32_bf16 v[92:95], v[132:135], v[210:213], v[92:95]
	v_mfma_f32_16x16x32_bf16 v[88:91], v[140:143], v[210:213], v[88:91]
	v_mfma_f32_16x16x32_bf16 v[88:91], v[136:139], v[206:209], v[88:91]
	v_mfma_f32_16x16x32_bf16 v[72:75], v[136:139], v[214:217], v[72:75]
	v_mfma_f32_16x16x32_bf16 v[72:75], v[140:143], v[218:221], v[72:75]
	v_mfma_f32_16x16x32_bf16 v[76:79], v[132:135], v[218:221], v[76:79]
	v_mfma_f32_16x16x32_bf16 v[76:79], v[128:131], v[214:217], v[76:79]
	s_setprio 0
	s_setprio 1
	v_mfma_f32_16x16x32_bf16 v[116:119], v[144:147], v[180:183], v[116:119]
	v_mfma_f32_16x16x32_bf16 v[116:119], v[148:151], v[194:197], v[116:119]
	v_mfma_f32_16x16x32_bf16 v[112:115], v[176:179], v[194:197], v[112:115]
	v_mfma_f32_16x16x32_bf16 v[112:115], v[172:175], v[180:183], v[112:115]
	v_mfma_f32_16x16x32_bf16 v[96:99], v[172:175], v[198:201], v[96:99]
	v_mfma_f32_16x16x32_bf16 v[96:99], v[176:179], v[202:205], v[96:99]
	v_mfma_f32_16x16x32_bf16 v[100:103], v[148:151], v[202:205], v[100:103]
	v_mfma_f32_16x16x32_bf16 v[100:103], v[144:147], v[198:201], v[100:103]
	v_mfma_f32_16x16x32_bf16 v[84:87], v[144:147], v[206:209], v[84:87]
	v_mfma_f32_16x16x32_bf16 v[84:87], v[148:151], v[210:213], v[84:87]
	v_mfma_f32_16x16x32_bf16 v[80:83], v[176:179], v[210:213], v[80:83]
	v_mfma_f32_16x16x32_bf16 v[80:83], v[172:175], v[206:209], v[80:83]
	v_mfma_f32_16x16x32_bf16 v[64:67], v[172:175], v[214:217], v[64:67]
	v_mfma_f32_16x16x32_bf16 v[64:67], v[176:179], v[218:221], v[64:67]
	v_mfma_f32_16x16x32_bf16 v[68:71], v[148:151], v[218:221], v[68:71]
	v_mfma_f32_16x16x32_bf16 v[68:71], v[144:147], v[214:217], v[68:71]
	s_barrier
	s_setprio 0
	s_add_i32 s54, s84, s65
	v_lshl_add_u64 v[222:223], v[222:223], 0, s[28:29]
	s_mov_b32 m0, s54
	ds_read_b128 v[180:183], v191 offset:49152
	v_xor_b32_e32 v253, 64, v191
	ds_read_b128 v[194:197], v253 offset:49152
	ds_read_b128 v[198:201], v191 offset:51200
	ds_read_b128 v[202:205], v253 offset:51200
	ds_read_b128 v[206:209], v191 offset:53248
	ds_read_b128 v[210:213], v253 offset:53248
	ds_read_b128 v[214:217], v191 offset:55296
	ds_read_b128 v[218:221], v253 offset:55296
	global_load_lds_dwordx4 v[222:223], off
	s_add_i32 m0, s54, 0x2000
	s_add_u32 s54, s58, 0xb0080
	v_lshl_add_u64 v[222:223], v[224:225], 0, s[28:29]
	s_addc_u32 s55, s59, 0
	s_add_i32 s58, s85, s65
	global_load_lds_dwordx4 v[222:223], off
	v_lshl_add_u64 v[222:223], s[54:55], 0, v[154:155]
	s_mov_b32 m0, s58
	s_nop 0
	global_load_lds_dwordx4 v[222:223], off
	v_lshl_add_u64 v[222:223], s[54:55], 0, v[162:163]
	s_add_i32 m0, s58, 0x2000
	s_nop 0
	global_load_lds_dwordx4 v[222:223], off
	v_lshl_add_u64 v[222:223], v[226:227], 0, s[28:29]
	s_mov_b32 m0, s3
	s_nop 0
	global_load_lds_dwordx4 v[222:223], off
	v_lshl_add_u64 v[222:223], v[228:229], 0, s[28:29]
	s_mov_b32 m0, s71
	s_nop 0
	global_load_lds_dwordx4 v[222:223], off
	s_waitcnt vmcnt(8)
	s_waitcnt lgkmcnt(0)
	s_setprio 1
	s_barrier
	v_mfma_f32_16x16x32_bf16 v[60:63], v[128:131], v[180:183], v[60:63]
	v_mfma_f32_16x16x32_bf16 v[60:63], v[132:135], v[194:197], v[60:63]
	v_mfma_f32_16x16x32_bf16 v[56:59], v[140:143], v[194:197], v[56:59]
	v_mfma_f32_16x16x32_bf16 v[56:59], v[136:139], v[180:183], v[56:59]
	v_mfma_f32_16x16x32_bf16 v[40:43], v[136:139], v[198:201], v[40:43]
	v_mfma_f32_16x16x32_bf16 v[40:43], v[140:143], v[202:205], v[40:43]
	v_mfma_f32_16x16x32_bf16 v[44:47], v[132:135], v[202:205], v[44:47]
	v_mfma_f32_16x16x32_bf16 v[44:47], v[128:131], v[198:201], v[44:47]
	v_mfma_f32_16x16x32_bf16 v[28:31], v[128:131], v[206:209], v[28:31]
	v_mfma_f32_16x16x32_bf16 v[28:31], v[132:135], v[210:213], v[28:31]
	v_mfma_f32_16x16x32_bf16 v[24:27], v[140:143], v[210:213], v[24:27]
	v_mfma_f32_16x16x32_bf16 v[24:27], v[136:139], v[206:209], v[24:27]
	v_mfma_f32_16x16x32_bf16 v[8:11], v[136:139], v[214:217], v[8:11]
	v_mfma_f32_16x16x32_bf16 v[8:11], v[140:143], v[218:221], v[8:11]
	v_mfma_f32_16x16x32_bf16 v[12:15], v[132:135], v[218:221], v[12:15]
	v_mfma_f32_16x16x32_bf16 v[12:15], v[128:131], v[214:217], v[12:15]
	s_setprio 0
	s_setprio 1
	v_mfma_f32_16x16x32_bf16 v[52:55], v[144:147], v[180:183], v[52:55]
	v_mfma_f32_16x16x32_bf16 v[52:55], v[148:151], v[194:197], v[52:55]
	v_mfma_f32_16x16x32_bf16 v[48:51], v[176:179], v[194:197], v[48:51]
	v_mfma_f32_16x16x32_bf16 v[48:51], v[172:175], v[180:183], v[48:51]
	v_mfma_f32_16x16x32_bf16 v[32:35], v[172:175], v[198:201], v[32:35]
	v_mfma_f32_16x16x32_bf16 v[32:35], v[176:179], v[202:205], v[32:35]
	v_mfma_f32_16x16x32_bf16 v[36:39], v[148:151], v[202:205], v[36:39]
	v_mfma_f32_16x16x32_bf16 v[36:39], v[144:147], v[198:201], v[36:39]
	v_mfma_f32_16x16x32_bf16 v[20:23], v[144:147], v[206:209], v[20:23]
	v_mfma_f32_16x16x32_bf16 v[20:23], v[148:151], v[210:213], v[20:23]
	v_mfma_f32_16x16x32_bf16 v[16:19], v[176:179], v[210:213], v[16:19]
	v_mfma_f32_16x16x32_bf16 v[16:19], v[172:175], v[206:209], v[16:19]
	v_mfma_f32_16x16x32_bf16 v[0:3], v[172:175], v[214:217], v[0:3]
	v_mfma_f32_16x16x32_bf16 v[0:3], v[176:179], v[218:221], v[0:3]
	v_mfma_f32_16x16x32_bf16 v[4:7], v[148:151], v[218:221], v[4:7]
	v_mfma_f32_16x16x32_bf16 v[4:7], v[144:147], v[214:217], v[4:7]
	s_barrier
	s_setprio 0
	s_add_i32 s83, s83, 2
	s_add_u32 s81, s81, 0x100
	s_addc_u32 s82, s82, 0
	s_cmp_gt_u32 s83, 41
	s_mov_b64 s[54:55], s[56:57]
	s_cbranch_scc0 .LBB0_159
	s_and_b64 vcc, exec, s[30:31]
	s_cbranch_vccz .LBB0_162
	s_barrier

.LBB0_254:
	s_ashr_i32 s61, s60, 31
	s_lshl_b64 s[62:63], s[60:61], 19
	s_add_u32 s62, s35, s62
	s_addc_u32 s63, s47, s63
	s_and_b64 s[64:65], s[12:13], exec
	s_cselect_b32 s3, s63, s69
	s_cselect_b32 s61, s62, s68
	s_ashr_i32 s59, s58, 31
	s_lshl_b64 s[64:65], s[58:59], 19
	s_add_u32 s64, s49, s64
	s_addc_u32 s65, s70, s65
	s_and_b64 s[92:93], s[12:13], exec
	s_cselect_b32 s91, s65, s67
	s_cselect_b32 s92, s64, s66
	s_lshl_b32 s59, s14, 8
	v_add_u32_e32 v0, s59, v182
	s_add_u32 s93, s66, 0x100
	s_waitcnt lgkmcnt(0)
	v_ashrrev_i32_e32 v1, 31, v0
	s_addc_u32 s94, s67, 0
	v_lshl_add_u64 v[72:73], v[0:1], 4, s[26:27]
	s_add_u32 s14, s68, 0x40080
	s_addc_u32 s15, s69, 0
	s_mov_b32 s95, -2
	s_mov_b64 s[66:67], 0
	s_cmp_eq_u32 s90, 1
	s_cbranch_scc1 .Lfa_2
	v_add_u32_e32 v74, s83, v181
	ds_read_b128 v[88:91], v74
	v_xor_b32_e32 v253, 64, v74
	ds_read_b128 v[108:111], v253
	ds_read_b128 v[128:131], v74 offset:2048
	ds_read_b128 v[144:147], v253 offset:2048
	v_add_u32_e32 v74, s84, v181
	ds_read_b128 v[148:151], v74
	v_xor_b32_e32 v253, 64, v74
	ds_read_b128 v[152:155], v253
	ds_read_b128 v[176:179], v74 offset:2048
	ds_read_b128 v[190:193], v253 offset:2048
	s_add_u32 s68, s14, 0xfffc0080
	s_addc_u32 s69, s15, -1
	s_and_b64 s[66:67], s[66:67], exec
	s_cselect_b32 s69, s3, s69
	s_cselect_b32 s68, s61, s68
	s_cselect_b32 s67, s91, s94
	s_cselect_b32 s66, s92, s93
	v_lshl_add_u64 v[74:75], s[14:15], 0, v[170:171]
	s_add_i32 m0, s74, 0xc000
	ds_read_b128 v[194:197], v187
	v_xor_b32_e32 v253, 64, v187
	ds_read_b128 v[198:201], v253
	ds_read_b128 v[202:205], v187 offset:2048
	ds_read_b128 v[206:209], v253 offset:2048
	ds_read_b128 v[210:213], v187 offset:4096
	ds_read_b128 v[214:217], v253 offset:4096
	ds_read_b128 v[218:221], v187 offset:6144
	ds_read_b128 v[222:225], v253 offset:6144
	global_load_lds_dwordx4 v[74:75], off
	v_lshl_add_u64 v[74:75], s[14:15], 0, v[168:169]
	s_add_i32 m0, s74, 0xe000
	s_nop 0
	global_load_lds_dwordx4 v[74:75], off
	s_waitcnt vmcnt(24)
	s_waitcnt lgkmcnt(0)
	s_setprio 1
	s_barrier
	v_mfma_f32_16x16x32_bf16 v[140:143], v[88:91], v[194:197], 0
	v_mfma_f32_16x16x32_bf16 v[136:139], v[128:131], v[194:197], 0
	v_mfma_f32_16x16x32_bf16 v[120:123], v[88:91], v[202:205], 0
	v_mfma_f32_16x16x32_bf16 v[116:119], v[128:131], v[202:205], 0
	v_mfma_f32_16x16x32_bf16 v[100:103], v[88:91], v[210:213], 0
	v_mfma_f32_16x16x32_bf16 v[96:99], v[128:131], v[210:213], 0
	v_mfma_f32_16x16x32_bf16 v[80:83], v[88:91], v[218:221], 0
	v_mfma_f32_16x16x32_bf16 v[74:77], v[128:131], v[218:221], 0
	v_mfma_f32_16x16x32_bf16 v[140:143], v[108:111], v[198:201], v[140:143]
	v_mfma_f32_16x16x32_bf16 v[136:139], v[144:147], v[198:201], v[136:139]
	v_mfma_f32_16x16x32_bf16 v[120:123], v[108:111], v[206:209], v[120:123]
	v_mfma_f32_16x16x32_bf16 v[116:119], v[144:147], v[206:209], v[116:119]
	v_mfma_f32_16x16x32_bf16 v[100:103], v[108:111], v[214:217], v[100:103]
	v_mfma_f32_16x16x32_bf16 v[96:99], v[144:147], v[214:217], v[96:99]
	v_mfma_f32_16x16x32_bf16 v[80:83], v[108:111], v[222:225], v[80:83]
	v_mfma_f32_16x16x32_bf16 v[74:77], v[144:147], v[222:225], v[74:77]
	s_setprio 0
	s_setprio 1
	v_mfma_f32_16x16x32_bf16 v[132:135], v[148:151], v[194:197], 0
	v_mfma_f32_16x16x32_bf16 v[124:127], v[176:179], v[194:197], 0
	v_mfma_f32_16x16x32_bf16 v[112:115], v[148:151], v[202:205], 0
	v_mfma_f32_16x16x32_bf16 v[104:107], v[176:179], v[202:205], 0
	v_mfma_f32_16x16x32_bf16 v[92:95], v[148:151], v[210:213], 0
	v_mfma_f32_16x16x32_bf16 v[84:87], v[176:179], v[210:213], 0
	v_mfma_f32_16x16x32_bf16 v[68:71], v[148:151], v[218:221], 0
	v_mfma_f32_16x16x32_bf16 v[64:67], v[176:179], v[218:221], 0
	v_mfma_f32_16x16x32_bf16 v[132:135], v[152:155], v[198:201], v[132:135]
	v_mfma_f32_16x16x32_bf16 v[124:127], v[190:193], v[198:201], v[124:127]
	v_mfma_f32_16x16x32_bf16 v[112:115], v[152:155], v[206:209], v[112:115]
	v_mfma_f32_16x16x32_bf16 v[104:107], v[190:193], v[206:209], v[104:107]
	v_mfma_f32_16x16x32_bf16 v[92:95], v[152:155], v[214:217], v[92:95]
	v_mfma_f32_16x16x32_bf16 v[84:87], v[190:193], v[214:217], v[84:87]
	v_mfma_f32_16x16x32_bf16 v[68:71], v[152:155], v[222:225], v[68:71]
	v_mfma_f32_16x16x32_bf16 v[64:67], v[190:193], v[222:225], v[64:67]
	s_barrier
	s_setprio 0
	s_add_i32 s96, s83, s71
	v_lshl_add_u64 v[226:227], s[66:67], 0, v[162:163]
	s_mov_b32 m0, s96
	ds_read_b128 v[194:197], v187 offset:16384
	v_xor_b32_e32 v253, 64, v187
	ds_read_b128 v[198:201], v253 offset:16384
	ds_read_b128 v[202:205], v187 offset:18432
	ds_read_b128 v[206:209], v253 offset:18432
	ds_read_b128 v[210:213], v187 offset:20480
	ds_read_b128 v[214:217], v253 offset:20480
	ds_read_b128 v[218:221], v187 offset:22528
	ds_read_b128 v[222:225], v253 offset:22528
	global_load_lds_dwordx4 v[226:227], off
	s_add_i32 m0, s96, 0x2000
	s_add_u32 s96, s66, 0x40000
	v_lshl_add_u64 v[228:229], s[66:67], 0, v[166:167]
	s_addc_u32 s97, s67, 0
	s_add_i32 vcc_lo, s84, s71
	global_load_lds_dwordx4 v[228:229], off
	v_lshl_add_u64 v[78:79], s[96:97], 0, v[162:163]
	s_mov_b32 m0, vcc_lo
	v_lshl_add_u64 v[230:231], s[68:69], 0, v[160:161]
	global_load_lds_dwordx4 v[78:79], off
	v_lshl_add_u64 v[78:79], s[96:97], 0, v[166:167]
	s_add_i32 m0, vcc_lo, 0x2000
	v_lshl_add_u64 v[232:233], s[68:69], 0, v[164:165]
	global_load_lds_dwordx4 v[78:79], off
	s_mov_b32 m0, s74
	s_nop 0
	global_load_lds_dwordx4 v[230:231], off
	s_mov_b32 m0, s75
	s_nop 0
	global_load_lds_dwordx4 v[232:233], off
	s_waitcnt vmcnt(24)
	s_waitcnt lgkmcnt(0)
	s_setprio 1
	s_barrier
	v_mfma_f32_16x16x32_bf16 v[60:63], v[88:91], v[194:197], 0
	v_mfma_f32_16x16x32_bf16 v[56:59], v[128:131], v[194:197], 0
	v_mfma_f32_16x16x32_bf16 v[44:47], v[88:91], v[202:205], 0
	v_mfma_f32_16x16x32_bf16 v[40:43], v[128:131], v[202:205], 0
	v_mfma_f32_16x16x32_bf16 v[28:31], v[88:91], v[210:213], 0
	v_mfma_f32_16x16x32_bf16 v[24:27], v[128:131], v[210:213], 0
	v_mfma_f32_16x16x32_bf16 v[12:15], v[88:91], v[218:221], 0
	v_mfma_f32_16x16x32_bf16 v[8:11], v[128:131], v[218:221], 0
	v_mfma_f32_16x16x32_bf16 v[60:63], v[108:111], v[198:201], v[60:63]
	v_mfma_f32_16x16x32_bf16 v[56:59], v[144:147], v[198:201], v[56:59]
	v_mfma_f32_16x16x32_bf16 v[44:47], v[108:111], v[206:209], v[44:47]
	v_mfma_f32_16x16x32_bf16 v[40:43], v[144:147], v[206:209], v[40:43]
	v_mfma_f32_16x16x32_bf16 v[28:31], v[108:111], v[214:217], v[28:31]
	v_mfma_f32_16x16x32_bf16 v[24:27], v[144:147], v[214:217], v[24:27]
	v_mfma_f32_16x16x32_bf16 v[12:15], v[108:111], v[222:225], v[12:15]
	v_mfma_f32_16x16x32_bf16 v[8:11], v[144:147], v[222:225], v[8:11]
	s_setprio 0
	s_setprio 1
	v_mfma_f32_16x16x32_bf16 v[52:55], v[148:151], v[194:197], 0
	v_mfma_f32_16x16x32_bf16 v[48:51], v[176:179], v[194:197], 0
	v_mfma_f32_16x16x32_bf16 v[36:39], v[148:151], v[202:205], 0
	v_mfma_f32_16x16x32_bf16 v[32:35], v[176:179], v[202:205], 0
	v_mfma_f32_16x16x32_bf16 v[20:23], v[148:151], v[210:213], 0
	v_mfma_f32_16x16x32_bf16 v[16:19], v[176:179], v[210:213], 0
	v_mfma_f32_16x16x32_bf16 v[4:7], v[148:151], v[218:221], 0
	v_mfma_f32_16x16x32_bf16 v[0:3], v[176:179], v[218:221], 0
	v_mfma_f32_16x16x32_bf16 v[52:55], v[152:155], v[198:201], v[52:55]
	v_mfma_f32_16x16x32_bf16 v[48:51], v[190:193], v[198:201], v[48:51]
	v_mfma_f32_16x16x32_bf16 v[36:39], v[152:155], v[206:209], v[36:39]
	v_mfma_f32_16x16x32_bf16 v[32:35], v[190:193], v[206:209], v[32:35]
	v_mfma_f32_16x16x32_bf16 v[20:23], v[152:155], v[214:217], v[20:23]
	v_mfma_f32_16x16x32_bf16 v[16:19], v[190:193], v[214:217], v[16:19]
	v_mfma_f32_16x16x32_bf16 v[4:7], v[152:155], v[222:225], v[4:7]
	v_mfma_f32_16x16x32_bf16 v[0:3], v[190:193], v[222:225], v[0:3]
	s_barrier
	s_setprio 0
	s_add_i32 s96, 0, 0x18000
	v_add_u32_e32 v78, s96, v181
	s_add_i32 s97, 0, 0x1c000
	ds_read_b128 v[88:91], v78
	v_xor_b32_e32 v253, 64, v78
	ds_read_b128 v[108:111], v253
	ds_read_b128 v[128:131], v78 offset:2048
	ds_read_b128 v[144:147], v253 offset:2048
	v_add_u32_e32 v78, s97, v181
	ds_read_b128 v[148:151], v78
	v_xor_b32_e32 v253, 64, v78
	ds_read_b128 v[152:155], v253
	ds_read_b128 v[176:179], v78 offset:2048
	ds_read_b128 v[190:193], v253 offset:2048
	s_add_u32 s68, s68, 0x40000
	s_addc_u32 s69, s69, 0
	s_mov_b32 m0, s76
	v_lshl_add_u64 v[78:79], s[68:69], 0, v[160:161]
	ds_read_b128 v[194:197], v187 offset:32768
	v_xor_b32_e32 v253, 64, v187
	ds_read_b128 v[198:201], v253 offset:32768
	ds_read_b128 v[202:205], v187 offset:34816
	ds_read_b128 v[206:209], v253 offset:34816
	ds_read_b128 v[210:213], v187 offset:36864
	ds_read_b128 v[214:217], v253 offset:36864
	ds_read_b128 v[218:221], v187 offset:38912
	ds_read_b128 v[222:225], v253 offset:38912
	global_load_lds_dwordx4 v[78:79], off
	v_lshl_add_u64 v[78:79], s[68:69], 0, v[164:165]
	s_mov_b32 m0, s77
	s_nop 0
	global_load_lds_dwordx4 v[78:79], off
	s_waitcnt vmcnt(8)
	s_waitcnt lgkmcnt(0)
	s_setprio 1
	s_barrier
	v_mfma_f32_16x16x32_bf16 v[140:143], v[88:91], v[194:197], v[140:143]
	v_mfma_f32_16x16x32_bf16 v[136:139], v[128:131], v[194:197], v[136:139]
	v_mfma_f32_16x16x32_bf16 v[120:123], v[88:91], v[202:205], v[120:123]
	v_mfma_f32_16x16x32_bf16 v[116:119], v[128:131], v[202:205], v[116:119]
	v_mfma_f32_16x16x32_bf16 v[100:103], v[88:91], v[210:213], v[100:103]
	v_mfma_f32_16x16x32_bf16 v[96:99], v[128:131], v[210:213], v[96:99]
	v_mfma_f32_16x16x32_bf16 v[78:81], v[88:91], v[218:221], v[80:83]
	v_mfma_f32_16x16x32_bf16 v[74:77], v[128:131], v[218:221], v[74:77]
	v_mfma_f32_16x16x32_bf16 v[140:143], v[108:111], v[198:201], v[140:143]
	v_mfma_f32_16x16x32_bf16 v[136:139], v[144:147], v[198:201], v[136:139]
	v_mfma_f32_16x16x32_bf16 v[120:123], v[108:111], v[206:209], v[120:123]
	v_mfma_f32_16x16x32_bf16 v[116:119], v[144:147], v[206:209], v[116:119]
	v_mfma_f32_16x16x32_bf16 v[100:103], v[108:111], v[214:217], v[100:103]
	v_mfma_f32_16x16x32_bf16 v[96:99], v[144:147], v[214:217], v[96:99]
	v_mfma_f32_16x16x32_bf16 v[80:83], v[108:111], v[222:225], v[78:81]
	v_mfma_f32_16x16x32_bf16 v[76:79], v[144:147], v[222:225], v[74:77]
	s_setprio 0
	s_setprio 1
	v_mfma_f32_16x16x32_bf16 v[132:135], v[148:151], v[194:197], v[132:135]
	v_mfma_f32_16x16x32_bf16 v[132:135], v[152:155], v[198:201], v[132:135]
	v_mfma_f32_16x16x32_bf16 v[124:127], v[190:193], v[198:201], v[124:127]
	v_mfma_f32_16x16x32_bf16 v[124:127], v[176:179], v[194:197], v[124:127]
	v_mfma_f32_16x16x32_bf16 v[104:107], v[176:179], v[202:205], v[104:107]
	v_mfma_f32_16x16x32_bf16 v[104:107], v[190:193], v[206:209], v[104:107]
	v_mfma_f32_16x16x32_bf16 v[112:115], v[152:155], v[206:209], v[112:115]
	v_mfma_f32_16x16x32_bf16 v[112:115], v[148:151], v[202:205], v[112:115]
	v_mfma_f32_16x16x32_bf16 v[92:95], v[148:151], v[210:213], v[92:95]
	v_mfma_f32_16x16x32_bf16 v[92:95], v[152:155], v[214:217], v[92:95]
	v_mfma_f32_16x16x32_bf16 v[84:87], v[190:193], v[214:217], v[84:87]
	v_mfma_f32_16x16x32_bf16 v[84:87], v[176:179], v[210:213], v[84:87]
	v_mfma_f32_16x16x32_bf16 v[64:67], v[176:179], v[218:221], v[64:67]
	v_mfma_f32_16x16x32_bf16 v[64:67], v[190:193], v[222:225], v[64:67]
	v_mfma_f32_16x16x32_bf16 v[68:71], v[152:155], v[222:225], v[68:71]
	v_mfma_f32_16x16x32_bf16 v[68:71], v[148:151], v[218:221], v[68:71]
	s_barrier
	s_setprio 0
	s_add_i32 s68, s96, s71
	v_lshl_add_u64 v[74:75], v[226:227], 0, s[28:29]
	s_mov_b32 m0, s68
	ds_read_b128 v[194:197], v187 offset:49152
	v_xor_b32_e32 v253, 64, v187
	ds_read_b128 v[198:201], v253 offset:49152
	ds_read_b128 v[202:205], v187 offset:51200
	ds_read_b128 v[206:209], v253 offset:51200
	ds_read_b128 v[210:213], v187 offset:53248
	ds_read_b128 v[214:217], v253 offset:53248
	ds_read_b128 v[218:221], v187 offset:55296
	ds_read_b128 v[222:225], v253 offset:55296
	global_load_lds_dwordx4 v[74:75], off
	s_add_i32 m0, s68, 0x2000
	s_add_u32 s66, s66, 0x40080
	v_lshl_add_u64 v[74:75], v[228:229], 0, s[28:29]
	s_addc_u32 s67, s67, 0
	s_add_i32 s68, s97, s71
	global_load_lds_dwordx4 v[74:75], off
	v_lshl_add_u64 v[74:75], s[66:67], 0, v[162:163]
	s_mov_b32 m0, s68
	s_nop 0
	global_load_lds_dwordx4 v[74:75], off
	v_lshl_add_u64 v[74:75], s[66:67], 0, v[166:167]
	s_add_i32 m0, s68, 0x2000
	s_nop 0
	global_load_lds_dwordx4 v[74:75], off
	v_lshl_add_u64 v[74:75], v[230:231], 0, s[28:29]
	s_mov_b32 m0, s78
	s_nop 0
	global_load_lds_dwordx4 v[74:75], off
	v_lshl_add_u64 v[74:75], v[232:233], 0, s[28:29]
	s_mov_b32 m0, s79
	s_nop 0
	global_load_lds_dwordx4 v[74:75], off
	s_waitcnt vmcnt(8)
	s_waitcnt lgkmcnt(0)
	s_setprio 1
	s_barrier
	v_mfma_f32_16x16x32_bf16 v[60:63], v[88:91], v[194:197], v[60:63]
	v_mfma_f32_16x16x32_bf16 v[60:63], v[108:111], v[198:201], v[60:63]
	v_mfma_f32_16x16x32_bf16 v[56:59], v[144:147], v[198:201], v[56:59]
	v_mfma_f32_16x16x32_bf16 v[56:59], v[128:131], v[194:197], v[56:59]
	v_mfma_f32_16x16x32_bf16 v[40:43], v[128:131], v[202:205], v[40:43]
	v_mfma_f32_16x16x32_bf16 v[40:43], v[144:147], v[206:209], v[40:43]
	v_mfma_f32_16x16x32_bf16 v[44:47], v[108:111], v[206:209], v[44:47]
	v_mfma_f32_16x16x32_bf16 v[44:47], v[88:91], v[202:205], v[44:47]
	v_mfma_f32_16x16x32_bf16 v[28:31], v[88:91], v[210:213], v[28:31]
	v_mfma_f32_16x16x32_bf16 v[28:31], v[108:111], v[214:217], v[28:31]
	v_mfma_f32_16x16x32_bf16 v[24:27], v[144:147], v[214:217], v[24:27]
	v_mfma_f32_16x16x32_bf16 v[24:27], v[128:131], v[210:213], v[24:27]
	v_mfma_f32_16x16x32_bf16 v[8:11], v[128:131], v[218:221], v[8:11]
	v_mfma_f32_16x16x32_bf16 v[8:11], v[144:147], v[222:225], v[8:11]
	v_mfma_f32_16x16x32_bf16 v[12:15], v[108:111], v[222:225], v[12:15]
	v_mfma_f32_16x16x32_bf16 v[12:15], v[88:91], v[218:221], v[12:15]
	s_setprio 0
	s_setprio 1
	v_mfma_f32_16x16x32_bf16 v[52:55], v[148:151], v[194:197], v[52:55]
	v_mfma_f32_16x16x32_bf16 v[52:55], v[152:155], v[198:201], v[52:55]
	v_mfma_f32_16x16x32_bf16 v[48:51], v[190:193], v[198:201], v[48:51]
	v_mfma_f32_16x16x32_bf16 v[48:51], v[176:179], v[194:197], v[48:51]
	v_mfma_f32_16x16x32_bf16 v[32:35], v[176:179], v[202:205], v[32:35]
	v_mfma_f32_16x16x32_bf16 v[32:35], v[190:193], v[206:209], v[32:35]
	v_mfma_f32_16x16x32_bf16 v[36:39], v[152:155], v[206:209], v[36:39]
	v_mfma_f32_16x16x32_bf16 v[36:39], v[148:151], v[202:205], v[36:39]
	v_mfma_f32_16x16x32_bf16 v[20:23], v[148:151], v[210:213], v[20:23]
	v_mfma_f32_16x16x32_bf16 v[20:23], v[152:155], v[214:217], v[20:23]
	v_mfma_f32_16x16x32_bf16 v[16:19], v[190:193], v[214:217], v[16:19]
	v_mfma_f32_16x16x32_bf16 v[16:19], v[176:179], v[210:213], v[16:19]
	v_mfma_f32_16x16x32_bf16 v[0:3], v[176:179], v[218:221], v[0:3]
	v_mfma_f32_16x16x32_bf16 v[0:3], v[190:193], v[222:225], v[0:3]
	v_mfma_f32_16x16x32_bf16 v[4:7], v[152:155], v[222:225], v[4:7]
	v_mfma_f32_16x16x32_bf16 v[4:7], v[148:151], v[218:221], v[4:7]
	s_barrier
	s_setprio 0
	s_add_i32 s95, s95, 2
	s_add_u32 s93, s93, 0x100
	s_addc_u32 s94, s94, 0
	s_add_u32 s14, s14, 0x100
	s_addc_u32 s15, s15, 0
	s_branch .LBB0_256
.Lfa_2:
	v_add_u32_e32 v74, s83, v181
	ds_read_b128 v[88:91], v74
	v_xor_b32_e32 v253, 64, v74
	ds_read_b128 v[108:111], v253
	ds_read_b128 v[128:131], v74 offset:2048
	ds_read_b128 v[144:147], v253 offset:2048
	v_add_u32_e32 v74, s84, v181
	ds_read_b128 v[148:151], v74
	v_xor_b32_e32 v253, 64, v74
	ds_read_b128 v[152:155], v253
	ds_read_b128 v[176:179], v74 offset:2048
	ds_read_b128 v[190:193], v253 offset:2048
	s_add_u32 s68, s14, 0xfffc0080
	s_addc_u32 s69, s15, -1
	s_and_b64 s[66:67], s[66:67], exec
	s_cselect_b32 s69, s3, s69
	s_cselect_b32 s68, s61, s68
	s_cselect_b32 s67, s91, s94
	s_cselect_b32 s66, s92, s93
	v_lshl_add_u64 v[74:75], s[14:15], 0, v[170:171]
	s_add_i32 m0, s74, 0xc000
	ds_read_b128 v[194:197], v187
	v_xor_b32_e32 v253, 64, v187
	ds_read_b128 v[198:201], v253
	ds_read_b128 v[202:205], v187 offset:2048
	ds_read_b128 v[206:209], v253 offset:2048
	ds_read_b128 v[210:213], v187 offset:4096
	ds_read_b128 v[214:217], v253 offset:4096
	ds_read_b128 v[218:221], v187 offset:6144
	ds_read_b128 v[222:225], v253 offset:6144
	global_load_lds_dwordx4 v[74:75], off
	v_lshl_add_u64 v[74:75], s[14:15], 0, v[168:169]
	s_add_i32 m0, s74, 0xe000
	s_nop 0
	global_load_lds_dwordx4 v[74:75], off
	s_waitcnt vmcnt(8)
	s_waitcnt lgkmcnt(0)
	s_setprio 1
	s_barrier
	v_mfma_f32_16x16x32_bf16 v[140:143], v[88:91], v[194:197], 0
	v_mfma_f32_16x16x32_bf16 v[136:139], v[128:131], v[194:197], 0
	v_mfma_f32_16x16x32_bf16 v[120:123], v[88:91], v[202:205], 0
	v_mfma_f32_16x16x32_bf16 v[116:119], v[128:131], v[202:205], 0
	v_mfma_f32_16x16x32_bf16 v[100:103], v[88:91], v[210:213], 0
	v_mfma_f32_16x16x32_bf16 v[96:99], v[128:131], v[210:213], 0
	v_mfma_f32_16x16x32_bf16 v[80:83], v[88:91], v[218:221], 0
	v_mfma_f32_16x16x32_bf16 v[74:77], v[128:131], v[218:221], 0
	v_mfma_f32_16x16x32_bf16 v[140:143], v[108:111], v[198:201], v[140:143]
	v_mfma_f32_16x16x32_bf16 v[136:139], v[144:147], v[198:201], v[136:139]
	v_mfma_f32_16x16x32_bf16 v[120:123], v[108:111], v[206:209], v[120:123]
	v_mfma_f32_16x16x32_bf16 v[116:119], v[144:147], v[206:209], v[116:119]
	v_mfma_f32_16x16x32_bf16 v[100:103], v[108:111], v[214:217], v[100:103]
	v_mfma_f32_16x16x32_bf16 v[96:99], v[144:147], v[214:217], v[96:99]
	v_mfma_f32_16x16x32_bf16 v[80:83], v[108:111], v[222:225], v[80:83]
	v_mfma_f32_16x16x32_bf16 v[74:77], v[144:147], v[222:225], v[74:77]
	s_setprio 0
	s_setprio 1
	v_mfma_f32_16x16x32_bf16 v[132:135], v[148:151], v[194:197], 0
	v_mfma_f32_16x16x32_bf16 v[124:127], v[176:179], v[194:197], 0
	v_mfma_f32_16x16x32_bf16 v[112:115], v[148:151], v[202:205], 0
	v_mfma_f32_16x16x32_bf16 v[104:107], v[176:179], v[202:205], 0
	v_mfma_f32_16x16x32_bf16 v[92:95], v[148:151], v[210:213], 0
	v_mfma_f32_16x16x32_bf16 v[84:87], v[176:179], v[210:213], 0
	v_mfma_f32_16x16x32_bf16 v[68:71], v[148:151], v[218:221], 0
	v_mfma_f32_16x16x32_bf16 v[64:67], v[176:179], v[218:221], 0
	v_mfma_f32_16x16x32_bf16 v[132:135], v[152:155], v[198:201], v[132:135]
	v_mfma_f32_16x16x32_bf16 v[124:127], v[190:193], v[198:201], v[124:127]
	v_mfma_f32_16x16x32_bf16 v[112:115], v[152:155], v[206:209], v[112:115]
	v_mfma_f32_16x16x32_bf16 v[104:107], v[190:193], v[206:209], v[104:107]
	v_mfma_f32_16x16x32_bf16 v[92:95], v[152:155], v[214:217], v[92:95]
	v_mfma_f32_16x16x32_bf16 v[84:87], v[190:193], v[214:217], v[84:87]
	v_mfma_f32_16x16x32_bf16 v[68:71], v[152:155], v[222:225], v[68:71]
	v_mfma_f32_16x16x32_bf16 v[64:67], v[190:193], v[222:225], v[64:67]
	s_barrier
	s_setprio 0
	s_add_i32 s96, s83, s71
	v_lshl_add_u64 v[226:227], s[66:67], 0, v[162:163]
	s_mov_b32 m0, s96
	ds_read_b128 v[194:197], v187 offset:16384
	v_xor_b32_e32 v253, 64, v187
	ds_read_b128 v[198:201], v253 offset:16384
	ds_read_b128 v[202:205], v187 offset:18432
	ds_read_b128 v[206:209], v253 offset:18432
	ds_read_b128 v[210:213], v187 offset:20480
	ds_read_b128 v[214:217], v253 offset:20480
	ds_read_b128 v[218:221], v187 offset:22528
	ds_read_b128 v[222:225], v253 offset:22528
	global_load_lds_dwordx4 v[226:227], off
	s_add_i32 m0, s96, 0x2000
	s_add_u32 s96, s66, 0x40000
	v_lshl_add_u64 v[228:229], s[66:67], 0, v[166:167]
	s_addc_u32 s97, s67, 0
	s_add_i32 vcc_lo, s84, s71
	global_load_lds_dwordx4 v[228:229], off
	v_lshl_add_u64 v[78:79], s[96:97], 0, v[162:163]
	s_mov_b32 m0, vcc_lo
	v_lshl_add_u64 v[230:231], s[68:69], 0, v[160:161]
	global_load_lds_dwordx4 v[78:79], off
	v_lshl_add_u64 v[78:79], s[96:97], 0, v[166:167]
	s_add_i32 m0, vcc_lo, 0x2000
	v_lshl_add_u64 v[232:233], s[68:69], 0, v[164:165]
	global_load_lds_dwordx4 v[78:79], off
	s_mov_b32 m0, s74
	s_nop 0
	global_load_lds_dwordx4 v[230:231], off
	s_mov_b32 m0, s75
	s_nop 0
	global_load_lds_dwordx4 v[232:233], off
	s_waitcnt vmcnt(8)
	s_waitcnt lgkmcnt(0)
	s_setprio 1
	s_barrier
	v_mfma_f32_16x16x32_bf16 v[60:63], v[88:91], v[194:197], 0
	v_mfma_f32_16x16x32_bf16 v[56:59], v[128:131], v[194:197], 0
	v_mfma_f32_16x16x32_bf16 v[44:47], v[88:91], v[202:205], 0
	v_mfma_f32_16x16x32_bf16 v[40:43], v[128:131], v[202:205], 0
	v_mfma_f32_16x16x32_bf16 v[28:31], v[88:91], v[210:213], 0
	v_mfma_f32_16x16x32_bf16 v[24:27], v[128:131], v[210:213], 0
	v_mfma_f32_16x16x32_bf16 v[12:15], v[88:91], v[218:221], 0
	v_mfma_f32_16x16x32_bf16 v[8:11], v[128:131], v[218:221], 0
	v_mfma_f32_16x16x32_bf16 v[60:63], v[108:111], v[198:201], v[60:63]
	v_mfma_f32_16x16x32_bf16 v[56:59], v[144:147], v[198:201], v[56:59]
	v_mfma_f32_16x16x32_bf16 v[44:47], v[108:111], v[206:209], v[44:47]
	v_mfma_f32_16x16x32_bf16 v[40:43], v[144:147], v[206:209], v[40:43]
	v_mfma_f32_16x16x32_bf16 v[28:31], v[108:111], v[214:217], v[28:31]
	v_mfma_f32_16x16x32_bf16 v[24:27], v[144:147], v[214:217], v[24:27]
	v_mfma_f32_16x16x32_bf16 v[12:15], v[108:111], v[222:225], v[12:15]
	v_mfma_f32_16x16x32_bf16 v[8:11], v[144:147], v[222:225], v[8:11]
	s_setprio 0
	s_setprio 1
	v_mfma_f32_16x16x32_bf16 v[52:55], v[148:151], v[194:197], 0
	v_mfma_f32_16x16x32_bf16 v[48:51], v[176:179], v[194:197], 0
	v_mfma_f32_16x16x32_bf16 v[36:39], v[148:151], v[202:205], 0
	v_mfma_f32_16x16x32_bf16 v[32:35], v[176:179], v[202:205], 0
	v_mfma_f32_16x16x32_bf16 v[20:23], v[148:151], v[210:213], 0
	v_mfma_f32_16x16x32_bf16 v[16:19], v[176:179], v[210:213], 0
	v_mfma_f32_16x16x32_bf16 v[4:7], v[148:151], v[218:221], 0
	v_mfma_f32_16x16x32_bf16 v[0:3], v[176:179], v[218:221], 0
	v_mfma_f32_16x16x32_bf16 v[52:55], v[152:155], v[198:201], v[52:55]
	v_mfma_f32_16x16x32_bf16 v[48:51], v[190:193], v[198:201], v[48:51]
	v_mfma_f32_16x16x32_bf16 v[36:39], v[152:155], v[206:209], v[36:39]
	v_mfma_f32_16x16x32_bf16 v[32:35], v[190:193], v[206:209], v[32:35]
	v_mfma_f32_16x16x32_bf16 v[20:23], v[152:155], v[214:217], v[20:23]
	v_mfma_f32_16x16x32_bf16 v[16:19], v[190:193], v[214:217], v[16:19]
	v_mfma_f32_16x16x32_bf16 v[4:7], v[152:155], v[222:225], v[4:7]
	v_mfma_f32_16x16x32_bf16 v[0:3], v[190:193], v[222:225], v[0:3]
	s_barrier
	s_setprio 0
	s_add_i32 s96, 0, 0x18000
	v_add_u32_e32 v78, s96, v181
	s_add_i32 s97, 0, 0x1c000
	ds_read_b128 v[88:91], v78
	v_xor_b32_e32 v253, 64, v78
	ds_read_b128 v[108:111], v253
	ds_read_b128 v[128:131], v78 offset:2048
	ds_read_b128 v[144:147], v253 offset:2048
	v_add_u32_e32 v78, s97, v181
	ds_read_b128 v[148:151], v78
	v_xor_b32_e32 v253, 64, v78
	ds_read_b128 v[152:155], v253
	ds_read_b128 v[176:179], v78 offset:2048
	ds_read_b128 v[190:193], v253 offset:2048
	s_add_u32 s68, s68, 0x40000
	s_addc_u32 s69, s69, 0
	s_mov_b32 m0, s76
	v_lshl_add_u64 v[78:79], s[68:69], 0, v[160:161]
	ds_read_b128 v[194:197], v187 offset:32768
	v_xor_b32_e32 v253, 64, v187
	ds_read_b128 v[198:201], v253 offset:32768
	ds_read_b128 v[202:205], v187 offset:34816
	ds_read_b128 v[206:209], v253 offset:34816
	ds_read_b128 v[210:213], v187 offset:36864
	ds_read_b128 v[214:217], v253 offset:36864
	ds_read_b128 v[218:221], v187 offset:38912
	ds_read_b128 v[222:225], v253 offset:38912
	global_load_lds_dwordx4 v[78:79], off
	v_lshl_add_u64 v[78:79], s[68:69], 0, v[164:165]
	s_mov_b32 m0, s77
	s_nop 0
	global_load_lds_dwordx4 v[78:79], off
	s_waitcnt vmcnt(8)
	s_waitcnt lgkmcnt(0)
	s_setprio 1
	s_barrier
	v_mfma_f32_16x16x32_bf16 v[140:143], v[88:91], v[194:197], v[140:143]
	v_mfma_f32_16x16x32_bf16 v[136:139], v[128:131], v[194:197], v[136:139]
	v_mfma_f32_16x16x32_bf16 v[120:123], v[88:91], v[202:205], v[120:123]
	v_mfma_f32_16x16x32_bf16 v[116:119], v[128:131], v[202:205], v[116:119]
	v_mfma_f32_16x16x32_bf16 v[100:103], v[88:91], v[210:213], v[100:103]
	v_mfma_f32_16x16x32_bf16 v[96:99], v[128:131], v[210:213], v[96:99]
	v_mfma_f32_16x16x32_bf16 v[78:81], v[88:91], v[218:221], v[80:83]
	v_mfma_f32_16x16x32_bf16 v[74:77], v[128:131], v[218:221], v[74:77]
	v_mfma_f32_16x16x32_bf16 v[140:143], v[108:111], v[198:201], v[140:143]
	v_mfma_f32_16x16x32_bf16 v[136:139], v[144:147], v[198:201], v[136:139]
	v_mfma_f32_16x16x32_bf16 v[120:123], v[108:111], v[206:209], v[120:123]
	v_mfma_f32_16x16x32_bf16 v[116:119], v[144:147], v[206:209], v[116:119]
	v_mfma_f32_16x16x32_bf16 v[100:103], v[108:111], v[214:217], v[100:103]
	v_mfma_f32_16x16x32_bf16 v[96:99], v[144:147], v[214:217], v[96:99]
	v_mfma_f32_16x16x32_bf16 v[80:83], v[108:111], v[222:225], v[78:81]
	v_mfma_f32_16x16x32_bf16 v[76:79], v[144:147], v[222:225], v[74:77]
	s_setprio 0
	s_setprio 1
	v_mfma_f32_16x16x32_bf16 v[132:135], v[148:151], v[194:197], v[132:135]
	v_mfma_f32_16x16x32_bf16 v[132:135], v[152:155], v[198:201], v[132:135]
	v_mfma_f32_16x16x32_bf16 v[124:127], v[190:193], v[198:201], v[124:127]
	v_mfma_f32_16x16x32_bf16 v[124:127], v[176:179], v[194:197], v[124:127]
	v_mfma_f32_16x16x32_bf16 v[104:107], v[176:179], v[202:205], v[104:107]
	v_mfma_f32_16x16x32_bf16 v[104:107], v[190:193], v[206:209], v[104:107]
	v_mfma_f32_16x16x32_bf16 v[112:115], v[152:155], v[206:209], v[112:115]
	v_mfma_f32_16x16x32_bf16 v[112:115], v[148:151], v[202:205], v[112:115]
	v_mfma_f32_16x16x32_bf16 v[92:95], v[148:151], v[210:213], v[92:95]
	v_mfma_f32_16x16x32_bf16 v[92:95], v[152:155], v[214:217], v[92:95]
	v_mfma_f32_16x16x32_bf16 v[84:87], v[190:193], v[214:217], v[84:87]
	v_mfma_f32_16x16x32_bf16 v[84:87], v[176:179], v[210:213], v[84:87]
	v_mfma_f32_16x16x32_bf16 v[64:67], v[176:179], v[218:221], v[64:67]
	v_mfma_f32_16x16x32_bf16 v[64:67], v[190:193], v[222:225], v[64:67]
	v_mfma_f32_16x16x32_bf16 v[68:71], v[152:155], v[222:225], v[68:71]
	v_mfma_f32_16x16x32_bf16 v[68:71], v[148:151], v[218:221], v[68:71]
	s_barrier
	s_setprio 0
	s_add_i32 s68, s96, s71
	v_lshl_add_u64 v[74:75], v[226:227], 0, s[28:29]
	s_mov_b32 m0, s68
	ds_read_b128 v[194:197], v187 offset:49152
	v_xor_b32_e32 v253, 64, v187
	ds_read_b128 v[198:201], v253 offset:49152
	ds_read_b128 v[202:205], v187 offset:51200
	ds_read_b128 v[206:209], v253 offset:51200
	ds_read_b128 v[210:213], v187 offset:53248
	ds_read_b128 v[214:217], v253 offset:53248
	ds_read_b128 v[218:221], v187 offset:55296
	ds_read_b128 v[222:225], v253 offset:55296
	global_load_lds_dwordx4 v[74:75], off
	s_add_i32 m0, s68, 0x2000
	s_add_u32 s66, s66, 0x40080
	v_lshl_add_u64 v[74:75], v[228:229], 0, s[28:29]
	s_addc_u32 s67, s67, 0
	s_add_i32 s68, s97, s71
	global_load_lds_dwordx4 v[74:75], off
	v_lshl_add_u64 v[74:75], s[66:67], 0, v[162:163]
	s_mov_b32 m0, s68
	s_nop 0
	global_load_lds_dwordx4 v[74:75], off
	v_lshl_add_u64 v[74:75], s[66:67], 0, v[166:167]
	s_add_i32 m0, s68, 0x2000
	s_nop 0
	global_load_lds_dwordx4 v[74:75], off
	v_lshl_add_u64 v[74:75], v[230:231], 0, s[28:29]
	s_mov_b32 m0, s78
	s_nop 0
	global_load_lds_dwordx4 v[74:75], off
	v_lshl_add_u64 v[74:75], v[232:233], 0, s[28:29]
	s_mov_b32 m0, s79
	s_nop 0
	global_load_lds_dwordx4 v[74:75], off
	s_waitcnt vmcnt(8)
	s_waitcnt lgkmcnt(0)
	s_setprio 1
	s_barrier
	v_mfma_f32_16x16x32_bf16 v[60:63], v[88:91], v[194:197], v[60:63]
	v_mfma_f32_16x16x32_bf16 v[60:63], v[108:111], v[198:201], v[60:63]
	v_mfma_f32_16x16x32_bf16 v[56:59], v[144:147], v[198:201], v[56:59]
	v_mfma_f32_16x16x32_bf16 v[56:59], v[128:131], v[194:197], v[56:59]
	v_mfma_f32_16x16x32_bf16 v[40:43], v[128:131], v[202:205], v[40:43]
	v_mfma_f32_16x16x32_bf16 v[40:43], v[144:147], v[206:209], v[40:43]
	v_mfma_f32_16x16x32_bf16 v[44:47], v[108:111], v[206:209], v[44:47]
	v_mfma_f32_16x16x32_bf16 v[44:47], v[88:91], v[202:205], v[44:47]
	v_mfma_f32_16x16x32_bf16 v[28:31], v[88:91], v[210:213], v[28:31]
	v_mfma_f32_16x16x32_bf16 v[28:31], v[108:111], v[214:217], v[28:31]
	v_mfma_f32_16x16x32_bf16 v[24:27], v[144:147], v[214:217], v[24:27]
	v_mfma_f32_16x16x32_bf16 v[24:27], v[128:131], v[210:213], v[24:27]
	v_mfma_f32_16x16x32_bf16 v[8:11], v[128:131], v[218:221], v[8:11]
	v_mfma_f32_16x16x32_bf16 v[8:11], v[144:147], v[222:225], v[8:11]
	v_mfma_f32_16x16x32_bf16 v[12:15], v[108:111], v[222:225], v[12:15]
	v_mfma_f32_16x16x32_bf16 v[12:15], v[88:91], v[218:221], v[12:15]
	s_setprio 0
	s_setprio 1
	v_mfma_f32_16x16x32_bf16 v[52:55], v[148:151], v[194:197], v[52:55]
	v_mfma_f32_16x16x32_bf16 v[52:55], v[152:155], v[198:201], v[52:55]
	v_mfma_f32_16x16x32_bf16 v[48:51], v[190:193], v[198:201], v[48:51]
	v_mfma_f32_16x16x32_bf16 v[48:51], v[176:179], v[194:197], v[48:51]
	v_mfma_f32_16x16x32_bf16 v[32:35], v[176:179], v[202:205], v[32:35]
	v_mfma_f32_16x16x32_bf16 v[32:35], v[190:193], v[206:209], v[32:35]
	v_mfma_f32_16x16x32_bf16 v[36:39], v[152:155], v[206:209], v[36:39]
	v_mfma_f32_16x16x32_bf16 v[36:39], v[148:151], v[202:205], v[36:39]
	v_mfma_f32_16x16x32_bf16 v[20:23], v[148:151], v[210:213], v[20:23]
	v_mfma_f32_16x16x32_bf16 v[20:23], v[152:155], v[214:217], v[20:23]
	v_mfma_f32_16x16x32_bf16 v[16:19], v[190:193], v[214:217], v[16:19]
	v_mfma_f32_16x16x32_bf16 v[16:19], v[176:179], v[210:213], v[16:19]
	v_mfma_f32_16x16x32_bf16 v[0:3], v[176:179], v[218:221], v[0:3]
	v_mfma_f32_16x16x32_bf16 v[0:3], v[190:193], v[222:225], v[0:3]
	v_mfma_f32_16x16x32_bf16 v[4:7], v[152:155], v[222:225], v[4:7]
	v_mfma_f32_16x16x32_bf16 v[4:7], v[148:151], v[218:221], v[4:7]
	s_barrier
	s_setprio 0
	s_add_i32 s95, s95, 2
	s_add_u32 s93, s93, 0x100
	s_addc_u32 s94, s94, 0
	s_add_u32 s14, s14, 0x100
	s_addc_u32 s15, s15, 0
	s_branch .LBB0_256
.LBB0_255:
	v_add_u32_e32 v74, s83, v181
	ds_read_b128 v[88:91], v74
	v_xor_b32_e32 v253, 64, v74
	ds_read_b128 v[108:111], v253
	ds_read_b128 v[128:131], v74 offset:2048
	ds_read_b128 v[144:147], v253 offset:2048
	v_add_u32_e32 v74, s84, v181
	ds_read_b128 v[148:151], v74
	v_xor_b32_e32 v253, 64, v74
	ds_read_b128 v[152:155], v253
	ds_read_b128 v[176:179], v74 offset:2048
	ds_read_b128 v[190:193], v253 offset:2048
	s_add_u32 s68, s14, 0xfffc0080
	s_addc_u32 s69, s15, -1
	s_and_b64 s[66:67], s[66:67], exec
	s_cselect_b32 s69, s3, s69
	s_cselect_b32 s68, s61, s68
	s_cselect_b32 s67, s91, s94
	s_cselect_b32 s66, s92, s93
	v_lshl_add_u64 v[74:75], s[14:15], 0, v[170:171]
	s_add_i32 m0, s74, 0xc000
	ds_read_b128 v[194:197], v187
	v_xor_b32_e32 v253, 64, v187
	ds_read_b128 v[198:201], v253
	ds_read_b128 v[202:205], v187 offset:2048
	ds_read_b128 v[206:209], v253 offset:2048
	ds_read_b128 v[210:213], v187 offset:4096
	ds_read_b128 v[214:217], v253 offset:4096
	ds_read_b128 v[218:221], v187 offset:6144
	ds_read_b128 v[222:225], v253 offset:6144
	global_load_lds_dwordx4 v[74:75], off
	v_lshl_add_u64 v[74:75], s[14:15], 0, v[168:169]
	s_add_i32 m0, s74, 0xe000
	s_nop 0
	global_load_lds_dwordx4 v[74:75], off
	s_waitcnt vmcnt(8)
	s_waitcnt lgkmcnt(0)
	s_setprio 1
	s_barrier
	v_mfma_f32_16x16x32_bf16 v[140:143], v[88:91], v[194:197], v[140:143]
	v_mfma_f32_16x16x32_bf16 v[136:139], v[128:131], v[194:197], v[136:139]
	v_mfma_f32_16x16x32_bf16 v[120:123], v[88:91], v[202:205], v[120:123]
	v_mfma_f32_16x16x32_bf16 v[116:119], v[128:131], v[202:205], v[116:119]
	v_mfma_f32_16x16x32_bf16 v[100:103], v[88:91], v[210:213], v[100:103]
	v_mfma_f32_16x16x32_bf16 v[96:99], v[128:131], v[210:213], v[96:99]
	v_mfma_f32_16x16x32_bf16 v[80:83], v[88:91], v[218:221], v[80:83]
	v_mfma_f32_16x16x32_bf16 v[74:77], v[128:131], v[218:221], v[76:79]
	v_mfma_f32_16x16x32_bf16 v[140:143], v[108:111], v[198:201], v[140:143]
	v_mfma_f32_16x16x32_bf16 v[136:139], v[144:147], v[198:201], v[136:139]
	v_mfma_f32_16x16x32_bf16 v[120:123], v[108:111], v[206:209], v[120:123]
	v_mfma_f32_16x16x32_bf16 v[116:119], v[144:147], v[206:209], v[116:119]
	v_mfma_f32_16x16x32_bf16 v[100:103], v[108:111], v[214:217], v[100:103]
	v_mfma_f32_16x16x32_bf16 v[96:99], v[144:147], v[214:217], v[96:99]
	v_mfma_f32_16x16x32_bf16 v[80:83], v[108:111], v[222:225], v[80:83]
	v_mfma_f32_16x16x32_bf16 v[74:77], v[144:147], v[222:225], v[74:77]
	s_setprio 0
	s_setprio 1
	v_mfma_f32_16x16x32_bf16 v[132:135], v[148:151], v[194:197], v[132:135]
	v_mfma_f32_16x16x32_bf16 v[132:135], v[152:155], v[198:201], v[132:135]
	v_mfma_f32_16x16x32_bf16 v[124:127], v[190:193], v[198:201], v[124:127]
	v_mfma_f32_16x16x32_bf16 v[124:127], v[176:179], v[194:197], v[124:127]
	v_mfma_f32_16x16x32_bf16 v[104:107], v[176:179], v[202:205], v[104:107]
	v_mfma_f32_16x16x32_bf16 v[104:107], v[190:193], v[206:209], v[104:107]
	v_mfma_f32_16x16x32_bf16 v[112:115], v[152:155], v[206:209], v[112:115]
	v_mfma_f32_16x16x32_bf16 v[112:115], v[148:151], v[202:205], v[112:115]
	v_mfma_f32_16x16x32_bf16 v[92:95], v[148:151], v[210:213], v[92:95]
	v_mfma_f32_16x16x32_bf16 v[92:95], v[152:155], v[214:217], v[92:95]
	v_mfma_f32_16x16x32_bf16 v[84:87], v[190:193], v[214:217], v[84:87]
	v_mfma_f32_16x16x32_bf16 v[84:87], v[176:179], v[210:213], v[84:87]
	v_mfma_f32_16x16x32_bf16 v[64:67], v[176:179], v[218:221], v[64:67]
	v_mfma_f32_16x16x32_bf16 v[64:67], v[190:193], v[222:225], v[64:67]
	v_mfma_f32_16x16x32_bf16 v[68:71], v[152:155], v[222:225], v[68:71]
	v_mfma_f32_16x16x32_bf16 v[68:71], v[148:151], v[218:221], v[68:71]
	s_barrier
	s_setprio 0
	s_add_i32 s96, s83, s71
	v_lshl_add_u64 v[226:227], s[66:67], 0, v[162:163]
	s_mov_b32 m0, s96
	ds_read_b128 v[194:197], v187 offset:16384
	v_xor_b32_e32 v253, 64, v187
	ds_read_b128 v[198:201], v253 offset:16384
	ds_read_b128 v[202:205], v187 offset:18432
	ds_read_b128 v[206:209], v253 offset:18432
	ds_read_b128 v[210:213], v187 offset:20480
	ds_read_b128 v[214:217], v253 offset:20480
	ds_read_b128 v[218:221], v187 offset:22528
	ds_read_b128 v[222:225], v253 offset:22528
	global_load_lds_dwordx4 v[226:227], off
	s_add_i32 m0, s96, 0x2000
	s_add_u32 s96, s66, 0x40000
	v_lshl_add_u64 v[228:229], s[66:67], 0, v[166:167]
	s_addc_u32 s97, s67, 0
	s_add_i32 vcc_lo, s84, s71
	global_load_lds_dwordx4 v[228:229], off
	v_lshl_add_u64 v[78:79], s[96:97], 0, v[162:163]
	s_mov_b32 m0, vcc_lo
	v_lshl_add_u64 v[230:231], s[68:69], 0, v[160:161]
	global_load_lds_dwordx4 v[78:79], off
	v_lshl_add_u64 v[78:79], s[96:97], 0, v[166:167]
	s_add_i32 m0, vcc_lo, 0x2000
	v_lshl_add_u64 v[232:233], s[68:69], 0, v[164:165]
	global_load_lds_dwordx4 v[78:79], off
	s_mov_b32 m0, s74
	s_nop 0
	global_load_lds_dwordx4 v[230:231], off
	s_mov_b32 m0, s75
	s_nop 0
	global_load_lds_dwordx4 v[232:233], off
	s_waitcnt vmcnt(8)
	s_waitcnt lgkmcnt(0)
	s_setprio 1
	s_barrier
	v_mfma_f32_16x16x32_bf16 v[60:63], v[88:91], v[194:197], v[60:63]
	v_mfma_f32_16x16x32_bf16 v[60:63], v[108:111], v[198:201], v[60:63]
	v_mfma_f32_16x16x32_bf16 v[56:59], v[144:147], v[198:201], v[56:59]
	v_mfma_f32_16x16x32_bf16 v[56:59], v[128:131], v[194:197], v[56:59]
	v_mfma_f32_16x16x32_bf16 v[40:43], v[128:131], v[202:205], v[40:43]
	v_mfma_f32_16x16x32_bf16 v[40:43], v[144:147], v[206:209], v[40:43]
	v_mfma_f32_16x16x32_bf16 v[44:47], v[108:111], v[206:209], v[44:47]
	v_mfma_f32_16x16x32_bf16 v[44:47], v[88:91], v[202:205], v[44:47]
	v_mfma_f32_16x16x32_bf16 v[28:31], v[88:91], v[210:213], v[28:31]
	v_mfma_f32_16x16x32_bf16 v[28:31], v[108:111], v[214:217], v[28:31]
	v_mfma_f32_16x16x32_bf16 v[24:27], v[144:147], v[214:217], v[24:27]
	v_mfma_f32_16x16x32_bf16 v[24:27], v[128:131], v[210:213], v[24:27]
	v_mfma_f32_16x16x32_bf16 v[8:11], v[128:131], v[218:221], v[8:11]
	v_mfma_f32_16x16x32_bf16 v[8:11], v[144:147], v[222:225], v[8:11]
	v_mfma_f32_16x16x32_bf16 v[12:15], v[108:111], v[222:225], v[12:15]
	v_mfma_f32_16x16x32_bf16 v[12:15], v[88:91], v[218:221], v[12:15]
	s_setprio 0
	s_setprio 1
	v_mfma_f32_16x16x32_bf16 v[52:55], v[148:151], v[194:197], v[52:55]
	v_mfma_f32_16x16x32_bf16 v[52:55], v[152:155], v[198:201], v[52:55]
	v_mfma_f32_16x16x32_bf16 v[48:51], v[190:193], v[198:201], v[48:51]
	v_mfma_f32_16x16x32_bf16 v[48:51], v[176:179], v[194:197], v[48:51]
	v_mfma_f32_16x16x32_bf16 v[32:35], v[176:179], v[202:205], v[32:35]
	v_mfma_f32_16x16x32_bf16 v[32:35], v[190:193], v[206:209], v[32:35]
	v_mfma_f32_16x16x32_bf16 v[36:39], v[152:155], v[206:209], v[36:39]
	v_mfma_f32_16x16x32_bf16 v[36:39], v[148:151], v[202:205], v[36:39]
	v_mfma_f32_16x16x32_bf16 v[20:23], v[148:151], v[210:213], v[20:23]
	v_mfma_f32_16x16x32_bf16 v[20:23], v[152:155], v[214:217], v[20:23]
	v_mfma_f32_16x16x32_bf16 v[16:19], v[190:193], v[214:217], v[16:19]
	v_mfma_f32_16x16x32_bf16 v[16:19], v[176:179], v[210:213], v[16:19]
	v_mfma_f32_16x16x32_bf16 v[0:3], v[176:179], v[218:221], v[0:3]
	v_mfma_f32_16x16x32_bf16 v[0:3], v[190:193], v[222:225], v[0:3]
	v_mfma_f32_16x16x32_bf16 v[4:7], v[152:155], v[222:225], v[4:7]
	v_mfma_f32_16x16x32_bf16 v[4:7], v[148:151], v[218:221], v[4:7]
	s_barrier
	s_setprio 0
	s_add_i32 s96, 0, 0x18000
	v_add_u32_e32 v78, s96, v181
	s_add_i32 s97, 0, 0x1c000
	ds_read_b128 v[88:91], v78
	v_xor_b32_e32 v253, 64, v78
	ds_read_b128 v[108:111], v253
	ds_read_b128 v[128:131], v78 offset:2048
	ds_read_b128 v[144:147], v253 offset:2048
	v_add_u32_e32 v78, s97, v181
	ds_read_b128 v[148:151], v78
	v_xor_b32_e32 v253, 64, v78
	ds_read_b128 v[152:155], v253
	ds_read_b128 v[176:179], v78 offset:2048
	ds_read_b128 v[190:193], v253 offset:2048
	s_add_u32 s68, s68, 0x40000
	s_addc_u32 s69, s69, 0
	s_mov_b32 m0, s76
	v_lshl_add_u64 v[78:79], s[68:69], 0, v[160:161]
	ds_read_b128 v[194:197], v187 offset:32768
	v_xor_b32_e32 v253, 64, v187
	ds_read_b128 v[198:201], v253 offset:32768
	ds_read_b128 v[202:205], v187 offset:34816
	ds_read_b128 v[206:209], v253 offset:34816
	ds_read_b128 v[210:213], v187 offset:36864
	ds_read_b128 v[214:217], v253 offset:36864
	ds_read_b128 v[218:221], v187 offset:38912
	ds_read_b128 v[222:225], v253 offset:38912
	global_load_lds_dwordx4 v[78:79], off
	v_lshl_add_u64 v[78:79], s[68:69], 0, v[164:165]
	s_mov_b32 m0, s77
	s_nop 0
	global_load_lds_dwordx4 v[78:79], off
	s_waitcnt vmcnt(8)
	s_waitcnt lgkmcnt(0)
	s_setprio 1
	s_barrier
	v_mfma_f32_16x16x32_bf16 v[140:143], v[88:91], v[194:197], v[140:143]
	v_mfma_f32_16x16x32_bf16 v[136:139], v[128:131], v[194:197], v[136:139]
	v_mfma_f32_16x16x32_bf16 v[120:123], v[88:91], v[202:205], v[120:123]
	v_mfma_f32_16x16x32_bf16 v[116:119], v[128:131], v[202:205], v[116:119]
	v_mfma_f32_16x16x32_bf16 v[100:103], v[88:91], v[210:213], v[100:103]
	v_mfma_f32_16x16x32_bf16 v[96:99], v[128:131], v[210:213], v[96:99]
	v_mfma_f32_16x16x32_bf16 v[78:81], v[88:91], v[218:221], v[80:83]
	v_mfma_f32_16x16x32_bf16 v[74:77], v[128:131], v[218:221], v[74:77]
	v_mfma_f32_16x16x32_bf16 v[140:143], v[108:111], v[198:201], v[140:143]
	v_mfma_f32_16x16x32_bf16 v[136:139], v[144:147], v[198:201], v[136:139]
	v_mfma_f32_16x16x32_bf16 v[120:123], v[108:111], v[206:209], v[120:123]
	v_mfma_f32_16x16x32_bf16 v[116:119], v[144:147], v[206:209], v[116:119]
	v_mfma_f32_16x16x32_bf16 v[100:103], v[108:111], v[214:217], v[100:103]
	v_mfma_f32_16x16x32_bf16 v[96:99], v[144:147], v[214:217], v[96:99]
	v_mfma_f32_16x16x32_bf16 v[80:83], v[108:111], v[222:225], v[78:81]
	v_mfma_f32_16x16x32_bf16 v[76:79], v[144:147], v[222:225], v[74:77]
	s_setprio 0
	s_setprio 1
	v_mfma_f32_16x16x32_bf16 v[132:135], v[148:151], v[194:197], v[132:135]
	v_mfma_f32_16x16x32_bf16 v[132:135], v[152:155], v[198:201], v[132:135]
	v_mfma_f32_16x16x32_bf16 v[124:127], v[190:193], v[198:201], v[124:127]
	v_mfma_f32_16x16x32_bf16 v[124:127], v[176:179], v[194:197], v[124:127]
	v_mfma_f32_16x16x32_bf16 v[104:107], v[176:179], v[202:205], v[104:107]
	v_mfma_f32_16x16x32_bf16 v[104:107], v[190:193], v[206:209], v[104:107]
	v_mfma_f32_16x16x32_bf16 v[112:115], v[152:155], v[206:209], v[112:115]
	v_mfma_f32_16x16x32_bf16 v[112:115], v[148:151], v[202:205], v[112:115]
	v_mfma_f32_16x16x32_bf16 v[92:95], v[148:151], v[210:213], v[92:95]
	v_mfma_f32_16x16x32_bf16 v[92:95], v[152:155], v[214:217], v[92:95]
	v_mfma_f32_16x16x32_bf16 v[84:87], v[190:193], v[214:217], v[84:87]
	v_mfma_f32_16x16x32_bf16 v[84:87], v[176:179], v[210:213], v[84:87]
	v_mfma_f32_16x16x32_bf16 v[64:67], v[176:179], v[218:221], v[64:67]
	v_mfma_f32_16x16x32_bf16 v[64:67], v[190:193], v[222:225], v[64:67]
	v_mfma_f32_16x16x32_bf16 v[68:71], v[152:155], v[222:225], v[68:71]
	v_mfma_f32_16x16x32_bf16 v[68:71], v[148:151], v[218:221], v[68:71]
	s_barrier
	s_setprio 0
	s_add_i32 s68, s96, s71
	v_lshl_add_u64 v[74:75], v[226:227], 0, s[28:29]
	s_mov_b32 m0, s68
	ds_read_b128 v[194:197], v187 offset:49152
	v_xor_b32_e32 v253, 64, v187
	ds_read_b128 v[198:201], v253 offset:49152
	ds_read_b128 v[202:205], v187 offset:51200
	ds_read_b128 v[206:209], v253 offset:51200
	ds_read_b128 v[210:213], v187 offset:53248
	ds_read_b128 v[214:217], v253 offset:53248
	ds_read_b128 v[218:221], v187 offset:55296
	ds_read_b128 v[222:225], v253 offset:55296
	global_load_lds_dwordx4 v[74:75], off
	s_add_i32 m0, s68, 0x2000
	s_add_u32 s66, s66, 0x40080
	v_lshl_add_u64 v[74:75], v[228:229], 0, s[28:29]
	s_addc_u32 s67, s67, 0
	s_add_i32 s68, s97, s71
	global_load_lds_dwordx4 v[74:75], off
	v_lshl_add_u64 v[74:75], s[66:67], 0, v[162:163]
	s_mov_b32 m0, s68
	s_nop 0
	global_load_lds_dwordx4 v[74:75], off
	v_lshl_add_u64 v[74:75], s[66:67], 0, v[166:167]
	s_add_i32 m0, s68, 0x2000
	s_nop 0
	global_load_lds_dwordx4 v[74:75], off
	v_lshl_add_u64 v[74:75], v[230:231], 0, s[28:29]
	s_mov_b32 m0, s78
	s_nop 0
	global_load_lds_dwordx4 v[74:75], off
	v_lshl_add_u64 v[74:75], v[232:233], 0, s[28:29]
	s_mov_b32 m0, s79
	s_nop 0
	global_load_lds_dwordx4 v[74:75], off
	s_waitcnt vmcnt(8)
	s_waitcnt lgkmcnt(0)
	s_setprio 1
	s_barrier
	v_mfma_f32_16x16x32_bf16 v[60:63], v[88:91], v[194:197], v[60:63]
	v_mfma_f32_16x16x32_bf16 v[60:63], v[108:111], v[198:201], v[60:63]
	v_mfma_f32_16x16x32_bf16 v[56:59], v[144:147], v[198:201], v[56:59]
	v_mfma_f32_16x16x32_bf16 v[56:59], v[128:131], v[194:197], v[56:59]
	v_mfma_f32_16x16x32_bf16 v[40:43], v[128:131], v[202:205], v[40:43]
	v_mfma_f32_16x16x32_bf16 v[40:43], v[144:147], v[206:209], v[40:43]
	v_mfma_f32_16x16x32_bf16 v[44:47], v[108:111], v[206:209], v[44:47]
	v_mfma_f32_16x16x32_bf16 v[44:47], v[88:91], v[202:205], v[44:47]
	v_mfma_f32_16x16x32_bf16 v[28:31], v[88:91], v[210:213], v[28:31]
	v_mfma_f32_16x16x32_bf16 v[28:31], v[108:111], v[214:217], v[28:31]
	v_mfma_f32_16x16x32_bf16 v[24:27], v[144:147], v[214:217], v[24:27]
	v_mfma_f32_16x16x32_bf16 v[24:27], v[128:131], v[210:213], v[24:27]
	v_mfma_f32_16x16x32_bf16 v[8:11], v[128:131], v[218:221], v[8:11]
	v_mfma_f32_16x16x32_bf16 v[8:11], v[144:147], v[222:225], v[8:11]
	v_mfma_f32_16x16x32_bf16 v[12:15], v[108:111], v[222:225], v[12:15]
	v_mfma_f32_16x16x32_bf16 v[12:15], v[88:91], v[218:221], v[12:15]
	s_setprio 0
	s_setprio 1
	v_mfma_f32_16x16x32_bf16 v[52:55], v[148:151], v[194:197], v[52:55]
	v_mfma_f32_16x16x32_bf16 v[52:55], v[152:155], v[198:201], v[52:55]
	v_mfma_f32_16x16x32_bf16 v[48:51], v[190:193], v[198:201], v[48:51]
	v_mfma_f32_16x16x32_bf16 v[48:51], v[176:179], v[194:197], v[48:51]
	v_mfma_f32_16x16x32_bf16 v[32:35], v[176:179], v[202:205], v[32:35]
	v_mfma_f32_16x16x32_bf16 v[32:35], v[190:193], v[206:209], v[32:35]
	v_mfma_f32_16x16x32_bf16 v[36:39], v[152:155], v[206:209], v[36:39]
	v_mfma_f32_16x16x32_bf16 v[36:39], v[148:151], v[202:205], v[36:39]
	v_mfma_f32_16x16x32_bf16 v[20:23], v[148:151], v[210:213], v[20:23]
	v_mfma_f32_16x16x32_bf16 v[20:23], v[152:155], v[214:217], v[20:23]
	v_mfma_f32_16x16x32_bf16 v[16:19], v[190:193], v[214:217], v[16:19]
	v_mfma_f32_16x16x32_bf16 v[16:19], v[176:179], v[210:213], v[16:19]
	v_mfma_f32_16x16x32_bf16 v[0:3], v[176:179], v[218:221], v[0:3]
	v_mfma_f32_16x16x32_bf16 v[0:3], v[190:193], v[222:225], v[0:3]
	v_mfma_f32_16x16x32_bf16 v[4:7], v[152:155], v[222:225], v[4:7]
	v_mfma_f32_16x16x32_bf16 v[4:7], v[148:151], v[218:221], v[4:7]
	s_barrier
	s_setprio 0
	s_add_i32 s95, s95, 2
	s_add_u32 s93, s93, 0x100
	s_addc_u32 s94, s94, 0
	s_add_u32 s14, s14, 0x100
	s_addc_u32 s15, s15, 0
	s_cmp_gt_u32 s95, 13
	s_cbranch_scc1 .LBB0_258

.LBB0_439:
	s_ashr_i32 s53, s52, 31
	s_lshl_b64 s[54:55], s[52:53], 20
	s_add_u32 s54, s35, s54
	s_addc_u32 s55, s66, s55
	s_and_b64 s[56:57], s[12:13], exec
	s_cselect_b32 s15, s55, s63
	s_cselect_b32 s53, s54, s62
	s_ashr_i32 s51, s50, 31
	s_lshl_b64 s[56:57], s[50:51], 20
	s_add_u32 s56, s67, s56
	s_addc_u32 s57, s68, s57
	s_and_b64 s[64:65], s[12:13], exec
	s_cselect_b32 s51, s57, s61
	s_cselect_b32 s59, s56, s60
	s_add_u32 s81, s60, 0x100
	s_addc_u32 s82, s61, 0
	s_add_u32 s60, s62, 0x80080
	s_addc_u32 s61, s63, 0
	s_mov_b32 s83, -2
	s_waitcnt lgkmcnt(0)
	s_cmp_eq_u32 s74, 1
	s_cbranch_scc1 .Lfa_3
	ds_read_b128 v[128:131], v189
	v_xor_b32_e32 v253, 64, v189
	ds_read_b128 v[132:135], v253
	ds_read_b128 v[136:139], v189 offset:2048
	ds_read_b128 v[140:143], v253 offset:2048
	ds_read_b128 v[144:147], v190
	v_xor_b32_e32 v253, 64, v190
	ds_read_b128 v[148:151], v253
	ds_read_b128 v[172:175], v190 offset:2048
	ds_read_b128 v[176:179], v253 offset:2048
	s_add_u32 s62, s60, 0xfff80080
	s_addc_u32 s63, s61, -1
	s_cmp_eq_u32 s83, 28
	s_cselect_b32 s65, s15, s63
	s_cselect_b32 s64, s53, s62
	s_cselect_b32 s63, s51, s82
	s_cselect_b32 s62, s59, s81
	v_lshl_add_u64 v[222:223], s[60:61], 0, v[166:167]
	s_add_i32 m0, s70, 0xc000
	ds_read_b128 v[180:183], v191
	v_xor_b32_e32 v253, 64, v191
	ds_read_b128 v[194:197], v253
	ds_read_b128 v[198:201], v191 offset:2048
	ds_read_b128 v[202:205], v253 offset:2048
	ds_read_b128 v[206:209], v191 offset:4096
	ds_read_b128 v[210:213], v253 offset:4096
	ds_read_b128 v[214:217], v191 offset:6144
	ds_read_b128 v[218:221], v253 offset:6144
	global_load_lds_dwordx4 v[222:223], off
	v_lshl_add_u64 v[222:223], s[60:61], 0, v[164:165]
	s_add_i32 m0, s70, 0xe000
	s_nop 0
	global_load_lds_dwordx4 v[222:223], off
	s_waitcnt vmcnt(24)
	s_waitcnt lgkmcnt(0)
	s_setprio 1
	s_barrier
	v_mfma_f32_16x16x32_bf16 v[124:127], v[128:131], v[180:183], 0
	v_mfma_f32_16x16x32_bf16 v[120:123], v[136:139], v[180:183], 0
	v_mfma_f32_16x16x32_bf16 v[108:111], v[128:131], v[198:201], 0
	v_mfma_f32_16x16x32_bf16 v[104:107], v[136:139], v[198:201], 0
	v_mfma_f32_16x16x32_bf16 v[92:95], v[128:131], v[206:209], 0
	v_mfma_f32_16x16x32_bf16 v[88:91], v[136:139], v[206:209], 0
	v_mfma_f32_16x16x32_bf16 v[76:79], v[128:131], v[214:217], 0
	v_mfma_f32_16x16x32_bf16 v[72:75], v[136:139], v[214:217], 0
	v_mfma_f32_16x16x32_bf16 v[124:127], v[132:135], v[194:197], v[124:127]
	v_mfma_f32_16x16x32_bf16 v[120:123], v[140:143], v[194:197], v[120:123]
	v_mfma_f32_16x16x32_bf16 v[108:111], v[132:135], v[202:205], v[108:111]
	v_mfma_f32_16x16x32_bf16 v[104:107], v[140:143], v[202:205], v[104:107]
	v_mfma_f32_16x16x32_bf16 v[92:95], v[132:135], v[210:213], v[92:95]
	v_mfma_f32_16x16x32_bf16 v[88:91], v[140:143], v[210:213], v[88:91]
	v_mfma_f32_16x16x32_bf16 v[76:79], v[132:135], v[218:221], v[76:79]
	v_mfma_f32_16x16x32_bf16 v[72:75], v[140:143], v[218:221], v[72:75]
	s_setprio 0
	s_setprio 1
	v_mfma_f32_16x16x32_bf16 v[116:119], v[144:147], v[180:183], 0
	v_mfma_f32_16x16x32_bf16 v[112:115], v[172:175], v[180:183], 0
	v_mfma_f32_16x16x32_bf16 v[100:103], v[144:147], v[198:201], 0
	v_mfma_f32_16x16x32_bf16 v[96:99], v[172:175], v[198:201], 0
	v_mfma_f32_16x16x32_bf16 v[84:87], v[144:147], v[206:209], 0
	v_mfma_f32_16x16x32_bf16 v[80:83], v[172:175], v[206:209], 0
	v_mfma_f32_16x16x32_bf16 v[68:71], v[144:147], v[214:217], 0
	v_mfma_f32_16x16x32_bf16 v[64:67], v[172:175], v[214:217], 0
	v_mfma_f32_16x16x32_bf16 v[116:119], v[148:151], v[194:197], v[116:119]
	v_mfma_f32_16x16x32_bf16 v[112:115], v[176:179], v[194:197], v[112:115]
	v_mfma_f32_16x16x32_bf16 v[100:103], v[148:151], v[202:205], v[100:103]
	v_mfma_f32_16x16x32_bf16 v[96:99], v[176:179], v[202:205], v[96:99]
	v_mfma_f32_16x16x32_bf16 v[84:87], v[148:151], v[210:213], v[84:87]
	v_mfma_f32_16x16x32_bf16 v[80:83], v[176:179], v[210:213], v[80:83]
	v_mfma_f32_16x16x32_bf16 v[68:71], v[148:151], v[218:221], v[68:71]
	v_mfma_f32_16x16x32_bf16 v[64:67], v[176:179], v[218:221], v[64:67]
	s_barrier
	s_setprio 0
	s_add_i32 s84, s79, s69
	v_lshl_add_u64 v[222:223], s[62:63], 0, v[154:155]
	s_mov_b32 m0, s84
	ds_read_b128 v[180:183], v191 offset:16384
	v_xor_b32_e32 v253, 64, v191
	ds_read_b128 v[194:197], v253 offset:16384
	ds_read_b128 v[198:201], v191 offset:18432
	ds_read_b128 v[202:205], v253 offset:18432
	ds_read_b128 v[206:209], v191 offset:20480
	ds_read_b128 v[210:213], v253 offset:20480
	ds_read_b128 v[214:217], v191 offset:22528
	ds_read_b128 v[218:221], v253 offset:22528
	global_load_lds_dwordx4 v[222:223], off
	s_add_i32 m0, s84, 0x2000
	s_add_u32 s84, s62, 0x80000
	v_lshl_add_u64 v[224:225], s[62:63], 0, v[162:163]
	s_addc_u32 s85, s63, 0
	s_add_i32 s86, s80, s69
	global_load_lds_dwordx4 v[224:225], off
	v_lshl_add_u64 v[226:227], s[84:85], 0, v[154:155]
	s_mov_b32 m0, s86
	v_lshl_add_u64 v[228:229], s[64:65], 0, v[160:161]
	global_load_lds_dwordx4 v[226:227], off
	v_lshl_add_u64 v[226:227], s[84:85], 0, v[162:163]
	s_add_i32 m0, s86, 0x2000
	s_nop 0
	global_load_lds_dwordx4 v[226:227], off
	v_lshl_add_u64 v[226:227], s[64:65], 0, v[152:153]
	s_mov_b32 m0, s70
	s_nop 0
	global_load_lds_dwordx4 v[226:227], off
	s_mov_b32 m0, s71
	s_nop 0
	global_load_lds_dwordx4 v[228:229], off
	s_waitcnt vmcnt(24)
	s_waitcnt lgkmcnt(0)
	s_setprio 1
	s_barrier
	v_mfma_f32_16x16x32_bf16 v[60:63], v[128:131], v[180:183], 0
	v_mfma_f32_16x16x32_bf16 v[56:59], v[136:139], v[180:183], 0
	v_mfma_f32_16x16x32_bf16 v[44:47], v[128:131], v[198:201], 0
	v_mfma_f32_16x16x32_bf16 v[40:43], v[136:139], v[198:201], 0
	v_mfma_f32_16x16x32_bf16 v[28:31], v[128:131], v[206:209], 0
	v_mfma_f32_16x16x32_bf16 v[24:27], v[136:139], v[206:209], 0
	v_mfma_f32_16x16x32_bf16 v[12:15], v[128:131], v[214:217], 0
	v_mfma_f32_16x16x32_bf16 v[8:11], v[136:139], v[214:217], 0
	v_mfma_f32_16x16x32_bf16 v[60:63], v[132:135], v[194:197], v[60:63]
	v_mfma_f32_16x16x32_bf16 v[56:59], v[140:143], v[194:197], v[56:59]
	v_mfma_f32_16x16x32_bf16 v[44:47], v[132:135], v[202:205], v[44:47]
	v_mfma_f32_16x16x32_bf16 v[40:43], v[140:143], v[202:205], v[40:43]
	v_mfma_f32_16x16x32_bf16 v[28:31], v[132:135], v[210:213], v[28:31]
	v_mfma_f32_16x16x32_bf16 v[24:27], v[140:143], v[210:213], v[24:27]
	v_mfma_f32_16x16x32_bf16 v[12:15], v[132:135], v[218:221], v[12:15]
	v_mfma_f32_16x16x32_bf16 v[8:11], v[140:143], v[218:221], v[8:11]
	s_setprio 0
	s_setprio 1
	v_mfma_f32_16x16x32_bf16 v[52:55], v[144:147], v[180:183], 0
	v_mfma_f32_16x16x32_bf16 v[48:51], v[172:175], v[180:183], 0
	v_mfma_f32_16x16x32_bf16 v[36:39], v[144:147], v[198:201], 0
	v_mfma_f32_16x16x32_bf16 v[32:35], v[172:175], v[198:201], 0
	v_mfma_f32_16x16x32_bf16 v[20:23], v[144:147], v[206:209], 0
	v_mfma_f32_16x16x32_bf16 v[16:19], v[172:175], v[206:209], 0
	v_mfma_f32_16x16x32_bf16 v[4:7], v[144:147], v[214:217], 0
	v_mfma_f32_16x16x32_bf16 v[0:3], v[172:175], v[214:217], 0
	v_mfma_f32_16x16x32_bf16 v[52:55], v[148:151], v[194:197], v[52:55]
	v_mfma_f32_16x16x32_bf16 v[48:51], v[176:179], v[194:197], v[48:51]
	v_mfma_f32_16x16x32_bf16 v[36:39], v[148:151], v[202:205], v[36:39]
	v_mfma_f32_16x16x32_bf16 v[32:35], v[176:179], v[202:205], v[32:35]
	v_mfma_f32_16x16x32_bf16 v[20:23], v[148:151], v[210:213], v[20:23]
	v_mfma_f32_16x16x32_bf16 v[16:19], v[176:179], v[210:213], v[16:19]
	v_mfma_f32_16x16x32_bf16 v[4:7], v[148:151], v[218:221], v[4:7]
	v_mfma_f32_16x16x32_bf16 v[0:3], v[176:179], v[218:221], v[0:3]
	s_barrier
	s_setprio 0
	s_add_i32 s84, 0, 0x18000
	s_add_i32 s85, 0, 0x1c000
	v_add_u32_e32 v140, s84, v186
	v_add_u32_e32 v176, s85, v186
	ds_read_b128 v[128:131], v140
	v_xor_b32_e32 v253, 64, v140
	ds_read_b128 v[132:135], v253
	ds_read_b128 v[136:139], v140 offset:2048
	ds_read_b128 v[140:143], v253 offset:2048
	ds_read_b128 v[144:147], v176
	v_xor_b32_e32 v253, 64, v176
	ds_read_b128 v[148:151], v253
	ds_read_b128 v[172:175], v176 offset:2048
	ds_read_b128 v[176:179], v253 offset:2048
	s_add_u32 s64, s64, 0x80000
	s_addc_u32 s65, s65, 0
	s_mov_b32 m0, s72
	v_lshl_add_u64 v[230:231], s[64:65], 0, v[152:153]
	ds_read_b128 v[180:183], v191 offset:32768
	v_xor_b32_e32 v253, 64, v191
	ds_read_b128 v[194:197], v253 offset:32768
	ds_read_b128 v[198:201], v191 offset:34816
	ds_read_b128 v[202:205], v253 offset:34816
	ds_read_b128 v[206:209], v191 offset:36864
	ds_read_b128 v[210:213], v253 offset:36864
	ds_read_b128 v[214:217], v191 offset:38912
	ds_read_b128 v[218:221], v253 offset:38912
	global_load_lds_dwordx4 v[230:231], off
	v_lshl_add_u64 v[230:231], s[64:65], 0, v[160:161]
	s_mov_b32 m0, s73
	s_nop 0
	global_load_lds_dwordx4 v[230:231], off
	s_waitcnt vmcnt(8)
	s_waitcnt lgkmcnt(0)
	s_setprio 1
	s_barrier
	v_mfma_f32_16x16x32_bf16 v[124:127], v[128:131], v[180:183], v[124:127]
	v_mfma_f32_16x16x32_bf16 v[124:127], v[132:135], v[194:197], v[124:127]
	v_mfma_f32_16x16x32_bf16 v[120:123], v[140:143], v[194:197], v[120:123]
	v_mfma_f32_16x16x32_bf16 v[120:123], v[136:139], v[180:183], v[120:123]
	v_mfma_f32_16x16x32_bf16 v[104:107], v[136:139], v[198:201], v[104:107]
	v_mfma_f32_16x16x32_bf16 v[104:107], v[140:143], v[202:205], v[104:107]
	v_mfma_f32_16x16x32_bf16 v[108:111], v[132:135], v[202:205], v[108:111]
	v_mfma_f32_16x16x32_bf16 v[108:111], v[128:131], v[198:201], v[108:111]
	v_mfma_f32_16x16x32_bf16 v[92:95], v[128:131], v[206:209], v[92:95]
	v_mfma_f32_16x16x32_bf16 v[92:95], v[132:135], v[210:213], v[92:95]
	v_mfma_f32_16x16x32_bf16 v[88:91], v[140:143], v[210:213], v[88:91]
	v_mfma_f32_16x16x32_bf16 v[88:91], v[136:139], v[206:209], v[88:91]
	v_mfma_f32_16x16x32_bf16 v[72:75], v[136:139], v[214:217], v[72:75]
	v_mfma_f32_16x16x32_bf16 v[72:75], v[140:143], v[218:221], v[72:75]
	v_mfma_f32_16x16x32_bf16 v[76:79], v[132:135], v[218:221], v[76:79]
	v_mfma_f32_16x16x32_bf16 v[76:79], v[128:131], v[214:217], v[76:79]
	s_setprio 0
	s_setprio 1
	v_mfma_f32_16x16x32_bf16 v[116:119], v[144:147], v[180:183], v[116:119]
	v_mfma_f32_16x16x32_bf16 v[116:119], v[148:151], v[194:197], v[116:119]
	v_mfma_f32_16x16x32_bf16 v[112:115], v[176:179], v[194:197], v[112:115]
	v_mfma_f32_16x16x32_bf16 v[112:115], v[172:175], v[180:183], v[112:115]
	v_mfma_f32_16x16x32_bf16 v[96:99], v[172:175], v[198:201], v[96:99]
	v_mfma_f32_16x16x32_bf16 v[96:99], v[176:179], v[202:205], v[96:99]
	v_mfma_f32_16x16x32_bf16 v[100:103], v[148:151], v[202:205], v[100:103]
	v_mfma_f32_16x16x32_bf16 v[100:103], v[144:147], v[198:201], v[100:103]
	v_mfma_f32_16x16x32_bf16 v[84:87], v[144:147], v[206:209], v[84:87]
	v_mfma_f32_16x16x32_bf16 v[84:87], v[148:151], v[210:213], v[84:87]
	v_mfma_f32_16x16x32_bf16 v[80:83], v[176:179], v[210:213], v[80:83]
	v_mfma_f32_16x16x32_bf16 v[80:83], v[172:175], v[206:209], v[80:83]
	v_mfma_f32_16x16x32_bf16 v[64:67], v[172:175], v[214:217], v[64:67]
	v_mfma_f32_16x16x32_bf16 v[64:67], v[176:179], v[218:221], v[64:67]
	v_mfma_f32_16x16x32_bf16 v[68:71], v[148:151], v[218:221], v[68:71]
	v_mfma_f32_16x16x32_bf16 v[68:71], v[144:147], v[214:217], v[68:71]
	s_barrier
	s_setprio 0
	s_add_i32 s64, s84, s69
	v_lshl_add_u64 v[222:223], v[222:223], 0, s[26:27]
	s_mov_b32 m0, s64
	ds_read_b128 v[180:183], v191 offset:49152
	v_xor_b32_e32 v253, 64, v191
	ds_read_b128 v[194:197], v253 offset:49152
	ds_read_b128 v[198:201], v191 offset:51200
	ds_read_b128 v[202:205], v253 offset:51200
	ds_read_b128 v[206:209], v191 offset:53248
	ds_read_b128 v[210:213], v253 offset:53248
	ds_read_b128 v[214:217], v191 offset:55296
	ds_read_b128 v[218:221], v253 offset:55296
	global_load_lds_dwordx4 v[222:223], off
	s_add_i32 m0, s64, 0x2000
	s_add_u32 s62, s62, 0x80080
	v_lshl_add_u64 v[222:223], v[224:225], 0, s[26:27]
	s_addc_u32 s63, s63, 0
	s_add_i32 s64, s85, s69
	global_load_lds_dwordx4 v[222:223], off
	v_lshl_add_u64 v[222:223], s[62:63], 0, v[154:155]
	s_mov_b32 m0, s64
	s_nop 0
	global_load_lds_dwordx4 v[222:223], off
	v_lshl_add_u64 v[222:223], s[62:63], 0, v[162:163]
	s_add_i32 m0, s64, 0x2000
	s_nop 0
	global_load_lds_dwordx4 v[222:223], off
	v_lshl_add_u64 v[222:223], v[226:227], 0, s[26:27]
	s_mov_b32 m0, s3
	s_nop 0
	global_load_lds_dwordx4 v[222:223], off
	v_lshl_add_u64 v[222:223], v[228:229], 0, s[26:27]
	s_mov_b32 m0, s75
	s_nop 0
	global_load_lds_dwordx4 v[222:223], off
	s_waitcnt vmcnt(8)
	s_waitcnt lgkmcnt(0)
	s_setprio 1
	s_barrier
	v_mfma_f32_16x16x32_bf16 v[60:63], v[128:131], v[180:183], v[60:63]
	v_mfma_f32_16x16x32_bf16 v[60:63], v[132:135], v[194:197], v[60:63]
	v_mfma_f32_16x16x32_bf16 v[56:59], v[140:143], v[194:197], v[56:59]
	v_mfma_f32_16x16x32_bf16 v[56:59], v[136:139], v[180:183], v[56:59]
	v_mfma_f32_16x16x32_bf16 v[40:43], v[136:139], v[198:201], v[40:43]
	v_mfma_f32_16x16x32_bf16 v[40:43], v[140:143], v[202:205], v[40:43]
	v_mfma_f32_16x16x32_bf16 v[44:47], v[132:135], v[202:205], v[44:47]
	v_mfma_f32_16x16x32_bf16 v[44:47], v[128:131], v[198:201], v[44:47]
	v_mfma_f32_16x16x32_bf16 v[28:31], v[128:131], v[206:209], v[28:31]
	v_mfma_f32_16x16x32_bf16 v[28:31], v[132:135], v[210:213], v[28:31]
	v_mfma_f32_16x16x32_bf16 v[24:27], v[140:143], v[210:213], v[24:27]
	v_mfma_f32_16x16x32_bf16 v[24:27], v[136:139], v[206:209], v[24:27]
	v_mfma_f32_16x16x32_bf16 v[8:11], v[136:139], v[214:217], v[8:11]
	v_mfma_f32_16x16x32_bf16 v[8:11], v[140:143], v[218:221], v[8:11]
	v_mfma_f32_16x16x32_bf16 v[12:15], v[132:135], v[218:221], v[12:15]
	v_mfma_f32_16x16x32_bf16 v[12:15], v[128:131], v[214:217], v[12:15]
	s_setprio 0
	s_setprio 1
	v_mfma_f32_16x16x32_bf16 v[52:55], v[144:147], v[180:183], v[52:55]
	v_mfma_f32_16x16x32_bf16 v[52:55], v[148:151], v[194:197], v[52:55]
	v_mfma_f32_16x16x32_bf16 v[48:51], v[176:179], v[194:197], v[48:51]
	v_mfma_f32_16x16x32_bf16 v[48:51], v[172:175], v[180:183], v[48:51]
	v_mfma_f32_16x16x32_bf16 v[32:35], v[172:175], v[198:201], v[32:35]
	v_mfma_f32_16x16x32_bf16 v[32:35], v[176:179], v[202:205], v[32:35]
	v_mfma_f32_16x16x32_bf16 v[36:39], v[148:151], v[202:205], v[36:39]
	v_mfma_f32_16x16x32_bf16 v[36:39], v[144:147], v[198:201], v[36:39]
	v_mfma_f32_16x16x32_bf16 v[20:23], v[144:147], v[206:209], v[20:23]
	v_mfma_f32_16x16x32_bf16 v[20:23], v[148:151], v[210:213], v[20:23]
	v_mfma_f32_16x16x32_bf16 v[16:19], v[176:179], v[210:213], v[16:19]
	v_mfma_f32_16x16x32_bf16 v[16:19], v[172:175], v[206:209], v[16:19]
	v_mfma_f32_16x16x32_bf16 v[0:3], v[172:175], v[214:217], v[0:3]
	v_mfma_f32_16x16x32_bf16 v[0:3], v[176:179], v[218:221], v[0:3]
	v_mfma_f32_16x16x32_bf16 v[4:7], v[148:151], v[218:221], v[4:7]
	v_mfma_f32_16x16x32_bf16 v[4:7], v[144:147], v[214:217], v[4:7]
	s_barrier
	s_setprio 0
	s_add_i32 s83, s83, 2
	s_add_u32 s81, s81, 0x100
	s_addc_u32 s82, s82, 0
	s_add_u32 s60, s60, 0x100
	s_addc_u32 s61, s61, 0
	s_cmp_gt_u32 s83, 29
	s_branch .LBB0_440
.Lfa_3:
	ds_read_b128 v[128:131], v189
	v_xor_b32_e32 v253, 64, v189
	ds_read_b128 v[132:135], v253
	ds_read_b128 v[136:139], v189 offset:2048
	ds_read_b128 v[140:143], v253 offset:2048
	ds_read_b128 v[144:147], v190
	v_xor_b32_e32 v253, 64, v190
	ds_read_b128 v[148:151], v253
	ds_read_b128 v[172:175], v190 offset:2048
	ds_read_b128 v[176:179], v253 offset:2048
	s_add_u32 s62, s60, 0xfff80080
	s_addc_u32 s63, s61, -1
	s_cmp_eq_u32 s83, 28
	s_cselect_b32 s65, s15, s63
	s_cselect_b32 s64, s53, s62
	s_cselect_b32 s63, s51, s82
	s_cselect_b32 s62, s59, s81
	v_lshl_add_u64 v[222:223], s[60:61], 0, v[166:167]
	s_add_i32 m0, s70, 0xc000
	ds_read_b128 v[180:183], v191
	v_xor_b32_e32 v253, 64, v191
	ds_read_b128 v[194:197], v253
	ds_read_b128 v[198:201], v191 offset:2048
	ds_read_b128 v[202:205], v253 offset:2048
	ds_read_b128 v[206:209], v191 offset:4096
	ds_read_b128 v[210:213], v253 offset:4096
	ds_read_b128 v[214:217], v191 offset:6144
	ds_read_b128 v[218:221], v253 offset:6144
	global_load_lds_dwordx4 v[222:223], off
	v_lshl_add_u64 v[222:223], s[60:61], 0, v[164:165]
	s_add_i32 m0, s70, 0xe000
	s_nop 0
	global_load_lds_dwordx4 v[222:223], off
	s_waitcnt vmcnt(8)
	s_waitcnt lgkmcnt(0)
	s_setprio 1
	s_barrier
	v_mfma_f32_16x16x32_bf16 v[124:127], v[128:131], v[180:183], 0
	v_mfma_f32_16x16x32_bf16 v[120:123], v[136:139], v[180:183], 0
	v_mfma_f32_16x16x32_bf16 v[108:111], v[128:131], v[198:201], 0
	v_mfma_f32_16x16x32_bf16 v[104:107], v[136:139], v[198:201], 0
	v_mfma_f32_16x16x32_bf16 v[92:95], v[128:131], v[206:209], 0
	v_mfma_f32_16x16x32_bf16 v[88:91], v[136:139], v[206:209], 0
	v_mfma_f32_16x16x32_bf16 v[76:79], v[128:131], v[214:217], 0
	v_mfma_f32_16x16x32_bf16 v[72:75], v[136:139], v[214:217], 0
	v_mfma_f32_16x16x32_bf16 v[124:127], v[132:135], v[194:197], v[124:127]
	v_mfma_f32_16x16x32_bf16 v[120:123], v[140:143], v[194:197], v[120:123]
	v_mfma_f32_16x16x32_bf16 v[108:111], v[132:135], v[202:205], v[108:111]
	v_mfma_f32_16x16x32_bf16 v[104:107], v[140:143], v[202:205], v[104:107]
	v_mfma_f32_16x16x32_bf16 v[92:95], v[132:135], v[210:213], v[92:95]
	v_mfma_f32_16x16x32_bf16 v[88:91], v[140:143], v[210:213], v[88:91]
	v_mfma_f32_16x16x32_bf16 v[76:79], v[132:135], v[218:221], v[76:79]
	v_mfma_f32_16x16x32_bf16 v[72:75], v[140:143], v[218:221], v[72:75]
	s_setprio 0
	s_setprio 1
	v_mfma_f32_16x16x32_bf16 v[116:119], v[144:147], v[180:183], 0
	v_mfma_f32_16x16x32_bf16 v[112:115], v[172:175], v[180:183], 0
	v_mfma_f32_16x16x32_bf16 v[100:103], v[144:147], v[198:201], 0
	v_mfma_f32_16x16x32_bf16 v[96:99], v[172:175], v[198:201], 0
	v_mfma_f32_16x16x32_bf16 v[84:87], v[144:147], v[206:209], 0
	v_mfma_f32_16x16x32_bf16 v[80:83], v[172:175], v[206:209], 0
	v_mfma_f32_16x16x32_bf16 v[68:71], v[144:147], v[214:217], 0
	v_mfma_f32_16x16x32_bf16 v[64:67], v[172:175], v[214:217], 0
	v_mfma_f32_16x16x32_bf16 v[116:119], v[148:151], v[194:197], v[116:119]
	v_mfma_f32_16x16x32_bf16 v[112:115], v[176:179], v[194:197], v[112:115]
	v_mfma_f32_16x16x32_bf16 v[100:103], v[148:151], v[202:205], v[100:103]
	v_mfma_f32_16x16x32_bf16 v[96:99], v[176:179], v[202:205], v[96:99]
	v_mfma_f32_16x16x32_bf16 v[84:87], v[148:151], v[210:213], v[84:87]
	v_mfma_f32_16x16x32_bf16 v[80:83], v[176:179], v[210:213], v[80:83]
	v_mfma_f32_16x16x32_bf16 v[68:71], v[148:151], v[218:221], v[68:71]
	v_mfma_f32_16x16x32_bf16 v[64:67], v[176:179], v[218:221], v[64:67]
	s_barrier
	s_setprio 0
	s_add_i32 s84, s79, s69
	v_lshl_add_u64 v[222:223], s[62:63], 0, v[154:155]
	s_mov_b32 m0, s84
	ds_read_b128 v[180:183], v191 offset:16384
	v_xor_b32_e32 v253, 64, v191
	ds_read_b128 v[194:197], v253 offset:16384
	ds_read_b128 v[198:201], v191 offset:18432
	ds_read_b128 v[202:205], v253 offset:18432
	ds_read_b128 v[206:209], v191 offset:20480
	ds_read_b128 v[210:213], v253 offset:20480
	ds_read_b128 v[214:217], v191 offset:22528
	ds_read_b128 v[218:221], v253 offset:22528
	global_load_lds_dwordx4 v[222:223], off
	s_add_i32 m0, s84, 0x2000
	s_add_u32 s84, s62, 0x80000
	v_lshl_add_u64 v[224:225], s[62:63], 0, v[162:163]
	s_addc_u32 s85, s63, 0
	s_add_i32 s86, s80, s69
	global_load_lds_dwordx4 v[224:225], off
	v_lshl_add_u64 v[226:227], s[84:85], 0, v[154:155]
	s_mov_b32 m0, s86
	v_lshl_add_u64 v[228:229], s[64:65], 0, v[160:161]
	global_load_lds_dwordx4 v[226:227], off
	v_lshl_add_u64 v[226:227], s[84:85], 0, v[162:163]
	s_add_i32 m0, s86, 0x2000
	s_nop 0
	global_load_lds_dwordx4 v[226:227], off
	v_lshl_add_u64 v[226:227], s[64:65], 0, v[152:153]
	s_mov_b32 m0, s70
	s_nop 0
	global_load_lds_dwordx4 v[226:227], off
	s_mov_b32 m0, s71
	s_nop 0
	global_load_lds_dwordx4 v[228:229], off
	s_waitcnt vmcnt(8)
	s_waitcnt lgkmcnt(0)
	s_setprio 1
	s_barrier
	v_mfma_f32_16x16x32_bf16 v[60:63], v[128:131], v[180:183], 0
	v_mfma_f32_16x16x32_bf16 v[56:59], v[136:139], v[180:183], 0
	v_mfma_f32_16x16x32_bf16 v[44:47], v[128:131], v[198:201], 0
	v_mfma_f32_16x16x32_bf16 v[40:43], v[136:139], v[198:201], 0
	v_mfma_f32_16x16x32_bf16 v[28:31], v[128:131], v[206:209], 0
	v_mfma_f32_16x16x32_bf16 v[24:27], v[136:139], v[206:209], 0
	v_mfma_f32_16x16x32_bf16 v[12:15], v[128:131], v[214:217], 0
	v_mfma_f32_16x16x32_bf16 v[8:11], v[136:139], v[214:217], 0
	v_mfma_f32_16x16x32_bf16 v[60:63], v[132:135], v[194:197], v[60:63]
	v_mfma_f32_16x16x32_bf16 v[56:59], v[140:143], v[194:197], v[56:59]
	v_mfma_f32_16x16x32_bf16 v[44:47], v[132:135], v[202:205], v[44:47]
	v_mfma_f32_16x16x32_bf16 v[40:43], v[140:143], v[202:205], v[40:43]
	v_mfma_f32_16x16x32_bf16 v[28:31], v[132:135], v[210:213], v[28:31]
	v_mfma_f32_16x16x32_bf16 v[24:27], v[140:143], v[210:213], v[24:27]
	v_mfma_f32_16x16x32_bf16 v[12:15], v[132:135], v[218:221], v[12:15]
	v_mfma_f32_16x16x32_bf16 v[8:11], v[140:143], v[218:221], v[8:11]
	s_setprio 0
	s_setprio 1
	v_mfma_f32_16x16x32_bf16 v[52:55], v[144:147], v[180:183], 0
	v_mfma_f32_16x16x32_bf16 v[48:51], v[172:175], v[180:183], 0
	v_mfma_f32_16x16x32_bf16 v[36:39], v[144:147], v[198:201], 0
	v_mfma_f32_16x16x32_bf16 v[32:35], v[172:175], v[198:201], 0
	v_mfma_f32_16x16x32_bf16 v[20:23], v[144:147], v[206:209], 0
	v_mfma_f32_16x16x32_bf16 v[16:19], v[172:175], v[206:209], 0
	v_mfma_f32_16x16x32_bf16 v[4:7], v[144:147], v[214:217], 0
	v_mfma_f32_16x16x32_bf16 v[0:3], v[172:175], v[214:217], 0
	v_mfma_f32_16x16x32_bf16 v[52:55], v[148:151], v[194:197], v[52:55]
	v_mfma_f32_16x16x32_bf16 v[48:51], v[176:179], v[194:197], v[48:51]
	v_mfma_f32_16x16x32_bf16 v[36:39], v[148:151], v[202:205], v[36:39]
	v_mfma_f32_16x16x32_bf16 v[32:35], v[176:179], v[202:205], v[32:35]
	v_mfma_f32_16x16x32_bf16 v[20:23], v[148:151], v[210:213], v[20:23]
	v_mfma_f32_16x16x32_bf16 v[16:19], v[176:179], v[210:213], v[16:19]
	v_mfma_f32_16x16x32_bf16 v[4:7], v[148:151], v[218:221], v[4:7]
	v_mfma_f32_16x16x32_bf16 v[0:3], v[176:179], v[218:221], v[0:3]
	s_barrier
	s_setprio 0
	s_add_i32 s84, 0, 0x18000
	s_add_i32 s85, 0, 0x1c000
	v_add_u32_e32 v140, s84, v186
	v_add_u32_e32 v176, s85, v186
	ds_read_b128 v[128:131], v140
	v_xor_b32_e32 v253, 64, v140
	ds_read_b128 v[132:135], v253
	ds_read_b128 v[136:139], v140 offset:2048
	ds_read_b128 v[140:143], v253 offset:2048
	ds_read_b128 v[144:147], v176
	v_xor_b32_e32 v253, 64, v176
	ds_read_b128 v[148:151], v253
	ds_read_b128 v[172:175], v176 offset:2048
	ds_read_b128 v[176:179], v253 offset:2048
	s_add_u32 s64, s64, 0x80000
	s_addc_u32 s65, s65, 0
	s_mov_b32 m0, s72
	v_lshl_add_u64 v[230:231], s[64:65], 0, v[152:153]
	ds_read_b128 v[180:183], v191 offset:32768
	v_xor_b32_e32 v253, 64, v191
	ds_read_b128 v[194:197], v253 offset:32768
	ds_read_b128 v[198:201], v191 offset:34816
	ds_read_b128 v[202:205], v253 offset:34816
	ds_read_b128 v[206:209], v191 offset:36864
	ds_read_b128 v[210:213], v253 offset:36864
	ds_read_b128 v[214:217], v191 offset:38912
	ds_read_b128 v[218:221], v253 offset:38912
	global_load_lds_dwordx4 v[230:231], off
	v_lshl_add_u64 v[230:231], s[64:65], 0, v[160:161]
	s_mov_b32 m0, s73
	s_nop 0
	global_load_lds_dwordx4 v[230:231], off
	s_waitcnt vmcnt(8)
	s_waitcnt lgkmcnt(0)
	s_setprio 1
	s_barrier
	v_mfma_f32_16x16x32_bf16 v[124:127], v[128:131], v[180:183], v[124:127]
	v_mfma_f32_16x16x32_bf16 v[124:127], v[132:135], v[194:197], v[124:127]
	v_mfma_f32_16x16x32_bf16 v[120:123], v[140:143], v[194:197], v[120:123]
	v_mfma_f32_16x16x32_bf16 v[120:123], v[136:139], v[180:183], v[120:123]
	v_mfma_f32_16x16x32_bf16 v[104:107], v[136:139], v[198:201], v[104:107]
	v_mfma_f32_16x16x32_bf16 v[104:107], v[140:143], v[202:205], v[104:107]
	v_mfma_f32_16x16x32_bf16 v[108:111], v[132:135], v[202:205], v[108:111]
	v_mfma_f32_16x16x32_bf16 v[108:111], v[128:131], v[198:201], v[108:111]
	v_mfma_f32_16x16x32_bf16 v[92:95], v[128:131], v[206:209], v[92:95]
	v_mfma_f32_16x16x32_bf16 v[92:95], v[132:135], v[210:213], v[92:95]
	v_mfma_f32_16x16x32_bf16 v[88:91], v[140:143], v[210:213], v[88:91]
	v_mfma_f32_16x16x32_bf16 v[88:91], v[136:139], v[206:209], v[88:91]
	v_mfma_f32_16x16x32_bf16 v[72:75], v[136:139], v[214:217], v[72:75]
	v_mfma_f32_16x16x32_bf16 v[72:75], v[140:143], v[218:221], v[72:75]
	v_mfma_f32_16x16x32_bf16 v[76:79], v[132:135], v[218:221], v[76:79]
	v_mfma_f32_16x16x32_bf16 v[76:79], v[128:131], v[214:217], v[76:79]
	s_setprio 0
	s_setprio 1
	v_mfma_f32_16x16x32_bf16 v[116:119], v[144:147], v[180:183], v[116:119]
	v_mfma_f32_16x16x32_bf16 v[116:119], v[148:151], v[194:197], v[116:119]
	v_mfma_f32_16x16x32_bf16 v[112:115], v[176:179], v[194:197], v[112:115]
	v_mfma_f32_16x16x32_bf16 v[112:115], v[172:175], v[180:183], v[112:115]
	v_mfma_f32_16x16x32_bf16 v[96:99], v[172:175], v[198:201], v[96:99]
	v_mfma_f32_16x16x32_bf16 v[96:99], v[176:179], v[202:205], v[96:99]
	v_mfma_f32_16x16x32_bf16 v[100:103], v[148:151], v[202:205], v[100:103]
	v_mfma_f32_16x16x32_bf16 v[100:103], v[144:147], v[198:201], v[100:103]
	v_mfma_f32_16x16x32_bf16 v[84:87], v[144:147], v[206:209], v[84:87]
	v_mfma_f32_16x16x32_bf16 v[84:87], v[148:151], v[210:213], v[84:87]
	v_mfma_f32_16x16x32_bf16 v[80:83], v[176:179], v[210:213], v[80:83]
	v_mfma_f32_16x16x32_bf16 v[80:83], v[172:175], v[206:209], v[80:83]
	v_mfma_f32_16x16x32_bf16 v[64:67], v[172:175], v[214:217], v[64:67]
	v_mfma_f32_16x16x32_bf16 v[64:67], v[176:179], v[218:221], v[64:67]
	v_mfma_f32_16x16x32_bf16 v[68:71], v[148:151], v[218:221], v[68:71]
	v_mfma_f32_16x16x32_bf16 v[68:71], v[144:147], v[214:217], v[68:71]
	s_barrier
	s_setprio 0
	s_add_i32 s64, s84, s69
	v_lshl_add_u64 v[222:223], v[222:223], 0, s[26:27]
	s_mov_b32 m0, s64
	ds_read_b128 v[180:183], v191 offset:49152
	v_xor_b32_e32 v253, 64, v191
	ds_read_b128 v[194:197], v253 offset:49152
	ds_read_b128 v[198:201], v191 offset:51200
	ds_read_b128 v[202:205], v253 offset:51200
	ds_read_b128 v[206:209], v191 offset:53248
	ds_read_b128 v[210:213], v253 offset:53248
	ds_read_b128 v[214:217], v191 offset:55296
	ds_read_b128 v[218:221], v253 offset:55296
	global_load_lds_dwordx4 v[222:223], off
	s_add_i32 m0, s64, 0x2000
	s_add_u32 s62, s62, 0x80080
	v_lshl_add_u64 v[222:223], v[224:225], 0, s[26:27]
	s_addc_u32 s63, s63, 0
	s_add_i32 s64, s85, s69
	global_load_lds_dwordx4 v[222:223], off
	v_lshl_add_u64 v[222:223], s[62:63], 0, v[154:155]
	s_mov_b32 m0, s64
	s_nop 0
	global_load_lds_dwordx4 v[222:223], off
	v_lshl_add_u64 v[222:223], s[62:63], 0, v[162:163]
	s_add_i32 m0, s64, 0x2000
	s_nop 0
	global_load_lds_dwordx4 v[222:223], off
	v_lshl_add_u64 v[222:223], v[226:227], 0, s[26:27]
	s_mov_b32 m0, s3
	s_nop 0
	global_load_lds_dwordx4 v[222:223], off
	v_lshl_add_u64 v[222:223], v[228:229], 0, s[26:27]
	s_mov_b32 m0, s75
	s_nop 0
	global_load_lds_dwordx4 v[222:223], off
	s_waitcnt vmcnt(8)
	s_waitcnt lgkmcnt(0)
	s_setprio 1
	s_barrier
	v_mfma_f32_16x16x32_bf16 v[60:63], v[128:131], v[180:183], v[60:63]
	v_mfma_f32_16x16x32_bf16 v[60:63], v[132:135], v[194:197], v[60:63]
	v_mfma_f32_16x16x32_bf16 v[56:59], v[140:143], v[194:197], v[56:59]
	v_mfma_f32_16x16x32_bf16 v[56:59], v[136:139], v[180:183], v[56:59]
	v_mfma_f32_16x16x32_bf16 v[40:43], v[136:139], v[198:201], v[40:43]
	v_mfma_f32_16x16x32_bf16 v[40:43], v[140:143], v[202:205], v[40:43]
	v_mfma_f32_16x16x32_bf16 v[44:47], v[132:135], v[202:205], v[44:47]
	v_mfma_f32_16x16x32_bf16 v[44:47], v[128:131], v[198:201], v[44:47]
	v_mfma_f32_16x16x32_bf16 v[28:31], v[128:131], v[206:209], v[28:31]
	v_mfma_f32_16x16x32_bf16 v[28:31], v[132:135], v[210:213], v[28:31]
	v_mfma_f32_16x16x32_bf16 v[24:27], v[140:143], v[210:213], v[24:27]
	v_mfma_f32_16x16x32_bf16 v[24:27], v[136:139], v[206:209], v[24:27]
	v_mfma_f32_16x16x32_bf16 v[8:11], v[136:139], v[214:217], v[8:11]
	v_mfma_f32_16x16x32_bf16 v[8:11], v[140:143], v[218:221], v[8:11]
	v_mfma_f32_16x16x32_bf16 v[12:15], v[132:135], v[218:221], v[12:15]
	v_mfma_f32_16x16x32_bf16 v[12:15], v[128:131], v[214:217], v[12:15]
	s_setprio 0
	s_setprio 1
	v_mfma_f32_16x16x32_bf16 v[52:55], v[144:147], v[180:183], v[52:55]
	v_mfma_f32_16x16x32_bf16 v[52:55], v[148:151], v[194:197], v[52:55]
	v_mfma_f32_16x16x32_bf16 v[48:51], v[176:179], v[194:197], v[48:51]
	v_mfma_f32_16x16x32_bf16 v[48:51], v[172:175], v[180:183], v[48:51]
	v_mfma_f32_16x16x32_bf16 v[32:35], v[172:175], v[198:201], v[32:35]
	v_mfma_f32_16x16x32_bf16 v[32:35], v[176:179], v[202:205], v[32:35]
	v_mfma_f32_16x16x32_bf16 v[36:39], v[148:151], v[202:205], v[36:39]
	v_mfma_f32_16x16x32_bf16 v[36:39], v[144:147], v[198:201], v[36:39]
	v_mfma_f32_16x16x32_bf16 v[20:23], v[144:147], v[206:209], v[20:23]
	v_mfma_f32_16x16x32_bf16 v[20:23], v[148:151], v[210:213], v[20:23]
	v_mfma_f32_16x16x32_bf16 v[16:19], v[176:179], v[210:213], v[16:19]
	v_mfma_f32_16x16x32_bf16 v[16:19], v[172:175], v[206:209], v[16:19]
	v_mfma_f32_16x16x32_bf16 v[0:3], v[172:175], v[214:217], v[0:3]
	v_mfma_f32_16x16x32_bf16 v[0:3], v[176:179], v[218:221], v[0:3]
	v_mfma_f32_16x16x32_bf16 v[4:7], v[148:151], v[218:221], v[4:7]
	v_mfma_f32_16x16x32_bf16 v[4:7], v[144:147], v[214:217], v[4:7]
	s_barrier
	s_setprio 0
	s_add_i32 s83, s83, 2
	s_add_u32 s81, s81, 0x100
	s_addc_u32 s82, s82, 0
	s_add_u32 s60, s60, 0x100
	s_addc_u32 s61, s61, 0
	s_cmp_gt_u32 s83, 29
.LBB0_440:
	ds_read_b128 v[128:131], v189
	v_xor_b32_e32 v253, 64, v189
	ds_read_b128 v[132:135], v253
	ds_read_b128 v[136:139], v189 offset:2048
	ds_read_b128 v[140:143], v253 offset:2048
	ds_read_b128 v[144:147], v190
	v_xor_b32_e32 v253, 64, v190
	ds_read_b128 v[148:151], v253
	ds_read_b128 v[172:175], v190 offset:2048
	ds_read_b128 v[176:179], v253 offset:2048
	s_add_u32 s62, s60, 0xfff80080
	s_addc_u32 s63, s61, -1
	s_cmp_eq_u32 s83, 28
	s_cselect_b32 s65, s15, s63
	s_cselect_b32 s64, s53, s62
	s_cselect_b32 s63, s51, s82
	s_cselect_b32 s62, s59, s81
	v_lshl_add_u64 v[222:223], s[60:61], 0, v[166:167]
	s_add_i32 m0, s70, 0xc000
	ds_read_b128 v[180:183], v191
	v_xor_b32_e32 v253, 64, v191
	ds_read_b128 v[194:197], v253
	ds_read_b128 v[198:201], v191 offset:2048
	ds_read_b128 v[202:205], v253 offset:2048
	ds_read_b128 v[206:209], v191 offset:4096
	ds_read_b128 v[210:213], v253 offset:4096
	ds_read_b128 v[214:217], v191 offset:6144
	ds_read_b128 v[218:221], v253 offset:6144
	global_load_lds_dwordx4 v[222:223], off
	v_lshl_add_u64 v[222:223], s[60:61], 0, v[164:165]
	s_add_i32 m0, s70, 0xe000
	s_nop 0
	global_load_lds_dwordx4 v[222:223], off
	s_waitcnt vmcnt(8)
	s_waitcnt lgkmcnt(0)
	s_setprio 1
	s_barrier
	v_mfma_f32_16x16x32_bf16 v[124:127], v[128:131], v[180:183], v[124:127]
	v_mfma_f32_16x16x32_bf16 v[124:127], v[132:135], v[194:197], v[124:127]
	v_mfma_f32_16x16x32_bf16 v[120:123], v[140:143], v[194:197], v[120:123]
	v_mfma_f32_16x16x32_bf16 v[120:123], v[136:139], v[180:183], v[120:123]
	v_mfma_f32_16x16x32_bf16 v[104:107], v[136:139], v[198:201], v[104:107]
	v_mfma_f32_16x16x32_bf16 v[104:107], v[140:143], v[202:205], v[104:107]
	v_mfma_f32_16x16x32_bf16 v[108:111], v[132:135], v[202:205], v[108:111]
	v_mfma_f32_16x16x32_bf16 v[108:111], v[128:131], v[198:201], v[108:111]
	v_mfma_f32_16x16x32_bf16 v[92:95], v[128:131], v[206:209], v[92:95]
	v_mfma_f32_16x16x32_bf16 v[92:95], v[132:135], v[210:213], v[92:95]
	v_mfma_f32_16x16x32_bf16 v[88:91], v[140:143], v[210:213], v[88:91]
	v_mfma_f32_16x16x32_bf16 v[88:91], v[136:139], v[206:209], v[88:91]
	v_mfma_f32_16x16x32_bf16 v[72:75], v[136:139], v[214:217], v[72:75]
	v_mfma_f32_16x16x32_bf16 v[72:75], v[140:143], v[218:221], v[72:75]
	v_mfma_f32_16x16x32_bf16 v[76:79], v[132:135], v[218:221], v[76:79]
	v_mfma_f32_16x16x32_bf16 v[76:79], v[128:131], v[214:217], v[76:79]
	s_setprio 0
	s_setprio 1
	v_mfma_f32_16x16x32_bf16 v[116:119], v[144:147], v[180:183], v[116:119]
	v_mfma_f32_16x16x32_bf16 v[116:119], v[148:151], v[194:197], v[116:119]
	v_mfma_f32_16x16x32_bf16 v[112:115], v[176:179], v[194:197], v[112:115]
	v_mfma_f32_16x16x32_bf16 v[112:115], v[172:175], v[180:183], v[112:115]
	v_mfma_f32_16x16x32_bf16 v[96:99], v[172:175], v[198:201], v[96:99]
	v_mfma_f32_16x16x32_bf16 v[96:99], v[176:179], v[202:205], v[96:99]
	v_mfma_f32_16x16x32_bf16 v[100:103], v[148:151], v[202:205], v[100:103]
	v_mfma_f32_16x16x32_bf16 v[100:103], v[144:147], v[198:201], v[100:103]
	v_mfma_f32_16x16x32_bf16 v[84:87], v[144:147], v[206:209], v[84:87]
	v_mfma_f32_16x16x32_bf16 v[84:87], v[148:151], v[210:213], v[84:87]
	v_mfma_f32_16x16x32_bf16 v[80:83], v[176:179], v[210:213], v[80:83]
	v_mfma_f32_16x16x32_bf16 v[80:83], v[172:175], v[206:209], v[80:83]
	v_mfma_f32_16x16x32_bf16 v[64:67], v[172:175], v[214:217], v[64:67]
	v_mfma_f32_16x16x32_bf16 v[64:67], v[176:179], v[218:221], v[64:67]
	v_mfma_f32_16x16x32_bf16 v[68:71], v[148:151], v[218:221], v[68:71]
	v_mfma_f32_16x16x32_bf16 v[68:71], v[144:147], v[214:217], v[68:71]
	s_barrier
	s_setprio 0
	s_add_i32 s84, s79, s69
	v_lshl_add_u64 v[222:223], s[62:63], 0, v[154:155]
	s_mov_b32 m0, s84
	ds_read_b128 v[180:183], v191 offset:16384
	v_xor_b32_e32 v253, 64, v191
	ds_read_b128 v[194:197], v253 offset:16384
	ds_read_b128 v[198:201], v191 offset:18432
	ds_read_b128 v[202:205], v253 offset:18432
	ds_read_b128 v[206:209], v191 offset:20480
	ds_read_b128 v[210:213], v253 offset:20480
	ds_read_b128 v[214:217], v191 offset:22528
	ds_read_b128 v[218:221], v253 offset:22528
	global_load_lds_dwordx4 v[222:223], off
	s_add_i32 m0, s84, 0x2000
	s_add_u32 s84, s62, 0x80000
	v_lshl_add_u64 v[224:225], s[62:63], 0, v[162:163]
	s_addc_u32 s85, s63, 0
	s_add_i32 s86, s80, s69
	global_load_lds_dwordx4 v[224:225], off
	v_lshl_add_u64 v[226:227], s[84:85], 0, v[154:155]
	s_mov_b32 m0, s86
	v_lshl_add_u64 v[228:229], s[64:65], 0, v[160:161]
	global_load_lds_dwordx4 v[226:227], off
	v_lshl_add_u64 v[226:227], s[84:85], 0, v[162:163]
	s_add_i32 m0, s86, 0x2000
	s_nop 0
	global_load_lds_dwordx4 v[226:227], off
	v_lshl_add_u64 v[226:227], s[64:65], 0, v[152:153]
	s_mov_b32 m0, s70
	s_nop 0
	global_load_lds_dwordx4 v[226:227], off
	s_mov_b32 m0, s71
	s_nop 0
	global_load_lds_dwordx4 v[228:229], off
	s_waitcnt vmcnt(8)
	s_waitcnt lgkmcnt(0)
	s_setprio 1
	s_barrier
	v_mfma_f32_16x16x32_bf16 v[60:63], v[128:131], v[180:183], v[60:63]
	v_mfma_f32_16x16x32_bf16 v[60:63], v[132:135], v[194:197], v[60:63]
	v_mfma_f32_16x16x32_bf16 v[56:59], v[140:143], v[194:197], v[56:59]
	v_mfma_f32_16x16x32_bf16 v[56:59], v[136:139], v[180:183], v[56:59]
	v_mfma_f32_16x16x32_bf16 v[40:43], v[136:139], v[198:201], v[40:43]
	v_mfma_f32_16x16x32_bf16 v[40:43], v[140:143], v[202:205], v[40:43]
	v_mfma_f32_16x16x32_bf16 v[44:47], v[132:135], v[202:205], v[44:47]
	v_mfma_f32_16x16x32_bf16 v[44:47], v[128:131], v[198:201], v[44:47]
	v_mfma_f32_16x16x32_bf16 v[28:31], v[128:131], v[206:209], v[28:31]
	v_mfma_f32_16x16x32_bf16 v[28:31], v[132:135], v[210:213], v[28:31]
	v_mfma_f32_16x16x32_bf16 v[24:27], v[140:143], v[210:213], v[24:27]
	v_mfma_f32_16x16x32_bf16 v[24:27], v[136:139], v[206:209], v[24:27]
	v_mfma_f32_16x16x32_bf16 v[8:11], v[136:139], v[214:217], v[8:11]
	v_mfma_f32_16x16x32_bf16 v[8:11], v[140:143], v[218:221], v[8:11]
	v_mfma_f32_16x16x32_bf16 v[12:15], v[132:135], v[218:221], v[12:15]
	v_mfma_f32_16x16x32_bf16 v[12:15], v[128:131], v[214:217], v[12:15]
	s_setprio 0
	s_setprio 1
	v_mfma_f32_16x16x32_bf16 v[52:55], v[144:147], v[180:183], v[52:55]
	v_mfma_f32_16x16x32_bf16 v[52:55], v[148:151], v[194:197], v[52:55]
	v_mfma_f32_16x16x32_bf16 v[48:51], v[176:179], v[194:197], v[48:51]
	v_mfma_f32_16x16x32_bf16 v[48:51], v[172:175], v[180:183], v[48:51]
	v_mfma_f32_16x16x32_bf16 v[32:35], v[172:175], v[198:201], v[32:35]
	v_mfma_f32_16x16x32_bf16 v[32:35], v[176:179], v[202:205], v[32:35]
	v_mfma_f32_16x16x32_bf16 v[36:39], v[148:151], v[202:205], v[36:39]
	v_mfma_f32_16x16x32_bf16 v[36:39], v[144:147], v[198:201], v[36:39]
	v_mfma_f32_16x16x32_bf16 v[20:23], v[144:147], v[206:209], v[20:23]
	v_mfma_f32_16x16x32_bf16 v[20:23], v[148:151], v[210:213], v[20:23]
	v_mfma_f32_16x16x32_bf16 v[16:19], v[176:179], v[210:213], v[16:19]
	v_mfma_f32_16x16x32_bf16 v[16:19], v[172:175], v[206:209], v[16:19]
	v_mfma_f32_16x16x32_bf16 v[0:3], v[172:175], v[214:217], v[0:3]
	v_mfma_f32_16x16x32_bf16 v[0:3], v[176:179], v[218:221], v[0:3]
	v_mfma_f32_16x16x32_bf16 v[4:7], v[148:151], v[218:221], v[4:7]
	v_mfma_f32_16x16x32_bf16 v[4:7], v[144:147], v[214:217], v[4:7]
	s_barrier
	s_setprio 0
	s_add_i32 s84, 0, 0x18000
	s_add_i32 s85, 0, 0x1c000
	v_add_u32_e32 v140, s84, v186
	v_add_u32_e32 v176, s85, v186
	ds_read_b128 v[128:131], v140
	v_xor_b32_e32 v253, 64, v140
	ds_read_b128 v[132:135], v253
	ds_read_b128 v[136:139], v140 offset:2048
	ds_read_b128 v[140:143], v253 offset:2048
	ds_read_b128 v[144:147], v176
	v_xor_b32_e32 v253, 64, v176
	ds_read_b128 v[148:151], v253
	ds_read_b128 v[172:175], v176 offset:2048
	ds_read_b128 v[176:179], v253 offset:2048
	s_add_u32 s64, s64, 0x80000
	s_addc_u32 s65, s65, 0
	s_mov_b32 m0, s72
	v_lshl_add_u64 v[230:231], s[64:65], 0, v[152:153]
	ds_read_b128 v[180:183], v191 offset:32768
	v_xor_b32_e32 v253, 64, v191
	ds_read_b128 v[194:197], v253 offset:32768
	ds_read_b128 v[198:201], v191 offset:34816
	ds_read_b128 v[202:205], v253 offset:34816
	ds_read_b128 v[206:209], v191 offset:36864
	ds_read_b128 v[210:213], v253 offset:36864
	ds_read_b128 v[214:217], v191 offset:38912
	ds_read_b128 v[218:221], v253 offset:38912
	global_load_lds_dwordx4 v[230:231], off
	v_lshl_add_u64 v[230:231], s[64:65], 0, v[160:161]
	s_mov_b32 m0, s73
	s_nop 0
	global_load_lds_dwordx4 v[230:231], off
	s_waitcnt vmcnt(8)
	s_waitcnt lgkmcnt(0)
	s_setprio 1
	s_barrier
	v_mfma_f32_16x16x32_bf16 v[124:127], v[128:131], v[180:183], v[124:127]
	v_mfma_f32_16x16x32_bf16 v[124:127], v[132:135], v[194:197], v[124:127]
	v_mfma_f32_16x16x32_bf16 v[120:123], v[140:143], v[194:197], v[120:123]
	v_mfma_f32_16x16x32_bf16 v[120:123], v[136:139], v[180:183], v[120:123]
	v_mfma_f32_16x16x32_bf16 v[104:107], v[136:139], v[198:201], v[104:107]
	v_mfma_f32_16x16x32_bf16 v[104:107], v[140:143], v[202:205], v[104:107]
	v_mfma_f32_16x16x32_bf16 v[108:111], v[132:135], v[202:205], v[108:111]
	v_mfma_f32_16x16x32_bf16 v[108:111], v[128:131], v[198:201], v[108:111]
	v_mfma_f32_16x16x32_bf16 v[92:95], v[128:131], v[206:209], v[92:95]
	v_mfma_f32_16x16x32_bf16 v[92:95], v[132:135], v[210:213], v[92:95]
	v_mfma_f32_16x16x32_bf16 v[88:91], v[140:143], v[210:213], v[88:91]
	v_mfma_f32_16x16x32_bf16 v[88:91], v[136:139], v[206:209], v[88:91]
	v_mfma_f32_16x16x32_bf16 v[72:75], v[136:139], v[214:217], v[72:75]
	v_mfma_f32_16x16x32_bf16 v[72:75], v[140:143], v[218:221], v[72:75]
	v_mfma_f32_16x16x32_bf16 v[76:79], v[132:135], v[218:221], v[76:79]
	v_mfma_f32_16x16x32_bf16 v[76:79], v[128:131], v[214:217], v[76:79]
	s_setprio 0
	s_setprio 1
	v_mfma_f32_16x16x32_bf16 v[116:119], v[144:147], v[180:183], v[116:119]
	v_mfma_f32_16x16x32_bf16 v[116:119], v[148:151], v[194:197], v[116:119]
	v_mfma_f32_16x16x32_bf16 v[112:115], v[176:179], v[194:197], v[112:115]
	v_mfma_f32_16x16x32_bf16 v[112:115], v[172:175], v[180:183], v[112:115]
	v_mfma_f32_16x16x32_bf16 v[96:99], v[172:175], v[198:201], v[96:99]
	v_mfma_f32_16x16x32_bf16 v[96:99], v[176:179], v[202:205], v[96:99]
	v_mfma_f32_16x16x32_bf16 v[100:103], v[148:151], v[202:205], v[100:103]
	v_mfma_f32_16x16x32_bf16 v[100:103], v[144:147], v[198:201], v[100:103]
	v_mfma_f32_16x16x32_bf16 v[84:87], v[144:147], v[206:209], v[84:87]
	v_mfma_f32_16x16x32_bf16 v[84:87], v[148:151], v[210:213], v[84:87]
	v_mfma_f32_16x16x32_bf16 v[80:83], v[176:179], v[210:213], v[80:83]
	v_mfma_f32_16x16x32_bf16 v[80:83], v[172:175], v[206:209], v[80:83]
	v_mfma_f32_16x16x32_bf16 v[64:67], v[172:175], v[214:217], v[64:67]
	v_mfma_f32_16x16x32_bf16 v[64:67], v[176:179], v[218:221], v[64:67]
	v_mfma_f32_16x16x32_bf16 v[68:71], v[148:151], v[218:221], v[68:71]
	v_mfma_f32_16x16x32_bf16 v[68:71], v[144:147], v[214:217], v[68:71]
	s_barrier
	s_setprio 0
	s_add_i32 s64, s84, s69
	v_lshl_add_u64 v[222:223], v[222:223], 0, s[26:27]
	s_mov_b32 m0, s64
	ds_read_b128 v[180:183], v191 offset:49152
	v_xor_b32_e32 v253, 64, v191
	ds_read_b128 v[194:197], v253 offset:49152
	ds_read_b128 v[198:201], v191 offset:51200
	ds_read_b128 v[202:205], v253 offset:51200
	ds_read_b128 v[206:209], v191 offset:53248
	ds_read_b128 v[210:213], v253 offset:53248
	ds_read_b128 v[214:217], v191 offset:55296
	ds_read_b128 v[218:221], v253 offset:55296
	global_load_lds_dwordx4 v[222:223], off
	s_add_i32 m0, s64, 0x2000
	s_add_u32 s62, s62, 0x80080
	v_lshl_add_u64 v[222:223], v[224:225], 0, s[26:27]
	s_addc_u32 s63, s63, 0
	s_add_i32 s64, s85, s69
	global_load_lds_dwordx4 v[222:223], off
	v_lshl_add_u64 v[222:223], s[62:63], 0, v[154:155]
	s_mov_b32 m0, s64
	s_nop 0
	global_load_lds_dwordx4 v[222:223], off
	v_lshl_add_u64 v[222:223], s[62:63], 0, v[162:163]
	s_add_i32 m0, s64, 0x2000
	s_nop 0
	global_load_lds_dwordx4 v[222:223], off
	v_lshl_add_u64 v[222:223], v[226:227], 0, s[26:27]
	s_mov_b32 m0, s3
	s_nop 0
	global_load_lds_dwordx4 v[222:223], off
	v_lshl_add_u64 v[222:223], v[228:229], 0, s[26:27]
	s_mov_b32 m0, s75
	s_nop 0
	global_load_lds_dwordx4 v[222:223], off
	s_waitcnt vmcnt(8)
	s_waitcnt lgkmcnt(0)
	s_setprio 1
	s_barrier
	v_mfma_f32_16x16x32_bf16 v[60:63], v[128:131], v[180:183], v[60:63]
	v_mfma_f32_16x16x32_bf16 v[60:63], v[132:135], v[194:197], v[60:63]
	v_mfma_f32_16x16x32_bf16 v[56:59], v[140:143], v[194:197], v[56:59]
	v_mfma_f32_16x16x32_bf16 v[56:59], v[136:139], v[180:183], v[56:59]
	v_mfma_f32_16x16x32_bf16 v[40:43], v[136:139], v[198:201], v[40:43]
	v_mfma_f32_16x16x32_bf16 v[40:43], v[140:143], v[202:205], v[40:43]
	v_mfma_f32_16x16x32_bf16 v[44:47], v[132:135], v[202:205], v[44:47]
	v_mfma_f32_16x16x32_bf16 v[44:47], v[128:131], v[198:201], v[44:47]
	v_mfma_f32_16x16x32_bf16 v[28:31], v[128:131], v[206:209], v[28:31]
	v_mfma_f32_16x16x32_bf16 v[28:31], v[132:135], v[210:213], v[28:31]
	v_mfma_f32_16x16x32_bf16 v[24:27], v[140:143], v[210:213], v[24:27]
	v_mfma_f32_16x16x32_bf16 v[24:27], v[136:139], v[206:209], v[24:27]
	v_mfma_f32_16x16x32_bf16 v[8:11], v[136:139], v[214:217], v[8:11]
	v_mfma_f32_16x16x32_bf16 v[8:11], v[140:143], v[218:221], v[8:11]
	v_mfma_f32_16x16x32_bf16 v[12:15], v[132:135], v[218:221], v[12:15]
	v_mfma_f32_16x16x32_bf16 v[12:15], v[128:131], v[214:217], v[12:15]
	s_setprio 0
	s_setprio 1
	v_mfma_f32_16x16x32_bf16 v[52:55], v[144:147], v[180:183], v[52:55]
	v_mfma_f32_16x16x32_bf16 v[52:55], v[148:151], v[194:197], v[52:55]
	v_mfma_f32_16x16x32_bf16 v[48:51], v[176:179], v[194:197], v[48:51]
	v_mfma_f32_16x16x32_bf16 v[48:51], v[172:175], v[180:183], v[48:51]
	v_mfma_f32_16x16x32_bf16 v[32:35], v[172:175], v[198:201], v[32:35]
	v_mfma_f32_16x16x32_bf16 v[32:35], v[176:179], v[202:205], v[32:35]
	v_mfma_f32_16x16x32_bf16 v[36:39], v[148:151], v[202:205], v[36:39]
	v_mfma_f32_16x16x32_bf16 v[36:39], v[144:147], v[198:201], v[36:39]
	v_mfma_f32_16x16x32_bf16 v[20:23], v[144:147], v[206:209], v[20:23]
	v_mfma_f32_16x16x32_bf16 v[20:23], v[148:151], v[210:213], v[20:23]
	v_mfma_f32_16x16x32_bf16 v[16:19], v[176:179], v[210:213], v[16:19]
	v_mfma_f32_16x16x32_bf16 v[16:19], v[172:175], v[206:209], v[16:19]
	v_mfma_f32_16x16x32_bf16 v[0:3], v[172:175], v[214:217], v[0:3]
	v_mfma_f32_16x16x32_bf16 v[0:3], v[176:179], v[218:221], v[0:3]
	v_mfma_f32_16x16x32_bf16 v[4:7], v[148:151], v[218:221], v[4:7]
	v_mfma_f32_16x16x32_bf16 v[4:7], v[144:147], v[214:217], v[4:7]
	s_barrier
	s_setprio 0
	s_add_i32 s83, s83, 2
	s_add_u32 s81, s81, 0x100
	s_addc_u32 s82, s82, 0
	s_add_u32 s60, s60, 0x100
	s_addc_u32 s61, s61, 0
	s_cmp_gt_u32 s83, 29
	s_cbranch_scc0 .LBB0_440
	s_and_b64 vcc, exec, s[28:29]
	s_cbranch_vccz .LBB0_443
	s_barrier

.LBB0_525:
	s_ashr_i32 s29, s28, 31
	s_lshl_b64 s[30:31], s[28:29], 19
	s_add_u32 s30, s3, s30
	s_addc_u32 s31, s35, s31
	s_and_b64 s[44:45], s[10:11], exec
	s_cselect_b32 s29, s31, s51
	s_cselect_b32 s70, s30, s50
	s_ashr_i32 s27, s26, 31
	s_lshl_b64 s[44:45], s[26:27], 19
	s_add_u32 s44, s52, s44
	s_addc_u32 s45, s53, s45
	s_and_b64 s[72:73], s[10:11], exec
	s_cselect_b32 s71, s45, s49
	s_cselect_b32 s72, s44, s48
	s_lshl_b32 s27, s46, 8
	v_add_u32_e32 v0, s27, v148
	s_add_u32 s73, s48, 0x100
	v_ashrrev_i32_e32 v1, 31, v0
	s_addc_u32 s74, s49, 0
	v_lshl_add_u64 v[144:145], v[0:1], 4, s[16:17]
	s_add_u32 s46, s50, 0x40080
	s_addc_u32 s47, s51, 0
	s_mov_b32 s75, -2
	s_mov_b64 s[48:49], 0
	s_cmp_eq_u32 s61, 1
	s_cbranch_scc1 .Lfa_4
	v_add_u32_e32 v153, s66, v147
	ds_read_b128 v[160:163], v153
	v_xor_b32_e32 v253, 64, v153
	ds_read_b128 v[164:167], v253
	ds_read_b128 v[168:171], v153 offset:2048
	ds_read_b128 v[172:175], v253 offset:2048
	v_add_u32_e32 v153, s67, v147
	ds_read_b128 v[176:179], v153
	v_xor_b32_e32 v253, 64, v153
	ds_read_b128 v[180:183], v253
	ds_read_b128 v[186:189], v153 offset:2048
	ds_read_b128 v[190:193], v253 offset:2048
	s_add_u32 s50, s46, 0xfffc0080
	s_addc_u32 s51, s47, -1
	s_and_b64 s[48:49], s[48:49], exec
	s_cselect_b32 s51, s29, s51
	s_cselect_b32 s50, s70, s50
	s_cselect_b32 s49, s71, s74
	s_cselect_b32 s48, s72, s73
	v_lshl_add_u64 v[154:155], s[46:47], 0, v[138:139]
	s_add_i32 m0, s57, 0xc000
	ds_read_b128 v[194:197], v150
	v_xor_b32_e32 v253, 64, v150
	ds_read_b128 v[198:201], v253
	ds_read_b128 v[202:205], v150 offset:2048
	ds_read_b128 v[206:209], v253 offset:2048
	ds_read_b128 v[210:213], v150 offset:4096
	ds_read_b128 v[214:217], v253 offset:4096
	ds_read_b128 v[218:221], v150 offset:6144
	ds_read_b128 v[222:225], v253 offset:6144
	global_load_lds_dwordx4 v[154:155], off
	v_lshl_add_u64 v[154:155], s[46:47], 0, v[136:137]
	s_add_i32 m0, s57, 0xe000
	s_nop 0
	global_load_lds_dwordx4 v[154:155], off
	s_waitcnt vmcnt(16)
	s_waitcnt lgkmcnt(0)
	s_setprio 1
	s_barrier
	v_mfma_f32_16x16x32_bf16 v[124:127], v[160:163], v[194:197], 0
	v_mfma_f32_16x16x32_bf16 v[116:119], v[168:171], v[194:197], 0
	v_mfma_f32_16x16x32_bf16 v[108:111], v[160:163], v[202:205], 0
	v_mfma_f32_16x16x32_bf16 v[100:103], v[168:171], v[202:205], 0
	v_mfma_f32_16x16x32_bf16 v[92:95], v[160:163], v[210:213], 0
	v_mfma_f32_16x16x32_bf16 v[84:87], v[168:171], v[210:213], 0
	v_mfma_f32_16x16x32_bf16 v[76:79], v[160:163], v[218:221], 0
	v_mfma_f32_16x16x32_bf16 v[68:71], v[168:171], v[218:221], 0
	v_mfma_f32_16x16x32_bf16 v[124:127], v[164:167], v[198:201], v[124:127]
	v_mfma_f32_16x16x32_bf16 v[116:119], v[172:175], v[198:201], v[116:119]
	v_mfma_f32_16x16x32_bf16 v[108:111], v[164:167], v[206:209], v[108:111]
	v_mfma_f32_16x16x32_bf16 v[100:103], v[172:175], v[206:209], v[100:103]
	v_mfma_f32_16x16x32_bf16 v[92:95], v[164:167], v[214:217], v[92:95]
	v_mfma_f32_16x16x32_bf16 v[84:87], v[172:175], v[214:217], v[84:87]
	v_mfma_f32_16x16x32_bf16 v[76:79], v[164:167], v[222:225], v[76:79]
	v_mfma_f32_16x16x32_bf16 v[68:71], v[172:175], v[222:225], v[68:71]
	s_setprio 0
	s_setprio 1
	v_mfma_f32_16x16x32_bf16 v[120:123], v[176:179], v[194:197], 0
	v_mfma_f32_16x16x32_bf16 v[112:115], v[186:189], v[194:197], 0
	v_mfma_f32_16x16x32_bf16 v[104:107], v[176:179], v[202:205], 0
	v_mfma_f32_16x16x32_bf16 v[96:99], v[186:189], v[202:205], 0
	v_mfma_f32_16x16x32_bf16 v[88:91], v[176:179], v[210:213], 0
	v_mfma_f32_16x16x32_bf16 v[80:83], v[186:189], v[210:213], 0
	v_mfma_f32_16x16x32_bf16 v[72:75], v[176:179], v[218:221], 0
	v_mfma_f32_16x16x32_bf16 v[64:67], v[186:189], v[218:221], 0
	v_mfma_f32_16x16x32_bf16 v[120:123], v[180:183], v[198:201], v[120:123]
	v_mfma_f32_16x16x32_bf16 v[112:115], v[190:193], v[198:201], v[112:115]
	v_mfma_f32_16x16x32_bf16 v[104:107], v[180:183], v[206:209], v[104:107]
	v_mfma_f32_16x16x32_bf16 v[96:99], v[190:193], v[206:209], v[96:99]
	v_mfma_f32_16x16x32_bf16 v[88:91], v[180:183], v[214:217], v[88:91]
	v_mfma_f32_16x16x32_bf16 v[80:83], v[190:193], v[214:217], v[80:83]
	v_mfma_f32_16x16x32_bf16 v[72:75], v[180:183], v[222:225], v[72:75]
	v_mfma_f32_16x16x32_bf16 v[64:67], v[190:193], v[222:225], v[64:67]
	s_barrier
	s_setprio 0
	s_add_i32 s76, s66, s54
	v_lshl_add_u64 v[154:155], s[48:49], 0, v[132:133]
	s_mov_b32 m0, s76
	ds_read_b128 v[194:197], v150 offset:16384
	v_xor_b32_e32 v253, 64, v150
	ds_read_b128 v[198:201], v253 offset:16384
	ds_read_b128 v[202:205], v150 offset:18432
	ds_read_b128 v[206:209], v253 offset:18432
	ds_read_b128 v[210:213], v150 offset:20480
	ds_read_b128 v[214:217], v253 offset:20480
	ds_read_b128 v[218:221], v150 offset:22528
	ds_read_b128 v[222:225], v253 offset:22528
	global_load_lds_dwordx4 v[154:155], off
	s_add_i32 m0, s76, 0x2000
	s_add_u32 s76, s48, 0x40000
	v_lshl_add_u64 v[226:227], s[48:49], 0, v[128:129]
	s_addc_u32 s77, s49, 0
	s_add_i32 s78, s67, s54
	global_load_lds_dwordx4 v[226:227], off
	v_lshl_add_u64 v[228:229], s[76:77], 0, v[132:133]
	s_mov_b32 m0, s78
	v_lshl_add_u64 v[230:231], s[50:51], 0, v[130:131]
	global_load_lds_dwordx4 v[228:229], off
	v_lshl_add_u64 v[228:229], s[76:77], 0, v[128:129]
	s_add_i32 m0, s78, 0x2000
	s_nop 0
	global_load_lds_dwordx4 v[228:229], off
	v_lshl_add_u64 v[228:229], s[50:51], 0, v[134:135]
	s_mov_b32 m0, s57
	s_nop 0
	global_load_lds_dwordx4 v[228:229], off
	s_mov_b32 m0, s58
	s_nop 0
	global_load_lds_dwordx4 v[230:231], off
	s_waitcnt vmcnt(16)
	s_waitcnt lgkmcnt(0)
	s_setprio 1
	s_barrier
	v_mfma_f32_16x16x32_bf16 v[60:63], v[160:163], v[194:197], 0
	v_mfma_f32_16x16x32_bf16 v[52:55], v[168:171], v[194:197], 0
	v_mfma_f32_16x16x32_bf16 v[44:47], v[160:163], v[202:205], 0
	v_mfma_f32_16x16x32_bf16 v[36:39], v[168:171], v[202:205], 0
	v_mfma_f32_16x16x32_bf16 v[28:31], v[160:163], v[210:213], 0
	v_mfma_f32_16x16x32_bf16 v[20:23], v[168:171], v[210:213], 0
	v_mfma_f32_16x16x32_bf16 v[12:15], v[160:163], v[218:221], 0
	v_mfma_f32_16x16x32_bf16 v[4:7], v[168:171], v[218:221], 0
	v_mfma_f32_16x16x32_bf16 v[60:63], v[164:167], v[198:201], v[60:63]
	v_mfma_f32_16x16x32_bf16 v[52:55], v[172:175], v[198:201], v[52:55]
	v_mfma_f32_16x16x32_bf16 v[44:47], v[164:167], v[206:209], v[44:47]
	v_mfma_f32_16x16x32_bf16 v[36:39], v[172:175], v[206:209], v[36:39]
	v_mfma_f32_16x16x32_bf16 v[28:31], v[164:167], v[214:217], v[28:31]
	v_mfma_f32_16x16x32_bf16 v[20:23], v[172:175], v[214:217], v[20:23]
	v_mfma_f32_16x16x32_bf16 v[12:15], v[164:167], v[222:225], v[12:15]
	v_mfma_f32_16x16x32_bf16 v[4:7], v[172:175], v[222:225], v[4:7]
	s_setprio 0
	s_setprio 1
	v_mfma_f32_16x16x32_bf16 v[56:59], v[176:179], v[194:197], 0
	v_mfma_f32_16x16x32_bf16 v[48:51], v[186:189], v[194:197], 0
	v_mfma_f32_16x16x32_bf16 v[40:43], v[176:179], v[202:205], 0
	v_mfma_f32_16x16x32_bf16 v[32:35], v[186:189], v[202:205], 0
	v_mfma_f32_16x16x32_bf16 v[24:27], v[176:179], v[210:213], 0
	v_mfma_f32_16x16x32_bf16 v[16:19], v[186:189], v[210:213], 0
	v_mfma_f32_16x16x32_bf16 v[8:11], v[176:179], v[218:221], 0
	v_mfma_f32_16x16x32_bf16 v[0:3], v[186:189], v[218:221], 0
	v_mfma_f32_16x16x32_bf16 v[56:59], v[180:183], v[198:201], v[56:59]
	v_mfma_f32_16x16x32_bf16 v[48:51], v[190:193], v[198:201], v[48:51]
	v_mfma_f32_16x16x32_bf16 v[40:43], v[180:183], v[206:209], v[40:43]
	v_mfma_f32_16x16x32_bf16 v[32:35], v[190:193], v[206:209], v[32:35]
	v_mfma_f32_16x16x32_bf16 v[24:27], v[180:183], v[214:217], v[24:27]
	v_mfma_f32_16x16x32_bf16 v[16:19], v[190:193], v[214:217], v[16:19]
	v_mfma_f32_16x16x32_bf16 v[8:11], v[180:183], v[222:225], v[8:11]
	v_mfma_f32_16x16x32_bf16 v[0:3], v[190:193], v[222:225], v[0:3]
	s_barrier
	s_setprio 0
	s_add_i32 s76, 0, 0x18000
	v_add_u32_e32 v153, s76, v147
	s_add_i32 s77, 0, 0x1c000
	ds_read_b128 v[160:163], v153
	v_xor_b32_e32 v253, 64, v153
	ds_read_b128 v[164:167], v253
	ds_read_b128 v[168:171], v153 offset:2048
	ds_read_b128 v[172:175], v253 offset:2048
	v_add_u32_e32 v153, s77, v147
	ds_read_b128 v[176:179], v153
	v_xor_b32_e32 v253, 64, v153
	ds_read_b128 v[180:183], v253
	ds_read_b128 v[186:189], v153 offset:2048
	ds_read_b128 v[190:193], v253 offset:2048
	s_add_u32 s50, s50, 0x40000
	s_addc_u32 s51, s51, 0
	s_mov_b32 m0, s59
	v_lshl_add_u64 v[232:233], s[50:51], 0, v[134:135]
	ds_read_b128 v[194:197], v150 offset:32768
	v_xor_b32_e32 v253, 64, v150
	ds_read_b128 v[198:201], v253 offset:32768
	ds_read_b128 v[202:205], v150 offset:34816
	ds_read_b128 v[206:209], v253 offset:34816
	ds_read_b128 v[210:213], v150 offset:36864
	ds_read_b128 v[214:217], v253 offset:36864
	ds_read_b128 v[218:221], v150 offset:38912
	ds_read_b128 v[222:225], v253 offset:38912
	global_load_lds_dwordx4 v[232:233], off
	v_lshl_add_u64 v[232:233], s[50:51], 0, v[130:131]
	s_mov_b32 m0, s60
	s_nop 0
	global_load_lds_dwordx4 v[232:233], off
	s_waitcnt vmcnt(8)
	s_waitcnt lgkmcnt(0)
	s_setprio 1
	s_barrier
	v_mfma_f32_16x16x32_bf16 v[124:127], v[160:163], v[194:197], v[124:127]
	v_mfma_f32_16x16x32_bf16 v[124:127], v[164:167], v[198:201], v[124:127]
	v_mfma_f32_16x16x32_bf16 v[116:119], v[172:175], v[198:201], v[116:119]
	v_mfma_f32_16x16x32_bf16 v[116:119], v[168:171], v[194:197], v[116:119]
	v_mfma_f32_16x16x32_bf16 v[100:103], v[168:171], v[202:205], v[100:103]
	v_mfma_f32_16x16x32_bf16 v[100:103], v[172:175], v[206:209], v[100:103]
	v_mfma_f32_16x16x32_bf16 v[108:111], v[164:167], v[206:209], v[108:111]
	v_mfma_f32_16x16x32_bf16 v[108:111], v[160:163], v[202:205], v[108:111]
	v_mfma_f32_16x16x32_bf16 v[92:95], v[160:163], v[210:213], v[92:95]
	v_mfma_f32_16x16x32_bf16 v[92:95], v[164:167], v[214:217], v[92:95]
	v_mfma_f32_16x16x32_bf16 v[84:87], v[172:175], v[214:217], v[84:87]
	v_mfma_f32_16x16x32_bf16 v[84:87], v[168:171], v[210:213], v[84:87]
	v_mfma_f32_16x16x32_bf16 v[68:71], v[168:171], v[218:221], v[68:71]
	v_mfma_f32_16x16x32_bf16 v[68:71], v[172:175], v[222:225], v[68:71]
	v_mfma_f32_16x16x32_bf16 v[76:79], v[164:167], v[222:225], v[76:79]
	v_mfma_f32_16x16x32_bf16 v[76:79], v[160:163], v[218:221], v[76:79]
	s_setprio 0
	s_setprio 1
	v_mfma_f32_16x16x32_bf16 v[120:123], v[176:179], v[194:197], v[120:123]
	v_mfma_f32_16x16x32_bf16 v[120:123], v[180:183], v[198:201], v[120:123]
	v_mfma_f32_16x16x32_bf16 v[112:115], v[190:193], v[198:201], v[112:115]
	v_mfma_f32_16x16x32_bf16 v[112:115], v[186:189], v[194:197], v[112:115]
	v_mfma_f32_16x16x32_bf16 v[96:99], v[186:189], v[202:205], v[96:99]
	v_mfma_f32_16x16x32_bf16 v[96:99], v[190:193], v[206:209], v[96:99]
	v_mfma_f32_16x16x32_bf16 v[104:107], v[180:183], v[206:209], v[104:107]
	v_mfma_f32_16x16x32_bf16 v[104:107], v[176:179], v[202:205], v[104:107]
	v_mfma_f32_16x16x32_bf16 v[88:91], v[176:179], v[210:213], v[88:91]
	v_mfma_f32_16x16x32_bf16 v[88:91], v[180:183], v[214:217], v[88:91]
	v_mfma_f32_16x16x32_bf16 v[80:83], v[190:193], v[214:217], v[80:83]
	v_mfma_f32_16x16x32_bf16 v[80:83], v[186:189], v[210:213], v[80:83]
	v_mfma_f32_16x16x32_bf16 v[64:67], v[186:189], v[218:221], v[64:67]
	v_mfma_f32_16x16x32_bf16 v[64:67], v[190:193], v[222:225], v[64:67]
	v_mfma_f32_16x16x32_bf16 v[72:75], v[180:183], v[222:225], v[72:75]
	v_mfma_f32_16x16x32_bf16 v[72:75], v[176:179], v[218:221], v[72:75]
	s_barrier
	s_setprio 0
	s_add_i32 s50, s76, s54
	v_lshl_add_u64 v[154:155], v[154:155], 0, s[20:21]
	s_mov_b32 m0, s50
	ds_read_b128 v[194:197], v150 offset:49152
	v_xor_b32_e32 v253, 64, v150
	ds_read_b128 v[198:201], v253 offset:49152
	ds_read_b128 v[202:205], v150 offset:51200
	ds_read_b128 v[206:209], v253 offset:51200
	ds_read_b128 v[210:213], v150 offset:53248
	ds_read_b128 v[214:217], v253 offset:53248
	ds_read_b128 v[218:221], v150 offset:55296
	ds_read_b128 v[222:225], v253 offset:55296
	global_load_lds_dwordx4 v[154:155], off
	s_add_i32 m0, s50, 0x2000
	s_add_u32 s48, s48, 0x40080
	v_lshl_add_u64 v[154:155], v[226:227], 0, s[20:21]
	s_addc_u32 s49, s49, 0
	s_add_i32 s50, s77, s54
	global_load_lds_dwordx4 v[154:155], off
	v_lshl_add_u64 v[154:155], s[48:49], 0, v[132:133]
	s_mov_b32 m0, s50
	s_nop 0
	global_load_lds_dwordx4 v[154:155], off
	v_lshl_add_u64 v[154:155], s[48:49], 0, v[128:129]
	s_add_i32 m0, s50, 0x2000
	s_nop 0
	global_load_lds_dwordx4 v[154:155], off
	v_lshl_add_u64 v[154:155], v[228:229], 0, s[20:21]
	s_mov_b32 m0, s62
	s_nop 0
	global_load_lds_dwordx4 v[154:155], off
	v_lshl_add_u64 v[154:155], v[230:231], 0, s[20:21]
	s_mov_b32 m0, s63
	s_nop 0
	global_load_lds_dwordx4 v[154:155], off
	s_waitcnt vmcnt(8)
	s_waitcnt lgkmcnt(0)
	s_setprio 1
	s_barrier
	v_mfma_f32_16x16x32_bf16 v[60:63], v[160:163], v[194:197], v[60:63]
	v_mfma_f32_16x16x32_bf16 v[60:63], v[164:167], v[198:201], v[60:63]
	v_mfma_f32_16x16x32_bf16 v[52:55], v[172:175], v[198:201], v[52:55]
	v_mfma_f32_16x16x32_bf16 v[52:55], v[168:171], v[194:197], v[52:55]
	v_mfma_f32_16x16x32_bf16 v[36:39], v[168:171], v[202:205], v[36:39]
	v_mfma_f32_16x16x32_bf16 v[36:39], v[172:175], v[206:209], v[36:39]
	v_mfma_f32_16x16x32_bf16 v[44:47], v[164:167], v[206:209], v[44:47]
	v_mfma_f32_16x16x32_bf16 v[44:47], v[160:163], v[202:205], v[44:47]
	v_mfma_f32_16x16x32_bf16 v[28:31], v[160:163], v[210:213], v[28:31]
	v_mfma_f32_16x16x32_bf16 v[28:31], v[164:167], v[214:217], v[28:31]
	v_mfma_f32_16x16x32_bf16 v[20:23], v[172:175], v[214:217], v[20:23]
	v_mfma_f32_16x16x32_bf16 v[20:23], v[168:171], v[210:213], v[20:23]
	v_mfma_f32_16x16x32_bf16 v[4:7], v[168:171], v[218:221], v[4:7]
	v_mfma_f32_16x16x32_bf16 v[4:7], v[172:175], v[222:225], v[4:7]
	v_mfma_f32_16x16x32_bf16 v[12:15], v[164:167], v[222:225], v[12:15]
	v_mfma_f32_16x16x32_bf16 v[12:15], v[160:163], v[218:221], v[12:15]
	s_setprio 0
	s_setprio 1
	v_mfma_f32_16x16x32_bf16 v[56:59], v[176:179], v[194:197], v[56:59]
	v_mfma_f32_16x16x32_bf16 v[56:59], v[180:183], v[198:201], v[56:59]
	v_mfma_f32_16x16x32_bf16 v[48:51], v[190:193], v[198:201], v[48:51]
	v_mfma_f32_16x16x32_bf16 v[48:51], v[186:189], v[194:197], v[48:51]
	v_mfma_f32_16x16x32_bf16 v[32:35], v[186:189], v[202:205], v[32:35]
	v_mfma_f32_16x16x32_bf16 v[32:35], v[190:193], v[206:209], v[32:35]
	v_mfma_f32_16x16x32_bf16 v[40:43], v[180:183], v[206:209], v[40:43]
	v_mfma_f32_16x16x32_bf16 v[40:43], v[176:179], v[202:205], v[40:43]
	v_mfma_f32_16x16x32_bf16 v[24:27], v[176:179], v[210:213], v[24:27]
	v_mfma_f32_16x16x32_bf16 v[24:27], v[180:183], v[214:217], v[24:27]
	v_mfma_f32_16x16x32_bf16 v[16:19], v[190:193], v[214:217], v[16:19]
	v_mfma_f32_16x16x32_bf16 v[16:19], v[186:189], v[210:213], v[16:19]
	v_mfma_f32_16x16x32_bf16 v[0:3], v[186:189], v[218:221], v[0:3]
	v_mfma_f32_16x16x32_bf16 v[0:3], v[190:193], v[222:225], v[0:3]
	v_mfma_f32_16x16x32_bf16 v[8:11], v[180:183], v[222:225], v[8:11]
	v_mfma_f32_16x16x32_bf16 v[8:11], v[176:179], v[218:221], v[8:11]
	s_barrier
	s_setprio 0
	s_add_i32 s75, s75, 2
	s_add_u32 s73, s73, 0x100
	s_addc_u32 s74, s74, 0
	s_add_u32 s46, s46, 0x100
	s_addc_u32 s47, s47, 0
	s_branch .LBB0_527
.Lfa_4:
	v_add_u32_e32 v153, s66, v147
	ds_read_b128 v[160:163], v153
	v_xor_b32_e32 v253, 64, v153
	ds_read_b128 v[164:167], v253
	ds_read_b128 v[168:171], v153 offset:2048
	ds_read_b128 v[172:175], v253 offset:2048
	v_add_u32_e32 v153, s67, v147
	ds_read_b128 v[176:179], v153
	v_xor_b32_e32 v253, 64, v153
	ds_read_b128 v[180:183], v253
	ds_read_b128 v[186:189], v153 offset:2048
	ds_read_b128 v[190:193], v253 offset:2048
	s_add_u32 s50, s46, 0xfffc0080
	s_addc_u32 s51, s47, -1
	s_and_b64 s[48:49], s[48:49], exec
	s_cselect_b32 s51, s29, s51
	s_cselect_b32 s50, s70, s50
	s_cselect_b32 s49, s71, s74
	s_cselect_b32 s48, s72, s73
	v_lshl_add_u64 v[154:155], s[46:47], 0, v[138:139]
	s_add_i32 m0, s57, 0xc000
	ds_read_b128 v[194:197], v150
	v_xor_b32_e32 v253, 64, v150
	ds_read_b128 v[198:201], v253
	ds_read_b128 v[202:205], v150 offset:2048
	ds_read_b128 v[206:209], v253 offset:2048
	ds_read_b128 v[210:213], v150 offset:4096
	ds_read_b128 v[214:217], v253 offset:4096
	ds_read_b128 v[218:221], v150 offset:6144
	ds_read_b128 v[222:225], v253 offset:6144
	global_load_lds_dwordx4 v[154:155], off
	v_lshl_add_u64 v[154:155], s[46:47], 0, v[136:137]
	s_add_i32 m0, s57, 0xe000
	s_nop 0
	global_load_lds_dwordx4 v[154:155], off
	s_waitcnt vmcnt(8)
	s_waitcnt lgkmcnt(0)
	s_setprio 1
	s_barrier
	v_mfma_f32_16x16x32_bf16 v[124:127], v[160:163], v[194:197], 0
	v_mfma_f32_16x16x32_bf16 v[116:119], v[168:171], v[194:197], 0
	v_mfma_f32_16x16x32_bf16 v[108:111], v[160:163], v[202:205], 0
	v_mfma_f32_16x16x32_bf16 v[100:103], v[168:171], v[202:205], 0
	v_mfma_f32_16x16x32_bf16 v[92:95], v[160:163], v[210:213], 0
	v_mfma_f32_16x16x32_bf16 v[84:87], v[168:171], v[210:213], 0
	v_mfma_f32_16x16x32_bf16 v[76:79], v[160:163], v[218:221], 0
	v_mfma_f32_16x16x32_bf16 v[68:71], v[168:171], v[218:221], 0
	v_mfma_f32_16x16x32_bf16 v[124:127], v[164:167], v[198:201], v[124:127]
	v_mfma_f32_16x16x32_bf16 v[116:119], v[172:175], v[198:201], v[116:119]
	v_mfma_f32_16x16x32_bf16 v[108:111], v[164:167], v[206:209], v[108:111]
	v_mfma_f32_16x16x32_bf16 v[100:103], v[172:175], v[206:209], v[100:103]
	v_mfma_f32_16x16x32_bf16 v[92:95], v[164:167], v[214:217], v[92:95]
	v_mfma_f32_16x16x32_bf16 v[84:87], v[172:175], v[214:217], v[84:87]
	v_mfma_f32_16x16x32_bf16 v[76:79], v[164:167], v[222:225], v[76:79]
	v_mfma_f32_16x16x32_bf16 v[68:71], v[172:175], v[222:225], v[68:71]
	s_setprio 0
	s_setprio 1
	v_mfma_f32_16x16x32_bf16 v[120:123], v[176:179], v[194:197], 0
	v_mfma_f32_16x16x32_bf16 v[112:115], v[186:189], v[194:197], 0
	v_mfma_f32_16x16x32_bf16 v[104:107], v[176:179], v[202:205], 0
	v_mfma_f32_16x16x32_bf16 v[96:99], v[186:189], v[202:205], 0
	v_mfma_f32_16x16x32_bf16 v[88:91], v[176:179], v[210:213], 0
	v_mfma_f32_16x16x32_bf16 v[80:83], v[186:189], v[210:213], 0
	v_mfma_f32_16x16x32_bf16 v[72:75], v[176:179], v[218:221], 0
	v_mfma_f32_16x16x32_bf16 v[64:67], v[186:189], v[218:221], 0
	v_mfma_f32_16x16x32_bf16 v[120:123], v[180:183], v[198:201], v[120:123]
	v_mfma_f32_16x16x32_bf16 v[112:115], v[190:193], v[198:201], v[112:115]
	v_mfma_f32_16x16x32_bf16 v[104:107], v[180:183], v[206:209], v[104:107]
	v_mfma_f32_16x16x32_bf16 v[96:99], v[190:193], v[206:209], v[96:99]
	v_mfma_f32_16x16x32_bf16 v[88:91], v[180:183], v[214:217], v[88:91]
	v_mfma_f32_16x16x32_bf16 v[80:83], v[190:193], v[214:217], v[80:83]
	v_mfma_f32_16x16x32_bf16 v[72:75], v[180:183], v[222:225], v[72:75]
	v_mfma_f32_16x16x32_bf16 v[64:67], v[190:193], v[222:225], v[64:67]
	s_barrier
	s_setprio 0
	s_add_i32 s76, s66, s54
	v_lshl_add_u64 v[154:155], s[48:49], 0, v[132:133]
	s_mov_b32 m0, s76
	ds_read_b128 v[194:197], v150 offset:16384
	v_xor_b32_e32 v253, 64, v150
	ds_read_b128 v[198:201], v253 offset:16384
	ds_read_b128 v[202:205], v150 offset:18432
	ds_read_b128 v[206:209], v253 offset:18432
	ds_read_b128 v[210:213], v150 offset:20480
	ds_read_b128 v[214:217], v253 offset:20480
	ds_read_b128 v[218:221], v150 offset:22528
	ds_read_b128 v[222:225], v253 offset:22528
	global_load_lds_dwordx4 v[154:155], off
	s_add_i32 m0, s76, 0x2000
	s_add_u32 s76, s48, 0x40000
	v_lshl_add_u64 v[226:227], s[48:49], 0, v[128:129]
	s_addc_u32 s77, s49, 0
	s_add_i32 s78, s67, s54
	global_load_lds_dwordx4 v[226:227], off
	v_lshl_add_u64 v[228:229], s[76:77], 0, v[132:133]
	s_mov_b32 m0, s78
	v_lshl_add_u64 v[230:231], s[50:51], 0, v[130:131]
	global_load_lds_dwordx4 v[228:229], off
	v_lshl_add_u64 v[228:229], s[76:77], 0, v[128:129]
	s_add_i32 m0, s78, 0x2000
	s_nop 0
	global_load_lds_dwordx4 v[228:229], off
	v_lshl_add_u64 v[228:229], s[50:51], 0, v[134:135]
	s_mov_b32 m0, s57
	s_nop 0
	global_load_lds_dwordx4 v[228:229], off
	s_mov_b32 m0, s58
	s_nop 0
	global_load_lds_dwordx4 v[230:231], off
	s_waitcnt vmcnt(8)
	s_waitcnt lgkmcnt(0)
	s_setprio 1
	s_barrier
	v_mfma_f32_16x16x32_bf16 v[60:63], v[160:163], v[194:197], 0
	v_mfma_f32_16x16x32_bf16 v[52:55], v[168:171], v[194:197], 0
	v_mfma_f32_16x16x32_bf16 v[44:47], v[160:163], v[202:205], 0
	v_mfma_f32_16x16x32_bf16 v[36:39], v[168:171], v[202:205], 0
	v_mfma_f32_16x16x32_bf16 v[28:31], v[160:163], v[210:213], 0
	v_mfma_f32_16x16x32_bf16 v[20:23], v[168:171], v[210:213], 0
	v_mfma_f32_16x16x32_bf16 v[12:15], v[160:163], v[218:221], 0
	v_mfma_f32_16x16x32_bf16 v[4:7], v[168:171], v[218:221], 0
	v_mfma_f32_16x16x32_bf16 v[60:63], v[164:167], v[198:201], v[60:63]
	v_mfma_f32_16x16x32_bf16 v[52:55], v[172:175], v[198:201], v[52:55]
	v_mfma_f32_16x16x32_bf16 v[44:47], v[164:167], v[206:209], v[44:47]
	v_mfma_f32_16x16x32_bf16 v[36:39], v[172:175], v[206:209], v[36:39]
	v_mfma_f32_16x16x32_bf16 v[28:31], v[164:167], v[214:217], v[28:31]
	v_mfma_f32_16x16x32_bf16 v[20:23], v[172:175], v[214:217], v[20:23]
	v_mfma_f32_16x16x32_bf16 v[12:15], v[164:167], v[222:225], v[12:15]
	v_mfma_f32_16x16x32_bf16 v[4:7], v[172:175], v[222:225], v[4:7]
	s_setprio 0
	s_setprio 1
	v_mfma_f32_16x16x32_bf16 v[56:59], v[176:179], v[194:197], 0
	v_mfma_f32_16x16x32_bf16 v[48:51], v[186:189], v[194:197], 0
	v_mfma_f32_16x16x32_bf16 v[40:43], v[176:179], v[202:205], 0
	v_mfma_f32_16x16x32_bf16 v[32:35], v[186:189], v[202:205], 0
	v_mfma_f32_16x16x32_bf16 v[24:27], v[176:179], v[210:213], 0
	v_mfma_f32_16x16x32_bf16 v[16:19], v[186:189], v[210:213], 0
	v_mfma_f32_16x16x32_bf16 v[8:11], v[176:179], v[218:221], 0
	v_mfma_f32_16x16x32_bf16 v[0:3], v[186:189], v[218:221], 0
	v_mfma_f32_16x16x32_bf16 v[56:59], v[180:183], v[198:201], v[56:59]
	v_mfma_f32_16x16x32_bf16 v[48:51], v[190:193], v[198:201], v[48:51]
	v_mfma_f32_16x16x32_bf16 v[40:43], v[180:183], v[206:209], v[40:43]
	v_mfma_f32_16x16x32_bf16 v[32:35], v[190:193], v[206:209], v[32:35]
	v_mfma_f32_16x16x32_bf16 v[24:27], v[180:183], v[214:217], v[24:27]
	v_mfma_f32_16x16x32_bf16 v[16:19], v[190:193], v[214:217], v[16:19]
	v_mfma_f32_16x16x32_bf16 v[8:11], v[180:183], v[222:225], v[8:11]
	v_mfma_f32_16x16x32_bf16 v[0:3], v[190:193], v[222:225], v[0:3]
	s_barrier
	s_setprio 0
	s_add_i32 s76, 0, 0x18000
	v_add_u32_e32 v153, s76, v147
	s_add_i32 s77, 0, 0x1c000
	ds_read_b128 v[160:163], v153
	v_xor_b32_e32 v253, 64, v153
	ds_read_b128 v[164:167], v253
	ds_read_b128 v[168:171], v153 offset:2048
	ds_read_b128 v[172:175], v253 offset:2048
	v_add_u32_e32 v153, s77, v147
	ds_read_b128 v[176:179], v153
	v_xor_b32_e32 v253, 64, v153
	ds_read_b128 v[180:183], v253
	ds_read_b128 v[186:189], v153 offset:2048
	ds_read_b128 v[190:193], v253 offset:2048
	s_add_u32 s50, s50, 0x40000
	s_addc_u32 s51, s51, 0
	s_mov_b32 m0, s59
	v_lshl_add_u64 v[232:233], s[50:51], 0, v[134:135]
	ds_read_b128 v[194:197], v150 offset:32768
	v_xor_b32_e32 v253, 64, v150
	ds_read_b128 v[198:201], v253 offset:32768
	ds_read_b128 v[202:205], v150 offset:34816
	ds_read_b128 v[206:209], v253 offset:34816
	ds_read_b128 v[210:213], v150 offset:36864
	ds_read_b128 v[214:217], v253 offset:36864
	ds_read_b128 v[218:221], v150 offset:38912
	ds_read_b128 v[222:225], v253 offset:38912
	global_load_lds_dwordx4 v[232:233], off
	v_lshl_add_u64 v[232:233], s[50:51], 0, v[130:131]
	s_mov_b32 m0, s60
	s_nop 0
	global_load_lds_dwordx4 v[232:233], off
	s_waitcnt vmcnt(8)
	s_waitcnt lgkmcnt(0)
	s_setprio 1
	s_barrier
	v_mfma_f32_16x16x32_bf16 v[124:127], v[160:163], v[194:197], v[124:127]
	v_mfma_f32_16x16x32_bf16 v[124:127], v[164:167], v[198:201], v[124:127]
	v_mfma_f32_16x16x32_bf16 v[116:119], v[172:175], v[198:201], v[116:119]
	v_mfma_f32_16x16x32_bf16 v[116:119], v[168:171], v[194:197], v[116:119]
	v_mfma_f32_16x16x32_bf16 v[100:103], v[168:171], v[202:205], v[100:103]
	v_mfma_f32_16x16x32_bf16 v[100:103], v[172:175], v[206:209], v[100:103]
	v_mfma_f32_16x16x32_bf16 v[108:111], v[164:167], v[206:209], v[108:111]
	v_mfma_f32_16x16x32_bf16 v[108:111], v[160:163], v[202:205], v[108:111]
	v_mfma_f32_16x16x32_bf16 v[92:95], v[160:163], v[210:213], v[92:95]
	v_mfma_f32_16x16x32_bf16 v[92:95], v[164:167], v[214:217], v[92:95]
	v_mfma_f32_16x16x32_bf16 v[84:87], v[172:175], v[214:217], v[84:87]
	v_mfma_f32_16x16x32_bf16 v[84:87], v[168:171], v[210:213], v[84:87]
	v_mfma_f32_16x16x32_bf16 v[68:71], v[168:171], v[218:221], v[68:71]
	v_mfma_f32_16x16x32_bf16 v[68:71], v[172:175], v[222:225], v[68:71]
	v_mfma_f32_16x16x32_bf16 v[76:79], v[164:167], v[222:225], v[76:79]
	v_mfma_f32_16x16x32_bf16 v[76:79], v[160:163], v[218:221], v[76:79]
	s_setprio 0
	s_setprio 1
	v_mfma_f32_16x16x32_bf16 v[120:123], v[176:179], v[194:197], v[120:123]
	v_mfma_f32_16x16x32_bf16 v[120:123], v[180:183], v[198:201], v[120:123]
	v_mfma_f32_16x16x32_bf16 v[112:115], v[190:193], v[198:201], v[112:115]
	v_mfma_f32_16x16x32_bf16 v[112:115], v[186:189], v[194:197], v[112:115]
	v_mfma_f32_16x16x32_bf16 v[96:99], v[186:189], v[202:205], v[96:99]
	v_mfma_f32_16x16x32_bf16 v[96:99], v[190:193], v[206:209], v[96:99]
	v_mfma_f32_16x16x32_bf16 v[104:107], v[180:183], v[206:209], v[104:107]
	v_mfma_f32_16x16x32_bf16 v[104:107], v[176:179], v[202:205], v[104:107]
	v_mfma_f32_16x16x32_bf16 v[88:91], v[176:179], v[210:213], v[88:91]
	v_mfma_f32_16x16x32_bf16 v[88:91], v[180:183], v[214:217], v[88:91]
	v_mfma_f32_16x16x32_bf16 v[80:83], v[190:193], v[214:217], v[80:83]
	v_mfma_f32_16x16x32_bf16 v[80:83], v[186:189], v[210:213], v[80:83]
	v_mfma_f32_16x16x32_bf16 v[64:67], v[186:189], v[218:221], v[64:67]
	v_mfma_f32_16x16x32_bf16 v[64:67], v[190:193], v[222:225], v[64:67]
	v_mfma_f32_16x16x32_bf16 v[72:75], v[180:183], v[222:225], v[72:75]
	v_mfma_f32_16x16x32_bf16 v[72:75], v[176:179], v[218:221], v[72:75]
	s_barrier
	s_setprio 0
	s_add_i32 s50, s76, s54
	v_lshl_add_u64 v[154:155], v[154:155], 0, s[20:21]
	s_mov_b32 m0, s50
	ds_read_b128 v[194:197], v150 offset:49152
	v_xor_b32_e32 v253, 64, v150
	ds_read_b128 v[198:201], v253 offset:49152
	ds_read_b128 v[202:205], v150 offset:51200
	ds_read_b128 v[206:209], v253 offset:51200
	ds_read_b128 v[210:213], v150 offset:53248
	ds_read_b128 v[214:217], v253 offset:53248
	ds_read_b128 v[218:221], v150 offset:55296
	ds_read_b128 v[222:225], v253 offset:55296
	global_load_lds_dwordx4 v[154:155], off
	s_add_i32 m0, s50, 0x2000
	s_add_u32 s48, s48, 0x40080
	v_lshl_add_u64 v[154:155], v[226:227], 0, s[20:21]
	s_addc_u32 s49, s49, 0
	s_add_i32 s50, s77, s54
	global_load_lds_dwordx4 v[154:155], off
	v_lshl_add_u64 v[154:155], s[48:49], 0, v[132:133]
	s_mov_b32 m0, s50
	s_nop 0
	global_load_lds_dwordx4 v[154:155], off
	v_lshl_add_u64 v[154:155], s[48:49], 0, v[128:129]
	s_add_i32 m0, s50, 0x2000
	s_nop 0
	global_load_lds_dwordx4 v[154:155], off
	v_lshl_add_u64 v[154:155], v[228:229], 0, s[20:21]
	s_mov_b32 m0, s62
	s_nop 0
	global_load_lds_dwordx4 v[154:155], off
	v_lshl_add_u64 v[154:155], v[230:231], 0, s[20:21]
	s_mov_b32 m0, s63
	s_nop 0
	global_load_lds_dwordx4 v[154:155], off
	s_waitcnt vmcnt(8)
	s_waitcnt lgkmcnt(0)
	s_setprio 1
	s_barrier
	v_mfma_f32_16x16x32_bf16 v[60:63], v[160:163], v[194:197], v[60:63]
	v_mfma_f32_16x16x32_bf16 v[60:63], v[164:167], v[198:201], v[60:63]
	v_mfma_f32_16x16x32_bf16 v[52:55], v[172:175], v[198:201], v[52:55]
	v_mfma_f32_16x16x32_bf16 v[52:55], v[168:171], v[194:197], v[52:55]
	v_mfma_f32_16x16x32_bf16 v[36:39], v[168:171], v[202:205], v[36:39]
	v_mfma_f32_16x16x32_bf16 v[36:39], v[172:175], v[206:209], v[36:39]
	v_mfma_f32_16x16x32_bf16 v[44:47], v[164:167], v[206:209], v[44:47]
	v_mfma_f32_16x16x32_bf16 v[44:47], v[160:163], v[202:205], v[44:47]
	v_mfma_f32_16x16x32_bf16 v[28:31], v[160:163], v[210:213], v[28:31]
	v_mfma_f32_16x16x32_bf16 v[28:31], v[164:167], v[214:217], v[28:31]
	v_mfma_f32_16x16x32_bf16 v[20:23], v[172:175], v[214:217], v[20:23]
	v_mfma_f32_16x16x32_bf16 v[20:23], v[168:171], v[210:213], v[20:23]
	v_mfma_f32_16x16x32_bf16 v[4:7], v[168:171], v[218:221], v[4:7]
	v_mfma_f32_16x16x32_bf16 v[4:7], v[172:175], v[222:225], v[4:7]
	v_mfma_f32_16x16x32_bf16 v[12:15], v[164:167], v[222:225], v[12:15]
	v_mfma_f32_16x16x32_bf16 v[12:15], v[160:163], v[218:221], v[12:15]
	s_setprio 0
	s_setprio 1
	v_mfma_f32_16x16x32_bf16 v[56:59], v[176:179], v[194:197], v[56:59]
	v_mfma_f32_16x16x32_bf16 v[56:59], v[180:183], v[198:201], v[56:59]
	v_mfma_f32_16x16x32_bf16 v[48:51], v[190:193], v[198:201], v[48:51]
	v_mfma_f32_16x16x32_bf16 v[48:51], v[186:189], v[194:197], v[48:51]
	v_mfma_f32_16x16x32_bf16 v[32:35], v[186:189], v[202:205], v[32:35]
	v_mfma_f32_16x16x32_bf16 v[32:35], v[190:193], v[206:209], v[32:35]
	v_mfma_f32_16x16x32_bf16 v[40:43], v[180:183], v[206:209], v[40:43]
	v_mfma_f32_16x16x32_bf16 v[40:43], v[176:179], v[202:205], v[40:43]
	v_mfma_f32_16x16x32_bf16 v[24:27], v[176:179], v[210:213], v[24:27]
	v_mfma_f32_16x16x32_bf16 v[24:27], v[180:183], v[214:217], v[24:27]
	v_mfma_f32_16x16x32_bf16 v[16:19], v[190:193], v[214:217], v[16:19]
	v_mfma_f32_16x16x32_bf16 v[16:19], v[186:189], v[210:213], v[16:19]
	v_mfma_f32_16x16x32_bf16 v[0:3], v[186:189], v[218:221], v[0:3]
	v_mfma_f32_16x16x32_bf16 v[0:3], v[190:193], v[222:225], v[0:3]
	v_mfma_f32_16x16x32_bf16 v[8:11], v[180:183], v[222:225], v[8:11]
	v_mfma_f32_16x16x32_bf16 v[8:11], v[176:179], v[218:221], v[8:11]
	s_barrier
	s_setprio 0
	s_add_i32 s75, s75, 2
	s_add_u32 s73, s73, 0x100
	s_addc_u32 s74, s74, 0
	s_add_u32 s46, s46, 0x100
	s_addc_u32 s47, s47, 0
	s_branch .LBB0_527
.LBB0_526:
	v_add_u32_e32 v153, s66, v147
	ds_read_b128 v[160:163], v153
	v_xor_b32_e32 v253, 64, v153
	ds_read_b128 v[164:167], v253
	ds_read_b128 v[168:171], v153 offset:2048
	ds_read_b128 v[172:175], v253 offset:2048
	v_add_u32_e32 v153, s67, v147
	ds_read_b128 v[176:179], v153
	v_xor_b32_e32 v253, 64, v153
	ds_read_b128 v[180:183], v253
	ds_read_b128 v[186:189], v153 offset:2048
	ds_read_b128 v[190:193], v253 offset:2048
	s_add_u32 s50, s46, 0xfffc0080
	s_addc_u32 s51, s47, -1
	s_and_b64 s[48:49], s[48:49], exec
	s_cselect_b32 s51, s29, s51
	s_cselect_b32 s50, s70, s50
	s_cselect_b32 s49, s71, s74
	s_cselect_b32 s48, s72, s73
	v_lshl_add_u64 v[154:155], s[46:47], 0, v[138:139]
	s_add_i32 m0, s57, 0xc000
	ds_read_b128 v[194:197], v150
	v_xor_b32_e32 v253, 64, v150
	ds_read_b128 v[198:201], v253
	ds_read_b128 v[202:205], v150 offset:2048
	ds_read_b128 v[206:209], v253 offset:2048
	ds_read_b128 v[210:213], v150 offset:4096
	ds_read_b128 v[214:217], v253 offset:4096
	ds_read_b128 v[218:221], v150 offset:6144
	ds_read_b128 v[222:225], v253 offset:6144
	global_load_lds_dwordx4 v[154:155], off
	v_lshl_add_u64 v[154:155], s[46:47], 0, v[136:137]
	s_add_i32 m0, s57, 0xe000
	s_nop 0
	global_load_lds_dwordx4 v[154:155], off
	s_waitcnt vmcnt(8)
	s_waitcnt lgkmcnt(0)
	s_setprio 1
	s_barrier
	v_mfma_f32_16x16x32_bf16 v[124:127], v[160:163], v[194:197], v[124:127]
	v_mfma_f32_16x16x32_bf16 v[124:127], v[164:167], v[198:201], v[124:127]
	v_mfma_f32_16x16x32_bf16 v[116:119], v[172:175], v[198:201], v[116:119]
	v_mfma_f32_16x16x32_bf16 v[116:119], v[168:171], v[194:197], v[116:119]
	v_mfma_f32_16x16x32_bf16 v[100:103], v[168:171], v[202:205], v[100:103]
	v_mfma_f32_16x16x32_bf16 v[100:103], v[172:175], v[206:209], v[100:103]
	v_mfma_f32_16x16x32_bf16 v[108:111], v[164:167], v[206:209], v[108:111]
	v_mfma_f32_16x16x32_bf16 v[108:111], v[160:163], v[202:205], v[108:111]
	v_mfma_f32_16x16x32_bf16 v[92:95], v[160:163], v[210:213], v[92:95]
	v_mfma_f32_16x16x32_bf16 v[92:95], v[164:167], v[214:217], v[92:95]
	v_mfma_f32_16x16x32_bf16 v[84:87], v[172:175], v[214:217], v[84:87]
	v_mfma_f32_16x16x32_bf16 v[84:87], v[168:171], v[210:213], v[84:87]
	v_mfma_f32_16x16x32_bf16 v[68:71], v[168:171], v[218:221], v[68:71]
	v_mfma_f32_16x16x32_bf16 v[68:71], v[172:175], v[222:225], v[68:71]
	v_mfma_f32_16x16x32_bf16 v[76:79], v[164:167], v[222:225], v[76:79]
	v_mfma_f32_16x16x32_bf16 v[76:79], v[160:163], v[218:221], v[76:79]
	s_setprio 0
	s_setprio 1
	v_mfma_f32_16x16x32_bf16 v[120:123], v[176:179], v[194:197], v[120:123]
	v_mfma_f32_16x16x32_bf16 v[120:123], v[180:183], v[198:201], v[120:123]
	v_mfma_f32_16x16x32_bf16 v[112:115], v[190:193], v[198:201], v[112:115]
	v_mfma_f32_16x16x32_bf16 v[112:115], v[186:189], v[194:197], v[112:115]
	v_mfma_f32_16x16x32_bf16 v[96:99], v[186:189], v[202:205], v[96:99]
	v_mfma_f32_16x16x32_bf16 v[96:99], v[190:193], v[206:209], v[96:99]
	v_mfma_f32_16x16x32_bf16 v[104:107], v[180:183], v[206:209], v[104:107]
	v_mfma_f32_16x16x32_bf16 v[104:107], v[176:179], v[202:205], v[104:107]
	v_mfma_f32_16x16x32_bf16 v[88:91], v[176:179], v[210:213], v[88:91]
	v_mfma_f32_16x16x32_bf16 v[88:91], v[180:183], v[214:217], v[88:91]
	v_mfma_f32_16x16x32_bf16 v[80:83], v[190:193], v[214:217], v[80:83]
	v_mfma_f32_16x16x32_bf16 v[80:83], v[186:189], v[210:213], v[80:83]
	v_mfma_f32_16x16x32_bf16 v[64:67], v[186:189], v[218:221], v[64:67]
	v_mfma_f32_16x16x32_bf16 v[64:67], v[190:193], v[222:225], v[64:67]
	v_mfma_f32_16x16x32_bf16 v[72:75], v[180:183], v[222:225], v[72:75]
	v_mfma_f32_16x16x32_bf16 v[72:75], v[176:179], v[218:221], v[72:75]
	s_barrier
	s_setprio 0
	s_add_i32 s76, s66, s54
	v_lshl_add_u64 v[154:155], s[48:49], 0, v[132:133]
	s_mov_b32 m0, s76
	ds_read_b128 v[194:197], v150 offset:16384
	v_xor_b32_e32 v253, 64, v150
	ds_read_b128 v[198:201], v253 offset:16384
	ds_read_b128 v[202:205], v150 offset:18432
	ds_read_b128 v[206:209], v253 offset:18432
	ds_read_b128 v[210:213], v150 offset:20480
	ds_read_b128 v[214:217], v253 offset:20480
	ds_read_b128 v[218:221], v150 offset:22528
	ds_read_b128 v[222:225], v253 offset:22528
	global_load_lds_dwordx4 v[154:155], off
	s_add_i32 m0, s76, 0x2000
	s_add_u32 s76, s48, 0x40000
	v_lshl_add_u64 v[226:227], s[48:49], 0, v[128:129]
	s_addc_u32 s77, s49, 0
	s_add_i32 s78, s67, s54
	global_load_lds_dwordx4 v[226:227], off
	v_lshl_add_u64 v[228:229], s[76:77], 0, v[132:133]
	s_mov_b32 m0, s78
	v_lshl_add_u64 v[230:231], s[50:51], 0, v[130:131]
	global_load_lds_dwordx4 v[228:229], off
	v_lshl_add_u64 v[228:229], s[76:77], 0, v[128:129]
	s_add_i32 m0, s78, 0x2000
	s_nop 0
	global_load_lds_dwordx4 v[228:229], off
	v_lshl_add_u64 v[228:229], s[50:51], 0, v[134:135]
	s_mov_b32 m0, s57
	s_nop 0
	global_load_lds_dwordx4 v[228:229], off
	s_mov_b32 m0, s58
	s_nop 0
	global_load_lds_dwordx4 v[230:231], off
	s_waitcnt vmcnt(8)
	s_waitcnt lgkmcnt(0)
	s_setprio 1
	s_barrier
	v_mfma_f32_16x16x32_bf16 v[60:63], v[160:163], v[194:197], v[60:63]
	v_mfma_f32_16x16x32_bf16 v[60:63], v[164:167], v[198:201], v[60:63]
	v_mfma_f32_16x16x32_bf16 v[52:55], v[172:175], v[198:201], v[52:55]
	v_mfma_f32_16x16x32_bf16 v[52:55], v[168:171], v[194:197], v[52:55]
	v_mfma_f32_16x16x32_bf16 v[36:39], v[168:171], v[202:205], v[36:39]
	v_mfma_f32_16x16x32_bf16 v[36:39], v[172:175], v[206:209], v[36:39]
	v_mfma_f32_16x16x32_bf16 v[44:47], v[164:167], v[206:209], v[44:47]
	v_mfma_f32_16x16x32_bf16 v[44:47], v[160:163], v[202:205], v[44:47]
	v_mfma_f32_16x16x32_bf16 v[28:31], v[160:163], v[210:213], v[28:31]
	v_mfma_f32_16x16x32_bf16 v[28:31], v[164:167], v[214:217], v[28:31]
	v_mfma_f32_16x16x32_bf16 v[20:23], v[172:175], v[214:217], v[20:23]
	v_mfma_f32_16x16x32_bf16 v[20:23], v[168:171], v[210:213], v[20:23]
	v_mfma_f32_16x16x32_bf16 v[4:7], v[168:171], v[218:221], v[4:7]
	v_mfma_f32_16x16x32_bf16 v[4:7], v[172:175], v[222:225], v[4:7]
	v_mfma_f32_16x16x32_bf16 v[12:15], v[164:167], v[222:225], v[12:15]
	v_mfma_f32_16x16x32_bf16 v[12:15], v[160:163], v[218:221], v[12:15]
	s_setprio 0
	s_setprio 1
	v_mfma_f32_16x16x32_bf16 v[56:59], v[176:179], v[194:197], v[56:59]
	v_mfma_f32_16x16x32_bf16 v[56:59], v[180:183], v[198:201], v[56:59]
	v_mfma_f32_16x16x32_bf16 v[48:51], v[190:193], v[198:201], v[48:51]
	v_mfma_f32_16x16x32_bf16 v[48:51], v[186:189], v[194:197], v[48:51]
	v_mfma_f32_16x16x32_bf16 v[32:35], v[186:189], v[202:205], v[32:35]
	v_mfma_f32_16x16x32_bf16 v[32:35], v[190:193], v[206:209], v[32:35]
	v_mfma_f32_16x16x32_bf16 v[40:43], v[180:183], v[206:209], v[40:43]
	v_mfma_f32_16x16x32_bf16 v[40:43], v[176:179], v[202:205], v[40:43]
	v_mfma_f32_16x16x32_bf16 v[24:27], v[176:179], v[210:213], v[24:27]
	v_mfma_f32_16x16x32_bf16 v[24:27], v[180:183], v[214:217], v[24:27]
	v_mfma_f32_16x16x32_bf16 v[16:19], v[190:193], v[214:217], v[16:19]
	v_mfma_f32_16x16x32_bf16 v[16:19], v[186:189], v[210:213], v[16:19]
	v_mfma_f32_16x16x32_bf16 v[0:3], v[186:189], v[218:221], v[0:3]
	v_mfma_f32_16x16x32_bf16 v[0:3], v[190:193], v[222:225], v[0:3]
	v_mfma_f32_16x16x32_bf16 v[8:11], v[180:183], v[222:225], v[8:11]
	v_mfma_f32_16x16x32_bf16 v[8:11], v[176:179], v[218:221], v[8:11]
	s_barrier
	s_setprio 0
	s_add_i32 s76, 0, 0x18000
	v_add_u32_e32 v153, s76, v147
	s_add_i32 s77, 0, 0x1c000
	ds_read_b128 v[160:163], v153
	v_xor_b32_e32 v253, 64, v153
	ds_read_b128 v[164:167], v253
	ds_read_b128 v[168:171], v153 offset:2048
	ds_read_b128 v[172:175], v253 offset:2048
	v_add_u32_e32 v153, s77, v147
	ds_read_b128 v[176:179], v153
	v_xor_b32_e32 v253, 64, v153
	ds_read_b128 v[180:183], v253
	ds_read_b128 v[186:189], v153 offset:2048
	ds_read_b128 v[190:193], v253 offset:2048
	s_add_u32 s50, s50, 0x40000
	s_addc_u32 s51, s51, 0
	s_mov_b32 m0, s59
	v_lshl_add_u64 v[232:233], s[50:51], 0, v[134:135]
	ds_read_b128 v[194:197], v150 offset:32768
	v_xor_b32_e32 v253, 64, v150
	ds_read_b128 v[198:201], v253 offset:32768
	ds_read_b128 v[202:205], v150 offset:34816
	ds_read_b128 v[206:209], v253 offset:34816
	ds_read_b128 v[210:213], v150 offset:36864
	ds_read_b128 v[214:217], v253 offset:36864
	ds_read_b128 v[218:221], v150 offset:38912
	ds_read_b128 v[222:225], v253 offset:38912
	global_load_lds_dwordx4 v[232:233], off
	v_lshl_add_u64 v[232:233], s[50:51], 0, v[130:131]
	s_mov_b32 m0, s60
	s_nop 0
	global_load_lds_dwordx4 v[232:233], off
	s_waitcnt vmcnt(8)
	s_waitcnt lgkmcnt(0)
	s_setprio 1
	s_barrier
	v_mfma_f32_16x16x32_bf16 v[124:127], v[160:163], v[194:197], v[124:127]
	v_mfma_f32_16x16x32_bf16 v[124:127], v[164:167], v[198:201], v[124:127]
	v_mfma_f32_16x16x32_bf16 v[116:119], v[172:175], v[198:201], v[116:119]
	v_mfma_f32_16x16x32_bf16 v[116:119], v[168:171], v[194:197], v[116:119]
	v_mfma_f32_16x16x32_bf16 v[100:103], v[168:171], v[202:205], v[100:103]
	v_mfma_f32_16x16x32_bf16 v[100:103], v[172:175], v[206:209], v[100:103]
	v_mfma_f32_16x16x32_bf16 v[108:111], v[164:167], v[206:209], v[108:111]
	v_mfma_f32_16x16x32_bf16 v[108:111], v[160:163], v[202:205], v[108:111]
	v_mfma_f32_16x16x32_bf16 v[92:95], v[160:163], v[210:213], v[92:95]
	v_mfma_f32_16x16x32_bf16 v[92:95], v[164:167], v[214:217], v[92:95]
	v_mfma_f32_16x16x32_bf16 v[84:87], v[172:175], v[214:217], v[84:87]
	v_mfma_f32_16x16x32_bf16 v[84:87], v[168:171], v[210:213], v[84:87]
	v_mfma_f32_16x16x32_bf16 v[68:71], v[168:171], v[218:221], v[68:71]
	v_mfma_f32_16x16x32_bf16 v[68:71], v[172:175], v[222:225], v[68:71]
	v_mfma_f32_16x16x32_bf16 v[76:79], v[164:167], v[222:225], v[76:79]
	v_mfma_f32_16x16x32_bf16 v[76:79], v[160:163], v[218:221], v[76:79]
	s_setprio 0
	s_setprio 1
	v_mfma_f32_16x16x32_bf16 v[120:123], v[176:179], v[194:197], v[120:123]
	v_mfma_f32_16x16x32_bf16 v[120:123], v[180:183], v[198:201], v[120:123]
	v_mfma_f32_16x16x32_bf16 v[112:115], v[190:193], v[198:201], v[112:115]
	v_mfma_f32_16x16x32_bf16 v[112:115], v[186:189], v[194:197], v[112:115]
	v_mfma_f32_16x16x32_bf16 v[96:99], v[186:189], v[202:205], v[96:99]
	v_mfma_f32_16x16x32_bf16 v[96:99], v[190:193], v[206:209], v[96:99]
	v_mfma_f32_16x16x32_bf16 v[104:107], v[180:183], v[206:209], v[104:107]
	v_mfma_f32_16x16x32_bf16 v[104:107], v[176:179], v[202:205], v[104:107]
	v_mfma_f32_16x16x32_bf16 v[88:91], v[176:179], v[210:213], v[88:91]
	v_mfma_f32_16x16x32_bf16 v[88:91], v[180:183], v[214:217], v[88:91]
	v_mfma_f32_16x16x32_bf16 v[80:83], v[190:193], v[214:217], v[80:83]
	v_mfma_f32_16x16x32_bf16 v[80:83], v[186:189], v[210:213], v[80:83]
	v_mfma_f32_16x16x32_bf16 v[64:67], v[186:189], v[218:221], v[64:67]
	v_mfma_f32_16x16x32_bf16 v[64:67], v[190:193], v[222:225], v[64:67]
	v_mfma_f32_16x16x32_bf16 v[72:75], v[180:183], v[222:225], v[72:75]
	v_mfma_f32_16x16x32_bf16 v[72:75], v[176:179], v[218:221], v[72:75]
	s_barrier
	s_setprio 0
	s_add_i32 s50, s76, s54
	v_lshl_add_u64 v[154:155], v[154:155], 0, s[20:21]
	s_mov_b32 m0, s50
	ds_read_b128 v[194:197], v150 offset:49152
	v_xor_b32_e32 v253, 64, v150
	ds_read_b128 v[198:201], v253 offset:49152
	ds_read_b128 v[202:205], v150 offset:51200
	ds_read_b128 v[206:209], v253 offset:51200
	ds_read_b128 v[210:213], v150 offset:53248
	ds_read_b128 v[214:217], v253 offset:53248
	ds_read_b128 v[218:221], v150 offset:55296
	ds_read_b128 v[222:225], v253 offset:55296
	global_load_lds_dwordx4 v[154:155], off
	s_add_i32 m0, s50, 0x2000
	s_add_u32 s48, s48, 0x40080
	v_lshl_add_u64 v[154:155], v[226:227], 0, s[20:21]
	s_addc_u32 s49, s49, 0
	s_add_i32 s50, s77, s54
	global_load_lds_dwordx4 v[154:155], off
	v_lshl_add_u64 v[154:155], s[48:49], 0, v[132:133]
	s_mov_b32 m0, s50
	s_nop 0
	global_load_lds_dwordx4 v[154:155], off
	v_lshl_add_u64 v[154:155], s[48:49], 0, v[128:129]
	s_add_i32 m0, s50, 0x2000
	s_nop 0
	global_load_lds_dwordx4 v[154:155], off
	v_lshl_add_u64 v[154:155], v[228:229], 0, s[20:21]
	s_mov_b32 m0, s62
	s_nop 0
	global_load_lds_dwordx4 v[154:155], off
	v_lshl_add_u64 v[154:155], v[230:231], 0, s[20:21]
	s_mov_b32 m0, s63
	s_nop 0
	global_load_lds_dwordx4 v[154:155], off
	s_waitcnt vmcnt(8)
	s_waitcnt lgkmcnt(0)
	s_setprio 1
	s_barrier
	v_mfma_f32_16x16x32_bf16 v[60:63], v[160:163], v[194:197], v[60:63]
	v_mfma_f32_16x16x32_bf16 v[60:63], v[164:167], v[198:201], v[60:63]
	v_mfma_f32_16x16x32_bf16 v[52:55], v[172:175], v[198:201], v[52:55]
	v_mfma_f32_16x16x32_bf16 v[52:55], v[168:171], v[194:197], v[52:55]
	v_mfma_f32_16x16x32_bf16 v[36:39], v[168:171], v[202:205], v[36:39]
	v_mfma_f32_16x16x32_bf16 v[36:39], v[172:175], v[206:209], v[36:39]
	v_mfma_f32_16x16x32_bf16 v[44:47], v[164:167], v[206:209], v[44:47]
	v_mfma_f32_16x16x32_bf16 v[44:47], v[160:163], v[202:205], v[44:47]
	v_mfma_f32_16x16x32_bf16 v[28:31], v[160:163], v[210:213], v[28:31]
	v_mfma_f32_16x16x32_bf16 v[28:31], v[164:167], v[214:217], v[28:31]
	v_mfma_f32_16x16x32_bf16 v[20:23], v[172:175], v[214:217], v[20:23]
	v_mfma_f32_16x16x32_bf16 v[20:23], v[168:171], v[210:213], v[20:23]
	v_mfma_f32_16x16x32_bf16 v[4:7], v[168:171], v[218:221], v[4:7]
	v_mfma_f32_16x16x32_bf16 v[4:7], v[172:175], v[222:225], v[4:7]
	v_mfma_f32_16x16x32_bf16 v[12:15], v[164:167], v[222:225], v[12:15]
	v_mfma_f32_16x16x32_bf16 v[12:15], v[160:163], v[218:221], v[12:15]
	s_setprio 0
	s_setprio 1
	v_mfma_f32_16x16x32_bf16 v[56:59], v[176:179], v[194:197], v[56:59]
	v_mfma_f32_16x16x32_bf16 v[56:59], v[180:183], v[198:201], v[56:59]
	v_mfma_f32_16x16x32_bf16 v[48:51], v[190:193], v[198:201], v[48:51]
	v_mfma_f32_16x16x32_bf16 v[48:51], v[186:189], v[194:197], v[48:51]
	v_mfma_f32_16x16x32_bf16 v[32:35], v[186:189], v[202:205], v[32:35]
	v_mfma_f32_16x16x32_bf16 v[32:35], v[190:193], v[206:209], v[32:35]
	v_mfma_f32_16x16x32_bf16 v[40:43], v[180:183], v[206:209], v[40:43]
	v_mfma_f32_16x16x32_bf16 v[40:43], v[176:179], v[202:205], v[40:43]
	v_mfma_f32_16x16x32_bf16 v[24:27], v[176:179], v[210:213], v[24:27]
	v_mfma_f32_16x16x32_bf16 v[24:27], v[180:183], v[214:217], v[24:27]
	v_mfma_f32_16x16x32_bf16 v[16:19], v[190:193], v[214:217], v[16:19]
	v_mfma_f32_16x16x32_bf16 v[16:19], v[186:189], v[210:213], v[16:19]
	v_mfma_f32_16x16x32_bf16 v[0:3], v[186:189], v[218:221], v[0:3]
	v_mfma_f32_16x16x32_bf16 v[0:3], v[190:193], v[222:225], v[0:3]
	v_mfma_f32_16x16x32_bf16 v[8:11], v[180:183], v[222:225], v[8:11]
	v_mfma_f32_16x16x32_bf16 v[8:11], v[176:179], v[218:221], v[8:11]
	s_barrier
	s_setprio 0
	s_add_i32 s75, s75, 2
	s_add_u32 s73, s73, 0x100
	s_addc_u32 s74, s74, 0
	s_add_u32 s46, s46, 0x100
	s_addc_u32 s47, s47, 0
	s_cmp_gt_u32 s75, 13
	s_cbranch_scc1 .LBB0_529

.Llast_4:
	v_add_u32_e32 v153, s66, v147
	ds_read_b128 v[160:163], v153
	v_xor_b32_e32 v253, 64, v153
	ds_read_b128 v[164:167], v253
	ds_read_b128 v[168:171], v153 offset:2048
	ds_read_b128 v[172:175], v253 offset:2048
	v_add_u32_e32 v153, s67, v147
	ds_read_b128 v[176:179], v153
	v_xor_b32_e32 v253, 64, v153
	ds_read_b128 v[180:183], v253
	ds_read_b128 v[186:189], v153 offset:2048
	ds_read_b128 v[190:193], v253 offset:2048
	s_add_u32 s50, s46, 0xfffc0080
	s_addc_u32 s51, s47, -1
	s_and_b64 s[48:49], s[48:49], exec
	s_cselect_b32 s51, s29, s51
	s_cselect_b32 s50, s70, s50
	s_cselect_b32 s49, s71, s74
	s_cselect_b32 s48, s72, s73
	v_lshl_add_u64 v[154:155], s[46:47], 0, v[138:139]
	s_add_i32 m0, s57, 0xc000
	ds_read_b128 v[194:197], v150
	v_xor_b32_e32 v253, 64, v150
	ds_read_b128 v[198:201], v253
	ds_read_b128 v[202:205], v150 offset:2048
	ds_read_b128 v[206:209], v253 offset:2048
	ds_read_b128 v[210:213], v150 offset:4096
	ds_read_b128 v[214:217], v253 offset:4096
	ds_read_b128 v[218:221], v150 offset:6144
	ds_read_b128 v[222:225], v253 offset:6144
	global_load_lds_dwordx4 v[154:155], off
	v_lshl_add_u64 v[154:155], s[46:47], 0, v[136:137]
	s_add_i32 m0, s57, 0xe000
	s_nop 0
	global_load_lds_dwordx4 v[154:155], off
	s_waitcnt vmcnt(8)
	s_waitcnt lgkmcnt(0)
	s_setprio 1
	s_barrier
	v_mfma_f32_16x16x32_bf16 v[124:127], v[160:163], v[194:197], v[124:127]
	v_mfma_f32_16x16x32_bf16 v[124:127], v[164:167], v[198:201], v[124:127]
	v_mfma_f32_16x16x32_bf16 v[116:119], v[172:175], v[198:201], v[116:119]
	v_mfma_f32_16x16x32_bf16 v[116:119], v[168:171], v[194:197], v[116:119]
	v_mfma_f32_16x16x32_bf16 v[100:103], v[168:171], v[202:205], v[100:103]
	v_mfma_f32_16x16x32_bf16 v[100:103], v[172:175], v[206:209], v[100:103]
	v_mfma_f32_16x16x32_bf16 v[108:111], v[164:167], v[206:209], v[108:111]
	v_mfma_f32_16x16x32_bf16 v[108:111], v[160:163], v[202:205], v[108:111]
	v_mfma_f32_16x16x32_bf16 v[92:95], v[160:163], v[210:213], v[92:95]
	v_mfma_f32_16x16x32_bf16 v[92:95], v[164:167], v[214:217], v[92:95]
	v_mfma_f32_16x16x32_bf16 v[84:87], v[172:175], v[214:217], v[84:87]
	v_mfma_f32_16x16x32_bf16 v[84:87], v[168:171], v[210:213], v[84:87]
	v_mfma_f32_16x16x32_bf16 v[68:71], v[168:171], v[218:221], v[68:71]
	v_mfma_f32_16x16x32_bf16 v[68:71], v[172:175], v[222:225], v[68:71]
	v_mfma_f32_16x16x32_bf16 v[76:79], v[164:167], v[222:225], v[76:79]
	v_mfma_f32_16x16x32_bf16 v[76:79], v[160:163], v[218:221], v[76:79]
	s_setprio 0
	s_setprio 1
	v_mfma_f32_16x16x32_bf16 v[120:123], v[176:179], v[194:197], v[120:123]
	v_mfma_f32_16x16x32_bf16 v[120:123], v[180:183], v[198:201], v[120:123]
	v_mfma_f32_16x16x32_bf16 v[112:115], v[190:193], v[198:201], v[112:115]
	v_mfma_f32_16x16x32_bf16 v[112:115], v[186:189], v[194:197], v[112:115]
	v_mfma_f32_16x16x32_bf16 v[96:99], v[186:189], v[202:205], v[96:99]
	v_mfma_f32_16x16x32_bf16 v[96:99], v[190:193], v[206:209], v[96:99]
	v_mfma_f32_16x16x32_bf16 v[104:107], v[180:183], v[206:209], v[104:107]
	v_mfma_f32_16x16x32_bf16 v[104:107], v[176:179], v[202:205], v[104:107]
	v_mfma_f32_16x16x32_bf16 v[88:91], v[176:179], v[210:213], v[88:91]
	v_mfma_f32_16x16x32_bf16 v[88:91], v[180:183], v[214:217], v[88:91]
	v_mfma_f32_16x16x32_bf16 v[80:83], v[190:193], v[214:217], v[80:83]
	v_mfma_f32_16x16x32_bf16 v[80:83], v[186:189], v[210:213], v[80:83]
	v_mfma_f32_16x16x32_bf16 v[64:67], v[186:189], v[218:221], v[64:67]
	v_mfma_f32_16x16x32_bf16 v[64:67], v[190:193], v[222:225], v[64:67]
	v_mfma_f32_16x16x32_bf16 v[72:75], v[180:183], v[222:225], v[72:75]
	v_mfma_f32_16x16x32_bf16 v[72:75], v[176:179], v[218:221], v[72:75]
	s_barrier
	s_setprio 0
	s_add_i32 s76, s66, s54
	v_lshl_add_u64 v[154:155], s[48:49], 0, v[132:133]
	s_mov_b32 m0, s76
	ds_read_b128 v[194:197], v150 offset:16384
	v_xor_b32_e32 v253, 64, v150
	ds_read_b128 v[198:201], v253 offset:16384
	ds_read_b128 v[202:205], v150 offset:18432
	ds_read_b128 v[206:209], v253 offset:18432
	ds_read_b128 v[210:213], v150 offset:20480
	ds_read_b128 v[214:217], v253 offset:20480
	ds_read_b128 v[218:221], v150 offset:22528
	ds_read_b128 v[222:225], v253 offset:22528
	global_load_lds_dwordx4 v[154:155], off
	s_add_i32 m0, s76, 0x2000
	s_add_u32 s76, s48, 0x40000
	v_lshl_add_u64 v[226:227], s[48:49], 0, v[128:129]
	s_addc_u32 s77, s49, 0
	s_add_i32 s78, s67, s54
	global_load_lds_dwordx4 v[226:227], off
	v_lshl_add_u64 v[228:229], s[76:77], 0, v[132:133]
	s_mov_b32 m0, s78
	v_lshl_add_u64 v[230:231], s[50:51], 0, v[130:131]
	global_load_lds_dwordx4 v[228:229], off
	v_lshl_add_u64 v[228:229], s[76:77], 0, v[128:129]
	s_add_i32 m0, s78, 0x2000
	s_nop 0
	global_load_lds_dwordx4 v[228:229], off
	v_lshl_add_u64 v[228:229], s[50:51], 0, v[134:135]
	s_mov_b32 m0, s57
	s_nop 0
	global_load_lds_dwordx4 v[228:229], off
	s_mov_b32 m0, s58
	s_nop 0
	global_load_lds_dwordx4 v[230:231], off
	s_waitcnt vmcnt(8)
	s_waitcnt lgkmcnt(0)
	s_setprio 1
	s_barrier
	v_mfma_f32_16x16x32_bf16 v[60:63], v[160:163], v[194:197], v[60:63]
	v_mfma_f32_16x16x32_bf16 v[60:63], v[164:167], v[198:201], v[60:63]
	v_mfma_f32_16x16x32_bf16 v[52:55], v[172:175], v[198:201], v[52:55]
	v_mfma_f32_16x16x32_bf16 v[52:55], v[168:171], v[194:197], v[52:55]
	v_mfma_f32_16x16x32_bf16 v[36:39], v[168:171], v[202:205], v[36:39]
	v_mfma_f32_16x16x32_bf16 v[36:39], v[172:175], v[206:209], v[36:39]
	v_mfma_f32_16x16x32_bf16 v[44:47], v[164:167], v[206:209], v[44:47]
	v_mfma_f32_16x16x32_bf16 v[44:47], v[160:163], v[202:205], v[44:47]
	v_mfma_f32_16x16x32_bf16 v[28:31], v[160:163], v[210:213], v[28:31]
	v_mfma_f32_16x16x32_bf16 v[28:31], v[164:167], v[214:217], v[28:31]
	v_mfma_f32_16x16x32_bf16 v[20:23], v[172:175], v[214:217], v[20:23]
	v_mfma_f32_16x16x32_bf16 v[20:23], v[168:171], v[210:213], v[20:23]
	v_mfma_f32_16x16x32_bf16 v[4:7], v[168:171], v[218:221], v[4:7]
	v_mfma_f32_16x16x32_bf16 v[4:7], v[172:175], v[222:225], v[4:7]
	v_mfma_f32_16x16x32_bf16 v[12:15], v[164:167], v[222:225], v[12:15]
	v_mfma_f32_16x16x32_bf16 v[12:15], v[160:163], v[218:221], v[12:15]
	s_setprio 0
	s_setprio 1
	v_mfma_f32_16x16x32_bf16 v[56:59], v[176:179], v[194:197], v[56:59]
	v_mfma_f32_16x16x32_bf16 v[56:59], v[180:183], v[198:201], v[56:59]
	v_mfma_f32_16x16x32_bf16 v[48:51], v[190:193], v[198:201], v[48:51]
	v_mfma_f32_16x16x32_bf16 v[48:51], v[186:189], v[194:197], v[48:51]
	v_mfma_f32_16x16x32_bf16 v[32:35], v[186:189], v[202:205], v[32:35]
	v_mfma_f32_16x16x32_bf16 v[32:35], v[190:193], v[206:209], v[32:35]
	v_mfma_f32_16x16x32_bf16 v[40:43], v[180:183], v[206:209], v[40:43]
	v_mfma_f32_16x16x32_bf16 v[40:43], v[176:179], v[202:205], v[40:43]
	v_mfma_f32_16x16x32_bf16 v[24:27], v[176:179], v[210:213], v[24:27]
	v_mfma_f32_16x16x32_bf16 v[24:27], v[180:183], v[214:217], v[24:27]
	v_mfma_f32_16x16x32_bf16 v[16:19], v[190:193], v[214:217], v[16:19]
	v_mfma_f32_16x16x32_bf16 v[16:19], v[186:189], v[210:213], v[16:19]
	v_mfma_f32_16x16x32_bf16 v[0:3], v[186:189], v[218:221], v[0:3]
	v_mfma_f32_16x16x32_bf16 v[0:3], v[190:193], v[222:225], v[0:3]
	v_mfma_f32_16x16x32_bf16 v[8:11], v[180:183], v[222:225], v[8:11]
	v_mfma_f32_16x16x32_bf16 v[8:11], v[176:179], v[218:221], v[8:11]
	s_barrier
	s_setprio 0
	s_add_i32 s76, 0, 0x18000
	v_add_u32_e32 v153, s76, v147
	s_add_i32 s77, 0, 0x1c000
	ds_read_b128 v[160:163], v153
	v_xor_b32_e32 v253, 64, v153
	ds_read_b128 v[164:167], v253
	ds_read_b128 v[168:171], v153 offset:2048
	ds_read_b128 v[172:175], v253 offset:2048
	v_add_u32_e32 v153, s77, v147
	ds_read_b128 v[176:179], v153
	v_xor_b32_e32 v253, 64, v153
	ds_read_b128 v[180:183], v253
	ds_read_b128 v[186:189], v153 offset:2048
	ds_read_b128 v[190:193], v253 offset:2048
	s_add_u32 s50, s50, 0x40000
	s_addc_u32 s51, s51, 0
	s_mov_b32 m0, s59
	v_lshl_add_u64 v[232:233], s[50:51], 0, v[134:135]
	ds_read_b128 v[194:197], v150 offset:32768
	v_xor_b32_e32 v253, 64, v150
	ds_read_b128 v[198:201], v253 offset:32768
	ds_read_b128 v[202:205], v150 offset:34816
	ds_read_b128 v[206:209], v253 offset:34816
	ds_read_b128 v[210:213], v150 offset:36864
	ds_read_b128 v[214:217], v253 offset:36864
	ds_read_b128 v[218:221], v150 offset:38912
	ds_read_b128 v[222:225], v253 offset:38912
	global_load_lds_dwordx4 v[232:233], off
	v_lshl_add_u64 v[232:233], s[50:51], 0, v[130:131]
	s_mov_b32 m0, s60
	s_nop 0
	global_load_lds_dwordx4 v[232:233], off
	s_waitcnt vmcnt(8)
	s_waitcnt lgkmcnt(0)
	s_setprio 1
	s_barrier
	v_mfma_f32_16x16x32_bf16 v[124:127], v[160:163], v[194:197], v[124:127]
	v_mfma_f32_16x16x32_bf16 v[124:127], v[164:167], v[198:201], v[124:127]
	v_mfma_f32_16x16x32_bf16 v[116:119], v[172:175], v[198:201], v[116:119]
	v_mfma_f32_16x16x32_bf16 v[116:119], v[168:171], v[194:197], v[116:119]
	v_mfma_f32_16x16x32_bf16 v[100:103], v[168:171], v[202:205], v[100:103]
	v_mfma_f32_16x16x32_bf16 v[100:103], v[172:175], v[206:209], v[100:103]
	v_mfma_f32_16x16x32_bf16 v[108:111], v[164:167], v[206:209], v[108:111]
	v_mfma_f32_16x16x32_bf16 v[108:111], v[160:163], v[202:205], v[108:111]
	v_mfma_f32_16x16x32_bf16 v[92:95], v[160:163], v[210:213], v[92:95]
	v_mfma_f32_16x16x32_bf16 v[92:95], v[164:167], v[214:217], v[92:95]
	v_mfma_f32_16x16x32_bf16 v[84:87], v[172:175], v[214:217], v[84:87]
	v_mfma_f32_16x16x32_bf16 v[84:87], v[168:171], v[210:213], v[84:87]
	v_mfma_f32_16x16x32_bf16 v[68:71], v[168:171], v[218:221], v[68:71]
	v_mfma_f32_16x16x32_bf16 v[68:71], v[172:175], v[222:225], v[68:71]
	v_mfma_f32_16x16x32_bf16 v[76:79], v[164:167], v[222:225], v[76:79]
	v_mfma_f32_16x16x32_bf16 v[76:79], v[160:163], v[218:221], v[76:79]
	s_setprio 0
	s_setprio 1
	v_mfma_f32_16x16x32_bf16 v[120:123], v[176:179], v[194:197], v[120:123]
	v_mfma_f32_16x16x32_bf16 v[120:123], v[180:183], v[198:201], v[120:123]
	v_mfma_f32_16x16x32_bf16 v[112:115], v[190:193], v[198:201], v[112:115]
	v_mfma_f32_16x16x32_bf16 v[112:115], v[186:189], v[194:197], v[112:115]
	v_mfma_f32_16x16x32_bf16 v[96:99], v[186:189], v[202:205], v[96:99]
	v_mfma_f32_16x16x32_bf16 v[96:99], v[190:193], v[206:209], v[96:99]
	v_mfma_f32_16x16x32_bf16 v[104:107], v[180:183], v[206:209], v[104:107]
	v_mfma_f32_16x16x32_bf16 v[104:107], v[176:179], v[202:205], v[104:107]
	v_mfma_f32_16x16x32_bf16 v[88:91], v[176:179], v[210:213], v[88:91]
	v_mfma_f32_16x16x32_bf16 v[88:91], v[180:183], v[214:217], v[88:91]
	v_mfma_f32_16x16x32_bf16 v[80:83], v[190:193], v[214:217], v[80:83]
	v_mfma_f32_16x16x32_bf16 v[80:83], v[186:189], v[210:213], v[80:83]
	v_mfma_f32_16x16x32_bf16 v[64:67], v[186:189], v[218:221], v[64:67]
	v_mfma_f32_16x16x32_bf16 v[64:67], v[190:193], v[222:225], v[64:67]
	v_mfma_f32_16x16x32_bf16 v[72:75], v[180:183], v[222:225], v[72:75]
	v_mfma_f32_16x16x32_bf16 v[72:75], v[176:179], v[218:221], v[72:75]
	s_barrier
	s_setprio 0
	v_add_u32_e32 v234, 0x21000, v151
	ds_read_b128 v[236:239], v234
	ds_read_b128 v[240:243], v234 offset:256
	ds_read_b128 v[244:247], v234 offset:512
	ds_read_b128 v[248:251], v234 offset:768
	v_add_u32_e32 v235, s27, v146
	v_mul_u32_u24_e32 v235, 0x1600, v235
	v_lshl_or_b32 v234, s69, 7, v149
	v_lshl_add_u32 v235, v234, 1, v235
	s_add_i32 s50, s76, s54
	v_lshl_add_u64 v[154:155], v[154:155], 0, s[20:21]
	s_mov_b32 m0, s50
	ds_read_b128 v[194:197], v150 offset:49152
	v_xor_b32_e32 v253, 64, v150
	ds_read_b128 v[198:201], v253 offset:49152
	ds_read_b128 v[202:205], v150 offset:51200
	ds_read_b128 v[206:209], v253 offset:51200
	ds_read_b128 v[210:213], v150 offset:53248
	ds_read_b128 v[214:217], v253 offset:53248
	ds_read_b128 v[218:221], v150 offset:55296
	ds_read_b128 v[222:225], v253 offset:55296
	global_load_lds_dwordx4 v[154:155], off
	s_add_i32 m0, s50, 0x2000
	s_add_u32 s48, s48, 0x40080
	v_lshl_add_u64 v[154:155], v[226:227], 0, s[20:21]
	s_addc_u32 s49, s49, 0
	s_add_i32 s50, s77, s54
	global_load_lds_dwordx4 v[154:155], off
	v_lshl_add_u64 v[154:155], s[48:49], 0, v[132:133]
	s_mov_b32 m0, s50
	s_nop 0
	global_load_lds_dwordx4 v[154:155], off
	v_lshl_add_u64 v[154:155], s[48:49], 0, v[128:129]
	s_add_i32 m0, s50, 0x2000
	s_nop 0
	global_load_lds_dwordx4 v[154:155], off
	v_lshl_add_u64 v[154:155], v[228:229], 0, s[20:21]
	s_mov_b32 m0, s62
	s_nop 0
	global_load_lds_dwordx4 v[154:155], off
	v_lshl_add_u64 v[154:155], v[230:231], 0, s[20:21]
	s_mov_b32 m0, s63
	s_nop 0
	global_load_lds_dwordx4 v[154:155], off
	s_waitcnt lgkmcnt(8)
	v_add_f32_e32 v236, v236, v237
	v_add_f32_e32 v238, v238, v239
	v_add_f32_e32 v240, v240, v241
	v_add_f32_e32 v242, v242, v243
	v_add_f32_e32 v244, v244, v245
	v_add_f32_e32 v246, v246, v247
	v_add_f32_e32 v248, v248, v249
	v_add_f32_e32 v250, v250, v251
	v_add_f32_e32 v236, v236, v238
	v_add_f32_e32 v240, v240, v242
	v_add_f32_e32 v244, v244, v246
	v_add_f32_e32 v248, v248, v250
	v_fmamk_f32 v236, v236, 0x3a800000, v152
	v_fmamk_f32 v240, v240, 0x3a800000, v152
	v_fmamk_f32 v244, v244, 0x3a800000, v152
	v_fmamk_f32 v248, v248, 0x3a800000, v152
	v_rsq_f32_e32 v236, v236
	v_rsq_f32_e32 v240, v240
	v_rsq_f32_e32 v244, v244
	v_rsq_f32_e32 v248, v248
	v_mul_f32_e32 v252, 0xbfb8aa3b, v236
	v_mul_f32_e32 v254, v236, v236
	v_rcp_f32_e32 v254, v254
	v_pk_mul_f32 v[120:121], v[124:125], v[120:121]
	v_pk_mul_f32 v[122:123], v[126:127], v[122:123]
	v_pk_mul_f32 v[112:113], v[116:117], v[112:113]
	v_pk_mul_f32 v[114:115], v[118:119], v[114:115]
	v_pk_mul_f32 v[124:125], v[124:125], v[252:253] op_sel_hi:[1,0]
	v_pk_mul_f32 v[126:127], v[126:127], v[252:253] op_sel_hi:[1,0]
	v_pk_mul_f32 v[116:117], v[116:117], v[252:253] op_sel_hi:[1,0]
	v_pk_mul_f32 v[118:119], v[118:119], v[252:253] op_sel_hi:[1,0]
	v_exp_f32_e32 v124, v124
	v_exp_f32_e32 v125, v125
	v_exp_f32_e32 v126, v126
	v_exp_f32_e32 v127, v127
	v_exp_f32_e32 v116, v116
	v_exp_f32_e32 v117, v117
	v_exp_f32_e32 v118, v118
	v_exp_f32_e32 v119, v119
	v_pk_fma_f32 v[124:125], v[124:125], v[254:255], v[254:255] op_sel_hi:[1,0,0]
	v_pk_fma_f32 v[126:127], v[126:127], v[254:255], v[254:255] op_sel_hi:[1,0,0]
	v_pk_fma_f32 v[116:117], v[116:117], v[254:255], v[254:255] op_sel_hi:[1,0,0]
	v_pk_fma_f32 v[118:119], v[118:119], v[254:255], v[254:255] op_sel_hi:[1,0,0]
	v_rcp_f32_e32 v124, v124
	v_rcp_f32_e32 v125, v125
	v_rcp_f32_e32 v126, v126
	v_rcp_f32_e32 v127, v127
	v_rcp_f32_e32 v116, v116
	v_rcp_f32_e32 v117, v117
	v_rcp_f32_e32 v118, v118
	v_rcp_f32_e32 v119, v119
	v_pk_mul_f32 v[120:121], v[120:121], v[124:125]
	v_pk_mul_f32 v[122:123], v[122:123], v[126:127]
	v_pk_mul_f32 v[112:113], v[112:113], v[116:117]
	v_pk_mul_f32 v[114:115], v[114:115], v[118:119]
	v_cvt_pk_bf16_f32 v120, v120, v121
	v_cvt_pk_bf16_f32 v121, v122, v123
	v_cvt_pk_bf16_f32 v122, v112, v113
	v_cvt_pk_bf16_f32 v123, v114, v115
	global_store_dwordx4 v235, v[120:123], s[14:15]
	v_add_u32_e32 v234, 0x16000, v235
	v_mul_f32_e32 v252, 0xbfb8aa3b, v240
	v_mul_f32_e32 v254, v240, v240
	v_rcp_f32_e32 v254, v254
	v_pk_mul_f32 v[104:105], v[108:109], v[104:105]
	v_pk_mul_f32 v[106:107], v[110:111], v[106:107]
	v_pk_mul_f32 v[96:97], v[100:101], v[96:97]
	v_pk_mul_f32 v[98:99], v[102:103], v[98:99]
	v_pk_mul_f32 v[108:109], v[108:109], v[252:253] op_sel_hi:[1,0]
	v_pk_mul_f32 v[110:111], v[110:111], v[252:253] op_sel_hi:[1,0]
	v_pk_mul_f32 v[100:101], v[100:101], v[252:253] op_sel_hi:[1,0]
	v_pk_mul_f32 v[102:103], v[102:103], v[252:253] op_sel_hi:[1,0]
	v_exp_f32_e32 v108, v108
	v_exp_f32_e32 v109, v109
	v_exp_f32_e32 v110, v110
	v_exp_f32_e32 v111, v111
	v_exp_f32_e32 v100, v100
	v_exp_f32_e32 v101, v101
	v_exp_f32_e32 v102, v102
	v_exp_f32_e32 v103, v103
	v_pk_fma_f32 v[108:109], v[108:109], v[254:255], v[254:255] op_sel_hi:[1,0,0]
	v_pk_fma_f32 v[110:111], v[110:111], v[254:255], v[254:255] op_sel_hi:[1,0,0]
	v_pk_fma_f32 v[100:101], v[100:101], v[254:255], v[254:255] op_sel_hi:[1,0,0]
	v_pk_fma_f32 v[102:103], v[102:103], v[254:255], v[254:255] op_sel_hi:[1,0,0]
	v_rcp_f32_e32 v108, v108
	v_rcp_f32_e32 v109, v109
	v_rcp_f32_e32 v110, v110
	v_rcp_f32_e32 v111, v111
	v_rcp_f32_e32 v100, v100
	v_rcp_f32_e32 v101, v101
	v_rcp_f32_e32 v102, v102
	v_rcp_f32_e32 v103, v103
	v_pk_mul_f32 v[104:105], v[104:105], v[108:109]
	v_pk_mul_f32 v[106:107], v[106:107], v[110:111]
	v_pk_mul_f32 v[96:97], v[96:97], v[100:101]
	v_pk_mul_f32 v[98:99], v[98:99], v[102:103]
	v_cvt_pk_bf16_f32 v104, v104, v105
	v_cvt_pk_bf16_f32 v105, v106, v107
	v_cvt_pk_bf16_f32 v106, v96, v97
	v_cvt_pk_bf16_f32 v107, v98, v99
	global_store_dwordx4 v234, v[104:107], s[14:15]
	v_add_u32_e32 v235, 0x16000, v234
	v_mul_f32_e32 v252, 0xbfb8aa3b, v244
	v_mul_f32_e32 v254, v244, v244
	v_rcp_f32_e32 v254, v254
	v_pk_mul_f32 v[88:89], v[92:93], v[88:89]
	v_pk_mul_f32 v[90:91], v[94:95], v[90:91]
	v_pk_mul_f32 v[80:81], v[84:85], v[80:81]
	v_pk_mul_f32 v[82:83], v[86:87], v[82:83]
	v_pk_mul_f32 v[92:93], v[92:93], v[252:253] op_sel_hi:[1,0]
	v_pk_mul_f32 v[94:95], v[94:95], v[252:253] op_sel_hi:[1,0]
	v_pk_mul_f32 v[84:85], v[84:85], v[252:253] op_sel_hi:[1,0]
	v_pk_mul_f32 v[86:87], v[86:87], v[252:253] op_sel_hi:[1,0]
	v_exp_f32_e32 v92, v92
	v_exp_f32_e32 v93, v93
	v_exp_f32_e32 v94, v94
	v_exp_f32_e32 v95, v95
	v_exp_f32_e32 v84, v84
	v_exp_f32_e32 v85, v85
	v_exp_f32_e32 v86, v86
	v_exp_f32_e32 v87, v87
	v_pk_fma_f32 v[92:93], v[92:93], v[254:255], v[254:255] op_sel_hi:[1,0,0]
	v_pk_fma_f32 v[94:95], v[94:95], v[254:255], v[254:255] op_sel_hi:[1,0,0]
	v_pk_fma_f32 v[84:85], v[84:85], v[254:255], v[254:255] op_sel_hi:[1,0,0]
	v_pk_fma_f32 v[86:87], v[86:87], v[254:255], v[254:255] op_sel_hi:[1,0,0]
	v_rcp_f32_e32 v92, v92
	v_rcp_f32_e32 v93, v93
	v_rcp_f32_e32 v94, v94
	v_rcp_f32_e32 v95, v95
	v_rcp_f32_e32 v84, v84
	v_rcp_f32_e32 v85, v85
	v_rcp_f32_e32 v86, v86
	v_rcp_f32_e32 v87, v87
	v_pk_mul_f32 v[88:89], v[88:89], v[92:93]
	v_pk_mul_f32 v[90:91], v[90:91], v[94:95]
	v_pk_mul_f32 v[80:81], v[80:81], v[84:85]
	v_pk_mul_f32 v[82:83], v[82:83], v[86:87]
	v_cvt_pk_bf16_f32 v88, v88, v89
	v_cvt_pk_bf16_f32 v89, v90, v91
	v_cvt_pk_bf16_f32 v90, v80, v81
	v_cvt_pk_bf16_f32 v91, v82, v83
	global_store_dwordx4 v235, v[88:91], s[14:15]
	v_add_u32_e32 v234, 0x16000, v235
	v_mul_f32_e32 v252, 0xbfb8aa3b, v248
	v_mul_f32_e32 v254, v248, v248
	v_rcp_f32_e32 v254, v254
	v_pk_mul_f32 v[72:73], v[76:77], v[72:73]
	v_pk_mul_f32 v[74:75], v[78:79], v[74:75]
	v_pk_mul_f32 v[64:65], v[68:69], v[64:65]
	v_pk_mul_f32 v[66:67], v[70:71], v[66:67]
	v_pk_mul_f32 v[76:77], v[76:77], v[252:253] op_sel_hi:[1,0]
	v_pk_mul_f32 v[78:79], v[78:79], v[252:253] op_sel_hi:[1,0]
	v_pk_mul_f32 v[68:69], v[68:69], v[252:253] op_sel_hi:[1,0]
	v_pk_mul_f32 v[70:71], v[70:71], v[252:253] op_sel_hi:[1,0]
	v_exp_f32_e32 v76, v76
	v_exp_f32_e32 v77, v77
	v_exp_f32_e32 v78, v78
	v_exp_f32_e32 v79, v79
	v_exp_f32_e32 v68, v68
	v_exp_f32_e32 v69, v69
	v_exp_f32_e32 v70, v70
	v_exp_f32_e32 v71, v71
	v_pk_fma_f32 v[76:77], v[76:77], v[254:255], v[254:255] op_sel_hi:[1,0,0]
	v_pk_fma_f32 v[78:79], v[78:79], v[254:255], v[254:255] op_sel_hi:[1,0,0]
	v_pk_fma_f32 v[68:69], v[68:69], v[254:255], v[254:255] op_sel_hi:[1,0,0]
	v_pk_fma_f32 v[70:71], v[70:71], v[254:255], v[254:255] op_sel_hi:[1,0,0]
	v_rcp_f32_e32 v76, v76
	v_rcp_f32_e32 v77, v77
	v_rcp_f32_e32 v78, v78
	v_rcp_f32_e32 v79, v79
	v_rcp_f32_e32 v68, v68
	v_rcp_f32_e32 v69, v69
	v_rcp_f32_e32 v70, v70
	v_rcp_f32_e32 v71, v71
	v_pk_mul_f32 v[72:73], v[72:73], v[76:77]
	v_pk_mul_f32 v[74:75], v[74:75], v[78:79]
	v_pk_mul_f32 v[64:65], v[64:65], v[68:69]
	v_pk_mul_f32 v[66:67], v[66:67], v[70:71]
	v_cvt_pk_bf16_f32 v72, v72, v73
	v_cvt_pk_bf16_f32 v73, v74, v75
	v_cvt_pk_bf16_f32 v74, v64, v65
	v_cvt_pk_bf16_f32 v75, v66, v67
	global_store_dwordx4 v234, v[72:75], s[14:15]
	s_waitcnt vmcnt(12)
	s_waitcnt lgkmcnt(0)
	s_setprio 1
	s_barrier
	v_mfma_f32_16x16x32_bf16 v[60:63], v[160:163], v[194:197], v[60:63]
	v_mfma_f32_16x16x32_bf16 v[60:63], v[164:167], v[198:201], v[60:63]
	v_mfma_f32_16x16x32_bf16 v[52:55], v[172:175], v[198:201], v[52:55]
	v_mfma_f32_16x16x32_bf16 v[52:55], v[168:171], v[194:197], v[52:55]
	v_mfma_f32_16x16x32_bf16 v[36:39], v[168:171], v[202:205], v[36:39]
	v_mfma_f32_16x16x32_bf16 v[36:39], v[172:175], v[206:209], v[36:39]
	v_mfma_f32_16x16x32_bf16 v[44:47], v[164:167], v[206:209], v[44:47]
	v_mfma_f32_16x16x32_bf16 v[44:47], v[160:163], v[202:205], v[44:47]
	v_mfma_f32_16x16x32_bf16 v[28:31], v[160:163], v[210:213], v[28:31]
	v_mfma_f32_16x16x32_bf16 v[28:31], v[164:167], v[214:217], v[28:31]
	v_mfma_f32_16x16x32_bf16 v[20:23], v[172:175], v[214:217], v[20:23]
	v_mfma_f32_16x16x32_bf16 v[20:23], v[168:171], v[210:213], v[20:23]
	v_mfma_f32_16x16x32_bf16 v[4:7], v[168:171], v[218:221], v[4:7]
	v_mfma_f32_16x16x32_bf16 v[4:7], v[172:175], v[222:225], v[4:7]
	v_mfma_f32_16x16x32_bf16 v[12:15], v[164:167], v[222:225], v[12:15]
	v_mfma_f32_16x16x32_bf16 v[12:15], v[160:163], v[218:221], v[12:15]
	s_setprio 0
	s_setprio 1
	v_mfma_f32_16x16x32_bf16 v[56:59], v[176:179], v[194:197], v[56:59]
	v_mfma_f32_16x16x32_bf16 v[56:59], v[180:183], v[198:201], v[56:59]
	v_mfma_f32_16x16x32_bf16 v[48:51], v[190:193], v[198:201], v[48:51]
	v_mfma_f32_16x16x32_bf16 v[48:51], v[186:189], v[194:197], v[48:51]
	v_mfma_f32_16x16x32_bf16 v[32:35], v[186:189], v[202:205], v[32:35]
	v_mfma_f32_16x16x32_bf16 v[32:35], v[190:193], v[206:209], v[32:35]
	v_mfma_f32_16x16x32_bf16 v[40:43], v[180:183], v[206:209], v[40:43]
	v_mfma_f32_16x16x32_bf16 v[40:43], v[176:179], v[202:205], v[40:43]
	v_mfma_f32_16x16x32_bf16 v[24:27], v[176:179], v[210:213], v[24:27]
	v_mfma_f32_16x16x32_bf16 v[24:27], v[180:183], v[214:217], v[24:27]
	v_mfma_f32_16x16x32_bf16 v[16:19], v[190:193], v[214:217], v[16:19]
	v_mfma_f32_16x16x32_bf16 v[16:19], v[186:189], v[210:213], v[16:19]
	v_mfma_f32_16x16x32_bf16 v[0:3], v[186:189], v[218:221], v[0:3]
	v_mfma_f32_16x16x32_bf16 v[0:3], v[190:193], v[222:225], v[0:3]
	v_mfma_f32_16x16x32_bf16 v[8:11], v[180:183], v[222:225], v[8:11]
	v_mfma_f32_16x16x32_bf16 v[8:11], v[176:179], v[218:221], v[8:11]
	s_barrier
	s_setprio 0
	s_add_i32 s75, s75, 2
	s_add_u32 s73, s73, 0x100
	s_addc_u32 s74, s74, 0
	s_add_u32 s46, s46, 0x100
	s_addc_u32 s47, s47, 0

.LBB0_609:
	s_add_u32 s79, s56, 0x100
	s_addc_u32 s80, s57, 0
	s_mov_b32 s81, -2
	s_waitcnt lgkmcnt(0)
	s_cmp_eq_u32 s70, 1
	s_cbranch_scc1 .Lfa_5
	ds_read_b128 v[128:131], v189
	v_xor_b32_e32 v253, 64, v189
	ds_read_b128 v[132:135], v253
	ds_read_b128 v[136:139], v189 offset:2048
	ds_read_b128 v[140:143], v253 offset:2048
	ds_read_b128 v[144:147], v190
	v_xor_b32_e32 v253, 64, v190
	ds_read_b128 v[148:151], v253
	ds_read_b128 v[172:175], v190 offset:2048
	ds_read_b128 v[176:179], v253 offset:2048
	s_add_u32 s56, s54, 0x100
	s_addc_u32 s57, s55, 0
	s_cmp_eq_u32 s81, 40
	s_cselect_b32 s61, s17, s57
	s_cselect_b32 s60, s16, s56
	s_cselect_b32 s59, s53, s80
	s_cselect_b32 s58, s52, s79
	v_lshl_add_u64 v[222:223], s[54:55], 0, v[166:167]
	s_add_i32 m0, s66, 0xc000
	ds_read_b128 v[180:183], v191
	v_xor_b32_e32 v253, 64, v191
	ds_read_b128 v[194:197], v253
	ds_read_b128 v[198:201], v191 offset:2048
	ds_read_b128 v[202:205], v253 offset:2048
	ds_read_b128 v[206:209], v191 offset:4096
	ds_read_b128 v[210:213], v253 offset:4096
	ds_read_b128 v[214:217], v191 offset:6144
	ds_read_b128 v[218:221], v253 offset:6144
	global_load_lds_dwordx4 v[222:223], off
	v_lshl_add_u64 v[222:223], s[54:55], 0, v[164:165]
	s_add_i32 m0, s66, 0xe000
	s_nop 0
	global_load_lds_dwordx4 v[222:223], off
	s_waitcnt vmcnt(24)
	s_waitcnt lgkmcnt(0)
	s_setprio 1
	s_barrier
	v_mfma_f32_16x16x32_bf16 v[124:127], v[128:131], v[180:183], 0
	v_mfma_f32_16x16x32_bf16 v[120:123], v[136:139], v[180:183], 0
	v_mfma_f32_16x16x32_bf16 v[108:111], v[128:131], v[198:201], 0
	v_mfma_f32_16x16x32_bf16 v[104:107], v[136:139], v[198:201], 0
	v_mfma_f32_16x16x32_bf16 v[92:95], v[128:131], v[206:209], 0
	v_mfma_f32_16x16x32_bf16 v[88:91], v[136:139], v[206:209], 0
	v_mfma_f32_16x16x32_bf16 v[76:79], v[128:131], v[214:217], 0
	v_mfma_f32_16x16x32_bf16 v[72:75], v[136:139], v[214:217], 0
	v_mfma_f32_16x16x32_bf16 v[124:127], v[132:135], v[194:197], v[124:127]
	v_mfma_f32_16x16x32_bf16 v[120:123], v[140:143], v[194:197], v[120:123]
	v_mfma_f32_16x16x32_bf16 v[108:111], v[132:135], v[202:205], v[108:111]
	v_mfma_f32_16x16x32_bf16 v[104:107], v[140:143], v[202:205], v[104:107]
	v_mfma_f32_16x16x32_bf16 v[92:95], v[132:135], v[210:213], v[92:95]
	v_mfma_f32_16x16x32_bf16 v[88:91], v[140:143], v[210:213], v[88:91]
	v_mfma_f32_16x16x32_bf16 v[76:79], v[132:135], v[218:221], v[76:79]
	v_mfma_f32_16x16x32_bf16 v[72:75], v[140:143], v[218:221], v[72:75]
	s_setprio 0
	s_setprio 1
	v_mfma_f32_16x16x32_bf16 v[116:119], v[144:147], v[180:183], 0
	v_mfma_f32_16x16x32_bf16 v[112:115], v[172:175], v[180:183], 0
	v_mfma_f32_16x16x32_bf16 v[100:103], v[144:147], v[198:201], 0
	v_mfma_f32_16x16x32_bf16 v[96:99], v[172:175], v[198:201], 0
	v_mfma_f32_16x16x32_bf16 v[84:87], v[144:147], v[206:209], 0
	v_mfma_f32_16x16x32_bf16 v[80:83], v[172:175], v[206:209], 0
	v_mfma_f32_16x16x32_bf16 v[68:71], v[144:147], v[214:217], 0
	v_mfma_f32_16x16x32_bf16 v[64:67], v[172:175], v[214:217], 0
	v_mfma_f32_16x16x32_bf16 v[116:119], v[148:151], v[194:197], v[116:119]
	v_mfma_f32_16x16x32_bf16 v[112:115], v[176:179], v[194:197], v[112:115]
	v_mfma_f32_16x16x32_bf16 v[100:103], v[148:151], v[202:205], v[100:103]
	v_mfma_f32_16x16x32_bf16 v[96:99], v[176:179], v[202:205], v[96:99]
	v_mfma_f32_16x16x32_bf16 v[84:87], v[148:151], v[210:213], v[84:87]
	v_mfma_f32_16x16x32_bf16 v[80:83], v[176:179], v[210:213], v[80:83]
	v_mfma_f32_16x16x32_bf16 v[68:71], v[148:151], v[218:221], v[68:71]
	v_mfma_f32_16x16x32_bf16 v[64:67], v[176:179], v[218:221], v[64:67]
	s_barrier
	s_setprio 0
	s_add_i32 s54, s75, s65
	v_lshl_add_u64 v[222:223], s[58:59], 0, v[154:155]
	s_mov_b32 m0, s54
	ds_read_b128 v[180:183], v191 offset:16384
	v_xor_b32_e32 v253, 64, v191
	ds_read_b128 v[194:197], v253 offset:16384
	ds_read_b128 v[198:201], v191 offset:18432
	ds_read_b128 v[202:205], v253 offset:18432
	ds_read_b128 v[206:209], v191 offset:20480
	ds_read_b128 v[210:213], v253 offset:20480
	ds_read_b128 v[214:217], v191 offset:22528
	ds_read_b128 v[218:221], v253 offset:22528
	global_load_lds_dwordx4 v[222:223], off
	s_add_i32 m0, s54, 0x2000
	s_add_u32 s54, s58, 0xb0000
	v_lshl_add_u64 v[224:225], s[58:59], 0, v[162:163]
	s_addc_u32 s55, s59, 0
	s_add_i32 s82, s76, s65
	global_load_lds_dwordx4 v[224:225], off
	v_lshl_add_u64 v[226:227], s[54:55], 0, v[154:155]
	s_mov_b32 m0, s82
	v_lshl_add_u64 v[228:229], s[60:61], 0, v[160:161]
	global_load_lds_dwordx4 v[226:227], off
	v_lshl_add_u64 v[226:227], s[54:55], 0, v[162:163]
	s_add_i32 m0, s82, 0x2000
	s_nop 0
	global_load_lds_dwordx4 v[226:227], off
	v_lshl_add_u64 v[226:227], s[60:61], 0, v[152:153]
	s_mov_b32 m0, s66
	s_nop 0
	global_load_lds_dwordx4 v[226:227], off
	s_mov_b32 m0, s67
	s_nop 0
	global_load_lds_dwordx4 v[228:229], off
	s_waitcnt vmcnt(24)
	s_waitcnt lgkmcnt(0)
	s_setprio 1
	s_barrier
	v_mfma_f32_16x16x32_bf16 v[60:63], v[128:131], v[180:183], 0
	v_mfma_f32_16x16x32_bf16 v[56:59], v[136:139], v[180:183], 0
	v_mfma_f32_16x16x32_bf16 v[44:47], v[128:131], v[198:201], 0
	v_mfma_f32_16x16x32_bf16 v[40:43], v[136:139], v[198:201], 0
	v_mfma_f32_16x16x32_bf16 v[28:31], v[128:131], v[206:209], 0
	v_mfma_f32_16x16x32_bf16 v[24:27], v[136:139], v[206:209], 0
	v_mfma_f32_16x16x32_bf16 v[12:15], v[128:131], v[214:217], 0
	v_mfma_f32_16x16x32_bf16 v[8:11], v[136:139], v[214:217], 0
	v_mfma_f32_16x16x32_bf16 v[60:63], v[132:135], v[194:197], v[60:63]
	v_mfma_f32_16x16x32_bf16 v[56:59], v[140:143], v[194:197], v[56:59]
	v_mfma_f32_16x16x32_bf16 v[44:47], v[132:135], v[202:205], v[44:47]
	v_mfma_f32_16x16x32_bf16 v[40:43], v[140:143], v[202:205], v[40:43]
	v_mfma_f32_16x16x32_bf16 v[28:31], v[132:135], v[210:213], v[28:31]
	v_mfma_f32_16x16x32_bf16 v[24:27], v[140:143], v[210:213], v[24:27]
	v_mfma_f32_16x16x32_bf16 v[12:15], v[132:135], v[218:221], v[12:15]
	v_mfma_f32_16x16x32_bf16 v[8:11], v[140:143], v[218:221], v[8:11]
	s_setprio 0
	s_setprio 1
	v_mfma_f32_16x16x32_bf16 v[52:55], v[144:147], v[180:183], 0
	v_mfma_f32_16x16x32_bf16 v[48:51], v[172:175], v[180:183], 0
	v_mfma_f32_16x16x32_bf16 v[36:39], v[144:147], v[198:201], 0
	v_mfma_f32_16x16x32_bf16 v[32:35], v[172:175], v[198:201], 0
	v_mfma_f32_16x16x32_bf16 v[20:23], v[144:147], v[206:209], 0
	v_mfma_f32_16x16x32_bf16 v[16:19], v[172:175], v[206:209], 0
	v_mfma_f32_16x16x32_bf16 v[4:7], v[144:147], v[214:217], 0
	v_mfma_f32_16x16x32_bf16 v[0:3], v[172:175], v[214:217], 0
	v_mfma_f32_16x16x32_bf16 v[52:55], v[148:151], v[194:197], v[52:55]
	v_mfma_f32_16x16x32_bf16 v[48:51], v[176:179], v[194:197], v[48:51]
	v_mfma_f32_16x16x32_bf16 v[36:39], v[148:151], v[202:205], v[36:39]
	v_mfma_f32_16x16x32_bf16 v[32:35], v[176:179], v[202:205], v[32:35]
	v_mfma_f32_16x16x32_bf16 v[20:23], v[148:151], v[210:213], v[20:23]
	v_mfma_f32_16x16x32_bf16 v[16:19], v[176:179], v[210:213], v[16:19]
	v_mfma_f32_16x16x32_bf16 v[4:7], v[148:151], v[218:221], v[4:7]
	v_mfma_f32_16x16x32_bf16 v[0:3], v[176:179], v[218:221], v[0:3]
	s_barrier
	s_setprio 0
	s_add_i32 s82, 0, 0x18000
	s_add_i32 s83, 0, 0x1c000
	v_add_u32_e32 v140, s82, v186
	v_add_u32_e32 v176, s83, v186
	ds_read_b128 v[128:131], v140
	v_xor_b32_e32 v253, 64, v140
	ds_read_b128 v[132:135], v253
	ds_read_b128 v[136:139], v140 offset:2048
	ds_read_b128 v[140:143], v253 offset:2048
	ds_read_b128 v[144:147], v176
	v_xor_b32_e32 v253, 64, v176
	ds_read_b128 v[148:151], v253
	ds_read_b128 v[172:175], v176 offset:2048
	ds_read_b128 v[176:179], v253 offset:2048
	s_add_u32 s54, s60, 0xb0000
	s_addc_u32 s55, s61, 0
	s_mov_b32 m0, s68
	v_lshl_add_u64 v[230:231], s[54:55], 0, v[152:153]
	ds_read_b128 v[180:183], v191 offset:32768
	v_xor_b32_e32 v253, 64, v191
	ds_read_b128 v[194:197], v253 offset:32768
	ds_read_b128 v[198:201], v191 offset:34816
	ds_read_b128 v[202:205], v253 offset:34816
	ds_read_b128 v[206:209], v191 offset:36864
	ds_read_b128 v[210:213], v253 offset:36864
	ds_read_b128 v[214:217], v191 offset:38912
	ds_read_b128 v[218:221], v253 offset:38912
	global_load_lds_dwordx4 v[230:231], off
	v_lshl_add_u64 v[230:231], s[54:55], 0, v[160:161]
	s_mov_b32 m0, s69
	s_nop 0
	global_load_lds_dwordx4 v[230:231], off
	s_waitcnt vmcnt(8)
	s_waitcnt lgkmcnt(0)
	s_setprio 1
	s_barrier
	v_mfma_f32_16x16x32_bf16 v[124:127], v[128:131], v[180:183], v[124:127]
	v_mfma_f32_16x16x32_bf16 v[124:127], v[132:135], v[194:197], v[124:127]
	v_mfma_f32_16x16x32_bf16 v[120:123], v[140:143], v[194:197], v[120:123]
	v_mfma_f32_16x16x32_bf16 v[120:123], v[136:139], v[180:183], v[120:123]
	v_mfma_f32_16x16x32_bf16 v[104:107], v[136:139], v[198:201], v[104:107]
	v_mfma_f32_16x16x32_bf16 v[104:107], v[140:143], v[202:205], v[104:107]
	v_mfma_f32_16x16x32_bf16 v[108:111], v[132:135], v[202:205], v[108:111]
	v_mfma_f32_16x16x32_bf16 v[108:111], v[128:131], v[198:201], v[108:111]
	v_mfma_f32_16x16x32_bf16 v[92:95], v[128:131], v[206:209], v[92:95]
	v_mfma_f32_16x16x32_bf16 v[92:95], v[132:135], v[210:213], v[92:95]
	v_mfma_f32_16x16x32_bf16 v[88:91], v[140:143], v[210:213], v[88:91]
	v_mfma_f32_16x16x32_bf16 v[88:91], v[136:139], v[206:209], v[88:91]
	v_mfma_f32_16x16x32_bf16 v[72:75], v[136:139], v[214:217], v[72:75]
	v_mfma_f32_16x16x32_bf16 v[72:75], v[140:143], v[218:221], v[72:75]
	v_mfma_f32_16x16x32_bf16 v[76:79], v[132:135], v[218:221], v[76:79]
	v_mfma_f32_16x16x32_bf16 v[76:79], v[128:131], v[214:217], v[76:79]
	s_setprio 0
	s_setprio 1
	v_mfma_f32_16x16x32_bf16 v[116:119], v[144:147], v[180:183], v[116:119]
	v_mfma_f32_16x16x32_bf16 v[116:119], v[148:151], v[194:197], v[116:119]
	v_mfma_f32_16x16x32_bf16 v[112:115], v[176:179], v[194:197], v[112:115]
	v_mfma_f32_16x16x32_bf16 v[112:115], v[172:175], v[180:183], v[112:115]
	v_mfma_f32_16x16x32_bf16 v[96:99], v[172:175], v[198:201], v[96:99]
	v_mfma_f32_16x16x32_bf16 v[96:99], v[176:179], v[202:205], v[96:99]
	v_mfma_f32_16x16x32_bf16 v[100:103], v[148:151], v[202:205], v[100:103]
	v_mfma_f32_16x16x32_bf16 v[100:103], v[144:147], v[198:201], v[100:103]
	v_mfma_f32_16x16x32_bf16 v[84:87], v[144:147], v[206:209], v[84:87]
	v_mfma_f32_16x16x32_bf16 v[84:87], v[148:151], v[210:213], v[84:87]
	v_mfma_f32_16x16x32_bf16 v[80:83], v[176:179], v[210:213], v[80:83]
	v_mfma_f32_16x16x32_bf16 v[80:83], v[172:175], v[206:209], v[80:83]
	v_mfma_f32_16x16x32_bf16 v[64:67], v[172:175], v[214:217], v[64:67]
	v_mfma_f32_16x16x32_bf16 v[64:67], v[176:179], v[218:221], v[64:67]
	v_mfma_f32_16x16x32_bf16 v[68:71], v[148:151], v[218:221], v[68:71]
	v_mfma_f32_16x16x32_bf16 v[68:71], v[144:147], v[214:217], v[68:71]
	s_barrier
	s_setprio 0
	s_add_i32 s54, s82, s65
	v_lshl_add_u64 v[222:223], v[222:223], 0, s[28:29]
	s_mov_b32 m0, s54
	ds_read_b128 v[180:183], v191 offset:49152
	v_xor_b32_e32 v253, 64, v191
	ds_read_b128 v[194:197], v253 offset:49152
	ds_read_b128 v[198:201], v191 offset:51200
	ds_read_b128 v[202:205], v253 offset:51200
	ds_read_b128 v[206:209], v191 offset:53248
	ds_read_b128 v[210:213], v253 offset:53248
	ds_read_b128 v[214:217], v191 offset:55296
	ds_read_b128 v[218:221], v253 offset:55296
	global_load_lds_dwordx4 v[222:223], off
	s_add_i32 m0, s54, 0x2000
	s_add_u32 s54, s58, 0xb0080
	v_lshl_add_u64 v[222:223], v[224:225], 0, s[28:29]
	s_addc_u32 s55, s59, 0
	s_add_i32 s58, s83, s65
	global_load_lds_dwordx4 v[222:223], off
	v_lshl_add_u64 v[222:223], s[54:55], 0, v[154:155]
	s_mov_b32 m0, s58
	s_nop 0
	global_load_lds_dwordx4 v[222:223], off
	v_lshl_add_u64 v[222:223], s[54:55], 0, v[162:163]
	s_add_i32 m0, s58, 0x2000
	s_nop 0
	global_load_lds_dwordx4 v[222:223], off
	v_lshl_add_u64 v[222:223], v[226:227], 0, s[28:29]
	s_mov_b32 m0, s3
	s_nop 0
	global_load_lds_dwordx4 v[222:223], off
	v_lshl_add_u64 v[222:223], v[228:229], 0, s[28:29]
	s_mov_b32 m0, s71
	s_nop 0
	global_load_lds_dwordx4 v[222:223], off
	s_waitcnt vmcnt(8)
	s_waitcnt lgkmcnt(0)
	s_setprio 1
	s_barrier
	v_mfma_f32_16x16x32_bf16 v[60:63], v[128:131], v[180:183], v[60:63]
	v_mfma_f32_16x16x32_bf16 v[60:63], v[132:135], v[194:197], v[60:63]
	v_mfma_f32_16x16x32_bf16 v[56:59], v[140:143], v[194:197], v[56:59]
	v_mfma_f32_16x16x32_bf16 v[56:59], v[136:139], v[180:183], v[56:59]
	v_mfma_f32_16x16x32_bf16 v[40:43], v[136:139], v[198:201], v[40:43]
	v_mfma_f32_16x16x32_bf16 v[40:43], v[140:143], v[202:205], v[40:43]
	v_mfma_f32_16x16x32_bf16 v[44:47], v[132:135], v[202:205], v[44:47]
	v_mfma_f32_16x16x32_bf16 v[44:47], v[128:131], v[198:201], v[44:47]
	v_mfma_f32_16x16x32_bf16 v[28:31], v[128:131], v[206:209], v[28:31]
	v_mfma_f32_16x16x32_bf16 v[28:31], v[132:135], v[210:213], v[28:31]
	v_mfma_f32_16x16x32_bf16 v[24:27], v[140:143], v[210:213], v[24:27]
	v_mfma_f32_16x16x32_bf16 v[24:27], v[136:139], v[206:209], v[24:27]
	v_mfma_f32_16x16x32_bf16 v[8:11], v[136:139], v[214:217], v[8:11]
	v_mfma_f32_16x16x32_bf16 v[8:11], v[140:143], v[218:221], v[8:11]
	v_mfma_f32_16x16x32_bf16 v[12:15], v[132:135], v[218:221], v[12:15]
	v_mfma_f32_16x16x32_bf16 v[12:15], v[128:131], v[214:217], v[12:15]
	s_setprio 0
	s_setprio 1
	v_mfma_f32_16x16x32_bf16 v[52:55], v[144:147], v[180:183], v[52:55]
	v_mfma_f32_16x16x32_bf16 v[52:55], v[148:151], v[194:197], v[52:55]
	v_mfma_f32_16x16x32_bf16 v[48:51], v[176:179], v[194:197], v[48:51]
	v_mfma_f32_16x16x32_bf16 v[48:51], v[172:175], v[180:183], v[48:51]
	v_mfma_f32_16x16x32_bf16 v[32:35], v[172:175], v[198:201], v[32:35]
	v_mfma_f32_16x16x32_bf16 v[32:35], v[176:179], v[202:205], v[32:35]
	v_mfma_f32_16x16x32_bf16 v[36:39], v[148:151], v[202:205], v[36:39]
	v_mfma_f32_16x16x32_bf16 v[36:39], v[144:147], v[198:201], v[36:39]
	v_mfma_f32_16x16x32_bf16 v[20:23], v[144:147], v[206:209], v[20:23]
	v_mfma_f32_16x16x32_bf16 v[20:23], v[148:151], v[210:213], v[20:23]
	v_mfma_f32_16x16x32_bf16 v[16:19], v[176:179], v[210:213], v[16:19]
	v_mfma_f32_16x16x32_bf16 v[16:19], v[172:175], v[206:209], v[16:19]
	v_mfma_f32_16x16x32_bf16 v[0:3], v[172:175], v[214:217], v[0:3]
	v_mfma_f32_16x16x32_bf16 v[0:3], v[176:179], v[218:221], v[0:3]
	v_mfma_f32_16x16x32_bf16 v[4:7], v[148:151], v[218:221], v[4:7]
	v_mfma_f32_16x16x32_bf16 v[4:7], v[144:147], v[214:217], v[4:7]
	s_barrier
	s_setprio 0
	s_add_i32 s81, s81, 2
	s_add_u32 s79, s79, 0x100
	s_addc_u32 s80, s80, 0
	s_cmp_gt_u32 s81, 41
	s_mov_b64 s[54:55], s[56:57]
	s_branch .LBB0_610
.Lfa_5:
	ds_read_b128 v[128:131], v189
	v_xor_b32_e32 v253, 64, v189
	ds_read_b128 v[132:135], v253
	ds_read_b128 v[136:139], v189 offset:2048
	ds_read_b128 v[140:143], v253 offset:2048
	ds_read_b128 v[144:147], v190
	v_xor_b32_e32 v253, 64, v190
	ds_read_b128 v[148:151], v253
	ds_read_b128 v[172:175], v190 offset:2048
	ds_read_b128 v[176:179], v253 offset:2048
	s_add_u32 s56, s54, 0x100
	s_addc_u32 s57, s55, 0
	s_cmp_eq_u32 s81, 40
	s_cselect_b32 s61, s17, s57
	s_cselect_b32 s60, s16, s56
	s_cselect_b32 s59, s53, s80
	s_cselect_b32 s58, s52, s79
	v_lshl_add_u64 v[222:223], s[54:55], 0, v[166:167]
	s_add_i32 m0, s66, 0xc000
	ds_read_b128 v[180:183], v191
	v_xor_b32_e32 v253, 64, v191
	ds_read_b128 v[194:197], v253
	ds_read_b128 v[198:201], v191 offset:2048
	ds_read_b128 v[202:205], v253 offset:2048
	ds_read_b128 v[206:209], v191 offset:4096
	ds_read_b128 v[210:213], v253 offset:4096
	ds_read_b128 v[214:217], v191 offset:6144
	ds_read_b128 v[218:221], v253 offset:6144
	global_load_lds_dwordx4 v[222:223], off
	v_lshl_add_u64 v[222:223], s[54:55], 0, v[164:165]
	s_add_i32 m0, s66, 0xe000
	s_nop 0
	global_load_lds_dwordx4 v[222:223], off
	s_waitcnt vmcnt(8)
	s_waitcnt lgkmcnt(0)
	s_setprio 1
	s_barrier
	v_mfma_f32_16x16x32_bf16 v[124:127], v[128:131], v[180:183], 0
	v_mfma_f32_16x16x32_bf16 v[120:123], v[136:139], v[180:183], 0
	v_mfma_f32_16x16x32_bf16 v[108:111], v[128:131], v[198:201], 0
	v_mfma_f32_16x16x32_bf16 v[104:107], v[136:139], v[198:201], 0
	v_mfma_f32_16x16x32_bf16 v[92:95], v[128:131], v[206:209], 0
	v_mfma_f32_16x16x32_bf16 v[88:91], v[136:139], v[206:209], 0
	v_mfma_f32_16x16x32_bf16 v[76:79], v[128:131], v[214:217], 0
	v_mfma_f32_16x16x32_bf16 v[72:75], v[136:139], v[214:217], 0
	v_mfma_f32_16x16x32_bf16 v[124:127], v[132:135], v[194:197], v[124:127]
	v_mfma_f32_16x16x32_bf16 v[120:123], v[140:143], v[194:197], v[120:123]
	v_mfma_f32_16x16x32_bf16 v[108:111], v[132:135], v[202:205], v[108:111]
	v_mfma_f32_16x16x32_bf16 v[104:107], v[140:143], v[202:205], v[104:107]
	v_mfma_f32_16x16x32_bf16 v[92:95], v[132:135], v[210:213], v[92:95]
	v_mfma_f32_16x16x32_bf16 v[88:91], v[140:143], v[210:213], v[88:91]
	v_mfma_f32_16x16x32_bf16 v[76:79], v[132:135], v[218:221], v[76:79]
	v_mfma_f32_16x16x32_bf16 v[72:75], v[140:143], v[218:221], v[72:75]
	s_setprio 0
	s_setprio 1
	v_mfma_f32_16x16x32_bf16 v[116:119], v[144:147], v[180:183], 0
	v_mfma_f32_16x16x32_bf16 v[112:115], v[172:175], v[180:183], 0
	v_mfma_f32_16x16x32_bf16 v[100:103], v[144:147], v[198:201], 0
	v_mfma_f32_16x16x32_bf16 v[96:99], v[172:175], v[198:201], 0
	v_mfma_f32_16x16x32_bf16 v[84:87], v[144:147], v[206:209], 0
	v_mfma_f32_16x16x32_bf16 v[80:83], v[172:175], v[206:209], 0
	v_mfma_f32_16x16x32_bf16 v[68:71], v[144:147], v[214:217], 0
	v_mfma_f32_16x16x32_bf16 v[64:67], v[172:175], v[214:217], 0
	v_mfma_f32_16x16x32_bf16 v[116:119], v[148:151], v[194:197], v[116:119]
	v_mfma_f32_16x16x32_bf16 v[112:115], v[176:179], v[194:197], v[112:115]
	v_mfma_f32_16x16x32_bf16 v[100:103], v[148:151], v[202:205], v[100:103]
	v_mfma_f32_16x16x32_bf16 v[96:99], v[176:179], v[202:205], v[96:99]
	v_mfma_f32_16x16x32_bf16 v[84:87], v[148:151], v[210:213], v[84:87]
	v_mfma_f32_16x16x32_bf16 v[80:83], v[176:179], v[210:213], v[80:83]
	v_mfma_f32_16x16x32_bf16 v[68:71], v[148:151], v[218:221], v[68:71]
	v_mfma_f32_16x16x32_bf16 v[64:67], v[176:179], v[218:221], v[64:67]
	s_barrier
	s_setprio 0
	s_add_i32 s54, s75, s65
	v_lshl_add_u64 v[222:223], s[58:59], 0, v[154:155]
	s_mov_b32 m0, s54
	ds_read_b128 v[180:183], v191 offset:16384
	v_xor_b32_e32 v253, 64, v191
	ds_read_b128 v[194:197], v253 offset:16384
	ds_read_b128 v[198:201], v191 offset:18432
	ds_read_b128 v[202:205], v253 offset:18432
	ds_read_b128 v[206:209], v191 offset:20480
	ds_read_b128 v[210:213], v253 offset:20480
	ds_read_b128 v[214:217], v191 offset:22528
	ds_read_b128 v[218:221], v253 offset:22528
	global_load_lds_dwordx4 v[222:223], off
	s_add_i32 m0, s54, 0x2000
	s_add_u32 s54, s58, 0xb0000
	v_lshl_add_u64 v[224:225], s[58:59], 0, v[162:163]
	s_addc_u32 s55, s59, 0
	s_add_i32 s82, s76, s65
	global_load_lds_dwordx4 v[224:225], off
	v_lshl_add_u64 v[226:227], s[54:55], 0, v[154:155]
	s_mov_b32 m0, s82
	v_lshl_add_u64 v[228:229], s[60:61], 0, v[160:161]
	global_load_lds_dwordx4 v[226:227], off
	v_lshl_add_u64 v[226:227], s[54:55], 0, v[162:163]
	s_add_i32 m0, s82, 0x2000
	s_nop 0
	global_load_lds_dwordx4 v[226:227], off
	v_lshl_add_u64 v[226:227], s[60:61], 0, v[152:153]
	s_mov_b32 m0, s66
	s_nop 0
	global_load_lds_dwordx4 v[226:227], off
	s_mov_b32 m0, s67
	s_nop 0
	global_load_lds_dwordx4 v[228:229], off
	s_waitcnt vmcnt(8)
	s_waitcnt lgkmcnt(0)
	s_setprio 1
	s_barrier
	v_mfma_f32_16x16x32_bf16 v[60:63], v[128:131], v[180:183], 0
	v_mfma_f32_16x16x32_bf16 v[56:59], v[136:139], v[180:183], 0
	v_mfma_f32_16x16x32_bf16 v[44:47], v[128:131], v[198:201], 0
	v_mfma_f32_16x16x32_bf16 v[40:43], v[136:139], v[198:201], 0
	v_mfma_f32_16x16x32_bf16 v[28:31], v[128:131], v[206:209], 0
	v_mfma_f32_16x16x32_bf16 v[24:27], v[136:139], v[206:209], 0
	v_mfma_f32_16x16x32_bf16 v[12:15], v[128:131], v[214:217], 0
	v_mfma_f32_16x16x32_bf16 v[8:11], v[136:139], v[214:217], 0
	v_mfma_f32_16x16x32_bf16 v[60:63], v[132:135], v[194:197], v[60:63]
	v_mfma_f32_16x16x32_bf16 v[56:59], v[140:143], v[194:197], v[56:59]
	v_mfma_f32_16x16x32_bf16 v[44:47], v[132:135], v[202:205], v[44:47]
	v_mfma_f32_16x16x32_bf16 v[40:43], v[140:143], v[202:205], v[40:43]
	v_mfma_f32_16x16x32_bf16 v[28:31], v[132:135], v[210:213], v[28:31]
	v_mfma_f32_16x16x32_bf16 v[24:27], v[140:143], v[210:213], v[24:27]
	v_mfma_f32_16x16x32_bf16 v[12:15], v[132:135], v[218:221], v[12:15]
	v_mfma_f32_16x16x32_bf16 v[8:11], v[140:143], v[218:221], v[8:11]
	s_setprio 0
	s_setprio 1
	v_mfma_f32_16x16x32_bf16 v[52:55], v[144:147], v[180:183], 0
	v_mfma_f32_16x16x32_bf16 v[48:51], v[172:175], v[180:183], 0
	v_mfma_f32_16x16x32_bf16 v[36:39], v[144:147], v[198:201], 0
	v_mfma_f32_16x16x32_bf16 v[32:35], v[172:175], v[198:201], 0
	v_mfma_f32_16x16x32_bf16 v[20:23], v[144:147], v[206:209], 0
	v_mfma_f32_16x16x32_bf16 v[16:19], v[172:175], v[206:209], 0
	v_mfma_f32_16x16x32_bf16 v[4:7], v[144:147], v[214:217], 0
	v_mfma_f32_16x16x32_bf16 v[0:3], v[172:175], v[214:217], 0
	v_mfma_f32_16x16x32_bf16 v[52:55], v[148:151], v[194:197], v[52:55]
	v_mfma_f32_16x16x32_bf16 v[48:51], v[176:179], v[194:197], v[48:51]
	v_mfma_f32_16x16x32_bf16 v[36:39], v[148:151], v[202:205], v[36:39]
	v_mfma_f32_16x16x32_bf16 v[32:35], v[176:179], v[202:205], v[32:35]
	v_mfma_f32_16x16x32_bf16 v[20:23], v[148:151], v[210:213], v[20:23]
	v_mfma_f32_16x16x32_bf16 v[16:19], v[176:179], v[210:213], v[16:19]
	v_mfma_f32_16x16x32_bf16 v[4:7], v[148:151], v[218:221], v[4:7]
	v_mfma_f32_16x16x32_bf16 v[0:3], v[176:179], v[218:221], v[0:3]
	s_barrier
	s_setprio 0
	s_add_i32 s82, 0, 0x18000
	s_add_i32 s83, 0, 0x1c000
	v_add_u32_e32 v140, s82, v186
	v_add_u32_e32 v176, s83, v186
	ds_read_b128 v[128:131], v140
	v_xor_b32_e32 v253, 64, v140
	ds_read_b128 v[132:135], v253
	ds_read_b128 v[136:139], v140 offset:2048
	ds_read_b128 v[140:143], v253 offset:2048
	ds_read_b128 v[144:147], v176
	v_xor_b32_e32 v253, 64, v176
	ds_read_b128 v[148:151], v253
	ds_read_b128 v[172:175], v176 offset:2048
	ds_read_b128 v[176:179], v253 offset:2048
	s_add_u32 s54, s60, 0xb0000
	s_addc_u32 s55, s61, 0
	s_mov_b32 m0, s68
	v_lshl_add_u64 v[230:231], s[54:55], 0, v[152:153]
	ds_read_b128 v[180:183], v191 offset:32768
	v_xor_b32_e32 v253, 64, v191
	ds_read_b128 v[194:197], v253 offset:32768
	ds_read_b128 v[198:201], v191 offset:34816
	ds_read_b128 v[202:205], v253 offset:34816
	ds_read_b128 v[206:209], v191 offset:36864
	ds_read_b128 v[210:213], v253 offset:36864
	ds_read_b128 v[214:217], v191 offset:38912
	ds_read_b128 v[218:221], v253 offset:38912
	global_load_lds_dwordx4 v[230:231], off
	v_lshl_add_u64 v[230:231], s[54:55], 0, v[160:161]
	s_mov_b32 m0, s69
	s_nop 0
	global_load_lds_dwordx4 v[230:231], off
	s_waitcnt vmcnt(8)
	s_waitcnt lgkmcnt(0)
	s_setprio 1
	s_barrier
	v_mfma_f32_16x16x32_bf16 v[124:127], v[128:131], v[180:183], v[124:127]
	v_mfma_f32_16x16x32_bf16 v[124:127], v[132:135], v[194:197], v[124:127]
	v_mfma_f32_16x16x32_bf16 v[120:123], v[140:143], v[194:197], v[120:123]
	v_mfma_f32_16x16x32_bf16 v[120:123], v[136:139], v[180:183], v[120:123]
	v_mfma_f32_16x16x32_bf16 v[104:107], v[136:139], v[198:201], v[104:107]
	v_mfma_f32_16x16x32_bf16 v[104:107], v[140:143], v[202:205], v[104:107]
	v_mfma_f32_16x16x32_bf16 v[108:111], v[132:135], v[202:205], v[108:111]
	v_mfma_f32_16x16x32_bf16 v[108:111], v[128:131], v[198:201], v[108:111]
	v_mfma_f32_16x16x32_bf16 v[92:95], v[128:131], v[206:209], v[92:95]
	v_mfma_f32_16x16x32_bf16 v[92:95], v[132:135], v[210:213], v[92:95]
	v_mfma_f32_16x16x32_bf16 v[88:91], v[140:143], v[210:213], v[88:91]
	v_mfma_f32_16x16x32_bf16 v[88:91], v[136:139], v[206:209], v[88:91]
	v_mfma_f32_16x16x32_bf16 v[72:75], v[136:139], v[214:217], v[72:75]
	v_mfma_f32_16x16x32_bf16 v[72:75], v[140:143], v[218:221], v[72:75]
	v_mfma_f32_16x16x32_bf16 v[76:79], v[132:135], v[218:221], v[76:79]
	v_mfma_f32_16x16x32_bf16 v[76:79], v[128:131], v[214:217], v[76:79]
	s_setprio 0
	s_setprio 1
	v_mfma_f32_16x16x32_bf16 v[116:119], v[144:147], v[180:183], v[116:119]
	v_mfma_f32_16x16x32_bf16 v[116:119], v[148:151], v[194:197], v[116:119]
	v_mfma_f32_16x16x32_bf16 v[112:115], v[176:179], v[194:197], v[112:115]
	v_mfma_f32_16x16x32_bf16 v[112:115], v[172:175], v[180:183], v[112:115]
	v_mfma_f32_16x16x32_bf16 v[96:99], v[172:175], v[198:201], v[96:99]
	v_mfma_f32_16x16x32_bf16 v[96:99], v[176:179], v[202:205], v[96:99]
	v_mfma_f32_16x16x32_bf16 v[100:103], v[148:151], v[202:205], v[100:103]
	v_mfma_f32_16x16x32_bf16 v[100:103], v[144:147], v[198:201], v[100:103]
	v_mfma_f32_16x16x32_bf16 v[84:87], v[144:147], v[206:209], v[84:87]
	v_mfma_f32_16x16x32_bf16 v[84:87], v[148:151], v[210:213], v[84:87]
	v_mfma_f32_16x16x32_bf16 v[80:83], v[176:179], v[210:213], v[80:83]
	v_mfma_f32_16x16x32_bf16 v[80:83], v[172:175], v[206:209], v[80:83]
	v_mfma_f32_16x16x32_bf16 v[64:67], v[172:175], v[214:217], v[64:67]
	v_mfma_f32_16x16x32_bf16 v[64:67], v[176:179], v[218:221], v[64:67]
	v_mfma_f32_16x16x32_bf16 v[68:71], v[148:151], v[218:221], v[68:71]
	v_mfma_f32_16x16x32_bf16 v[68:71], v[144:147], v[214:217], v[68:71]
	s_barrier
	s_setprio 0
	s_add_i32 s54, s82, s65
	v_lshl_add_u64 v[222:223], v[222:223], 0, s[28:29]
	s_mov_b32 m0, s54
	ds_read_b128 v[180:183], v191 offset:49152
	v_xor_b32_e32 v253, 64, v191
	ds_read_b128 v[194:197], v253 offset:49152
	ds_read_b128 v[198:201], v191 offset:51200
	ds_read_b128 v[202:205], v253 offset:51200
	ds_read_b128 v[206:209], v191 offset:53248
	ds_read_b128 v[210:213], v253 offset:53248
	ds_read_b128 v[214:217], v191 offset:55296
	ds_read_b128 v[218:221], v253 offset:55296
	global_load_lds_dwordx4 v[222:223], off
	s_add_i32 m0, s54, 0x2000
	s_add_u32 s54, s58, 0xb0080
	v_lshl_add_u64 v[222:223], v[224:225], 0, s[28:29]
	s_addc_u32 s55, s59, 0
	s_add_i32 s58, s83, s65
	global_load_lds_dwordx4 v[222:223], off
	v_lshl_add_u64 v[222:223], s[54:55], 0, v[154:155]
	s_mov_b32 m0, s58
	s_nop 0
	global_load_lds_dwordx4 v[222:223], off
	v_lshl_add_u64 v[222:223], s[54:55], 0, v[162:163]
	s_add_i32 m0, s58, 0x2000
	s_nop 0
	global_load_lds_dwordx4 v[222:223], off
	v_lshl_add_u64 v[222:223], v[226:227], 0, s[28:29]
	s_mov_b32 m0, s3
	s_nop 0
	global_load_lds_dwordx4 v[222:223], off
	v_lshl_add_u64 v[222:223], v[228:229], 0, s[28:29]
	s_mov_b32 m0, s71
	s_nop 0
	global_load_lds_dwordx4 v[222:223], off
	s_waitcnt vmcnt(8)
	s_waitcnt lgkmcnt(0)
	s_setprio 1
	s_barrier
	v_mfma_f32_16x16x32_bf16 v[60:63], v[128:131], v[180:183], v[60:63]
	v_mfma_f32_16x16x32_bf16 v[60:63], v[132:135], v[194:197], v[60:63]
	v_mfma_f32_16x16x32_bf16 v[56:59], v[140:143], v[194:197], v[56:59]
	v_mfma_f32_16x16x32_bf16 v[56:59], v[136:139], v[180:183], v[56:59]
	v_mfma_f32_16x16x32_bf16 v[40:43], v[136:139], v[198:201], v[40:43]
	v_mfma_f32_16x16x32_bf16 v[40:43], v[140:143], v[202:205], v[40:43]
	v_mfma_f32_16x16x32_bf16 v[44:47], v[132:135], v[202:205], v[44:47]
	v_mfma_f32_16x16x32_bf16 v[44:47], v[128:131], v[198:201], v[44:47]
	v_mfma_f32_16x16x32_bf16 v[28:31], v[128:131], v[206:209], v[28:31]
	v_mfma_f32_16x16x32_bf16 v[28:31], v[132:135], v[210:213], v[28:31]
	v_mfma_f32_16x16x32_bf16 v[24:27], v[140:143], v[210:213], v[24:27]
	v_mfma_f32_16x16x32_bf16 v[24:27], v[136:139], v[206:209], v[24:27]
	v_mfma_f32_16x16x32_bf16 v[8:11], v[136:139], v[214:217], v[8:11]
	v_mfma_f32_16x16x32_bf16 v[8:11], v[140:143], v[218:221], v[8:11]
	v_mfma_f32_16x16x32_bf16 v[12:15], v[132:135], v[218:221], v[12:15]
	v_mfma_f32_16x16x32_bf16 v[12:15], v[128:131], v[214:217], v[12:15]
	s_setprio 0
	s_setprio 1
	v_mfma_f32_16x16x32_bf16 v[52:55], v[144:147], v[180:183], v[52:55]
	v_mfma_f32_16x16x32_bf16 v[52:55], v[148:151], v[194:197], v[52:55]
	v_mfma_f32_16x16x32_bf16 v[48:51], v[176:179], v[194:197], v[48:51]
	v_mfma_f32_16x16x32_bf16 v[48:51], v[172:175], v[180:183], v[48:51]
	v_mfma_f32_16x16x32_bf16 v[32:35], v[172:175], v[198:201], v[32:35]
	v_mfma_f32_16x16x32_bf16 v[32:35], v[176:179], v[202:205], v[32:35]
	v_mfma_f32_16x16x32_bf16 v[36:39], v[148:151], v[202:205], v[36:39]
	v_mfma_f32_16x16x32_bf16 v[36:39], v[144:147], v[198:201], v[36:39]
	v_mfma_f32_16x16x32_bf16 v[20:23], v[144:147], v[206:209], v[20:23]
	v_mfma_f32_16x16x32_bf16 v[20:23], v[148:151], v[210:213], v[20:23]
	v_mfma_f32_16x16x32_bf16 v[16:19], v[176:179], v[210:213], v[16:19]
	v_mfma_f32_16x16x32_bf16 v[16:19], v[172:175], v[206:209], v[16:19]
	v_mfma_f32_16x16x32_bf16 v[0:3], v[172:175], v[214:217], v[0:3]
	v_mfma_f32_16x16x32_bf16 v[0:3], v[176:179], v[218:221], v[0:3]
	v_mfma_f32_16x16x32_bf16 v[4:7], v[148:151], v[218:221], v[4:7]
	v_mfma_f32_16x16x32_bf16 v[4:7], v[144:147], v[214:217], v[4:7]
	s_barrier
	s_setprio 0
	s_add_i32 s81, s81, 2
	s_add_u32 s79, s79, 0x100
	s_addc_u32 s80, s80, 0
	s_cmp_gt_u32 s81, 41
	s_mov_b64 s[54:55], s[56:57]
.LBB0_610:
	ds_read_b128 v[128:131], v189
	v_xor_b32_e32 v253, 64, v189
	ds_read_b128 v[132:135], v253
	ds_read_b128 v[136:139], v189 offset:2048
	ds_read_b128 v[140:143], v253 offset:2048
	ds_read_b128 v[144:147], v190
	v_xor_b32_e32 v253, 64, v190
	ds_read_b128 v[148:151], v253
	ds_read_b128 v[172:175], v190 offset:2048
	ds_read_b128 v[176:179], v253 offset:2048
	s_add_u32 s56, s54, 0x100
	s_addc_u32 s57, s55, 0
	s_cmp_eq_u32 s81, 40
	s_cselect_b32 s61, s17, s57
	s_cselect_b32 s60, s16, s56
	s_cselect_b32 s59, s53, s80
	s_cselect_b32 s58, s52, s79
	v_lshl_add_u64 v[222:223], s[54:55], 0, v[166:167]
	s_add_i32 m0, s66, 0xc000
	ds_read_b128 v[180:183], v191
	v_xor_b32_e32 v253, 64, v191
	ds_read_b128 v[194:197], v253
	ds_read_b128 v[198:201], v191 offset:2048
	ds_read_b128 v[202:205], v253 offset:2048
	ds_read_b128 v[206:209], v191 offset:4096
	ds_read_b128 v[210:213], v253 offset:4096
	ds_read_b128 v[214:217], v191 offset:6144
	ds_read_b128 v[218:221], v253 offset:6144
	global_load_lds_dwordx4 v[222:223], off
	v_lshl_add_u64 v[222:223], s[54:55], 0, v[164:165]
	s_add_i32 m0, s66, 0xe000
	s_nop 0
	global_load_lds_dwordx4 v[222:223], off
	s_waitcnt vmcnt(8)
	s_waitcnt lgkmcnt(0)
	s_setprio 1
	s_barrier
	v_mfma_f32_16x16x32_bf16 v[124:127], v[128:131], v[180:183], v[124:127]
	v_mfma_f32_16x16x32_bf16 v[124:127], v[132:135], v[194:197], v[124:127]
	v_mfma_f32_16x16x32_bf16 v[120:123], v[140:143], v[194:197], v[120:123]
	v_mfma_f32_16x16x32_bf16 v[120:123], v[136:139], v[180:183], v[120:123]
	v_mfma_f32_16x16x32_bf16 v[104:107], v[136:139], v[198:201], v[104:107]
	v_mfma_f32_16x16x32_bf16 v[104:107], v[140:143], v[202:205], v[104:107]
	v_mfma_f32_16x16x32_bf16 v[108:111], v[132:135], v[202:205], v[108:111]
	v_mfma_f32_16x16x32_bf16 v[108:111], v[128:131], v[198:201], v[108:111]
	v_mfma_f32_16x16x32_bf16 v[92:95], v[128:131], v[206:209], v[92:95]
	v_mfma_f32_16x16x32_bf16 v[92:95], v[132:135], v[210:213], v[92:95]
	v_mfma_f32_16x16x32_bf16 v[88:91], v[140:143], v[210:213], v[88:91]
	v_mfma_f32_16x16x32_bf16 v[88:91], v[136:139], v[206:209], v[88:91]
	v_mfma_f32_16x16x32_bf16 v[72:75], v[136:139], v[214:217], v[72:75]
	v_mfma_f32_16x16x32_bf16 v[72:75], v[140:143], v[218:221], v[72:75]
	v_mfma_f32_16x16x32_bf16 v[76:79], v[132:135], v[218:221], v[76:79]
	v_mfma_f32_16x16x32_bf16 v[76:79], v[128:131], v[214:217], v[76:79]
	s_setprio 0
	s_setprio 1
	v_mfma_f32_16x16x32_bf16 v[116:119], v[144:147], v[180:183], v[116:119]
	v_mfma_f32_16x16x32_bf16 v[116:119], v[148:151], v[194:197], v[116:119]
	v_mfma_f32_16x16x32_bf16 v[112:115], v[176:179], v[194:197], v[112:115]
	v_mfma_f32_16x16x32_bf16 v[112:115], v[172:175], v[180:183], v[112:115]
	v_mfma_f32_16x16x32_bf16 v[96:99], v[172:175], v[198:201], v[96:99]
	v_mfma_f32_16x16x32_bf16 v[96:99], v[176:179], v[202:205], v[96:99]
	v_mfma_f32_16x16x32_bf16 v[100:103], v[148:151], v[202:205], v[100:103]
	v_mfma_f32_16x16x32_bf16 v[100:103], v[144:147], v[198:201], v[100:103]
	v_mfma_f32_16x16x32_bf16 v[84:87], v[144:147], v[206:209], v[84:87]
	v_mfma_f32_16x16x32_bf16 v[84:87], v[148:151], v[210:213], v[84:87]
	v_mfma_f32_16x16x32_bf16 v[80:83], v[176:179], v[210:213], v[80:83]
	v_mfma_f32_16x16x32_bf16 v[80:83], v[172:175], v[206:209], v[80:83]
	v_mfma_f32_16x16x32_bf16 v[64:67], v[172:175], v[214:217], v[64:67]
	v_mfma_f32_16x16x32_bf16 v[64:67], v[176:179], v[218:221], v[64:67]
	v_mfma_f32_16x16x32_bf16 v[68:71], v[148:151], v[218:221], v[68:71]
	v_mfma_f32_16x16x32_bf16 v[68:71], v[144:147], v[214:217], v[68:71]
	s_barrier
	s_setprio 0
	s_add_i32 s54, s75, s65
	v_lshl_add_u64 v[222:223], s[58:59], 0, v[154:155]
	s_mov_b32 m0, s54
	ds_read_b128 v[180:183], v191 offset:16384
	v_xor_b32_e32 v253, 64, v191
	ds_read_b128 v[194:197], v253 offset:16384
	ds_read_b128 v[198:201], v191 offset:18432
	ds_read_b128 v[202:205], v253 offset:18432
	ds_read_b128 v[206:209], v191 offset:20480
	ds_read_b128 v[210:213], v253 offset:20480
	ds_read_b128 v[214:217], v191 offset:22528
	ds_read_b128 v[218:221], v253 offset:22528
	global_load_lds_dwordx4 v[222:223], off
	s_add_i32 m0, s54, 0x2000
	s_add_u32 s54, s58, 0xb0000
	v_lshl_add_u64 v[224:225], s[58:59], 0, v[162:163]
	s_addc_u32 s55, s59, 0
	s_add_i32 s82, s76, s65
	global_load_lds_dwordx4 v[224:225], off
	v_lshl_add_u64 v[226:227], s[54:55], 0, v[154:155]
	s_mov_b32 m0, s82
	v_lshl_add_u64 v[228:229], s[60:61], 0, v[160:161]
	global_load_lds_dwordx4 v[226:227], off
	v_lshl_add_u64 v[226:227], s[54:55], 0, v[162:163]
	s_add_i32 m0, s82, 0x2000
	s_nop 0
	global_load_lds_dwordx4 v[226:227], off
	v_lshl_add_u64 v[226:227], s[60:61], 0, v[152:153]
	s_mov_b32 m0, s66
	s_nop 0
	global_load_lds_dwordx4 v[226:227], off
	s_mov_b32 m0, s67
	s_nop 0
	global_load_lds_dwordx4 v[228:229], off
	s_waitcnt vmcnt(8)
	s_waitcnt lgkmcnt(0)
	s_setprio 1
	s_barrier
	v_mfma_f32_16x16x32_bf16 v[60:63], v[128:131], v[180:183], v[60:63]
	v_mfma_f32_16x16x32_bf16 v[60:63], v[132:135], v[194:197], v[60:63]
	v_mfma_f32_16x16x32_bf16 v[56:59], v[140:143], v[194:197], v[56:59]
	v_mfma_f32_16x16x32_bf16 v[56:59], v[136:139], v[180:183], v[56:59]
	v_mfma_f32_16x16x32_bf16 v[40:43], v[136:139], v[198:201], v[40:43]
	v_mfma_f32_16x16x32_bf16 v[40:43], v[140:143], v[202:205], v[40:43]
	v_mfma_f32_16x16x32_bf16 v[44:47], v[132:135], v[202:205], v[44:47]
	v_mfma_f32_16x16x32_bf16 v[44:47], v[128:131], v[198:201], v[44:47]
	v_mfma_f32_16x16x32_bf16 v[28:31], v[128:131], v[206:209], v[28:31]
	v_mfma_f32_16x16x32_bf16 v[28:31], v[132:135], v[210:213], v[28:31]
	v_mfma_f32_16x16x32_bf16 v[24:27], v[140:143], v[210:213], v[24:27]
	v_mfma_f32_16x16x32_bf16 v[24:27], v[136:139], v[206:209], v[24:27]
	v_mfma_f32_16x16x32_bf16 v[8:11], v[136:139], v[214:217], v[8:11]
	v_mfma_f32_16x16x32_bf16 v[8:11], v[140:143], v[218:221], v[8:11]
	v_mfma_f32_16x16x32_bf16 v[12:15], v[132:135], v[218:221], v[12:15]
	v_mfma_f32_16x16x32_bf16 v[12:15], v[128:131], v[214:217], v[12:15]
	s_setprio 0
	s_setprio 1
	v_mfma_f32_16x16x32_bf16 v[52:55], v[144:147], v[180:183], v[52:55]
	v_mfma_f32_16x16x32_bf16 v[52:55], v[148:151], v[194:197], v[52:55]
	v_mfma_f32_16x16x32_bf16 v[48:51], v[176:179], v[194:197], v[48:51]
	v_mfma_f32_16x16x32_bf16 v[48:51], v[172:175], v[180:183], v[48:51]
	v_mfma_f32_16x16x32_bf16 v[32:35], v[172:175], v[198:201], v[32:35]
	v_mfma_f32_16x16x32_bf16 v[32:35], v[176:179], v[202:205], v[32:35]
	v_mfma_f32_16x16x32_bf16 v[36:39], v[148:151], v[202:205], v[36:39]
	v_mfma_f32_16x16x32_bf16 v[36:39], v[144:147], v[198:201], v[36:39]
	v_mfma_f32_16x16x32_bf16 v[20:23], v[144:147], v[206:209], v[20:23]
	v_mfma_f32_16x16x32_bf16 v[20:23], v[148:151], v[210:213], v[20:23]
	v_mfma_f32_16x16x32_bf16 v[16:19], v[176:179], v[210:213], v[16:19]
	v_mfma_f32_16x16x32_bf16 v[16:19], v[172:175], v[206:209], v[16:19]
	v_mfma_f32_16x16x32_bf16 v[0:3], v[172:175], v[214:217], v[0:3]
	v_mfma_f32_16x16x32_bf16 v[0:3], v[176:179], v[218:221], v[0:3]
	v_mfma_f32_16x16x32_bf16 v[4:7], v[148:151], v[218:221], v[4:7]
	v_mfma_f32_16x16x32_bf16 v[4:7], v[144:147], v[214:217], v[4:7]
	s_barrier
	s_setprio 0
	s_add_i32 s82, 0, 0x18000
	s_add_i32 s83, 0, 0x1c000
	v_add_u32_e32 v140, s82, v186
	v_add_u32_e32 v176, s83, v186
	ds_read_b128 v[128:131], v140
	v_xor_b32_e32 v253, 64, v140
	ds_read_b128 v[132:135], v253
	ds_read_b128 v[136:139], v140 offset:2048
	ds_read_b128 v[140:143], v253 offset:2048
	ds_read_b128 v[144:147], v176
	v_xor_b32_e32 v253, 64, v176
	ds_read_b128 v[148:151], v253
	ds_read_b128 v[172:175], v176 offset:2048
	ds_read_b128 v[176:179], v253 offset:2048
	s_add_u32 s54, s60, 0xb0000
	s_addc_u32 s55, s61, 0
	s_mov_b32 m0, s68
	v_lshl_add_u64 v[230:231], s[54:55], 0, v[152:153]
	ds_read_b128 v[180:183], v191 offset:32768
	v_xor_b32_e32 v253, 64, v191
	ds_read_b128 v[194:197], v253 offset:32768
	ds_read_b128 v[198:201], v191 offset:34816
	ds_read_b128 v[202:205], v253 offset:34816
	ds_read_b128 v[206:209], v191 offset:36864
	ds_read_b128 v[210:213], v253 offset:36864
	ds_read_b128 v[214:217], v191 offset:38912
	ds_read_b128 v[218:221], v253 offset:38912
	global_load_lds_dwordx4 v[230:231], off
	v_lshl_add_u64 v[230:231], s[54:55], 0, v[160:161]
	s_mov_b32 m0, s69
	s_nop 0
	global_load_lds_dwordx4 v[230:231], off
	s_waitcnt vmcnt(8)
	s_waitcnt lgkmcnt(0)
	s_setprio 1
	s_barrier
	v_mfma_f32_16x16x32_bf16 v[124:127], v[128:131], v[180:183], v[124:127]
	v_mfma_f32_16x16x32_bf16 v[124:127], v[132:135], v[194:197], v[124:127]
	v_mfma_f32_16x16x32_bf16 v[120:123], v[140:143], v[194:197], v[120:123]
	v_mfma_f32_16x16x32_bf16 v[120:123], v[136:139], v[180:183], v[120:123]
	v_mfma_f32_16x16x32_bf16 v[104:107], v[136:139], v[198:201], v[104:107]
	v_mfma_f32_16x16x32_bf16 v[104:107], v[140:143], v[202:205], v[104:107]
	v_mfma_f32_16x16x32_bf16 v[108:111], v[132:135], v[202:205], v[108:111]
	v_mfma_f32_16x16x32_bf16 v[108:111], v[128:131], v[198:201], v[108:111]
	v_mfma_f32_16x16x32_bf16 v[92:95], v[128:131], v[206:209], v[92:95]
	v_mfma_f32_16x16x32_bf16 v[92:95], v[132:135], v[210:213], v[92:95]
	v_mfma_f32_16x16x32_bf16 v[88:91], v[140:143], v[210:213], v[88:91]
	v_mfma_f32_16x16x32_bf16 v[88:91], v[136:139], v[206:209], v[88:91]
	v_mfma_f32_16x16x32_bf16 v[72:75], v[136:139], v[214:217], v[72:75]
	v_mfma_f32_16x16x32_bf16 v[72:75], v[140:143], v[218:221], v[72:75]
	v_mfma_f32_16x16x32_bf16 v[76:79], v[132:135], v[218:221], v[76:79]
	v_mfma_f32_16x16x32_bf16 v[76:79], v[128:131], v[214:217], v[76:79]
	s_setprio 0
	s_setprio 1
	v_mfma_f32_16x16x32_bf16 v[116:119], v[144:147], v[180:183], v[116:119]
	v_mfma_f32_16x16x32_bf16 v[116:119], v[148:151], v[194:197], v[116:119]
	v_mfma_f32_16x16x32_bf16 v[112:115], v[176:179], v[194:197], v[112:115]
	v_mfma_f32_16x16x32_bf16 v[112:115], v[172:175], v[180:183], v[112:115]
	v_mfma_f32_16x16x32_bf16 v[96:99], v[172:175], v[198:201], v[96:99]
	v_mfma_f32_16x16x32_bf16 v[96:99], v[176:179], v[202:205], v[96:99]
	v_mfma_f32_16x16x32_bf16 v[100:103], v[148:151], v[202:205], v[100:103]
	v_mfma_f32_16x16x32_bf16 v[100:103], v[144:147], v[198:201], v[100:103]
	v_mfma_f32_16x16x32_bf16 v[84:87], v[144:147], v[206:209], v[84:87]
	v_mfma_f32_16x16x32_bf16 v[84:87], v[148:151], v[210:213], v[84:87]
	v_mfma_f32_16x16x32_bf16 v[80:83], v[176:179], v[210:213], v[80:83]
	v_mfma_f32_16x16x32_bf16 v[80:83], v[172:175], v[206:209], v[80:83]
	v_mfma_f32_16x16x32_bf16 v[64:67], v[172:175], v[214:217], v[64:67]
	v_mfma_f32_16x16x32_bf16 v[64:67], v[176:179], v[218:221], v[64:67]
	v_mfma_f32_16x16x32_bf16 v[68:71], v[148:151], v[218:221], v[68:71]
	v_mfma_f32_16x16x32_bf16 v[68:71], v[144:147], v[214:217], v[68:71]
	s_barrier
	s_setprio 0
	s_add_i32 s54, s82, s65
	v_lshl_add_u64 v[222:223], v[222:223], 0, s[28:29]
	s_mov_b32 m0, s54
	ds_read_b128 v[180:183], v191 offset:49152
	v_xor_b32_e32 v253, 64, v191
	ds_read_b128 v[194:197], v253 offset:49152
	ds_read_b128 v[198:201], v191 offset:51200
	ds_read_b128 v[202:205], v253 offset:51200
	ds_read_b128 v[206:209], v191 offset:53248
	ds_read_b128 v[210:213], v253 offset:53248
	ds_read_b128 v[214:217], v191 offset:55296
	ds_read_b128 v[218:221], v253 offset:55296
	global_load_lds_dwordx4 v[222:223], off
	s_add_i32 m0, s54, 0x2000
	s_add_u32 s54, s58, 0xb0080
	v_lshl_add_u64 v[222:223], v[224:225], 0, s[28:29]
	s_addc_u32 s55, s59, 0
	s_add_i32 s58, s83, s65
	global_load_lds_dwordx4 v[222:223], off
	v_lshl_add_u64 v[222:223], s[54:55], 0, v[154:155]
	s_mov_b32 m0, s58
	s_nop 0
	global_load_lds_dwordx4 v[222:223], off
	v_lshl_add_u64 v[222:223], s[54:55], 0, v[162:163]
	s_add_i32 m0, s58, 0x2000
	s_nop 0
	global_load_lds_dwordx4 v[222:223], off
	v_lshl_add_u64 v[222:223], v[226:227], 0, s[28:29]
	s_mov_b32 m0, s3
	s_nop 0
	global_load_lds_dwordx4 v[222:223], off
	v_lshl_add_u64 v[222:223], v[228:229], 0, s[28:29]
	s_mov_b32 m0, s71
	s_nop 0
	global_load_lds_dwordx4 v[222:223], off
	s_waitcnt vmcnt(8)
	s_waitcnt lgkmcnt(0)
	s_setprio 1
	s_barrier
	v_mfma_f32_16x16x32_bf16 v[60:63], v[128:131], v[180:183], v[60:63]
	v_mfma_f32_16x16x32_bf16 v[60:63], v[132:135], v[194:197], v[60:63]
	v_mfma_f32_16x16x32_bf16 v[56:59], v[140:143], v[194:197], v[56:59]
	v_mfma_f32_16x16x32_bf16 v[56:59], v[136:139], v[180:183], v[56:59]
	v_mfma_f32_16x16x32_bf16 v[40:43], v[136:139], v[198:201], v[40:43]
	v_mfma_f32_16x16x32_bf16 v[40:43], v[140:143], v[202:205], v[40:43]
	v_mfma_f32_16x16x32_bf16 v[44:47], v[132:135], v[202:205], v[44:47]
	v_mfma_f32_16x16x32_bf16 v[44:47], v[128:131], v[198:201], v[44:47]
	v_mfma_f32_16x16x32_bf16 v[28:31], v[128:131], v[206:209], v[28:31]
	v_mfma_f32_16x16x32_bf16 v[28:31], v[132:135], v[210:213], v[28:31]
	v_mfma_f32_16x16x32_bf16 v[24:27], v[140:143], v[210:213], v[24:27]
	v_mfma_f32_16x16x32_bf16 v[24:27], v[136:139], v[206:209], v[24:27]
	v_mfma_f32_16x16x32_bf16 v[8:11], v[136:139], v[214:217], v[8:11]
	v_mfma_f32_16x16x32_bf16 v[8:11], v[140:143], v[218:221], v[8:11]
	v_mfma_f32_16x16x32_bf16 v[12:15], v[132:135], v[218:221], v[12:15]
	v_mfma_f32_16x16x32_bf16 v[12:15], v[128:131], v[214:217], v[12:15]
	s_setprio 0
	s_setprio 1
	v_mfma_f32_16x16x32_bf16 v[52:55], v[144:147], v[180:183], v[52:55]
	v_mfma_f32_16x16x32_bf16 v[52:55], v[148:151], v[194:197], v[52:55]
	v_mfma_f32_16x16x32_bf16 v[48:51], v[176:179], v[194:197], v[48:51]
	v_mfma_f32_16x16x32_bf16 v[48:51], v[172:175], v[180:183], v[48:51]
	v_mfma_f32_16x16x32_bf16 v[32:35], v[172:175], v[198:201], v[32:35]
	v_mfma_f32_16x16x32_bf16 v[32:35], v[176:179], v[202:205], v[32:35]
	v_mfma_f32_16x16x32_bf16 v[36:39], v[148:151], v[202:205], v[36:39]
	v_mfma_f32_16x16x32_bf16 v[36:39], v[144:147], v[198:201], v[36:39]
	v_mfma_f32_16x16x32_bf16 v[20:23], v[144:147], v[206:209], v[20:23]
	v_mfma_f32_16x16x32_bf16 v[20:23], v[148:151], v[210:213], v[20:23]
	v_mfma_f32_16x16x32_bf16 v[16:19], v[176:179], v[210:213], v[16:19]
	v_mfma_f32_16x16x32_bf16 v[16:19], v[172:175], v[206:209], v[16:19]
	v_mfma_f32_16x16x32_bf16 v[0:3], v[172:175], v[214:217], v[0:3]
	v_mfma_f32_16x16x32_bf16 v[0:3], v[176:179], v[218:221], v[0:3]
	v_mfma_f32_16x16x32_bf16 v[4:7], v[148:151], v[218:221], v[4:7]
	v_mfma_f32_16x16x32_bf16 v[4:7], v[144:147], v[214:217], v[4:7]
	s_barrier
	s_setprio 0
	s_add_i32 s81, s81, 2
	s_add_u32 s79, s79, 0x100
	s_addc_u32 s80, s80, 0
	s_cmp_gt_u32 s81, 41
	s_mov_b64 s[54:55], s[56:57]
	s_cbranch_scc0 .LBB0_610
	s_and_b64 vcc, exec, s[30:31]
	s_cbranch_vccz .LBB0_613
	s_barrier

.LBB0_873:
	s_ashr_i32 s49, s48, 31
	s_lshl_b64 s[50:51], s[48:49], 19
	s_add_u32 s50, s35, s50
	s_addc_u32 s51, s60, s51
	s_and_b64 s[52:53], s[10:11], exec
	s_cselect_b32 s49, s51, s59
	s_cselect_b32 s80, s50, s58
	s_ashr_i32 s47, s46, 31
	s_lshl_b64 s[52:53], s[46:47], 19
	s_add_u32 s52, s61, s52
	s_addc_u32 s53, s62, s53
	s_and_b64 s[82:83], s[10:11], exec
	s_cselect_b32 s81, s53, s57
	s_cselect_b32 s82, s52, s56
	s_lshl_b32 s47, s54, 8
	v_add_u32_e32 v0, s47, v151
	s_add_u32 s83, s56, 0x100
	v_ashrrev_i32_e32 v1, 31, v0
	s_addc_u32 s84, s57, 0
	v_lshl_add_u64 v[144:145], v[0:1], 4, s[20:21]
	s_add_u32 s54, s58, 0x40080
	s_addc_u32 s55, s59, 0
	s_mov_b32 s85, -2
	s_mov_b64 s[56:57], 0
	s_cmp_eq_u32 s68, 1
	s_cbranch_scc1 .Lfa_8
	v_add_u32_e32 v146, s73, v149
	ds_read_b128 v[162:165], v146
	v_xor_b32_e32 v253, 64, v146
	ds_read_b128 v[166:169], v253
	ds_read_b128 v[170:173], v146 offset:2048
	ds_read_b128 v[174:177], v253 offset:2048
	v_add_u32_e32 v146, s74, v149
	ds_read_b128 v[178:181], v146
	v_xor_b32_e32 v253, 64, v146
	ds_read_b128 v[186:189], v253
	ds_read_b128 v[190:193], v146 offset:2048
	ds_read_b128 v[194:197], v253 offset:2048
	s_add_u32 s58, s54, 0xfffc0080
	s_addc_u32 s59, s55, -1
	s_and_b64 s[56:57], s[56:57], exec
	s_cselect_b32 s59, s49, s59
	s_cselect_b32 s58, s80, s58
	s_cselect_b32 s57, s81, s84
	s_cselect_b32 s56, s82, s83
	v_lshl_add_u64 v[182:183], s[54:55], 0, v[138:139]
	s_add_i32 m0, s64, 0xc000
	ds_read_b128 v[198:201], v154
	v_xor_b32_e32 v253, 64, v154
	ds_read_b128 v[202:205], v253
	ds_read_b128 v[206:209], v154 offset:2048
	ds_read_b128 v[210:213], v253 offset:2048
	ds_read_b128 v[214:217], v154 offset:4096
	ds_read_b128 v[218:221], v253 offset:4096
	ds_read_b128 v[222:225], v154 offset:6144
	ds_read_b128 v[226:229], v253 offset:6144
	global_load_lds_dwordx4 v[182:183], off
	v_lshl_add_u64 v[182:183], s[54:55], 0, v[136:137]
	s_add_i32 m0, s64, 0xe000
	s_nop 0
	global_load_lds_dwordx4 v[182:183], off
	s_waitcnt vmcnt(24)
	s_waitcnt lgkmcnt(0)
	s_setprio 1
	s_barrier
	v_mfma_f32_16x16x32_bf16 v[124:127], v[162:165], v[198:201], 0
	v_mfma_f32_16x16x32_bf16 v[120:123], v[170:173], v[198:201], 0
	v_mfma_f32_16x16x32_bf16 v[112:115], v[162:165], v[206:209], 0
	v_mfma_f32_16x16x32_bf16 v[104:107], v[170:173], v[206:209], 0
	v_mfma_f32_16x16x32_bf16 v[96:99], v[162:165], v[214:217], 0
	v_mfma_f32_16x16x32_bf16 v[88:91], v[170:173], v[214:217], 0
	v_mfma_f32_16x16x32_bf16 v[80:83], v[162:165], v[222:225], 0
	v_mfma_f32_16x16x32_bf16 v[72:75], v[170:173], v[222:225], 0
	v_mfma_f32_16x16x32_bf16 v[124:127], v[166:169], v[202:205], v[124:127]
	v_mfma_f32_16x16x32_bf16 v[120:123], v[174:177], v[202:205], v[120:123]
	v_mfma_f32_16x16x32_bf16 v[112:115], v[166:169], v[210:213], v[112:115]
	v_mfma_f32_16x16x32_bf16 v[104:107], v[174:177], v[210:213], v[104:107]
	v_mfma_f32_16x16x32_bf16 v[96:99], v[166:169], v[218:221], v[96:99]
	v_mfma_f32_16x16x32_bf16 v[88:91], v[174:177], v[218:221], v[88:91]
	v_mfma_f32_16x16x32_bf16 v[80:83], v[166:169], v[226:229], v[80:83]
	v_mfma_f32_16x16x32_bf16 v[72:75], v[174:177], v[226:229], v[72:75]
	s_setprio 0
	s_setprio 1
	v_mfma_f32_16x16x32_bf16 v[116:119], v[178:181], v[198:201], 0
	v_mfma_f32_16x16x32_bf16 v[108:111], v[190:193], v[198:201], 0
	v_mfma_f32_16x16x32_bf16 v[100:103], v[178:181], v[206:209], 0
	v_mfma_f32_16x16x32_bf16 v[92:95], v[190:193], v[206:209], 0
	v_mfma_f32_16x16x32_bf16 v[84:87], v[178:181], v[214:217], 0
	v_mfma_f32_16x16x32_bf16 v[76:79], v[190:193], v[214:217], 0
	v_mfma_f32_16x16x32_bf16 v[68:71], v[178:181], v[222:225], 0
	v_mfma_f32_16x16x32_bf16 v[64:67], v[190:193], v[222:225], 0
	v_mfma_f32_16x16x32_bf16 v[116:119], v[186:189], v[202:205], v[116:119]
	v_mfma_f32_16x16x32_bf16 v[108:111], v[194:197], v[202:205], v[108:111]
	v_mfma_f32_16x16x32_bf16 v[100:103], v[186:189], v[210:213], v[100:103]
	v_mfma_f32_16x16x32_bf16 v[92:95], v[194:197], v[210:213], v[92:95]
	v_mfma_f32_16x16x32_bf16 v[84:87], v[186:189], v[218:221], v[84:87]
	v_mfma_f32_16x16x32_bf16 v[76:79], v[194:197], v[218:221], v[76:79]
	v_mfma_f32_16x16x32_bf16 v[68:71], v[186:189], v[226:229], v[68:71]
	v_mfma_f32_16x16x32_bf16 v[64:67], v[194:197], v[226:229], v[64:67]
	s_barrier
	s_setprio 0
	s_add_i32 s86, s73, s63
	v_lshl_add_u64 v[182:183], s[56:57], 0, v[130:131]
	s_mov_b32 m0, s86
	ds_read_b128 v[198:201], v154 offset:16384
	v_xor_b32_e32 v253, 64, v154
	ds_read_b128 v[202:205], v253 offset:16384
	ds_read_b128 v[206:209], v154 offset:18432
	ds_read_b128 v[210:213], v253 offset:18432
	ds_read_b128 v[214:217], v154 offset:20480
	ds_read_b128 v[218:221], v253 offset:20480
	ds_read_b128 v[222:225], v154 offset:22528
	ds_read_b128 v[226:229], v253 offset:22528
	global_load_lds_dwordx4 v[182:183], off
	s_add_i32 m0, s86, 0x2000
	s_add_u32 s86, s56, 0x40000
	v_lshl_add_u64 v[230:231], s[56:57], 0, v[134:135]
	s_addc_u32 s87, s57, 0
	s_add_i32 s88, s74, s63
	global_load_lds_dwordx4 v[230:231], off
	v_lshl_add_u64 v[232:233], s[86:87], 0, v[130:131]
	s_mov_b32 m0, s88
	v_lshl_add_u64 v[234:235], s[58:59], 0, v[132:133]
	global_load_lds_dwordx4 v[232:233], off
	v_lshl_add_u64 v[232:233], s[86:87], 0, v[134:135]
	s_add_i32 m0, s88, 0x2000
	s_nop 0
	global_load_lds_dwordx4 v[232:233], off
	v_lshl_add_u64 v[232:233], s[58:59], 0, v[128:129]
	s_mov_b32 m0, s64
	s_nop 0
	global_load_lds_dwordx4 v[232:233], off
	s_mov_b32 m0, s65
	s_nop 0
	global_load_lds_dwordx4 v[234:235], off
	s_waitcnt vmcnt(24)
	s_waitcnt lgkmcnt(0)
	s_setprio 1
	s_barrier
	v_mfma_f32_16x16x32_bf16 v[60:63], v[162:165], v[198:201], 0
	v_mfma_f32_16x16x32_bf16 v[56:59], v[170:173], v[198:201], 0
	v_mfma_f32_16x16x32_bf16 v[48:51], v[162:165], v[206:209], 0
	v_mfma_f32_16x16x32_bf16 v[40:43], v[170:173], v[206:209], 0
	v_mfma_f32_16x16x32_bf16 v[32:35], v[162:165], v[214:217], 0
	v_mfma_f32_16x16x32_bf16 v[24:27], v[170:173], v[214:217], 0
	v_mfma_f32_16x16x32_bf16 v[16:19], v[162:165], v[222:225], 0
	v_mfma_f32_16x16x32_bf16 v[8:11], v[170:173], v[222:225], 0
	v_mfma_f32_16x16x32_bf16 v[60:63], v[166:169], v[202:205], v[60:63]
	v_mfma_f32_16x16x32_bf16 v[56:59], v[174:177], v[202:205], v[56:59]
	v_mfma_f32_16x16x32_bf16 v[48:51], v[166:169], v[210:213], v[48:51]
	v_mfma_f32_16x16x32_bf16 v[40:43], v[174:177], v[210:213], v[40:43]
	v_mfma_f32_16x16x32_bf16 v[32:35], v[166:169], v[218:221], v[32:35]
	v_mfma_f32_16x16x32_bf16 v[24:27], v[174:177], v[218:221], v[24:27]
	v_mfma_f32_16x16x32_bf16 v[16:19], v[166:169], v[226:229], v[16:19]
	v_mfma_f32_16x16x32_bf16 v[8:11], v[174:177], v[226:229], v[8:11]
	s_setprio 0
	s_setprio 1
	v_mfma_f32_16x16x32_bf16 v[52:55], v[178:181], v[198:201], 0
	v_mfma_f32_16x16x32_bf16 v[44:47], v[190:193], v[198:201], 0
	v_mfma_f32_16x16x32_bf16 v[36:39], v[178:181], v[206:209], 0
	v_mfma_f32_16x16x32_bf16 v[28:31], v[190:193], v[206:209], 0
	v_mfma_f32_16x16x32_bf16 v[20:23], v[178:181], v[214:217], 0
	v_mfma_f32_16x16x32_bf16 v[12:15], v[190:193], v[214:217], 0
	v_mfma_f32_16x16x32_bf16 v[4:7], v[178:181], v[222:225], 0
	v_mfma_f32_16x16x32_bf16 v[0:3], v[190:193], v[222:225], 0
	v_mfma_f32_16x16x32_bf16 v[52:55], v[186:189], v[202:205], v[52:55]
	v_mfma_f32_16x16x32_bf16 v[44:47], v[194:197], v[202:205], v[44:47]
	v_mfma_f32_16x16x32_bf16 v[36:39], v[186:189], v[210:213], v[36:39]
	v_mfma_f32_16x16x32_bf16 v[28:31], v[194:197], v[210:213], v[28:31]
	v_mfma_f32_16x16x32_bf16 v[20:23], v[186:189], v[218:221], v[20:23]
	v_mfma_f32_16x16x32_bf16 v[12:15], v[194:197], v[218:221], v[12:15]
	v_mfma_f32_16x16x32_bf16 v[4:7], v[186:189], v[226:229], v[4:7]
	v_mfma_f32_16x16x32_bf16 v[0:3], v[194:197], v[226:229], v[0:3]
	s_barrier
	s_setprio 0
	s_add_i32 s86, 0, 0x18000
	v_add_u32_e32 v146, s86, v149
	s_add_i32 s87, 0, 0x1c000
	ds_read_b128 v[162:165], v146
	v_xor_b32_e32 v253, 64, v146
	ds_read_b128 v[166:169], v253
	ds_read_b128 v[170:173], v146 offset:2048
	ds_read_b128 v[174:177], v253 offset:2048
	v_add_u32_e32 v146, s87, v149
	ds_read_b128 v[178:181], v146
	v_xor_b32_e32 v253, 64, v146
	ds_read_b128 v[186:189], v253
	ds_read_b128 v[190:193], v146 offset:2048
	ds_read_b128 v[194:197], v253 offset:2048
	s_add_u32 s58, s58, 0x40000
	s_addc_u32 s59, s59, 0
	s_mov_b32 m0, s66
	v_lshl_add_u64 v[236:237], s[58:59], 0, v[128:129]
	ds_read_b128 v[198:201], v154 offset:32768
	v_xor_b32_e32 v253, 64, v154
	ds_read_b128 v[202:205], v253 offset:32768
	ds_read_b128 v[206:209], v154 offset:34816
	ds_read_b128 v[210:213], v253 offset:34816
	ds_read_b128 v[214:217], v154 offset:36864
	ds_read_b128 v[218:221], v253 offset:36864
	ds_read_b128 v[222:225], v154 offset:38912
	ds_read_b128 v[226:229], v253 offset:38912
	global_load_lds_dwordx4 v[236:237], off
	v_lshl_add_u64 v[236:237], s[58:59], 0, v[132:133]
	s_mov_b32 m0, s67
	s_nop 0
	global_load_lds_dwordx4 v[236:237], off
	s_waitcnt vmcnt(8)
	s_waitcnt lgkmcnt(0)
	s_setprio 1
	s_barrier
	v_mfma_f32_16x16x32_bf16 v[124:127], v[162:165], v[198:201], v[124:127]
	v_mfma_f32_16x16x32_bf16 v[124:127], v[166:169], v[202:205], v[124:127]
	v_mfma_f32_16x16x32_bf16 v[120:123], v[174:177], v[202:205], v[120:123]
	v_mfma_f32_16x16x32_bf16 v[120:123], v[170:173], v[198:201], v[120:123]
	v_mfma_f32_16x16x32_bf16 v[104:107], v[170:173], v[206:209], v[104:107]
	v_mfma_f32_16x16x32_bf16 v[104:107], v[174:177], v[210:213], v[104:107]
	v_mfma_f32_16x16x32_bf16 v[112:115], v[166:169], v[210:213], v[112:115]
	v_mfma_f32_16x16x32_bf16 v[112:115], v[162:165], v[206:209], v[112:115]
	v_mfma_f32_16x16x32_bf16 v[96:99], v[162:165], v[214:217], v[96:99]
	v_mfma_f32_16x16x32_bf16 v[96:99], v[166:169], v[218:221], v[96:99]
	v_mfma_f32_16x16x32_bf16 v[88:91], v[174:177], v[218:221], v[88:91]
	v_mfma_f32_16x16x32_bf16 v[88:91], v[170:173], v[214:217], v[88:91]
	v_mfma_f32_16x16x32_bf16 v[72:75], v[170:173], v[222:225], v[72:75]
	v_mfma_f32_16x16x32_bf16 v[72:75], v[174:177], v[226:229], v[72:75]
	v_mfma_f32_16x16x32_bf16 v[80:83], v[166:169], v[226:229], v[80:83]
	v_mfma_f32_16x16x32_bf16 v[80:83], v[162:165], v[222:225], v[80:83]
	s_setprio 0
	s_setprio 1
	v_mfma_f32_16x16x32_bf16 v[116:119], v[178:181], v[198:201], v[116:119]
	v_mfma_f32_16x16x32_bf16 v[116:119], v[186:189], v[202:205], v[116:119]
	v_mfma_f32_16x16x32_bf16 v[108:111], v[194:197], v[202:205], v[108:111]
	v_mfma_f32_16x16x32_bf16 v[108:111], v[190:193], v[198:201], v[108:111]
	v_mfma_f32_16x16x32_bf16 v[92:95], v[190:193], v[206:209], v[92:95]
	v_mfma_f32_16x16x32_bf16 v[92:95], v[194:197], v[210:213], v[92:95]
	v_mfma_f32_16x16x32_bf16 v[100:103], v[186:189], v[210:213], v[100:103]
	v_mfma_f32_16x16x32_bf16 v[100:103], v[178:181], v[206:209], v[100:103]
	v_mfma_f32_16x16x32_bf16 v[84:87], v[178:181], v[214:217], v[84:87]
	v_mfma_f32_16x16x32_bf16 v[84:87], v[186:189], v[218:221], v[84:87]
	v_mfma_f32_16x16x32_bf16 v[76:79], v[194:197], v[218:221], v[76:79]
	v_mfma_f32_16x16x32_bf16 v[76:79], v[190:193], v[214:217], v[76:79]
	v_mfma_f32_16x16x32_bf16 v[64:67], v[190:193], v[222:225], v[64:67]
	v_mfma_f32_16x16x32_bf16 v[64:67], v[194:197], v[226:229], v[64:67]
	v_mfma_f32_16x16x32_bf16 v[68:71], v[186:189], v[226:229], v[68:71]
	v_mfma_f32_16x16x32_bf16 v[68:71], v[178:181], v[222:225], v[68:71]
	s_barrier
	s_setprio 0
	s_add_i32 s58, s86, s63
	v_lshl_add_u64 v[182:183], v[182:183], 0, s[22:23]
	s_mov_b32 m0, s58
	ds_read_b128 v[198:201], v154 offset:49152
	v_xor_b32_e32 v253, 64, v154
	ds_read_b128 v[202:205], v253 offset:49152
	ds_read_b128 v[206:209], v154 offset:51200
	ds_read_b128 v[210:213], v253 offset:51200
	ds_read_b128 v[214:217], v154 offset:53248
	ds_read_b128 v[218:221], v253 offset:53248
	ds_read_b128 v[222:225], v154 offset:55296
	ds_read_b128 v[226:229], v253 offset:55296
	global_load_lds_dwordx4 v[182:183], off
	s_add_i32 m0, s58, 0x2000
	s_add_u32 s56, s56, 0x40080
	v_lshl_add_u64 v[182:183], v[230:231], 0, s[22:23]
	s_addc_u32 s57, s57, 0
	s_add_i32 s58, s87, s63
	global_load_lds_dwordx4 v[182:183], off
	v_lshl_add_u64 v[182:183], s[56:57], 0, v[130:131]
	s_mov_b32 m0, s58
	s_nop 0
	global_load_lds_dwordx4 v[182:183], off
	v_lshl_add_u64 v[182:183], s[56:57], 0, v[134:135]
	s_add_i32 m0, s58, 0x2000
	s_nop 0
	global_load_lds_dwordx4 v[182:183], off
	v_lshl_add_u64 v[182:183], v[232:233], 0, s[22:23]
	s_mov_b32 m0, s69
	s_nop 0
	global_load_lds_dwordx4 v[182:183], off
	v_lshl_add_u64 v[182:183], v[234:235], 0, s[22:23]
	s_mov_b32 m0, s70
	s_nop 0
	global_load_lds_dwordx4 v[182:183], off
	s_waitcnt vmcnt(8)
	s_waitcnt lgkmcnt(0)
	s_setprio 1
	s_barrier
	v_mfma_f32_16x16x32_bf16 v[60:63], v[162:165], v[198:201], v[60:63]
	v_mfma_f32_16x16x32_bf16 v[60:63], v[166:169], v[202:205], v[60:63]
	v_mfma_f32_16x16x32_bf16 v[56:59], v[174:177], v[202:205], v[56:59]
	v_mfma_f32_16x16x32_bf16 v[56:59], v[170:173], v[198:201], v[56:59]
	v_mfma_f32_16x16x32_bf16 v[40:43], v[170:173], v[206:209], v[40:43]
	v_mfma_f32_16x16x32_bf16 v[40:43], v[174:177], v[210:213], v[40:43]
	v_mfma_f32_16x16x32_bf16 v[48:51], v[166:169], v[210:213], v[48:51]
	v_mfma_f32_16x16x32_bf16 v[48:51], v[162:165], v[206:209], v[48:51]
	v_mfma_f32_16x16x32_bf16 v[32:35], v[162:165], v[214:217], v[32:35]
	v_mfma_f32_16x16x32_bf16 v[32:35], v[166:169], v[218:221], v[32:35]
	v_mfma_f32_16x16x32_bf16 v[24:27], v[174:177], v[218:221], v[24:27]
	v_mfma_f32_16x16x32_bf16 v[24:27], v[170:173], v[214:217], v[24:27]
	v_mfma_f32_16x16x32_bf16 v[8:11], v[170:173], v[222:225], v[8:11]
	v_mfma_f32_16x16x32_bf16 v[8:11], v[174:177], v[226:229], v[8:11]
	v_mfma_f32_16x16x32_bf16 v[16:19], v[166:169], v[226:229], v[16:19]
	v_mfma_f32_16x16x32_bf16 v[16:19], v[162:165], v[222:225], v[16:19]
	s_setprio 0
	s_setprio 1
	v_mfma_f32_16x16x32_bf16 v[52:55], v[178:181], v[198:201], v[52:55]
	v_mfma_f32_16x16x32_bf16 v[52:55], v[186:189], v[202:205], v[52:55]
	v_mfma_f32_16x16x32_bf16 v[44:47], v[194:197], v[202:205], v[44:47]
	v_mfma_f32_16x16x32_bf16 v[44:47], v[190:193], v[198:201], v[44:47]
	v_mfma_f32_16x16x32_bf16 v[28:31], v[190:193], v[206:209], v[28:31]
	v_mfma_f32_16x16x32_bf16 v[28:31], v[194:197], v[210:213], v[28:31]
	v_mfma_f32_16x16x32_bf16 v[36:39], v[186:189], v[210:213], v[36:39]
	v_mfma_f32_16x16x32_bf16 v[36:39], v[178:181], v[206:209], v[36:39]
	v_mfma_f32_16x16x32_bf16 v[20:23], v[178:181], v[214:217], v[20:23]
	v_mfma_f32_16x16x32_bf16 v[20:23], v[186:189], v[218:221], v[20:23]
	v_mfma_f32_16x16x32_bf16 v[12:15], v[194:197], v[218:221], v[12:15]
	v_mfma_f32_16x16x32_bf16 v[12:15], v[190:193], v[214:217], v[12:15]
	v_mfma_f32_16x16x32_bf16 v[0:3], v[190:193], v[222:225], v[0:3]
	v_mfma_f32_16x16x32_bf16 v[0:3], v[194:197], v[226:229], v[0:3]
	v_mfma_f32_16x16x32_bf16 v[4:7], v[186:189], v[226:229], v[4:7]
	v_mfma_f32_16x16x32_bf16 v[4:7], v[178:181], v[222:225], v[4:7]
	s_barrier
	s_setprio 0
	s_add_i32 s85, s85, 2
	s_add_u32 s83, s83, 0x100
	s_addc_u32 s84, s84, 0
	s_add_u32 s54, s54, 0x100
	s_addc_u32 s55, s55, 0
	s_branch .LBB0_875
.Lfa_8:
	v_add_u32_e32 v146, s73, v149
	ds_read_b128 v[162:165], v146
	v_xor_b32_e32 v253, 64, v146
	ds_read_b128 v[166:169], v253
	ds_read_b128 v[170:173], v146 offset:2048
	ds_read_b128 v[174:177], v253 offset:2048
	v_add_u32_e32 v146, s74, v149
	ds_read_b128 v[178:181], v146
	v_xor_b32_e32 v253, 64, v146
	ds_read_b128 v[186:189], v253
	ds_read_b128 v[190:193], v146 offset:2048
	ds_read_b128 v[194:197], v253 offset:2048
	s_add_u32 s58, s54, 0xfffc0080
	s_addc_u32 s59, s55, -1
	s_and_b64 s[56:57], s[56:57], exec
	s_cselect_b32 s59, s49, s59
	s_cselect_b32 s58, s80, s58
	s_cselect_b32 s57, s81, s84
	s_cselect_b32 s56, s82, s83
	v_lshl_add_u64 v[182:183], s[54:55], 0, v[138:139]
	s_add_i32 m0, s64, 0xc000
	ds_read_b128 v[198:201], v154
	v_xor_b32_e32 v253, 64, v154
	ds_read_b128 v[202:205], v253
	ds_read_b128 v[206:209], v154 offset:2048
	ds_read_b128 v[210:213], v253 offset:2048
	ds_read_b128 v[214:217], v154 offset:4096
	ds_read_b128 v[218:221], v253 offset:4096
	ds_read_b128 v[222:225], v154 offset:6144
	ds_read_b128 v[226:229], v253 offset:6144
	global_load_lds_dwordx4 v[182:183], off
	v_lshl_add_u64 v[182:183], s[54:55], 0, v[136:137]
	s_add_i32 m0, s64, 0xe000
	s_nop 0
	global_load_lds_dwordx4 v[182:183], off
	s_waitcnt vmcnt(8)
	s_waitcnt lgkmcnt(0)
	s_setprio 1
	s_barrier
	v_mfma_f32_16x16x32_bf16 v[124:127], v[162:165], v[198:201], 0
	v_mfma_f32_16x16x32_bf16 v[120:123], v[170:173], v[198:201], 0
	v_mfma_f32_16x16x32_bf16 v[112:115], v[162:165], v[206:209], 0
	v_mfma_f32_16x16x32_bf16 v[104:107], v[170:173], v[206:209], 0
	v_mfma_f32_16x16x32_bf16 v[96:99], v[162:165], v[214:217], 0
	v_mfma_f32_16x16x32_bf16 v[88:91], v[170:173], v[214:217], 0
	v_mfma_f32_16x16x32_bf16 v[80:83], v[162:165], v[222:225], 0
	v_mfma_f32_16x16x32_bf16 v[72:75], v[170:173], v[222:225], 0
	v_mfma_f32_16x16x32_bf16 v[124:127], v[166:169], v[202:205], v[124:127]
	v_mfma_f32_16x16x32_bf16 v[120:123], v[174:177], v[202:205], v[120:123]
	v_mfma_f32_16x16x32_bf16 v[112:115], v[166:169], v[210:213], v[112:115]
	v_mfma_f32_16x16x32_bf16 v[104:107], v[174:177], v[210:213], v[104:107]
	v_mfma_f32_16x16x32_bf16 v[96:99], v[166:169], v[218:221], v[96:99]
	v_mfma_f32_16x16x32_bf16 v[88:91], v[174:177], v[218:221], v[88:91]
	v_mfma_f32_16x16x32_bf16 v[80:83], v[166:169], v[226:229], v[80:83]
	v_mfma_f32_16x16x32_bf16 v[72:75], v[174:177], v[226:229], v[72:75]
	s_setprio 0
	s_setprio 1
	v_mfma_f32_16x16x32_bf16 v[116:119], v[178:181], v[198:201], 0
	v_mfma_f32_16x16x32_bf16 v[108:111], v[190:193], v[198:201], 0
	v_mfma_f32_16x16x32_bf16 v[100:103], v[178:181], v[206:209], 0
	v_mfma_f32_16x16x32_bf16 v[92:95], v[190:193], v[206:209], 0
	v_mfma_f32_16x16x32_bf16 v[84:87], v[178:181], v[214:217], 0
	v_mfma_f32_16x16x32_bf16 v[76:79], v[190:193], v[214:217], 0
	v_mfma_f32_16x16x32_bf16 v[68:71], v[178:181], v[222:225], 0
	v_mfma_f32_16x16x32_bf16 v[64:67], v[190:193], v[222:225], 0
	v_mfma_f32_16x16x32_bf16 v[116:119], v[186:189], v[202:205], v[116:119]
	v_mfma_f32_16x16x32_bf16 v[108:111], v[194:197], v[202:205], v[108:111]
	v_mfma_f32_16x16x32_bf16 v[100:103], v[186:189], v[210:213], v[100:103]
	v_mfma_f32_16x16x32_bf16 v[92:95], v[194:197], v[210:213], v[92:95]
	v_mfma_f32_16x16x32_bf16 v[84:87], v[186:189], v[218:221], v[84:87]
	v_mfma_f32_16x16x32_bf16 v[76:79], v[194:197], v[218:221], v[76:79]
	v_mfma_f32_16x16x32_bf16 v[68:71], v[186:189], v[226:229], v[68:71]
	v_mfma_f32_16x16x32_bf16 v[64:67], v[194:197], v[226:229], v[64:67]
	s_barrier
	s_setprio 0
	s_add_i32 s86, s73, s63
	v_lshl_add_u64 v[182:183], s[56:57], 0, v[130:131]
	s_mov_b32 m0, s86
	ds_read_b128 v[198:201], v154 offset:16384
	v_xor_b32_e32 v253, 64, v154
	ds_read_b128 v[202:205], v253 offset:16384
	ds_read_b128 v[206:209], v154 offset:18432
	ds_read_b128 v[210:213], v253 offset:18432
	ds_read_b128 v[214:217], v154 offset:20480
	ds_read_b128 v[218:221], v253 offset:20480
	ds_read_b128 v[222:225], v154 offset:22528
	ds_read_b128 v[226:229], v253 offset:22528
	global_load_lds_dwordx4 v[182:183], off
	s_add_i32 m0, s86, 0x2000
	s_add_u32 s86, s56, 0x40000
	v_lshl_add_u64 v[230:231], s[56:57], 0, v[134:135]
	s_addc_u32 s87, s57, 0
	s_add_i32 s88, s74, s63
	global_load_lds_dwordx4 v[230:231], off
	v_lshl_add_u64 v[232:233], s[86:87], 0, v[130:131]
	s_mov_b32 m0, s88
	v_lshl_add_u64 v[234:235], s[58:59], 0, v[132:133]
	global_load_lds_dwordx4 v[232:233], off
	v_lshl_add_u64 v[232:233], s[86:87], 0, v[134:135]
	s_add_i32 m0, s88, 0x2000
	s_nop 0
	global_load_lds_dwordx4 v[232:233], off
	v_lshl_add_u64 v[232:233], s[58:59], 0, v[128:129]
	s_mov_b32 m0, s64
	s_nop 0
	global_load_lds_dwordx4 v[232:233], off
	s_mov_b32 m0, s65
	s_nop 0
	global_load_lds_dwordx4 v[234:235], off
	s_waitcnt vmcnt(8)
	s_waitcnt lgkmcnt(0)
	s_setprio 1
	s_barrier
	v_mfma_f32_16x16x32_bf16 v[60:63], v[162:165], v[198:201], 0
	v_mfma_f32_16x16x32_bf16 v[56:59], v[170:173], v[198:201], 0
	v_mfma_f32_16x16x32_bf16 v[48:51], v[162:165], v[206:209], 0
	v_mfma_f32_16x16x32_bf16 v[40:43], v[170:173], v[206:209], 0
	v_mfma_f32_16x16x32_bf16 v[32:35], v[162:165], v[214:217], 0
	v_mfma_f32_16x16x32_bf16 v[24:27], v[170:173], v[214:217], 0
	v_mfma_f32_16x16x32_bf16 v[16:19], v[162:165], v[222:225], 0
	v_mfma_f32_16x16x32_bf16 v[8:11], v[170:173], v[222:225], 0
	v_mfma_f32_16x16x32_bf16 v[60:63], v[166:169], v[202:205], v[60:63]
	v_mfma_f32_16x16x32_bf16 v[56:59], v[174:177], v[202:205], v[56:59]
	v_mfma_f32_16x16x32_bf16 v[48:51], v[166:169], v[210:213], v[48:51]
	v_mfma_f32_16x16x32_bf16 v[40:43], v[174:177], v[210:213], v[40:43]
	v_mfma_f32_16x16x32_bf16 v[32:35], v[166:169], v[218:221], v[32:35]
	v_mfma_f32_16x16x32_bf16 v[24:27], v[174:177], v[218:221], v[24:27]
	v_mfma_f32_16x16x32_bf16 v[16:19], v[166:169], v[226:229], v[16:19]
	v_mfma_f32_16x16x32_bf16 v[8:11], v[174:177], v[226:229], v[8:11]
	s_setprio 0
	s_setprio 1
	v_mfma_f32_16x16x32_bf16 v[52:55], v[178:181], v[198:201], 0
	v_mfma_f32_16x16x32_bf16 v[44:47], v[190:193], v[198:201], 0
	v_mfma_f32_16x16x32_bf16 v[36:39], v[178:181], v[206:209], 0
	v_mfma_f32_16x16x32_bf16 v[28:31], v[190:193], v[206:209], 0
	v_mfma_f32_16x16x32_bf16 v[20:23], v[178:181], v[214:217], 0
	v_mfma_f32_16x16x32_bf16 v[12:15], v[190:193], v[214:217], 0
	v_mfma_f32_16x16x32_bf16 v[4:7], v[178:181], v[222:225], 0
	v_mfma_f32_16x16x32_bf16 v[0:3], v[190:193], v[222:225], 0
	v_mfma_f32_16x16x32_bf16 v[52:55], v[186:189], v[202:205], v[52:55]
	v_mfma_f32_16x16x32_bf16 v[44:47], v[194:197], v[202:205], v[44:47]
	v_mfma_f32_16x16x32_bf16 v[36:39], v[186:189], v[210:213], v[36:39]
	v_mfma_f32_16x16x32_bf16 v[28:31], v[194:197], v[210:213], v[28:31]
	v_mfma_f32_16x16x32_bf16 v[20:23], v[186:189], v[218:221], v[20:23]
	v_mfma_f32_16x16x32_bf16 v[12:15], v[194:197], v[218:221], v[12:15]
	v_mfma_f32_16x16x32_bf16 v[4:7], v[186:189], v[226:229], v[4:7]
	v_mfma_f32_16x16x32_bf16 v[0:3], v[194:197], v[226:229], v[0:3]
	s_barrier
	s_setprio 0
	s_add_i32 s86, 0, 0x18000
	v_add_u32_e32 v146, s86, v149
	s_add_i32 s87, 0, 0x1c000
	ds_read_b128 v[162:165], v146
	v_xor_b32_e32 v253, 64, v146
	ds_read_b128 v[166:169], v253
	ds_read_b128 v[170:173], v146 offset:2048
	ds_read_b128 v[174:177], v253 offset:2048
	v_add_u32_e32 v146, s87, v149
	ds_read_b128 v[178:181], v146
	v_xor_b32_e32 v253, 64, v146
	ds_read_b128 v[186:189], v253
	ds_read_b128 v[190:193], v146 offset:2048
	ds_read_b128 v[194:197], v253 offset:2048
	s_add_u32 s58, s58, 0x40000
	s_addc_u32 s59, s59, 0
	s_mov_b32 m0, s66
	v_lshl_add_u64 v[236:237], s[58:59], 0, v[128:129]
	ds_read_b128 v[198:201], v154 offset:32768
	v_xor_b32_e32 v253, 64, v154
	ds_read_b128 v[202:205], v253 offset:32768
	ds_read_b128 v[206:209], v154 offset:34816
	ds_read_b128 v[210:213], v253 offset:34816
	ds_read_b128 v[214:217], v154 offset:36864
	ds_read_b128 v[218:221], v253 offset:36864
	ds_read_b128 v[222:225], v154 offset:38912
	ds_read_b128 v[226:229], v253 offset:38912
	global_load_lds_dwordx4 v[236:237], off
	v_lshl_add_u64 v[236:237], s[58:59], 0, v[132:133]
	s_mov_b32 m0, s67
	s_nop 0
	global_load_lds_dwordx4 v[236:237], off
	s_waitcnt vmcnt(8)
	s_waitcnt lgkmcnt(0)
	s_setprio 1
	s_barrier
	v_mfma_f32_16x16x32_bf16 v[124:127], v[162:165], v[198:201], v[124:127]
	v_mfma_f32_16x16x32_bf16 v[124:127], v[166:169], v[202:205], v[124:127]
	v_mfma_f32_16x16x32_bf16 v[120:123], v[174:177], v[202:205], v[120:123]
	v_mfma_f32_16x16x32_bf16 v[120:123], v[170:173], v[198:201], v[120:123]
	v_mfma_f32_16x16x32_bf16 v[104:107], v[170:173], v[206:209], v[104:107]
	v_mfma_f32_16x16x32_bf16 v[104:107], v[174:177], v[210:213], v[104:107]
	v_mfma_f32_16x16x32_bf16 v[112:115], v[166:169], v[210:213], v[112:115]
	v_mfma_f32_16x16x32_bf16 v[112:115], v[162:165], v[206:209], v[112:115]
	v_mfma_f32_16x16x32_bf16 v[96:99], v[162:165], v[214:217], v[96:99]
	v_mfma_f32_16x16x32_bf16 v[96:99], v[166:169], v[218:221], v[96:99]
	v_mfma_f32_16x16x32_bf16 v[88:91], v[174:177], v[218:221], v[88:91]
	v_mfma_f32_16x16x32_bf16 v[88:91], v[170:173], v[214:217], v[88:91]
	v_mfma_f32_16x16x32_bf16 v[72:75], v[170:173], v[222:225], v[72:75]
	v_mfma_f32_16x16x32_bf16 v[72:75], v[174:177], v[226:229], v[72:75]
	v_mfma_f32_16x16x32_bf16 v[80:83], v[166:169], v[226:229], v[80:83]
	v_mfma_f32_16x16x32_bf16 v[80:83], v[162:165], v[222:225], v[80:83]
	s_setprio 0
	s_setprio 1
	v_mfma_f32_16x16x32_bf16 v[116:119], v[178:181], v[198:201], v[116:119]
	v_mfma_f32_16x16x32_bf16 v[116:119], v[186:189], v[202:205], v[116:119]
	v_mfma_f32_16x16x32_bf16 v[108:111], v[194:197], v[202:205], v[108:111]
	v_mfma_f32_16x16x32_bf16 v[108:111], v[190:193], v[198:201], v[108:111]
	v_mfma_f32_16x16x32_bf16 v[92:95], v[190:193], v[206:209], v[92:95]
	v_mfma_f32_16x16x32_bf16 v[92:95], v[194:197], v[210:213], v[92:95]
	v_mfma_f32_16x16x32_bf16 v[100:103], v[186:189], v[210:213], v[100:103]
	v_mfma_f32_16x16x32_bf16 v[100:103], v[178:181], v[206:209], v[100:103]
	v_mfma_f32_16x16x32_bf16 v[84:87], v[178:181], v[214:217], v[84:87]
	v_mfma_f32_16x16x32_bf16 v[84:87], v[186:189], v[218:221], v[84:87]
	v_mfma_f32_16x16x32_bf16 v[76:79], v[194:197], v[218:221], v[76:79]
	v_mfma_f32_16x16x32_bf16 v[76:79], v[190:193], v[214:217], v[76:79]
	v_mfma_f32_16x16x32_bf16 v[64:67], v[190:193], v[222:225], v[64:67]
	v_mfma_f32_16x16x32_bf16 v[64:67], v[194:197], v[226:229], v[64:67]
	v_mfma_f32_16x16x32_bf16 v[68:71], v[186:189], v[226:229], v[68:71]
	v_mfma_f32_16x16x32_bf16 v[68:71], v[178:181], v[222:225], v[68:71]
	s_barrier
	s_setprio 0
	s_add_i32 s58, s86, s63
	v_lshl_add_u64 v[182:183], v[182:183], 0, s[22:23]
	s_mov_b32 m0, s58
	ds_read_b128 v[198:201], v154 offset:49152
	v_xor_b32_e32 v253, 64, v154
	ds_read_b128 v[202:205], v253 offset:49152
	ds_read_b128 v[206:209], v154 offset:51200
	ds_read_b128 v[210:213], v253 offset:51200
	ds_read_b128 v[214:217], v154 offset:53248
	ds_read_b128 v[218:221], v253 offset:53248
	ds_read_b128 v[222:225], v154 offset:55296
	ds_read_b128 v[226:229], v253 offset:55296
	global_load_lds_dwordx4 v[182:183], off
	s_add_i32 m0, s58, 0x2000
	s_add_u32 s56, s56, 0x40080
	v_lshl_add_u64 v[182:183], v[230:231], 0, s[22:23]
	s_addc_u32 s57, s57, 0
	s_add_i32 s58, s87, s63
	global_load_lds_dwordx4 v[182:183], off
	v_lshl_add_u64 v[182:183], s[56:57], 0, v[130:131]
	s_mov_b32 m0, s58
	s_nop 0
	global_load_lds_dwordx4 v[182:183], off
	v_lshl_add_u64 v[182:183], s[56:57], 0, v[134:135]
	s_add_i32 m0, s58, 0x2000
	s_nop 0
	global_load_lds_dwordx4 v[182:183], off
	v_lshl_add_u64 v[182:183], v[232:233], 0, s[22:23]
	s_mov_b32 m0, s69
	s_nop 0
	global_load_lds_dwordx4 v[182:183], off
	v_lshl_add_u64 v[182:183], v[234:235], 0, s[22:23]
	s_mov_b32 m0, s70
	s_nop 0
	global_load_lds_dwordx4 v[182:183], off
	s_waitcnt vmcnt(8)
	s_waitcnt lgkmcnt(0)
	s_setprio 1
	s_barrier
	v_mfma_f32_16x16x32_bf16 v[60:63], v[162:165], v[198:201], v[60:63]
	v_mfma_f32_16x16x32_bf16 v[60:63], v[166:169], v[202:205], v[60:63]
	v_mfma_f32_16x16x32_bf16 v[56:59], v[174:177], v[202:205], v[56:59]
	v_mfma_f32_16x16x32_bf16 v[56:59], v[170:173], v[198:201], v[56:59]
	v_mfma_f32_16x16x32_bf16 v[40:43], v[170:173], v[206:209], v[40:43]
	v_mfma_f32_16x16x32_bf16 v[40:43], v[174:177], v[210:213], v[40:43]
	v_mfma_f32_16x16x32_bf16 v[48:51], v[166:169], v[210:213], v[48:51]
	v_mfma_f32_16x16x32_bf16 v[48:51], v[162:165], v[206:209], v[48:51]
	v_mfma_f32_16x16x32_bf16 v[32:35], v[162:165], v[214:217], v[32:35]
	v_mfma_f32_16x16x32_bf16 v[32:35], v[166:169], v[218:221], v[32:35]
	v_mfma_f32_16x16x32_bf16 v[24:27], v[174:177], v[218:221], v[24:27]
	v_mfma_f32_16x16x32_bf16 v[24:27], v[170:173], v[214:217], v[24:27]
	v_mfma_f32_16x16x32_bf16 v[8:11], v[170:173], v[222:225], v[8:11]
	v_mfma_f32_16x16x32_bf16 v[8:11], v[174:177], v[226:229], v[8:11]
	v_mfma_f32_16x16x32_bf16 v[16:19], v[166:169], v[226:229], v[16:19]
	v_mfma_f32_16x16x32_bf16 v[16:19], v[162:165], v[222:225], v[16:19]
	s_setprio 0
	s_setprio 1
	v_mfma_f32_16x16x32_bf16 v[52:55], v[178:181], v[198:201], v[52:55]
	v_mfma_f32_16x16x32_bf16 v[52:55], v[186:189], v[202:205], v[52:55]
	v_mfma_f32_16x16x32_bf16 v[44:47], v[194:197], v[202:205], v[44:47]
	v_mfma_f32_16x16x32_bf16 v[44:47], v[190:193], v[198:201], v[44:47]
	v_mfma_f32_16x16x32_bf16 v[28:31], v[190:193], v[206:209], v[28:31]
	v_mfma_f32_16x16x32_bf16 v[28:31], v[194:197], v[210:213], v[28:31]
	v_mfma_f32_16x16x32_bf16 v[36:39], v[186:189], v[210:213], v[36:39]
	v_mfma_f32_16x16x32_bf16 v[36:39], v[178:181], v[206:209], v[36:39]
	v_mfma_f32_16x16x32_bf16 v[20:23], v[178:181], v[214:217], v[20:23]
	v_mfma_f32_16x16x32_bf16 v[20:23], v[186:189], v[218:221], v[20:23]
	v_mfma_f32_16x16x32_bf16 v[12:15], v[194:197], v[218:221], v[12:15]
	v_mfma_f32_16x16x32_bf16 v[12:15], v[190:193], v[214:217], v[12:15]
	v_mfma_f32_16x16x32_bf16 v[0:3], v[190:193], v[222:225], v[0:3]
	v_mfma_f32_16x16x32_bf16 v[0:3], v[194:197], v[226:229], v[0:3]
	v_mfma_f32_16x16x32_bf16 v[4:7], v[186:189], v[226:229], v[4:7]
	v_mfma_f32_16x16x32_bf16 v[4:7], v[178:181], v[222:225], v[4:7]
	s_barrier
	s_setprio 0
	s_add_i32 s85, s85, 2
	s_add_u32 s83, s83, 0x100
	s_addc_u32 s84, s84, 0
	s_add_u32 s54, s54, 0x100
	s_addc_u32 s55, s55, 0
	s_branch .LBB0_875
.LBB0_874:
	v_add_u32_e32 v146, s73, v149
	ds_read_b128 v[162:165], v146
	v_xor_b32_e32 v253, 64, v146
	ds_read_b128 v[166:169], v253
	ds_read_b128 v[170:173], v146 offset:2048
	ds_read_b128 v[174:177], v253 offset:2048
	v_add_u32_e32 v146, s74, v149
	ds_read_b128 v[178:181], v146
	v_xor_b32_e32 v253, 64, v146
	ds_read_b128 v[186:189], v253
	ds_read_b128 v[190:193], v146 offset:2048
	ds_read_b128 v[194:197], v253 offset:2048
	s_add_u32 s58, s54, 0xfffc0080
	s_addc_u32 s59, s55, -1
	s_and_b64 s[56:57], s[56:57], exec
	s_cselect_b32 s59, s49, s59
	s_cselect_b32 s58, s80, s58
	s_cselect_b32 s57, s81, s84
	s_cselect_b32 s56, s82, s83
	v_lshl_add_u64 v[182:183], s[54:55], 0, v[138:139]
	s_add_i32 m0, s64, 0xc000
	ds_read_b128 v[198:201], v154
	v_xor_b32_e32 v253, 64, v154
	ds_read_b128 v[202:205], v253
	ds_read_b128 v[206:209], v154 offset:2048
	ds_read_b128 v[210:213], v253 offset:2048
	ds_read_b128 v[214:217], v154 offset:4096
	ds_read_b128 v[218:221], v253 offset:4096
	ds_read_b128 v[222:225], v154 offset:6144
	ds_read_b128 v[226:229], v253 offset:6144
	global_load_lds_dwordx4 v[182:183], off
	v_lshl_add_u64 v[182:183], s[54:55], 0, v[136:137]
	s_add_i32 m0, s64, 0xe000
	s_nop 0
	global_load_lds_dwordx4 v[182:183], off
	s_waitcnt vmcnt(8)
	s_waitcnt lgkmcnt(0)
	s_setprio 1
	s_barrier
	v_mfma_f32_16x16x32_bf16 v[124:127], v[162:165], v[198:201], v[124:127]
	v_mfma_f32_16x16x32_bf16 v[124:127], v[166:169], v[202:205], v[124:127]
	v_mfma_f32_16x16x32_bf16 v[120:123], v[174:177], v[202:205], v[120:123]
	v_mfma_f32_16x16x32_bf16 v[120:123], v[170:173], v[198:201], v[120:123]
	v_mfma_f32_16x16x32_bf16 v[104:107], v[170:173], v[206:209], v[104:107]
	v_mfma_f32_16x16x32_bf16 v[104:107], v[174:177], v[210:213], v[104:107]
	v_mfma_f32_16x16x32_bf16 v[112:115], v[166:169], v[210:213], v[112:115]
	v_mfma_f32_16x16x32_bf16 v[112:115], v[162:165], v[206:209], v[112:115]
	v_mfma_f32_16x16x32_bf16 v[96:99], v[162:165], v[214:217], v[96:99]
	v_mfma_f32_16x16x32_bf16 v[96:99], v[166:169], v[218:221], v[96:99]
	v_mfma_f32_16x16x32_bf16 v[88:91], v[174:177], v[218:221], v[88:91]
	v_mfma_f32_16x16x32_bf16 v[88:91], v[170:173], v[214:217], v[88:91]
	v_mfma_f32_16x16x32_bf16 v[72:75], v[170:173], v[222:225], v[72:75]
	v_mfma_f32_16x16x32_bf16 v[72:75], v[174:177], v[226:229], v[72:75]
	v_mfma_f32_16x16x32_bf16 v[80:83], v[166:169], v[226:229], v[80:83]
	v_mfma_f32_16x16x32_bf16 v[80:83], v[162:165], v[222:225], v[80:83]
	s_setprio 0
	s_setprio 1
	v_mfma_f32_16x16x32_bf16 v[116:119], v[178:181], v[198:201], v[116:119]
	v_mfma_f32_16x16x32_bf16 v[116:119], v[186:189], v[202:205], v[116:119]
	v_mfma_f32_16x16x32_bf16 v[108:111], v[194:197], v[202:205], v[108:111]
	v_mfma_f32_16x16x32_bf16 v[108:111], v[190:193], v[198:201], v[108:111]
	v_mfma_f32_16x16x32_bf16 v[92:95], v[190:193], v[206:209], v[92:95]
	v_mfma_f32_16x16x32_bf16 v[92:95], v[194:197], v[210:213], v[92:95]
	v_mfma_f32_16x16x32_bf16 v[100:103], v[186:189], v[210:213], v[100:103]
	v_mfma_f32_16x16x32_bf16 v[100:103], v[178:181], v[206:209], v[100:103]
	v_mfma_f32_16x16x32_bf16 v[84:87], v[178:181], v[214:217], v[84:87]
	v_mfma_f32_16x16x32_bf16 v[84:87], v[186:189], v[218:221], v[84:87]
	v_mfma_f32_16x16x32_bf16 v[76:79], v[194:197], v[218:221], v[76:79]
	v_mfma_f32_16x16x32_bf16 v[76:79], v[190:193], v[214:217], v[76:79]
	v_mfma_f32_16x16x32_bf16 v[64:67], v[190:193], v[222:225], v[64:67]
	v_mfma_f32_16x16x32_bf16 v[64:67], v[194:197], v[226:229], v[64:67]
	v_mfma_f32_16x16x32_bf16 v[68:71], v[186:189], v[226:229], v[68:71]
	v_mfma_f32_16x16x32_bf16 v[68:71], v[178:181], v[222:225], v[68:71]
	s_barrier
	s_setprio 0
	s_add_i32 s86, s73, s63
	v_lshl_add_u64 v[182:183], s[56:57], 0, v[130:131]
	s_mov_b32 m0, s86
	ds_read_b128 v[198:201], v154 offset:16384
	v_xor_b32_e32 v253, 64, v154
	ds_read_b128 v[202:205], v253 offset:16384
	ds_read_b128 v[206:209], v154 offset:18432
	ds_read_b128 v[210:213], v253 offset:18432
	ds_read_b128 v[214:217], v154 offset:20480
	ds_read_b128 v[218:221], v253 offset:20480
	ds_read_b128 v[222:225], v154 offset:22528
	ds_read_b128 v[226:229], v253 offset:22528
	global_load_lds_dwordx4 v[182:183], off
	s_add_i32 m0, s86, 0x2000
	s_add_u32 s86, s56, 0x40000
	v_lshl_add_u64 v[230:231], s[56:57], 0, v[134:135]
	s_addc_u32 s87, s57, 0
	s_add_i32 s88, s74, s63
	global_load_lds_dwordx4 v[230:231], off
	v_lshl_add_u64 v[232:233], s[86:87], 0, v[130:131]
	s_mov_b32 m0, s88
	v_lshl_add_u64 v[234:235], s[58:59], 0, v[132:133]
	global_load_lds_dwordx4 v[232:233], off
	v_lshl_add_u64 v[232:233], s[86:87], 0, v[134:135]
	s_add_i32 m0, s88, 0x2000
	s_nop 0
	global_load_lds_dwordx4 v[232:233], off
	v_lshl_add_u64 v[232:233], s[58:59], 0, v[128:129]
	s_mov_b32 m0, s64
	s_nop 0
	global_load_lds_dwordx4 v[232:233], off
	s_mov_b32 m0, s65
	s_nop 0
	global_load_lds_dwordx4 v[234:235], off
	s_waitcnt vmcnt(8)
	s_waitcnt lgkmcnt(0)
	s_setprio 1
	s_barrier
	v_mfma_f32_16x16x32_bf16 v[60:63], v[162:165], v[198:201], v[60:63]
	v_mfma_f32_16x16x32_bf16 v[60:63], v[166:169], v[202:205], v[60:63]
	v_mfma_f32_16x16x32_bf16 v[56:59], v[174:177], v[202:205], v[56:59]
	v_mfma_f32_16x16x32_bf16 v[56:59], v[170:173], v[198:201], v[56:59]
	v_mfma_f32_16x16x32_bf16 v[40:43], v[170:173], v[206:209], v[40:43]
	v_mfma_f32_16x16x32_bf16 v[40:43], v[174:177], v[210:213], v[40:43]
	v_mfma_f32_16x16x32_bf16 v[48:51], v[166:169], v[210:213], v[48:51]
	v_mfma_f32_16x16x32_bf16 v[48:51], v[162:165], v[206:209], v[48:51]
	v_mfma_f32_16x16x32_bf16 v[32:35], v[162:165], v[214:217], v[32:35]
	v_mfma_f32_16x16x32_bf16 v[32:35], v[166:169], v[218:221], v[32:35]
	v_mfma_f32_16x16x32_bf16 v[24:27], v[174:177], v[218:221], v[24:27]
	v_mfma_f32_16x16x32_bf16 v[24:27], v[170:173], v[214:217], v[24:27]
	v_mfma_f32_16x16x32_bf16 v[8:11], v[170:173], v[222:225], v[8:11]
	v_mfma_f32_16x16x32_bf16 v[8:11], v[174:177], v[226:229], v[8:11]
	v_mfma_f32_16x16x32_bf16 v[16:19], v[166:169], v[226:229], v[16:19]
	v_mfma_f32_16x16x32_bf16 v[16:19], v[162:165], v[222:225], v[16:19]
	s_setprio 0
	s_setprio 1
	v_mfma_f32_16x16x32_bf16 v[52:55], v[178:181], v[198:201], v[52:55]
	v_mfma_f32_16x16x32_bf16 v[52:55], v[186:189], v[202:205], v[52:55]
	v_mfma_f32_16x16x32_bf16 v[44:47], v[194:197], v[202:205], v[44:47]
	v_mfma_f32_16x16x32_bf16 v[44:47], v[190:193], v[198:201], v[44:47]
	v_mfma_f32_16x16x32_bf16 v[28:31], v[190:193], v[206:209], v[28:31]
	v_mfma_f32_16x16x32_bf16 v[28:31], v[194:197], v[210:213], v[28:31]
	v_mfma_f32_16x16x32_bf16 v[36:39], v[186:189], v[210:213], v[36:39]
	v_mfma_f32_16x16x32_bf16 v[36:39], v[178:181], v[206:209], v[36:39]
	v_mfma_f32_16x16x32_bf16 v[20:23], v[178:181], v[214:217], v[20:23]
	v_mfma_f32_16x16x32_bf16 v[20:23], v[186:189], v[218:221], v[20:23]
	v_mfma_f32_16x16x32_bf16 v[12:15], v[194:197], v[218:221], v[12:15]
	v_mfma_f32_16x16x32_bf16 v[12:15], v[190:193], v[214:217], v[12:15]
	v_mfma_f32_16x16x32_bf16 v[0:3], v[190:193], v[222:225], v[0:3]
	v_mfma_f32_16x16x32_bf16 v[0:3], v[194:197], v[226:229], v[0:3]
	v_mfma_f32_16x16x32_bf16 v[4:7], v[186:189], v[226:229], v[4:7]
	v_mfma_f32_16x16x32_bf16 v[4:7], v[178:181], v[222:225], v[4:7]
	s_barrier
	s_setprio 0
	s_add_i32 s86, 0, 0x18000
	v_add_u32_e32 v146, s86, v149
	s_add_i32 s87, 0, 0x1c000
	ds_read_b128 v[162:165], v146
	v_xor_b32_e32 v253, 64, v146
	ds_read_b128 v[166:169], v253
	ds_read_b128 v[170:173], v146 offset:2048
	ds_read_b128 v[174:177], v253 offset:2048
	v_add_u32_e32 v146, s87, v149
	ds_read_b128 v[178:181], v146
	v_xor_b32_e32 v253, 64, v146
	ds_read_b128 v[186:189], v253
	ds_read_b128 v[190:193], v146 offset:2048
	ds_read_b128 v[194:197], v253 offset:2048
	s_add_u32 s58, s58, 0x40000
	s_addc_u32 s59, s59, 0
	s_mov_b32 m0, s66
	v_lshl_add_u64 v[236:237], s[58:59], 0, v[128:129]
	ds_read_b128 v[198:201], v154 offset:32768
	v_xor_b32_e32 v253, 64, v154
	ds_read_b128 v[202:205], v253 offset:32768
	ds_read_b128 v[206:209], v154 offset:34816
	ds_read_b128 v[210:213], v253 offset:34816
	ds_read_b128 v[214:217], v154 offset:36864
	ds_read_b128 v[218:221], v253 offset:36864
	ds_read_b128 v[222:225], v154 offset:38912
	ds_read_b128 v[226:229], v253 offset:38912
	global_load_lds_dwordx4 v[236:237], off
	v_lshl_add_u64 v[236:237], s[58:59], 0, v[132:133]
	s_mov_b32 m0, s67
	s_nop 0
	global_load_lds_dwordx4 v[236:237], off
	s_waitcnt vmcnt(8)
	s_waitcnt lgkmcnt(0)
	s_setprio 1
	s_barrier
	v_mfma_f32_16x16x32_bf16 v[124:127], v[162:165], v[198:201], v[124:127]
	v_mfma_f32_16x16x32_bf16 v[124:127], v[166:169], v[202:205], v[124:127]
	v_mfma_f32_16x16x32_bf16 v[120:123], v[174:177], v[202:205], v[120:123]
	v_mfma_f32_16x16x32_bf16 v[120:123], v[170:173], v[198:201], v[120:123]
	v_mfma_f32_16x16x32_bf16 v[104:107], v[170:173], v[206:209], v[104:107]
	v_mfma_f32_16x16x32_bf16 v[104:107], v[174:177], v[210:213], v[104:107]
	v_mfma_f32_16x16x32_bf16 v[112:115], v[166:169], v[210:213], v[112:115]
	v_mfma_f32_16x16x32_bf16 v[112:115], v[162:165], v[206:209], v[112:115]
	v_mfma_f32_16x16x32_bf16 v[96:99], v[162:165], v[214:217], v[96:99]
	v_mfma_f32_16x16x32_bf16 v[96:99], v[166:169], v[218:221], v[96:99]
	v_mfma_f32_16x16x32_bf16 v[88:91], v[174:177], v[218:221], v[88:91]
	v_mfma_f32_16x16x32_bf16 v[88:91], v[170:173], v[214:217], v[88:91]
	v_mfma_f32_16x16x32_bf16 v[72:75], v[170:173], v[222:225], v[72:75]
	v_mfma_f32_16x16x32_bf16 v[72:75], v[174:177], v[226:229], v[72:75]
	v_mfma_f32_16x16x32_bf16 v[80:83], v[166:169], v[226:229], v[80:83]
	v_mfma_f32_16x16x32_bf16 v[80:83], v[162:165], v[222:225], v[80:83]
	s_setprio 0
	s_setprio 1
	v_mfma_f32_16x16x32_bf16 v[116:119], v[178:181], v[198:201], v[116:119]
	v_mfma_f32_16x16x32_bf16 v[116:119], v[186:189], v[202:205], v[116:119]
	v_mfma_f32_16x16x32_bf16 v[108:111], v[194:197], v[202:205], v[108:111]
	v_mfma_f32_16x16x32_bf16 v[108:111], v[190:193], v[198:201], v[108:111]
	v_mfma_f32_16x16x32_bf16 v[92:95], v[190:193], v[206:209], v[92:95]
	v_mfma_f32_16x16x32_bf16 v[92:95], v[194:197], v[210:213], v[92:95]
	v_mfma_f32_16x16x32_bf16 v[100:103], v[186:189], v[210:213], v[100:103]
	v_mfma_f32_16x16x32_bf16 v[100:103], v[178:181], v[206:209], v[100:103]
	v_mfma_f32_16x16x32_bf16 v[84:87], v[178:181], v[214:217], v[84:87]
	v_mfma_f32_16x16x32_bf16 v[84:87], v[186:189], v[218:221], v[84:87]
	v_mfma_f32_16x16x32_bf16 v[76:79], v[194:197], v[218:221], v[76:79]
	v_mfma_f32_16x16x32_bf16 v[76:79], v[190:193], v[214:217], v[76:79]
	v_mfma_f32_16x16x32_bf16 v[64:67], v[190:193], v[222:225], v[64:67]
	v_mfma_f32_16x16x32_bf16 v[64:67], v[194:197], v[226:229], v[64:67]
	v_mfma_f32_16x16x32_bf16 v[68:71], v[186:189], v[226:229], v[68:71]
	v_mfma_f32_16x16x32_bf16 v[68:71], v[178:181], v[222:225], v[68:71]
	s_barrier
	s_setprio 0
	s_add_i32 s58, s86, s63
	v_lshl_add_u64 v[182:183], v[182:183], 0, s[22:23]
	s_mov_b32 m0, s58
	ds_read_b128 v[198:201], v154 offset:49152
	v_xor_b32_e32 v253, 64, v154
	ds_read_b128 v[202:205], v253 offset:49152
	ds_read_b128 v[206:209], v154 offset:51200
	ds_read_b128 v[210:213], v253 offset:51200
	ds_read_b128 v[214:217], v154 offset:53248
	ds_read_b128 v[218:221], v253 offset:53248
	ds_read_b128 v[222:225], v154 offset:55296
	ds_read_b128 v[226:229], v253 offset:55296
	global_load_lds_dwordx4 v[182:183], off
	s_add_i32 m0, s58, 0x2000
	s_add_u32 s56, s56, 0x40080
	v_lshl_add_u64 v[182:183], v[230:231], 0, s[22:23]
	s_addc_u32 s57, s57, 0
	s_add_i32 s58, s87, s63
	global_load_lds_dwordx4 v[182:183], off
	v_lshl_add_u64 v[182:183], s[56:57], 0, v[130:131]
	s_mov_b32 m0, s58
	s_nop 0
	global_load_lds_dwordx4 v[182:183], off
	v_lshl_add_u64 v[182:183], s[56:57], 0, v[134:135]
	s_add_i32 m0, s58, 0x2000
	s_nop 0
	global_load_lds_dwordx4 v[182:183], off
	v_lshl_add_u64 v[182:183], v[232:233], 0, s[22:23]
	s_mov_b32 m0, s69
	s_nop 0
	global_load_lds_dwordx4 v[182:183], off
	v_lshl_add_u64 v[182:183], v[234:235], 0, s[22:23]
	s_mov_b32 m0, s70
	s_nop 0
	global_load_lds_dwordx4 v[182:183], off
	s_waitcnt vmcnt(8)
	s_waitcnt lgkmcnt(0)
	s_setprio 1
	s_barrier
	v_mfma_f32_16x16x32_bf16 v[60:63], v[162:165], v[198:201], v[60:63]
	v_mfma_f32_16x16x32_bf16 v[60:63], v[166:169], v[202:205], v[60:63]
	v_mfma_f32_16x16x32_bf16 v[56:59], v[174:177], v[202:205], v[56:59]
	v_mfma_f32_16x16x32_bf16 v[56:59], v[170:173], v[198:201], v[56:59]
	v_mfma_f32_16x16x32_bf16 v[40:43], v[170:173], v[206:209], v[40:43]
	v_mfma_f32_16x16x32_bf16 v[40:43], v[174:177], v[210:213], v[40:43]
	v_mfma_f32_16x16x32_bf16 v[48:51], v[166:169], v[210:213], v[48:51]
	v_mfma_f32_16x16x32_bf16 v[48:51], v[162:165], v[206:209], v[48:51]
	v_mfma_f32_16x16x32_bf16 v[32:35], v[162:165], v[214:217], v[32:35]
	v_mfma_f32_16x16x32_bf16 v[32:35], v[166:169], v[218:221], v[32:35]
	v_mfma_f32_16x16x32_bf16 v[24:27], v[174:177], v[218:221], v[24:27]
	v_mfma_f32_16x16x32_bf16 v[24:27], v[170:173], v[214:217], v[24:27]
	v_mfma_f32_16x16x32_bf16 v[8:11], v[170:173], v[222:225], v[8:11]
	v_mfma_f32_16x16x32_bf16 v[8:11], v[174:177], v[226:229], v[8:11]
	v_mfma_f32_16x16x32_bf16 v[16:19], v[166:169], v[226:229], v[16:19]
	v_mfma_f32_16x16x32_bf16 v[16:19], v[162:165], v[222:225], v[16:19]
	s_setprio 0
	s_setprio 1
	v_mfma_f32_16x16x32_bf16 v[52:55], v[178:181], v[198:201], v[52:55]
	v_mfma_f32_16x16x32_bf16 v[52:55], v[186:189], v[202:205], v[52:55]
	v_mfma_f32_16x16x32_bf16 v[44:47], v[194:197], v[202:205], v[44:47]
	v_mfma_f32_16x16x32_bf16 v[44:47], v[190:193], v[198:201], v[44:47]
	v_mfma_f32_16x16x32_bf16 v[28:31], v[190:193], v[206:209], v[28:31]
	v_mfma_f32_16x16x32_bf16 v[28:31], v[194:197], v[210:213], v[28:31]
	v_mfma_f32_16x16x32_bf16 v[36:39], v[186:189], v[210:213], v[36:39]
	v_mfma_f32_16x16x32_bf16 v[36:39], v[178:181], v[206:209], v[36:39]
	v_mfma_f32_16x16x32_bf16 v[20:23], v[178:181], v[214:217], v[20:23]
	v_mfma_f32_16x16x32_bf16 v[20:23], v[186:189], v[218:221], v[20:23]
	v_mfma_f32_16x16x32_bf16 v[12:15], v[194:197], v[218:221], v[12:15]
	v_mfma_f32_16x16x32_bf16 v[12:15], v[190:193], v[214:217], v[12:15]
	v_mfma_f32_16x16x32_bf16 v[0:3], v[190:193], v[222:225], v[0:3]
	v_mfma_f32_16x16x32_bf16 v[0:3], v[194:197], v[226:229], v[0:3]
	v_mfma_f32_16x16x32_bf16 v[4:7], v[186:189], v[226:229], v[4:7]
	v_mfma_f32_16x16x32_bf16 v[4:7], v[178:181], v[222:225], v[4:7]
	s_barrier
	s_setprio 0
	s_add_i32 s85, s85, 2
	s_add_u32 s83, s83, 0x100
	s_addc_u32 s84, s84, 0
	s_add_u32 s54, s54, 0x100
	s_addc_u32 s55, s55, 0
	s_cmp_gt_u32 s85, 13
	s_cbranch_scc1 .LBB0_877

.LBB0_1010:
	s_ashr_i32 s51, s50, 31
	s_lshl_b64 s[52:53], s[50:51], 19
	s_add_u32 s52, s33, s52
	s_addc_u32 s53, s35, s53
	s_and_b64 s[54:55], s[12:13], exec
	s_cselect_b32 s15, s53, s61
	s_cselect_b32 s51, s52, s60
	s_ashr_i32 s49, s48, 31
	s_lshl_b64 s[54:55], s[48:49], 19
	s_add_u32 s54, s64, s54
	s_addc_u32 s55, s65, s55
	s_and_b64 s[62:63], s[12:13], exec
	s_cselect_b32 s49, s55, s59
	s_cselect_b32 s57, s54, s58
	s_add_u32 s78, s58, 0x100
	s_addc_u32 s79, s59, 0
	s_add_u32 s58, s60, 0x40080
	s_addc_u32 s59, s61, 0
	s_mov_b32 s80, -2
	s_waitcnt lgkmcnt(0)
	s_cmp_eq_u32 s71, 1
	s_cbranch_scc1 .Lfa_9
	ds_read_b128 v[128:131], v188
	v_xor_b32_e32 v253, 64, v188
	ds_read_b128 v[132:135], v253
	ds_read_b128 v[136:139], v188 offset:2048
	ds_read_b128 v[140:143], v253 offset:2048
	ds_read_b128 v[144:147], v189
	v_xor_b32_e32 v253, 64, v189
	ds_read_b128 v[148:151], v253
	ds_read_b128 v[172:175], v189 offset:2048
	ds_read_b128 v[176:179], v253 offset:2048
	s_add_u32 s60, s58, 0xfffc0080
	s_addc_u32 s61, s59, -1
	s_cmp_eq_u32 s80, 12
	s_cselect_b32 s63, s15, s61
	s_cselect_b32 s62, s51, s60
	s_cselect_b32 s61, s49, s79
	s_cselect_b32 s60, s57, s78
	v_lshl_add_u64 v[220:221], s[58:59], 0, v[166:167]
	s_add_i32 m0, s67, 0xc000
	ds_read_b128 v[180:183], v190
	v_xor_b32_e32 v253, 64, v190
	ds_read_b128 v[192:195], v253
	ds_read_b128 v[196:199], v190 offset:2048
	ds_read_b128 v[200:203], v253 offset:2048
	ds_read_b128 v[204:207], v190 offset:4096
	ds_read_b128 v[208:211], v253 offset:4096
	ds_read_b128 v[212:215], v190 offset:6144
	ds_read_b128 v[216:219], v253 offset:6144
	global_load_lds_dwordx4 v[220:221], off
	v_lshl_add_u64 v[220:221], s[58:59], 0, v[164:165]
	s_add_i32 m0, s67, 0xe000
	s_nop 0
	global_load_lds_dwordx4 v[220:221], off
	s_waitcnt vmcnt(24)
	s_waitcnt lgkmcnt(0)
	s_setprio 1
	s_barrier
	v_mfma_f32_16x16x32_bf16 v[124:127], v[128:131], v[180:183], 0
	v_mfma_f32_16x16x32_bf16 v[120:123], v[136:139], v[180:183], 0
	v_mfma_f32_16x16x32_bf16 v[108:111], v[128:131], v[196:199], 0
	v_mfma_f32_16x16x32_bf16 v[104:107], v[136:139], v[196:199], 0
	v_mfma_f32_16x16x32_bf16 v[92:95], v[128:131], v[204:207], 0
	v_mfma_f32_16x16x32_bf16 v[88:91], v[136:139], v[204:207], 0
	v_mfma_f32_16x16x32_bf16 v[76:79], v[128:131], v[212:215], 0
	v_mfma_f32_16x16x32_bf16 v[72:75], v[136:139], v[212:215], 0
	v_mfma_f32_16x16x32_bf16 v[124:127], v[132:135], v[192:195], v[124:127]
	v_mfma_f32_16x16x32_bf16 v[120:123], v[140:143], v[192:195], v[120:123]
	v_mfma_f32_16x16x32_bf16 v[108:111], v[132:135], v[200:203], v[108:111]
	v_mfma_f32_16x16x32_bf16 v[104:107], v[140:143], v[200:203], v[104:107]
	v_mfma_f32_16x16x32_bf16 v[92:95], v[132:135], v[208:211], v[92:95]
	v_mfma_f32_16x16x32_bf16 v[88:91], v[140:143], v[208:211], v[88:91]
	v_mfma_f32_16x16x32_bf16 v[76:79], v[132:135], v[216:219], v[76:79]
	v_mfma_f32_16x16x32_bf16 v[72:75], v[140:143], v[216:219], v[72:75]
	s_setprio 0
	s_setprio 1
	v_mfma_f32_16x16x32_bf16 v[116:119], v[144:147], v[180:183], 0
	v_mfma_f32_16x16x32_bf16 v[112:115], v[172:175], v[180:183], 0
	v_mfma_f32_16x16x32_bf16 v[100:103], v[144:147], v[196:199], 0
	v_mfma_f32_16x16x32_bf16 v[96:99], v[172:175], v[196:199], 0
	v_mfma_f32_16x16x32_bf16 v[84:87], v[144:147], v[204:207], 0
	v_mfma_f32_16x16x32_bf16 v[80:83], v[172:175], v[204:207], 0
	v_mfma_f32_16x16x32_bf16 v[68:71], v[144:147], v[212:215], 0
	v_mfma_f32_16x16x32_bf16 v[64:67], v[172:175], v[212:215], 0
	v_mfma_f32_16x16x32_bf16 v[116:119], v[148:151], v[192:195], v[116:119]
	v_mfma_f32_16x16x32_bf16 v[112:115], v[176:179], v[192:195], v[112:115]
	v_mfma_f32_16x16x32_bf16 v[100:103], v[148:151], v[200:203], v[100:103]
	v_mfma_f32_16x16x32_bf16 v[96:99], v[176:179], v[200:203], v[96:99]
	v_mfma_f32_16x16x32_bf16 v[84:87], v[148:151], v[208:211], v[84:87]
	v_mfma_f32_16x16x32_bf16 v[80:83], v[176:179], v[208:211], v[80:83]
	v_mfma_f32_16x16x32_bf16 v[68:71], v[148:151], v[216:219], v[68:71]
	v_mfma_f32_16x16x32_bf16 v[64:67], v[176:179], v[216:219], v[64:67]
	s_barrier
	s_setprio 0
	s_add_i32 s81, s76, s66
	v_lshl_add_u64 v[220:221], s[60:61], 0, v[154:155]
	s_mov_b32 m0, s81
	ds_read_b128 v[180:183], v190 offset:16384
	v_xor_b32_e32 v253, 64, v190
	ds_read_b128 v[192:195], v253 offset:16384
	ds_read_b128 v[196:199], v190 offset:18432
	ds_read_b128 v[200:203], v253 offset:18432
	ds_read_b128 v[204:207], v190 offset:20480
	ds_read_b128 v[208:211], v253 offset:20480
	ds_read_b128 v[212:215], v190 offset:22528
	ds_read_b128 v[216:219], v253 offset:22528
	global_load_lds_dwordx4 v[220:221], off
	s_add_i32 m0, s81, 0x2000
	s_add_u32 s82, s60, 0x40000
	v_lshl_add_u64 v[222:223], s[60:61], 0, v[162:163]
	s_addc_u32 s83, s61, 0
	s_add_i32 s81, s77, s66
	global_load_lds_dwordx4 v[222:223], off
	v_lshl_add_u64 v[224:225], s[82:83], 0, v[154:155]
	s_mov_b32 m0, s81
	v_lshl_add_u64 v[226:227], s[62:63], 0, v[160:161]
	global_load_lds_dwordx4 v[224:225], off
	v_lshl_add_u64 v[224:225], s[82:83], 0, v[162:163]
	s_add_i32 m0, s81, 0x2000
	s_nop 0
	global_load_lds_dwordx4 v[224:225], off
	v_lshl_add_u64 v[224:225], s[62:63], 0, v[152:153]
	s_mov_b32 m0, s67
	s_nop 0
	global_load_lds_dwordx4 v[224:225], off
	s_mov_b32 m0, s68
	s_nop 0
	global_load_lds_dwordx4 v[226:227], off
	s_waitcnt vmcnt(24)
	s_waitcnt lgkmcnt(0)
	s_setprio 1
	s_barrier
	v_mfma_f32_16x16x32_bf16 v[60:63], v[128:131], v[180:183], 0
	v_mfma_f32_16x16x32_bf16 v[56:59], v[136:139], v[180:183], 0
	v_mfma_f32_16x16x32_bf16 v[44:47], v[128:131], v[196:199], 0
	v_mfma_f32_16x16x32_bf16 v[40:43], v[136:139], v[196:199], 0
	v_mfma_f32_16x16x32_bf16 v[28:31], v[128:131], v[204:207], 0
	v_mfma_f32_16x16x32_bf16 v[24:27], v[136:139], v[204:207], 0
	v_mfma_f32_16x16x32_bf16 v[12:15], v[128:131], v[212:215], 0
	v_mfma_f32_16x16x32_bf16 v[8:11], v[136:139], v[212:215], 0
	v_mfma_f32_16x16x32_bf16 v[60:63], v[132:135], v[192:195], v[60:63]
	v_mfma_f32_16x16x32_bf16 v[56:59], v[140:143], v[192:195], v[56:59]
	v_mfma_f32_16x16x32_bf16 v[44:47], v[132:135], v[200:203], v[44:47]
	v_mfma_f32_16x16x32_bf16 v[40:43], v[140:143], v[200:203], v[40:43]
	v_mfma_f32_16x16x32_bf16 v[28:31], v[132:135], v[208:211], v[28:31]
	v_mfma_f32_16x16x32_bf16 v[24:27], v[140:143], v[208:211], v[24:27]
	v_mfma_f32_16x16x32_bf16 v[12:15], v[132:135], v[216:219], v[12:15]
	v_mfma_f32_16x16x32_bf16 v[8:11], v[140:143], v[216:219], v[8:11]
	s_setprio 0
	s_setprio 1
	v_mfma_f32_16x16x32_bf16 v[52:55], v[144:147], v[180:183], 0
	v_mfma_f32_16x16x32_bf16 v[48:51], v[172:175], v[180:183], 0
	v_mfma_f32_16x16x32_bf16 v[36:39], v[144:147], v[196:199], 0
	v_mfma_f32_16x16x32_bf16 v[32:35], v[172:175], v[196:199], 0
	v_mfma_f32_16x16x32_bf16 v[20:23], v[144:147], v[204:207], 0
	v_mfma_f32_16x16x32_bf16 v[16:19], v[172:175], v[204:207], 0
	v_mfma_f32_16x16x32_bf16 v[4:7], v[144:147], v[212:215], 0
	v_mfma_f32_16x16x32_bf16 v[0:3], v[172:175], v[212:215], 0
	v_mfma_f32_16x16x32_bf16 v[52:55], v[148:151], v[192:195], v[52:55]
	v_mfma_f32_16x16x32_bf16 v[48:51], v[176:179], v[192:195], v[48:51]
	v_mfma_f32_16x16x32_bf16 v[36:39], v[148:151], v[200:203], v[36:39]
	v_mfma_f32_16x16x32_bf16 v[32:35], v[176:179], v[200:203], v[32:35]
	v_mfma_f32_16x16x32_bf16 v[20:23], v[148:151], v[208:211], v[20:23]
	v_mfma_f32_16x16x32_bf16 v[16:19], v[176:179], v[208:211], v[16:19]
	v_mfma_f32_16x16x32_bf16 v[4:7], v[148:151], v[216:219], v[4:7]
	v_mfma_f32_16x16x32_bf16 v[0:3], v[176:179], v[216:219], v[0:3]
	s_barrier
	s_setprio 0
	s_add_i32 s81, 0, 0x18000
	s_add_i32 s82, 0, 0x1c000
	v_add_u32_e32 v140, s81, v185
	v_add_u32_e32 v176, s82, v185
	ds_read_b128 v[128:131], v140
	v_xor_b32_e32 v253, 64, v140
	ds_read_b128 v[132:135], v253
	ds_read_b128 v[136:139], v140 offset:2048
	ds_read_b128 v[140:143], v253 offset:2048
	ds_read_b128 v[144:147], v176
	v_xor_b32_e32 v253, 64, v176
	ds_read_b128 v[148:151], v253
	ds_read_b128 v[172:175], v176 offset:2048
	ds_read_b128 v[176:179], v253 offset:2048
	s_add_u32 s62, s62, 0x40000
	s_addc_u32 s63, s63, 0
	s_mov_b32 m0, s69
	v_lshl_add_u64 v[228:229], s[62:63], 0, v[152:153]
	ds_read_b128 v[180:183], v190 offset:32768
	v_xor_b32_e32 v253, 64, v190
	ds_read_b128 v[192:195], v253 offset:32768
	ds_read_b128 v[196:199], v190 offset:34816
	ds_read_b128 v[200:203], v253 offset:34816
	ds_read_b128 v[204:207], v190 offset:36864
	ds_read_b128 v[208:211], v253 offset:36864
	ds_read_b128 v[212:215], v190 offset:38912
	ds_read_b128 v[216:219], v253 offset:38912
	global_load_lds_dwordx4 v[228:229], off
	v_lshl_add_u64 v[228:229], s[62:63], 0, v[160:161]
	s_mov_b32 m0, s70
	s_nop 0
	global_load_lds_dwordx4 v[228:229], off
	s_waitcnt vmcnt(8)
	s_waitcnt lgkmcnt(0)
	s_setprio 1
	s_barrier
	v_mfma_f32_16x16x32_bf16 v[124:127], v[128:131], v[180:183], v[124:127]
	v_mfma_f32_16x16x32_bf16 v[124:127], v[132:135], v[192:195], v[124:127]
	v_mfma_f32_16x16x32_bf16 v[120:123], v[140:143], v[192:195], v[120:123]
	v_mfma_f32_16x16x32_bf16 v[120:123], v[136:139], v[180:183], v[120:123]
	v_mfma_f32_16x16x32_bf16 v[104:107], v[136:139], v[196:199], v[104:107]
	v_mfma_f32_16x16x32_bf16 v[104:107], v[140:143], v[200:203], v[104:107]
	v_mfma_f32_16x16x32_bf16 v[108:111], v[132:135], v[200:203], v[108:111]
	v_mfma_f32_16x16x32_bf16 v[108:111], v[128:131], v[196:199], v[108:111]
	v_mfma_f32_16x16x32_bf16 v[92:95], v[128:131], v[204:207], v[92:95]
	v_mfma_f32_16x16x32_bf16 v[92:95], v[132:135], v[208:211], v[92:95]
	v_mfma_f32_16x16x32_bf16 v[88:91], v[140:143], v[208:211], v[88:91]
	v_mfma_f32_16x16x32_bf16 v[88:91], v[136:139], v[204:207], v[88:91]
	v_mfma_f32_16x16x32_bf16 v[72:75], v[136:139], v[212:215], v[72:75]
	v_mfma_f32_16x16x32_bf16 v[72:75], v[140:143], v[216:219], v[72:75]
	v_mfma_f32_16x16x32_bf16 v[76:79], v[132:135], v[216:219], v[76:79]
	v_mfma_f32_16x16x32_bf16 v[76:79], v[128:131], v[212:215], v[76:79]
	s_setprio 0
	s_setprio 1
	v_mfma_f32_16x16x32_bf16 v[116:119], v[144:147], v[180:183], v[116:119]
	v_mfma_f32_16x16x32_bf16 v[116:119], v[148:151], v[192:195], v[116:119]
	v_mfma_f32_16x16x32_bf16 v[112:115], v[176:179], v[192:195], v[112:115]
	v_mfma_f32_16x16x32_bf16 v[112:115], v[172:175], v[180:183], v[112:115]
	v_mfma_f32_16x16x32_bf16 v[96:99], v[172:175], v[196:199], v[96:99]
	v_mfma_f32_16x16x32_bf16 v[96:99], v[176:179], v[200:203], v[96:99]
	v_mfma_f32_16x16x32_bf16 v[100:103], v[148:151], v[200:203], v[100:103]
	v_mfma_f32_16x16x32_bf16 v[100:103], v[144:147], v[196:199], v[100:103]
	v_mfma_f32_16x16x32_bf16 v[84:87], v[144:147], v[204:207], v[84:87]
	v_mfma_f32_16x16x32_bf16 v[84:87], v[148:151], v[208:211], v[84:87]
	v_mfma_f32_16x16x32_bf16 v[80:83], v[176:179], v[208:211], v[80:83]
	v_mfma_f32_16x16x32_bf16 v[80:83], v[172:175], v[204:207], v[80:83]
	v_mfma_f32_16x16x32_bf16 v[64:67], v[172:175], v[212:215], v[64:67]
	v_mfma_f32_16x16x32_bf16 v[64:67], v[176:179], v[216:219], v[64:67]
	v_mfma_f32_16x16x32_bf16 v[68:71], v[148:151], v[216:219], v[68:71]
	v_mfma_f32_16x16x32_bf16 v[68:71], v[144:147], v[212:215], v[68:71]
	s_barrier
	s_setprio 0
	s_add_i32 s62, s81, s66
	v_lshl_add_u64 v[220:221], v[220:221], 0, s[26:27]
	s_mov_b32 m0, s62
	ds_read_b128 v[180:183], v190 offset:49152
	v_xor_b32_e32 v253, 64, v190
	ds_read_b128 v[192:195], v253 offset:49152
	ds_read_b128 v[196:199], v190 offset:51200
	ds_read_b128 v[200:203], v253 offset:51200
	ds_read_b128 v[204:207], v190 offset:53248
	ds_read_b128 v[208:211], v253 offset:53248
	ds_read_b128 v[212:215], v190 offset:55296
	ds_read_b128 v[216:219], v253 offset:55296
	global_load_lds_dwordx4 v[220:221], off
	s_add_i32 m0, s62, 0x2000
	s_add_u32 s60, s60, 0x40080
	v_lshl_add_u64 v[220:221], v[222:223], 0, s[26:27]
	s_addc_u32 s61, s61, 0
	s_add_i32 s62, s82, s66
	global_load_lds_dwordx4 v[220:221], off
	v_lshl_add_u64 v[220:221], s[60:61], 0, v[154:155]
	s_mov_b32 m0, s62
	s_nop 0
	global_load_lds_dwordx4 v[220:221], off
	v_lshl_add_u64 v[220:221], s[60:61], 0, v[162:163]
	s_add_i32 m0, s62, 0x2000
	s_nop 0
	global_load_lds_dwordx4 v[220:221], off
	v_lshl_add_u64 v[220:221], v[224:225], 0, s[26:27]
	s_mov_b32 m0, s3
	s_nop 0
	global_load_lds_dwordx4 v[220:221], off
	v_lshl_add_u64 v[220:221], v[226:227], 0, s[26:27]
	s_mov_b32 m0, s72
	s_nop 0
	global_load_lds_dwordx4 v[220:221], off
	s_waitcnt vmcnt(8)
	s_waitcnt lgkmcnt(0)
	s_setprio 1
	s_barrier
	v_mfma_f32_16x16x32_bf16 v[60:63], v[128:131], v[180:183], v[60:63]
	v_mfma_f32_16x16x32_bf16 v[60:63], v[132:135], v[192:195], v[60:63]
	v_mfma_f32_16x16x32_bf16 v[56:59], v[140:143], v[192:195], v[56:59]
	v_mfma_f32_16x16x32_bf16 v[56:59], v[136:139], v[180:183], v[56:59]
	v_mfma_f32_16x16x32_bf16 v[40:43], v[136:139], v[196:199], v[40:43]
	v_mfma_f32_16x16x32_bf16 v[40:43], v[140:143], v[200:203], v[40:43]
	v_mfma_f32_16x16x32_bf16 v[44:47], v[132:135], v[200:203], v[44:47]
	v_mfma_f32_16x16x32_bf16 v[44:47], v[128:131], v[196:199], v[44:47]
	v_mfma_f32_16x16x32_bf16 v[28:31], v[128:131], v[204:207], v[28:31]
	v_mfma_f32_16x16x32_bf16 v[28:31], v[132:135], v[208:211], v[28:31]
	v_mfma_f32_16x16x32_bf16 v[24:27], v[140:143], v[208:211], v[24:27]
	v_mfma_f32_16x16x32_bf16 v[24:27], v[136:139], v[204:207], v[24:27]
	v_mfma_f32_16x16x32_bf16 v[8:11], v[136:139], v[212:215], v[8:11]
	v_mfma_f32_16x16x32_bf16 v[8:11], v[140:143], v[216:219], v[8:11]
	v_mfma_f32_16x16x32_bf16 v[12:15], v[132:135], v[216:219], v[12:15]
	v_mfma_f32_16x16x32_bf16 v[12:15], v[128:131], v[212:215], v[12:15]
	s_setprio 0
	s_setprio 1
	v_mfma_f32_16x16x32_bf16 v[52:55], v[144:147], v[180:183], v[52:55]
	v_mfma_f32_16x16x32_bf16 v[52:55], v[148:151], v[192:195], v[52:55]
	v_mfma_f32_16x16x32_bf16 v[48:51], v[176:179], v[192:195], v[48:51]
	v_mfma_f32_16x16x32_bf16 v[48:51], v[172:175], v[180:183], v[48:51]
	v_mfma_f32_16x16x32_bf16 v[32:35], v[172:175], v[196:199], v[32:35]
	v_mfma_f32_16x16x32_bf16 v[32:35], v[176:179], v[200:203], v[32:35]
	v_mfma_f32_16x16x32_bf16 v[36:39], v[148:151], v[200:203], v[36:39]
	v_mfma_f32_16x16x32_bf16 v[36:39], v[144:147], v[196:199], v[36:39]
	v_mfma_f32_16x16x32_bf16 v[20:23], v[144:147], v[204:207], v[20:23]
	v_mfma_f32_16x16x32_bf16 v[20:23], v[148:151], v[208:211], v[20:23]
	v_mfma_f32_16x16x32_bf16 v[16:19], v[176:179], v[208:211], v[16:19]
	v_mfma_f32_16x16x32_bf16 v[16:19], v[172:175], v[204:207], v[16:19]
	v_mfma_f32_16x16x32_bf16 v[0:3], v[172:175], v[212:215], v[0:3]
	v_mfma_f32_16x16x32_bf16 v[0:3], v[176:179], v[216:219], v[0:3]
	v_mfma_f32_16x16x32_bf16 v[4:7], v[148:151], v[216:219], v[4:7]
	v_mfma_f32_16x16x32_bf16 v[4:7], v[144:147], v[212:215], v[4:7]
	s_barrier
	s_setprio 0
	s_add_i32 s80, s80, 2
	s_add_u32 s78, s78, 0x100
	s_addc_u32 s79, s79, 0
	s_add_u32 s58, s58, 0x100
	s_addc_u32 s59, s59, 0
	s_cmp_gt_u32 s80, 13
	s_branch .LBB0_1011
.Lfa_9:
	ds_read_b128 v[128:131], v188
	v_xor_b32_e32 v253, 64, v188
	ds_read_b128 v[132:135], v253
	ds_read_b128 v[136:139], v188 offset:2048
	ds_read_b128 v[140:143], v253 offset:2048
	ds_read_b128 v[144:147], v189
	v_xor_b32_e32 v253, 64, v189
	ds_read_b128 v[148:151], v253
	ds_read_b128 v[172:175], v189 offset:2048
	ds_read_b128 v[176:179], v253 offset:2048
	s_add_u32 s60, s58, 0xfffc0080
	s_addc_u32 s61, s59, -1
	s_cmp_eq_u32 s80, 12
	s_cselect_b32 s63, s15, s61
	s_cselect_b32 s62, s51, s60
	s_cselect_b32 s61, s49, s79
	s_cselect_b32 s60, s57, s78
	v_lshl_add_u64 v[220:221], s[58:59], 0, v[166:167]
	s_add_i32 m0, s67, 0xc000
	ds_read_b128 v[180:183], v190
	v_xor_b32_e32 v253, 64, v190
	ds_read_b128 v[192:195], v253
	ds_read_b128 v[196:199], v190 offset:2048
	ds_read_b128 v[200:203], v253 offset:2048
	ds_read_b128 v[204:207], v190 offset:4096
	ds_read_b128 v[208:211], v253 offset:4096
	ds_read_b128 v[212:215], v190 offset:6144
	ds_read_b128 v[216:219], v253 offset:6144
	global_load_lds_dwordx4 v[220:221], off
	v_lshl_add_u64 v[220:221], s[58:59], 0, v[164:165]
	s_add_i32 m0, s67, 0xe000
	s_nop 0
	global_load_lds_dwordx4 v[220:221], off
	s_waitcnt vmcnt(8)
	s_waitcnt lgkmcnt(0)
	s_setprio 1
	s_barrier
	v_mfma_f32_16x16x32_bf16 v[124:127], v[128:131], v[180:183], 0
	v_mfma_f32_16x16x32_bf16 v[120:123], v[136:139], v[180:183], 0
	v_mfma_f32_16x16x32_bf16 v[108:111], v[128:131], v[196:199], 0
	v_mfma_f32_16x16x32_bf16 v[104:107], v[136:139], v[196:199], 0
	v_mfma_f32_16x16x32_bf16 v[92:95], v[128:131], v[204:207], 0
	v_mfma_f32_16x16x32_bf16 v[88:91], v[136:139], v[204:207], 0
	v_mfma_f32_16x16x32_bf16 v[76:79], v[128:131], v[212:215], 0
	v_mfma_f32_16x16x32_bf16 v[72:75], v[136:139], v[212:215], 0
	v_mfma_f32_16x16x32_bf16 v[124:127], v[132:135], v[192:195], v[124:127]
	v_mfma_f32_16x16x32_bf16 v[120:123], v[140:143], v[192:195], v[120:123]
	v_mfma_f32_16x16x32_bf16 v[108:111], v[132:135], v[200:203], v[108:111]
	v_mfma_f32_16x16x32_bf16 v[104:107], v[140:143], v[200:203], v[104:107]
	v_mfma_f32_16x16x32_bf16 v[92:95], v[132:135], v[208:211], v[92:95]
	v_mfma_f32_16x16x32_bf16 v[88:91], v[140:143], v[208:211], v[88:91]
	v_mfma_f32_16x16x32_bf16 v[76:79], v[132:135], v[216:219], v[76:79]
	v_mfma_f32_16x16x32_bf16 v[72:75], v[140:143], v[216:219], v[72:75]
	s_setprio 0
	s_setprio 1
	v_mfma_f32_16x16x32_bf16 v[116:119], v[144:147], v[180:183], 0
	v_mfma_f32_16x16x32_bf16 v[112:115], v[172:175], v[180:183], 0
	v_mfma_f32_16x16x32_bf16 v[100:103], v[144:147], v[196:199], 0
	v_mfma_f32_16x16x32_bf16 v[96:99], v[172:175], v[196:199], 0
	v_mfma_f32_16x16x32_bf16 v[84:87], v[144:147], v[204:207], 0
	v_mfma_f32_16x16x32_bf16 v[80:83], v[172:175], v[204:207], 0
	v_mfma_f32_16x16x32_bf16 v[68:71], v[144:147], v[212:215], 0
	v_mfma_f32_16x16x32_bf16 v[64:67], v[172:175], v[212:215], 0
	v_mfma_f32_16x16x32_bf16 v[116:119], v[148:151], v[192:195], v[116:119]
	v_mfma_f32_16x16x32_bf16 v[112:115], v[176:179], v[192:195], v[112:115]
	v_mfma_f32_16x16x32_bf16 v[100:103], v[148:151], v[200:203], v[100:103]
	v_mfma_f32_16x16x32_bf16 v[96:99], v[176:179], v[200:203], v[96:99]
	v_mfma_f32_16x16x32_bf16 v[84:87], v[148:151], v[208:211], v[84:87]
	v_mfma_f32_16x16x32_bf16 v[80:83], v[176:179], v[208:211], v[80:83]
	v_mfma_f32_16x16x32_bf16 v[68:71], v[148:151], v[216:219], v[68:71]
	v_mfma_f32_16x16x32_bf16 v[64:67], v[176:179], v[216:219], v[64:67]
	s_barrier
	s_setprio 0
	s_add_i32 s81, s76, s66
	v_lshl_add_u64 v[220:221], s[60:61], 0, v[154:155]
	s_mov_b32 m0, s81
	ds_read_b128 v[180:183], v190 offset:16384
	v_xor_b32_e32 v253, 64, v190
	ds_read_b128 v[192:195], v253 offset:16384
	ds_read_b128 v[196:199], v190 offset:18432
	ds_read_b128 v[200:203], v253 offset:18432
	ds_read_b128 v[204:207], v190 offset:20480
	ds_read_b128 v[208:211], v253 offset:20480
	ds_read_b128 v[212:215], v190 offset:22528
	ds_read_b128 v[216:219], v253 offset:22528
	global_load_lds_dwordx4 v[220:221], off
	s_add_i32 m0, s81, 0x2000
	s_add_u32 s82, s60, 0x40000
	v_lshl_add_u64 v[222:223], s[60:61], 0, v[162:163]
	s_addc_u32 s83, s61, 0
	s_add_i32 s81, s77, s66
	global_load_lds_dwordx4 v[222:223], off
	v_lshl_add_u64 v[224:225], s[82:83], 0, v[154:155]
	s_mov_b32 m0, s81
	v_lshl_add_u64 v[226:227], s[62:63], 0, v[160:161]
	global_load_lds_dwordx4 v[224:225], off
	v_lshl_add_u64 v[224:225], s[82:83], 0, v[162:163]
	s_add_i32 m0, s81, 0x2000
	s_nop 0
	global_load_lds_dwordx4 v[224:225], off
	v_lshl_add_u64 v[224:225], s[62:63], 0, v[152:153]
	s_mov_b32 m0, s67
	s_nop 0
	global_load_lds_dwordx4 v[224:225], off
	s_mov_b32 m0, s68
	s_nop 0
	global_load_lds_dwordx4 v[226:227], off
	s_waitcnt vmcnt(8)
	s_waitcnt lgkmcnt(0)
	s_setprio 1
	s_barrier
	v_mfma_f32_16x16x32_bf16 v[60:63], v[128:131], v[180:183], 0
	v_mfma_f32_16x16x32_bf16 v[56:59], v[136:139], v[180:183], 0
	v_mfma_f32_16x16x32_bf16 v[44:47], v[128:131], v[196:199], 0
	v_mfma_f32_16x16x32_bf16 v[40:43], v[136:139], v[196:199], 0
	v_mfma_f32_16x16x32_bf16 v[28:31], v[128:131], v[204:207], 0
	v_mfma_f32_16x16x32_bf16 v[24:27], v[136:139], v[204:207], 0
	v_mfma_f32_16x16x32_bf16 v[12:15], v[128:131], v[212:215], 0
	v_mfma_f32_16x16x32_bf16 v[8:11], v[136:139], v[212:215], 0
	v_mfma_f32_16x16x32_bf16 v[60:63], v[132:135], v[192:195], v[60:63]
	v_mfma_f32_16x16x32_bf16 v[56:59], v[140:143], v[192:195], v[56:59]
	v_mfma_f32_16x16x32_bf16 v[44:47], v[132:135], v[200:203], v[44:47]
	v_mfma_f32_16x16x32_bf16 v[40:43], v[140:143], v[200:203], v[40:43]
	v_mfma_f32_16x16x32_bf16 v[28:31], v[132:135], v[208:211], v[28:31]
	v_mfma_f32_16x16x32_bf16 v[24:27], v[140:143], v[208:211], v[24:27]
	v_mfma_f32_16x16x32_bf16 v[12:15], v[132:135], v[216:219], v[12:15]
	v_mfma_f32_16x16x32_bf16 v[8:11], v[140:143], v[216:219], v[8:11]
	s_setprio 0
	s_setprio 1
	v_mfma_f32_16x16x32_bf16 v[52:55], v[144:147], v[180:183], 0
	v_mfma_f32_16x16x32_bf16 v[48:51], v[172:175], v[180:183], 0
	v_mfma_f32_16x16x32_bf16 v[36:39], v[144:147], v[196:199], 0
	v_mfma_f32_16x16x32_bf16 v[32:35], v[172:175], v[196:199], 0
	v_mfma_f32_16x16x32_bf16 v[20:23], v[144:147], v[204:207], 0
	v_mfma_f32_16x16x32_bf16 v[16:19], v[172:175], v[204:207], 0
	v_mfma_f32_16x16x32_bf16 v[4:7], v[144:147], v[212:215], 0
	v_mfma_f32_16x16x32_bf16 v[0:3], v[172:175], v[212:215], 0
	v_mfma_f32_16x16x32_bf16 v[52:55], v[148:151], v[192:195], v[52:55]
	v_mfma_f32_16x16x32_bf16 v[48:51], v[176:179], v[192:195], v[48:51]
	v_mfma_f32_16x16x32_bf16 v[36:39], v[148:151], v[200:203], v[36:39]
	v_mfma_f32_16x16x32_bf16 v[32:35], v[176:179], v[200:203], v[32:35]
	v_mfma_f32_16x16x32_bf16 v[20:23], v[148:151], v[208:211], v[20:23]
	v_mfma_f32_16x16x32_bf16 v[16:19], v[176:179], v[208:211], v[16:19]
	v_mfma_f32_16x16x32_bf16 v[4:7], v[148:151], v[216:219], v[4:7]
	v_mfma_f32_16x16x32_bf16 v[0:3], v[176:179], v[216:219], v[0:3]
	s_barrier
	s_setprio 0
	s_add_i32 s81, 0, 0x18000
	s_add_i32 s82, 0, 0x1c000
	v_add_u32_e32 v140, s81, v185
	v_add_u32_e32 v176, s82, v185
	ds_read_b128 v[128:131], v140
	v_xor_b32_e32 v253, 64, v140
	ds_read_b128 v[132:135], v253
	ds_read_b128 v[136:139], v140 offset:2048
	ds_read_b128 v[140:143], v253 offset:2048
	ds_read_b128 v[144:147], v176
	v_xor_b32_e32 v253, 64, v176
	ds_read_b128 v[148:151], v253
	ds_read_b128 v[172:175], v176 offset:2048
	ds_read_b128 v[176:179], v253 offset:2048
	s_add_u32 s62, s62, 0x40000
	s_addc_u32 s63, s63, 0
	s_mov_b32 m0, s69
	v_lshl_add_u64 v[228:229], s[62:63], 0, v[152:153]
	ds_read_b128 v[180:183], v190 offset:32768
	v_xor_b32_e32 v253, 64, v190
	ds_read_b128 v[192:195], v253 offset:32768
	ds_read_b128 v[196:199], v190 offset:34816
	ds_read_b128 v[200:203], v253 offset:34816
	ds_read_b128 v[204:207], v190 offset:36864
	ds_read_b128 v[208:211], v253 offset:36864
	ds_read_b128 v[212:215], v190 offset:38912
	ds_read_b128 v[216:219], v253 offset:38912
	global_load_lds_dwordx4 v[228:229], off
	v_lshl_add_u64 v[228:229], s[62:63], 0, v[160:161]
	s_mov_b32 m0, s70
	s_nop 0
	global_load_lds_dwordx4 v[228:229], off
	s_waitcnt vmcnt(8)
	s_waitcnt lgkmcnt(0)
	s_setprio 1
	s_barrier
	v_mfma_f32_16x16x32_bf16 v[124:127], v[128:131], v[180:183], v[124:127]
	v_mfma_f32_16x16x32_bf16 v[124:127], v[132:135], v[192:195], v[124:127]
	v_mfma_f32_16x16x32_bf16 v[120:123], v[140:143], v[192:195], v[120:123]
	v_mfma_f32_16x16x32_bf16 v[120:123], v[136:139], v[180:183], v[120:123]
	v_mfma_f32_16x16x32_bf16 v[104:107], v[136:139], v[196:199], v[104:107]
	v_mfma_f32_16x16x32_bf16 v[104:107], v[140:143], v[200:203], v[104:107]
	v_mfma_f32_16x16x32_bf16 v[108:111], v[132:135], v[200:203], v[108:111]
	v_mfma_f32_16x16x32_bf16 v[108:111], v[128:131], v[196:199], v[108:111]
	v_mfma_f32_16x16x32_bf16 v[92:95], v[128:131], v[204:207], v[92:95]
	v_mfma_f32_16x16x32_bf16 v[92:95], v[132:135], v[208:211], v[92:95]
	v_mfma_f32_16x16x32_bf16 v[88:91], v[140:143], v[208:211], v[88:91]
	v_mfma_f32_16x16x32_bf16 v[88:91], v[136:139], v[204:207], v[88:91]
	v_mfma_f32_16x16x32_bf16 v[72:75], v[136:139], v[212:215], v[72:75]
	v_mfma_f32_16x16x32_bf16 v[72:75], v[140:143], v[216:219], v[72:75]
	v_mfma_f32_16x16x32_bf16 v[76:79], v[132:135], v[216:219], v[76:79]
	v_mfma_f32_16x16x32_bf16 v[76:79], v[128:131], v[212:215], v[76:79]
	s_setprio 0
	s_setprio 1
	v_mfma_f32_16x16x32_bf16 v[116:119], v[144:147], v[180:183], v[116:119]
	v_mfma_f32_16x16x32_bf16 v[116:119], v[148:151], v[192:195], v[116:119]
	v_mfma_f32_16x16x32_bf16 v[112:115], v[176:179], v[192:195], v[112:115]
	v_mfma_f32_16x16x32_bf16 v[112:115], v[172:175], v[180:183], v[112:115]
	v_mfma_f32_16x16x32_bf16 v[96:99], v[172:175], v[196:199], v[96:99]
	v_mfma_f32_16x16x32_bf16 v[96:99], v[176:179], v[200:203], v[96:99]
	v_mfma_f32_16x16x32_bf16 v[100:103], v[148:151], v[200:203], v[100:103]
	v_mfma_f32_16x16x32_bf16 v[100:103], v[144:147], v[196:199], v[100:103]
	v_mfma_f32_16x16x32_bf16 v[84:87], v[144:147], v[204:207], v[84:87]
	v_mfma_f32_16x16x32_bf16 v[84:87], v[148:151], v[208:211], v[84:87]
	v_mfma_f32_16x16x32_bf16 v[80:83], v[176:179], v[208:211], v[80:83]
	v_mfma_f32_16x16x32_bf16 v[80:83], v[172:175], v[204:207], v[80:83]
	v_mfma_f32_16x16x32_bf16 v[64:67], v[172:175], v[212:215], v[64:67]
	v_mfma_f32_16x16x32_bf16 v[64:67], v[176:179], v[216:219], v[64:67]
	v_mfma_f32_16x16x32_bf16 v[68:71], v[148:151], v[216:219], v[68:71]
	v_mfma_f32_16x16x32_bf16 v[68:71], v[144:147], v[212:215], v[68:71]
	s_barrier
	s_setprio 0
	s_add_i32 s62, s81, s66
	v_lshl_add_u64 v[220:221], v[220:221], 0, s[26:27]
	s_mov_b32 m0, s62
	ds_read_b128 v[180:183], v190 offset:49152
	v_xor_b32_e32 v253, 64, v190
	ds_read_b128 v[192:195], v253 offset:49152
	ds_read_b128 v[196:199], v190 offset:51200
	ds_read_b128 v[200:203], v253 offset:51200
	ds_read_b128 v[204:207], v190 offset:53248
	ds_read_b128 v[208:211], v253 offset:53248
	ds_read_b128 v[212:215], v190 offset:55296
	ds_read_b128 v[216:219], v253 offset:55296
	global_load_lds_dwordx4 v[220:221], off
	s_add_i32 m0, s62, 0x2000
	s_add_u32 s60, s60, 0x40080
	v_lshl_add_u64 v[220:221], v[222:223], 0, s[26:27]
	s_addc_u32 s61, s61, 0
	s_add_i32 s62, s82, s66
	global_load_lds_dwordx4 v[220:221], off
	v_lshl_add_u64 v[220:221], s[60:61], 0, v[154:155]
	s_mov_b32 m0, s62
	s_nop 0
	global_load_lds_dwordx4 v[220:221], off
	v_lshl_add_u64 v[220:221], s[60:61], 0, v[162:163]
	s_add_i32 m0, s62, 0x2000
	s_nop 0
	global_load_lds_dwordx4 v[220:221], off
	v_lshl_add_u64 v[220:221], v[224:225], 0, s[26:27]
	s_mov_b32 m0, s3
	s_nop 0
	global_load_lds_dwordx4 v[220:221], off
	v_lshl_add_u64 v[220:221], v[226:227], 0, s[26:27]
	s_mov_b32 m0, s72
	s_nop 0
	global_load_lds_dwordx4 v[220:221], off
	s_waitcnt vmcnt(8)
	s_waitcnt lgkmcnt(0)
	s_setprio 1
	s_barrier
	v_mfma_f32_16x16x32_bf16 v[60:63], v[128:131], v[180:183], v[60:63]
	v_mfma_f32_16x16x32_bf16 v[60:63], v[132:135], v[192:195], v[60:63]
	v_mfma_f32_16x16x32_bf16 v[56:59], v[140:143], v[192:195], v[56:59]
	v_mfma_f32_16x16x32_bf16 v[56:59], v[136:139], v[180:183], v[56:59]
	v_mfma_f32_16x16x32_bf16 v[40:43], v[136:139], v[196:199], v[40:43]
	v_mfma_f32_16x16x32_bf16 v[40:43], v[140:143], v[200:203], v[40:43]
	v_mfma_f32_16x16x32_bf16 v[44:47], v[132:135], v[200:203], v[44:47]
	v_mfma_f32_16x16x32_bf16 v[44:47], v[128:131], v[196:199], v[44:47]
	v_mfma_f32_16x16x32_bf16 v[28:31], v[128:131], v[204:207], v[28:31]
	v_mfma_f32_16x16x32_bf16 v[28:31], v[132:135], v[208:211], v[28:31]
	v_mfma_f32_16x16x32_bf16 v[24:27], v[140:143], v[208:211], v[24:27]
	v_mfma_f32_16x16x32_bf16 v[24:27], v[136:139], v[204:207], v[24:27]
	v_mfma_f32_16x16x32_bf16 v[8:11], v[136:139], v[212:215], v[8:11]
	v_mfma_f32_16x16x32_bf16 v[8:11], v[140:143], v[216:219], v[8:11]
	v_mfma_f32_16x16x32_bf16 v[12:15], v[132:135], v[216:219], v[12:15]
	v_mfma_f32_16x16x32_bf16 v[12:15], v[128:131], v[212:215], v[12:15]
	s_setprio 0
	s_setprio 1
	v_mfma_f32_16x16x32_bf16 v[52:55], v[144:147], v[180:183], v[52:55]
	v_mfma_f32_16x16x32_bf16 v[52:55], v[148:151], v[192:195], v[52:55]
	v_mfma_f32_16x16x32_bf16 v[48:51], v[176:179], v[192:195], v[48:51]
	v_mfma_f32_16x16x32_bf16 v[48:51], v[172:175], v[180:183], v[48:51]
	v_mfma_f32_16x16x32_bf16 v[32:35], v[172:175], v[196:199], v[32:35]
	v_mfma_f32_16x16x32_bf16 v[32:35], v[176:179], v[200:203], v[32:35]
	v_mfma_f32_16x16x32_bf16 v[36:39], v[148:151], v[200:203], v[36:39]
	v_mfma_f32_16x16x32_bf16 v[36:39], v[144:147], v[196:199], v[36:39]
	v_mfma_f32_16x16x32_bf16 v[20:23], v[144:147], v[204:207], v[20:23]
	v_mfma_f32_16x16x32_bf16 v[20:23], v[148:151], v[208:211], v[20:23]
	v_mfma_f32_16x16x32_bf16 v[16:19], v[176:179], v[208:211], v[16:19]
	v_mfma_f32_16x16x32_bf16 v[16:19], v[172:175], v[204:207], v[16:19]
	v_mfma_f32_16x16x32_bf16 v[0:3], v[172:175], v[212:215], v[0:3]
	v_mfma_f32_16x16x32_bf16 v[0:3], v[176:179], v[216:219], v[0:3]
	v_mfma_f32_16x16x32_bf16 v[4:7], v[148:151], v[216:219], v[4:7]
	v_mfma_f32_16x16x32_bf16 v[4:7], v[144:147], v[212:215], v[4:7]
	s_barrier
	s_setprio 0
	s_add_i32 s80, s80, 2
	s_add_u32 s78, s78, 0x100
	s_addc_u32 s79, s79, 0
	s_add_u32 s58, s58, 0x100
	s_addc_u32 s59, s59, 0
	s_cmp_gt_u32 s80, 13
.LBB0_1011:
	ds_read_b128 v[128:131], v188
	v_xor_b32_e32 v253, 64, v188
	ds_read_b128 v[132:135], v253
	ds_read_b128 v[136:139], v188 offset:2048
	ds_read_b128 v[140:143], v253 offset:2048
	ds_read_b128 v[144:147], v189
	v_xor_b32_e32 v253, 64, v189
	ds_read_b128 v[148:151], v253
	ds_read_b128 v[172:175], v189 offset:2048
	ds_read_b128 v[176:179], v253 offset:2048
	s_add_u32 s60, s58, 0xfffc0080
	s_addc_u32 s61, s59, -1
	s_cmp_eq_u32 s80, 12
	s_cselect_b32 s63, s15, s61
	s_cselect_b32 s62, s51, s60
	s_cselect_b32 s61, s49, s79
	s_cselect_b32 s60, s57, s78
	v_lshl_add_u64 v[220:221], s[58:59], 0, v[166:167]
	s_add_i32 m0, s67, 0xc000
	ds_read_b128 v[180:183], v190
	v_xor_b32_e32 v253, 64, v190
	ds_read_b128 v[192:195], v253
	ds_read_b128 v[196:199], v190 offset:2048
	ds_read_b128 v[200:203], v253 offset:2048
	ds_read_b128 v[204:207], v190 offset:4096
	ds_read_b128 v[208:211], v253 offset:4096
	ds_read_b128 v[212:215], v190 offset:6144
	ds_read_b128 v[216:219], v253 offset:6144
	global_load_lds_dwordx4 v[220:221], off
	v_lshl_add_u64 v[220:221], s[58:59], 0, v[164:165]
	s_add_i32 m0, s67, 0xe000
	s_nop 0
	global_load_lds_dwordx4 v[220:221], off
	s_waitcnt vmcnt(8)
	s_waitcnt lgkmcnt(0)
	s_setprio 1
	s_barrier
	v_mfma_f32_16x16x32_bf16 v[124:127], v[128:131], v[180:183], v[124:127]
	v_mfma_f32_16x16x32_bf16 v[124:127], v[132:135], v[192:195], v[124:127]
	v_mfma_f32_16x16x32_bf16 v[120:123], v[140:143], v[192:195], v[120:123]
	v_mfma_f32_16x16x32_bf16 v[120:123], v[136:139], v[180:183], v[120:123]
	v_mfma_f32_16x16x32_bf16 v[104:107], v[136:139], v[196:199], v[104:107]
	v_mfma_f32_16x16x32_bf16 v[104:107], v[140:143], v[200:203], v[104:107]
	v_mfma_f32_16x16x32_bf16 v[108:111], v[132:135], v[200:203], v[108:111]
	v_mfma_f32_16x16x32_bf16 v[108:111], v[128:131], v[196:199], v[108:111]
	v_mfma_f32_16x16x32_bf16 v[92:95], v[128:131], v[204:207], v[92:95]
	v_mfma_f32_16x16x32_bf16 v[92:95], v[132:135], v[208:211], v[92:95]
	v_mfma_f32_16x16x32_bf16 v[88:91], v[140:143], v[208:211], v[88:91]
	v_mfma_f32_16x16x32_bf16 v[88:91], v[136:139], v[204:207], v[88:91]
	v_mfma_f32_16x16x32_bf16 v[72:75], v[136:139], v[212:215], v[72:75]
	v_mfma_f32_16x16x32_bf16 v[72:75], v[140:143], v[216:219], v[72:75]
	v_mfma_f32_16x16x32_bf16 v[76:79], v[132:135], v[216:219], v[76:79]
	v_mfma_f32_16x16x32_bf16 v[76:79], v[128:131], v[212:215], v[76:79]
	s_setprio 0
	s_setprio 1
	v_mfma_f32_16x16x32_bf16 v[116:119], v[144:147], v[180:183], v[116:119]
	v_mfma_f32_16x16x32_bf16 v[116:119], v[148:151], v[192:195], v[116:119]
	v_mfma_f32_16x16x32_bf16 v[112:115], v[176:179], v[192:195], v[112:115]
	v_mfma_f32_16x16x32_bf16 v[112:115], v[172:175], v[180:183], v[112:115]
	v_mfma_f32_16x16x32_bf16 v[96:99], v[172:175], v[196:199], v[96:99]
	v_mfma_f32_16x16x32_bf16 v[96:99], v[176:179], v[200:203], v[96:99]
	v_mfma_f32_16x16x32_bf16 v[100:103], v[148:151], v[200:203], v[100:103]
	v_mfma_f32_16x16x32_bf16 v[100:103], v[144:147], v[196:199], v[100:103]
	v_mfma_f32_16x16x32_bf16 v[84:87], v[144:147], v[204:207], v[84:87]
	v_mfma_f32_16x16x32_bf16 v[84:87], v[148:151], v[208:211], v[84:87]
	v_mfma_f32_16x16x32_bf16 v[80:83], v[176:179], v[208:211], v[80:83]
	v_mfma_f32_16x16x32_bf16 v[80:83], v[172:175], v[204:207], v[80:83]
	v_mfma_f32_16x16x32_bf16 v[64:67], v[172:175], v[212:215], v[64:67]
	v_mfma_f32_16x16x32_bf16 v[64:67], v[176:179], v[216:219], v[64:67]
	v_mfma_f32_16x16x32_bf16 v[68:71], v[148:151], v[216:219], v[68:71]
	v_mfma_f32_16x16x32_bf16 v[68:71], v[144:147], v[212:215], v[68:71]
	s_barrier
	s_setprio 0
	s_add_i32 s81, s76, s66
	v_lshl_add_u64 v[220:221], s[60:61], 0, v[154:155]
	s_mov_b32 m0, s81
	ds_read_b128 v[180:183], v190 offset:16384
	v_xor_b32_e32 v253, 64, v190
	ds_read_b128 v[192:195], v253 offset:16384
	ds_read_b128 v[196:199], v190 offset:18432
	ds_read_b128 v[200:203], v253 offset:18432
	ds_read_b128 v[204:207], v190 offset:20480
	ds_read_b128 v[208:211], v253 offset:20480
	ds_read_b128 v[212:215], v190 offset:22528
	ds_read_b128 v[216:219], v253 offset:22528
	global_load_lds_dwordx4 v[220:221], off
	s_add_i32 m0, s81, 0x2000
	s_add_u32 s82, s60, 0x40000
	v_lshl_add_u64 v[222:223], s[60:61], 0, v[162:163]
	s_addc_u32 s83, s61, 0
	s_add_i32 s81, s77, s66
	global_load_lds_dwordx4 v[222:223], off
	v_lshl_add_u64 v[224:225], s[82:83], 0, v[154:155]
	s_mov_b32 m0, s81
	v_lshl_add_u64 v[226:227], s[62:63], 0, v[160:161]
	global_load_lds_dwordx4 v[224:225], off
	v_lshl_add_u64 v[224:225], s[82:83], 0, v[162:163]
	s_add_i32 m0, s81, 0x2000
	s_nop 0
	global_load_lds_dwordx4 v[224:225], off
	v_lshl_add_u64 v[224:225], s[62:63], 0, v[152:153]
	s_mov_b32 m0, s67
	s_nop 0
	global_load_lds_dwordx4 v[224:225], off
	s_mov_b32 m0, s68
	s_nop 0
	global_load_lds_dwordx4 v[226:227], off
	s_waitcnt vmcnt(8)
	s_waitcnt lgkmcnt(0)
	s_setprio 1
	s_barrier
	v_mfma_f32_16x16x32_bf16 v[60:63], v[128:131], v[180:183], v[60:63]
	v_mfma_f32_16x16x32_bf16 v[60:63], v[132:135], v[192:195], v[60:63]
	v_mfma_f32_16x16x32_bf16 v[56:59], v[140:143], v[192:195], v[56:59]
	v_mfma_f32_16x16x32_bf16 v[56:59], v[136:139], v[180:183], v[56:59]
	v_mfma_f32_16x16x32_bf16 v[40:43], v[136:139], v[196:199], v[40:43]
	v_mfma_f32_16x16x32_bf16 v[40:43], v[140:143], v[200:203], v[40:43]
	v_mfma_f32_16x16x32_bf16 v[44:47], v[132:135], v[200:203], v[44:47]
	v_mfma_f32_16x16x32_bf16 v[44:47], v[128:131], v[196:199], v[44:47]
	v_mfma_f32_16x16x32_bf16 v[28:31], v[128:131], v[204:207], v[28:31]
	v_mfma_f32_16x16x32_bf16 v[28:31], v[132:135], v[208:211], v[28:31]
	v_mfma_f32_16x16x32_bf16 v[24:27], v[140:143], v[208:211], v[24:27]
	v_mfma_f32_16x16x32_bf16 v[24:27], v[136:139], v[204:207], v[24:27]
	v_mfma_f32_16x16x32_bf16 v[8:11], v[136:139], v[212:215], v[8:11]
	v_mfma_f32_16x16x32_bf16 v[8:11], v[140:143], v[216:219], v[8:11]
	v_mfma_f32_16x16x32_bf16 v[12:15], v[132:135], v[216:219], v[12:15]
	v_mfma_f32_16x16x32_bf16 v[12:15], v[128:131], v[212:215], v[12:15]
	s_setprio 0
	s_setprio 1
	v_mfma_f32_16x16x32_bf16 v[52:55], v[144:147], v[180:183], v[52:55]
	v_mfma_f32_16x16x32_bf16 v[52:55], v[148:151], v[192:195], v[52:55]
	v_mfma_f32_16x16x32_bf16 v[48:51], v[176:179], v[192:195], v[48:51]
	v_mfma_f32_16x16x32_bf16 v[48:51], v[172:175], v[180:183], v[48:51]
	v_mfma_f32_16x16x32_bf16 v[32:35], v[172:175], v[196:199], v[32:35]
	v_mfma_f32_16x16x32_bf16 v[32:35], v[176:179], v[200:203], v[32:35]
	v_mfma_f32_16x16x32_bf16 v[36:39], v[148:151], v[200:203], v[36:39]
	v_mfma_f32_16x16x32_bf16 v[36:39], v[144:147], v[196:199], v[36:39]
	v_mfma_f32_16x16x32_bf16 v[20:23], v[144:147], v[204:207], v[20:23]
	v_mfma_f32_16x16x32_bf16 v[20:23], v[148:151], v[208:211], v[20:23]
	v_mfma_f32_16x16x32_bf16 v[16:19], v[176:179], v[208:211], v[16:19]
	v_mfma_f32_16x16x32_bf16 v[16:19], v[172:175], v[204:207], v[16:19]
	v_mfma_f32_16x16x32_bf16 v[0:3], v[172:175], v[212:215], v[0:3]
	v_mfma_f32_16x16x32_bf16 v[0:3], v[176:179], v[216:219], v[0:3]
	v_mfma_f32_16x16x32_bf16 v[4:7], v[148:151], v[216:219], v[4:7]
	v_mfma_f32_16x16x32_bf16 v[4:7], v[144:147], v[212:215], v[4:7]
	s_barrier
	s_setprio 0
	s_add_i32 s81, 0, 0x18000
	s_add_i32 s82, 0, 0x1c000
	v_add_u32_e32 v140, s81, v185
	v_add_u32_e32 v176, s82, v185
	ds_read_b128 v[128:131], v140
	v_xor_b32_e32 v253, 64, v140
	ds_read_b128 v[132:135], v253
	ds_read_b128 v[136:139], v140 offset:2048
	ds_read_b128 v[140:143], v253 offset:2048
	ds_read_b128 v[144:147], v176
	v_xor_b32_e32 v253, 64, v176
	ds_read_b128 v[148:151], v253
	ds_read_b128 v[172:175], v176 offset:2048
	ds_read_b128 v[176:179], v253 offset:2048
	s_add_u32 s62, s62, 0x40000
	s_addc_u32 s63, s63, 0
	s_mov_b32 m0, s69
	v_lshl_add_u64 v[228:229], s[62:63], 0, v[152:153]
	ds_read_b128 v[180:183], v190 offset:32768
	v_xor_b32_e32 v253, 64, v190
	ds_read_b128 v[192:195], v253 offset:32768
	ds_read_b128 v[196:199], v190 offset:34816
	ds_read_b128 v[200:203], v253 offset:34816
	ds_read_b128 v[204:207], v190 offset:36864
	ds_read_b128 v[208:211], v253 offset:36864
	ds_read_b128 v[212:215], v190 offset:38912
	ds_read_b128 v[216:219], v253 offset:38912
	global_load_lds_dwordx4 v[228:229], off
	v_lshl_add_u64 v[228:229], s[62:63], 0, v[160:161]
	s_mov_b32 m0, s70
	s_nop 0
	global_load_lds_dwordx4 v[228:229], off
	s_waitcnt vmcnt(8)
	s_waitcnt lgkmcnt(0)
	s_setprio 1
	s_barrier
	v_mfma_f32_16x16x32_bf16 v[124:127], v[128:131], v[180:183], v[124:127]
	v_mfma_f32_16x16x32_bf16 v[124:127], v[132:135], v[192:195], v[124:127]
	v_mfma_f32_16x16x32_bf16 v[120:123], v[140:143], v[192:195], v[120:123]
	v_mfma_f32_16x16x32_bf16 v[120:123], v[136:139], v[180:183], v[120:123]
	v_mfma_f32_16x16x32_bf16 v[104:107], v[136:139], v[196:199], v[104:107]
	v_mfma_f32_16x16x32_bf16 v[104:107], v[140:143], v[200:203], v[104:107]
	v_mfma_f32_16x16x32_bf16 v[108:111], v[132:135], v[200:203], v[108:111]
	v_mfma_f32_16x16x32_bf16 v[108:111], v[128:131], v[196:199], v[108:111]
	v_mfma_f32_16x16x32_bf16 v[92:95], v[128:131], v[204:207], v[92:95]
	v_mfma_f32_16x16x32_bf16 v[92:95], v[132:135], v[208:211], v[92:95]
	v_mfma_f32_16x16x32_bf16 v[88:91], v[140:143], v[208:211], v[88:91]
	v_mfma_f32_16x16x32_bf16 v[88:91], v[136:139], v[204:207], v[88:91]
	v_mfma_f32_16x16x32_bf16 v[72:75], v[136:139], v[212:215], v[72:75]
	v_mfma_f32_16x16x32_bf16 v[72:75], v[140:143], v[216:219], v[72:75]
	v_mfma_f32_16x16x32_bf16 v[76:79], v[132:135], v[216:219], v[76:79]
	v_mfma_f32_16x16x32_bf16 v[76:79], v[128:131], v[212:215], v[76:79]
	s_setprio 0
	s_setprio 1
	v_mfma_f32_16x16x32_bf16 v[116:119], v[144:147], v[180:183], v[116:119]
	v_mfma_f32_16x16x32_bf16 v[116:119], v[148:151], v[192:195], v[116:119]
	v_mfma_f32_16x16x32_bf16 v[112:115], v[176:179], v[192:195], v[112:115]
	v_mfma_f32_16x16x32_bf16 v[112:115], v[172:175], v[180:183], v[112:115]
	v_mfma_f32_16x16x32_bf16 v[96:99], v[172:175], v[196:199], v[96:99]
	v_mfma_f32_16x16x32_bf16 v[96:99], v[176:179], v[200:203], v[96:99]
	v_mfma_f32_16x16x32_bf16 v[100:103], v[148:151], v[200:203], v[100:103]
	v_mfma_f32_16x16x32_bf16 v[100:103], v[144:147], v[196:199], v[100:103]
	v_mfma_f32_16x16x32_bf16 v[84:87], v[144:147], v[204:207], v[84:87]
	v_mfma_f32_16x16x32_bf16 v[84:87], v[148:151], v[208:211], v[84:87]
	v_mfma_f32_16x16x32_bf16 v[80:83], v[176:179], v[208:211], v[80:83]
	v_mfma_f32_16x16x32_bf16 v[80:83], v[172:175], v[204:207], v[80:83]
	v_mfma_f32_16x16x32_bf16 v[64:67], v[172:175], v[212:215], v[64:67]
	v_mfma_f32_16x16x32_bf16 v[64:67], v[176:179], v[216:219], v[64:67]
	v_mfma_f32_16x16x32_bf16 v[68:71], v[148:151], v[216:219], v[68:71]
	v_mfma_f32_16x16x32_bf16 v[68:71], v[144:147], v[212:215], v[68:71]
	s_barrier
	s_setprio 0
	s_add_i32 s62, s81, s66
	v_lshl_add_u64 v[220:221], v[220:221], 0, s[26:27]
	s_mov_b32 m0, s62
	ds_read_b128 v[180:183], v190 offset:49152
	v_xor_b32_e32 v253, 64, v190
	ds_read_b128 v[192:195], v253 offset:49152
	ds_read_b128 v[196:199], v190 offset:51200
	ds_read_b128 v[200:203], v253 offset:51200
	ds_read_b128 v[204:207], v190 offset:53248
	ds_read_b128 v[208:211], v253 offset:53248
	ds_read_b128 v[212:215], v190 offset:55296
	ds_read_b128 v[216:219], v253 offset:55296
	global_load_lds_dwordx4 v[220:221], off
	s_add_i32 m0, s62, 0x2000
	s_add_u32 s60, s60, 0x40080
	v_lshl_add_u64 v[220:221], v[222:223], 0, s[26:27]
	s_addc_u32 s61, s61, 0
	s_add_i32 s62, s82, s66
	global_load_lds_dwordx4 v[220:221], off
	v_lshl_add_u64 v[220:221], s[60:61], 0, v[154:155]
	s_mov_b32 m0, s62
	s_nop 0
	global_load_lds_dwordx4 v[220:221], off
	v_lshl_add_u64 v[220:221], s[60:61], 0, v[162:163]
	s_add_i32 m0, s62, 0x2000
	s_nop 0
	global_load_lds_dwordx4 v[220:221], off
	v_lshl_add_u64 v[220:221], v[224:225], 0, s[26:27]
	s_mov_b32 m0, s3
	s_nop 0
	global_load_lds_dwordx4 v[220:221], off
	v_lshl_add_u64 v[220:221], v[226:227], 0, s[26:27]
	s_mov_b32 m0, s72
	s_nop 0
	global_load_lds_dwordx4 v[220:221], off
	s_waitcnt vmcnt(8)
	s_waitcnt lgkmcnt(0)
	s_setprio 1
	s_barrier
	v_mfma_f32_16x16x32_bf16 v[60:63], v[128:131], v[180:183], v[60:63]
	v_mfma_f32_16x16x32_bf16 v[60:63], v[132:135], v[192:195], v[60:63]
	v_mfma_f32_16x16x32_bf16 v[56:59], v[140:143], v[192:195], v[56:59]
	v_mfma_f32_16x16x32_bf16 v[56:59], v[136:139], v[180:183], v[56:59]
	v_mfma_f32_16x16x32_bf16 v[40:43], v[136:139], v[196:199], v[40:43]
	v_mfma_f32_16x16x32_bf16 v[40:43], v[140:143], v[200:203], v[40:43]
	v_mfma_f32_16x16x32_bf16 v[44:47], v[132:135], v[200:203], v[44:47]
	v_mfma_f32_16x16x32_bf16 v[44:47], v[128:131], v[196:199], v[44:47]
	v_mfma_f32_16x16x32_bf16 v[28:31], v[128:131], v[204:207], v[28:31]
	v_mfma_f32_16x16x32_bf16 v[28:31], v[132:135], v[208:211], v[28:31]
	v_mfma_f32_16x16x32_bf16 v[24:27], v[140:143], v[208:211], v[24:27]
	v_mfma_f32_16x16x32_bf16 v[24:27], v[136:139], v[204:207], v[24:27]
	v_mfma_f32_16x16x32_bf16 v[8:11], v[136:139], v[212:215], v[8:11]
	v_mfma_f32_16x16x32_bf16 v[8:11], v[140:143], v[216:219], v[8:11]
	v_mfma_f32_16x16x32_bf16 v[12:15], v[132:135], v[216:219], v[12:15]
	v_mfma_f32_16x16x32_bf16 v[12:15], v[128:131], v[212:215], v[12:15]
	s_setprio 0
	s_setprio 1
	v_mfma_f32_16x16x32_bf16 v[52:55], v[144:147], v[180:183], v[52:55]
	v_mfma_f32_16x16x32_bf16 v[52:55], v[148:151], v[192:195], v[52:55]
	v_mfma_f32_16x16x32_bf16 v[48:51], v[176:179], v[192:195], v[48:51]
	v_mfma_f32_16x16x32_bf16 v[48:51], v[172:175], v[180:183], v[48:51]
	v_mfma_f32_16x16x32_bf16 v[32:35], v[172:175], v[196:199], v[32:35]
	v_mfma_f32_16x16x32_bf16 v[32:35], v[176:179], v[200:203], v[32:35]
	v_mfma_f32_16x16x32_bf16 v[36:39], v[148:151], v[200:203], v[36:39]
	v_mfma_f32_16x16x32_bf16 v[36:39], v[144:147], v[196:199], v[36:39]
	v_mfma_f32_16x16x32_bf16 v[20:23], v[144:147], v[204:207], v[20:23]
	v_mfma_f32_16x16x32_bf16 v[20:23], v[148:151], v[208:211], v[20:23]
	v_mfma_f32_16x16x32_bf16 v[16:19], v[176:179], v[208:211], v[16:19]
	v_mfma_f32_16x16x32_bf16 v[16:19], v[172:175], v[204:207], v[16:19]
	v_mfma_f32_16x16x32_bf16 v[0:3], v[172:175], v[212:215], v[0:3]
	v_mfma_f32_16x16x32_bf16 v[0:3], v[176:179], v[216:219], v[0:3]
	v_mfma_f32_16x16x32_bf16 v[4:7], v[148:151], v[216:219], v[4:7]
	v_mfma_f32_16x16x32_bf16 v[4:7], v[144:147], v[212:215], v[4:7]
	s_barrier
	s_setprio 0
	s_add_i32 s80, s80, 2
	s_add_u32 s78, s78, 0x100
	s_addc_u32 s79, s79, 0
	s_add_u32 s58, s58, 0x100
	s_addc_u32 s59, s59, 0
	s_cmp_gt_u32 s80, 13
	s_cbranch_scc0 .LBB0_1011
	s_and_b64 vcc, exec, s[28:29]
	s_cbranch_vccz .LBB0_1014
	s_barrier

.LBB0_1096:
	s_ashr_i32 s25, s24, 31
	s_lshl_b64 s[26:27], s[24:25], 19
	s_add_u32 s26, s3, s26
	s_addc_u32 s27, s33, s27
	s_and_b64 s[28:29], s[6:7], exec
	s_cselect_b32 s25, s27, s47
	s_cselect_b32 s65, s26, s46
	s_ashr_i32 s23, s22, 31
	s_lshl_b64 s[28:29], s[22:23], 19
	s_add_u32 s28, s35, s28
	s_addc_u32 s29, s48, s29
	s_and_b64 s[66:67], s[6:7], exec
	s_cselect_b32 s66, s29, s45
	s_cselect_b32 s67, s28, s44
	s_lshl_b32 s23, s30, 8
	v_add_u32_e32 v0, s23, v148
	s_add_u32 s68, s44, 0x100
	v_ashrrev_i32_e32 v1, 31, v0
	s_addc_u32 s69, s45, 0
	v_lshl_add_u64 v[144:145], v[0:1], 4, s[12:13]
	s_add_u32 s30, s46, 0x40080
	s_addc_u32 s31, s47, 0
	s_mov_b32 s70, -2
	s_mov_b64 s[44:45], 0
	s_cmp_eq_u32 s56, 1
	s_cbranch_scc1 .Lfa_10
	v_add_u32_e32 v153, s61, v147
	ds_read_b128 v[160:163], v153
	v_xor_b32_e32 v253, 64, v153
	ds_read_b128 v[164:167], v253
	ds_read_b128 v[168:171], v153 offset:2048
	ds_read_b128 v[172:175], v253 offset:2048
	v_add_u32_e32 v153, s62, v147
	ds_read_b128 v[176:179], v153
	v_xor_b32_e32 v253, 64, v153
	ds_read_b128 v[180:183], v253
	ds_read_b128 v[184:187], v153 offset:2048
	ds_read_b128 v[188:191], v253 offset:2048
	s_add_u32 s46, s30, 0xfffc0080
	s_addc_u32 s47, s31, -1
	s_and_b64 s[44:45], s[44:45], exec
	s_cselect_b32 s47, s25, s47
	s_cselect_b32 s46, s65, s46
	s_cselect_b32 s45, s66, s69
	s_cselect_b32 s44, s67, s68
	v_lshl_add_u64 v[154:155], s[30:31], 0, v[138:139]
	s_add_i32 m0, s52, 0xc000
	ds_read_b128 v[192:195], v150
	v_xor_b32_e32 v253, 64, v150
	ds_read_b128 v[196:199], v253
	ds_read_b128 v[200:203], v150 offset:2048
	ds_read_b128 v[204:207], v253 offset:2048
	ds_read_b128 v[208:211], v150 offset:4096
	ds_read_b128 v[212:215], v253 offset:4096
	ds_read_b128 v[216:219], v150 offset:6144
	ds_read_b128 v[220:223], v253 offset:6144
	global_load_lds_dwordx4 v[154:155], off
	v_lshl_add_u64 v[154:155], s[30:31], 0, v[136:137]
	s_add_i32 m0, s52, 0xe000
	s_nop 0
	global_load_lds_dwordx4 v[154:155], off
	s_waitcnt vmcnt(16)
	s_waitcnt lgkmcnt(0)
	s_setprio 1
	s_barrier
	v_mfma_f32_16x16x32_bf16 v[124:127], v[160:163], v[192:195], 0
	v_mfma_f32_16x16x32_bf16 v[116:119], v[168:171], v[192:195], 0
	v_mfma_f32_16x16x32_bf16 v[108:111], v[160:163], v[200:203], 0
	v_mfma_f32_16x16x32_bf16 v[100:103], v[168:171], v[200:203], 0
	v_mfma_f32_16x16x32_bf16 v[92:95], v[160:163], v[208:211], 0
	v_mfma_f32_16x16x32_bf16 v[84:87], v[168:171], v[208:211], 0
	v_mfma_f32_16x16x32_bf16 v[76:79], v[160:163], v[216:219], 0
	v_mfma_f32_16x16x32_bf16 v[68:71], v[168:171], v[216:219], 0
	v_mfma_f32_16x16x32_bf16 v[124:127], v[164:167], v[196:199], v[124:127]
	v_mfma_f32_16x16x32_bf16 v[116:119], v[172:175], v[196:199], v[116:119]
	v_mfma_f32_16x16x32_bf16 v[108:111], v[164:167], v[204:207], v[108:111]
	v_mfma_f32_16x16x32_bf16 v[100:103], v[172:175], v[204:207], v[100:103]
	v_mfma_f32_16x16x32_bf16 v[92:95], v[164:167], v[212:215], v[92:95]
	v_mfma_f32_16x16x32_bf16 v[84:87], v[172:175], v[212:215], v[84:87]
	v_mfma_f32_16x16x32_bf16 v[76:79], v[164:167], v[220:223], v[76:79]
	v_mfma_f32_16x16x32_bf16 v[68:71], v[172:175], v[220:223], v[68:71]
	s_setprio 0
	s_setprio 1
	v_mfma_f32_16x16x32_bf16 v[120:123], v[176:179], v[192:195], 0
	v_mfma_f32_16x16x32_bf16 v[112:115], v[184:187], v[192:195], 0
	v_mfma_f32_16x16x32_bf16 v[104:107], v[176:179], v[200:203], 0
	v_mfma_f32_16x16x32_bf16 v[96:99], v[184:187], v[200:203], 0
	v_mfma_f32_16x16x32_bf16 v[88:91], v[176:179], v[208:211], 0
	v_mfma_f32_16x16x32_bf16 v[80:83], v[184:187], v[208:211], 0
	v_mfma_f32_16x16x32_bf16 v[72:75], v[176:179], v[216:219], 0
	v_mfma_f32_16x16x32_bf16 v[64:67], v[184:187], v[216:219], 0
	v_mfma_f32_16x16x32_bf16 v[120:123], v[180:183], v[196:199], v[120:123]
	v_mfma_f32_16x16x32_bf16 v[112:115], v[188:191], v[196:199], v[112:115]
	v_mfma_f32_16x16x32_bf16 v[104:107], v[180:183], v[204:207], v[104:107]
	v_mfma_f32_16x16x32_bf16 v[96:99], v[188:191], v[204:207], v[96:99]
	v_mfma_f32_16x16x32_bf16 v[88:91], v[180:183], v[212:215], v[88:91]
	v_mfma_f32_16x16x32_bf16 v[80:83], v[188:191], v[212:215], v[80:83]
	v_mfma_f32_16x16x32_bf16 v[72:75], v[180:183], v[220:223], v[72:75]
	v_mfma_f32_16x16x32_bf16 v[64:67], v[188:191], v[220:223], v[64:67]
	s_barrier
	s_setprio 0
	s_add_i32 s71, s61, s49
	v_lshl_add_u64 v[154:155], s[44:45], 0, v[132:133]
	s_mov_b32 m0, s71
	ds_read_b128 v[192:195], v150 offset:16384
	v_xor_b32_e32 v253, 64, v150
	ds_read_b128 v[196:199], v253 offset:16384
	ds_read_b128 v[200:203], v150 offset:18432
	ds_read_b128 v[204:207], v253 offset:18432
	ds_read_b128 v[208:211], v150 offset:20480
	ds_read_b128 v[212:215], v253 offset:20480
	ds_read_b128 v[216:219], v150 offset:22528
	ds_read_b128 v[220:223], v253 offset:22528
	global_load_lds_dwordx4 v[154:155], off
	s_add_i32 m0, s71, 0x2000
	s_add_u32 s72, s44, 0x40000
	v_lshl_add_u64 v[224:225], s[44:45], 0, v[128:129]
	s_addc_u32 s73, s45, 0
	s_add_i32 s71, s62, s49
	global_load_lds_dwordx4 v[224:225], off
	v_lshl_add_u64 v[226:227], s[72:73], 0, v[132:133]
	s_mov_b32 m0, s71
	v_lshl_add_u64 v[228:229], s[46:47], 0, v[130:131]
	global_load_lds_dwordx4 v[226:227], off
	v_lshl_add_u64 v[226:227], s[72:73], 0, v[128:129]
	s_add_i32 m0, s71, 0x2000
	s_nop 0
	global_load_lds_dwordx4 v[226:227], off
	v_lshl_add_u64 v[226:227], s[46:47], 0, v[134:135]
	s_mov_b32 m0, s52
	s_nop 0
	global_load_lds_dwordx4 v[226:227], off
	s_mov_b32 m0, s53
	s_nop 0
	global_load_lds_dwordx4 v[228:229], off
	s_waitcnt vmcnt(16)
	s_waitcnt lgkmcnt(0)
	s_setprio 1
	s_barrier
	v_mfma_f32_16x16x32_bf16 v[60:63], v[160:163], v[192:195], 0
	v_mfma_f32_16x16x32_bf16 v[52:55], v[168:171], v[192:195], 0
	v_mfma_f32_16x16x32_bf16 v[44:47], v[160:163], v[200:203], 0
	v_mfma_f32_16x16x32_bf16 v[36:39], v[168:171], v[200:203], 0
	v_mfma_f32_16x16x32_bf16 v[28:31], v[160:163], v[208:211], 0
	v_mfma_f32_16x16x32_bf16 v[20:23], v[168:171], v[208:211], 0
	v_mfma_f32_16x16x32_bf16 v[12:15], v[160:163], v[216:219], 0
	v_mfma_f32_16x16x32_bf16 v[4:7], v[168:171], v[216:219], 0
	v_mfma_f32_16x16x32_bf16 v[60:63], v[164:167], v[196:199], v[60:63]
	v_mfma_f32_16x16x32_bf16 v[52:55], v[172:175], v[196:199], v[52:55]
	v_mfma_f32_16x16x32_bf16 v[44:47], v[164:167], v[204:207], v[44:47]
	v_mfma_f32_16x16x32_bf16 v[36:39], v[172:175], v[204:207], v[36:39]
	v_mfma_f32_16x16x32_bf16 v[28:31], v[164:167], v[212:215], v[28:31]
	v_mfma_f32_16x16x32_bf16 v[20:23], v[172:175], v[212:215], v[20:23]
	v_mfma_f32_16x16x32_bf16 v[12:15], v[164:167], v[220:223], v[12:15]
	v_mfma_f32_16x16x32_bf16 v[4:7], v[172:175], v[220:223], v[4:7]
	s_setprio 0
	s_setprio 1
	v_mfma_f32_16x16x32_bf16 v[56:59], v[176:179], v[192:195], 0
	v_mfma_f32_16x16x32_bf16 v[48:51], v[184:187], v[192:195], 0
	v_mfma_f32_16x16x32_bf16 v[40:43], v[176:179], v[200:203], 0
	v_mfma_f32_16x16x32_bf16 v[32:35], v[184:187], v[200:203], 0
	v_mfma_f32_16x16x32_bf16 v[24:27], v[176:179], v[208:211], 0
	v_mfma_f32_16x16x32_bf16 v[16:19], v[184:187], v[208:211], 0
	v_mfma_f32_16x16x32_bf16 v[8:11], v[176:179], v[216:219], 0
	v_mfma_f32_16x16x32_bf16 v[0:3], v[184:187], v[216:219], 0
	v_mfma_f32_16x16x32_bf16 v[56:59], v[180:183], v[196:199], v[56:59]
	v_mfma_f32_16x16x32_bf16 v[48:51], v[188:191], v[196:199], v[48:51]
	v_mfma_f32_16x16x32_bf16 v[40:43], v[180:183], v[204:207], v[40:43]
	v_mfma_f32_16x16x32_bf16 v[32:35], v[188:191], v[204:207], v[32:35]
	v_mfma_f32_16x16x32_bf16 v[24:27], v[180:183], v[212:215], v[24:27]
	v_mfma_f32_16x16x32_bf16 v[16:19], v[188:191], v[212:215], v[16:19]
	v_mfma_f32_16x16x32_bf16 v[8:11], v[180:183], v[220:223], v[8:11]
	v_mfma_f32_16x16x32_bf16 v[0:3], v[188:191], v[220:223], v[0:3]
	s_barrier
	s_setprio 0
	s_add_i32 s71, 0, 0x18000
	v_add_u32_e32 v153, s71, v147
	s_add_i32 s72, 0, 0x1c000
	ds_read_b128 v[160:163], v153
	v_xor_b32_e32 v253, 64, v153
	ds_read_b128 v[164:167], v253
	ds_read_b128 v[168:171], v153 offset:2048
	ds_read_b128 v[172:175], v253 offset:2048
	v_add_u32_e32 v153, s72, v147
	ds_read_b128 v[176:179], v153
	v_xor_b32_e32 v253, 64, v153
	ds_read_b128 v[180:183], v253
	ds_read_b128 v[184:187], v153 offset:2048
	ds_read_b128 v[188:191], v253 offset:2048
	s_add_u32 s46, s46, 0x40000
	s_addc_u32 s47, s47, 0
	s_mov_b32 m0, s54
	v_lshl_add_u64 v[230:231], s[46:47], 0, v[134:135]
	ds_read_b128 v[192:195], v150 offset:32768
	v_xor_b32_e32 v253, 64, v150
	ds_read_b128 v[196:199], v253 offset:32768
	ds_read_b128 v[200:203], v150 offset:34816
	ds_read_b128 v[204:207], v253 offset:34816
	ds_read_b128 v[208:211], v150 offset:36864
	ds_read_b128 v[212:215], v253 offset:36864
	ds_read_b128 v[216:219], v150 offset:38912
	ds_read_b128 v[220:223], v253 offset:38912
	global_load_lds_dwordx4 v[230:231], off
	v_lshl_add_u64 v[230:231], s[46:47], 0, v[130:131]
	s_mov_b32 m0, s55
	s_nop 0
	global_load_lds_dwordx4 v[230:231], off
	s_waitcnt vmcnt(8)
	s_waitcnt lgkmcnt(0)
	s_setprio 1
	s_barrier
	v_mfma_f32_16x16x32_bf16 v[124:127], v[160:163], v[192:195], v[124:127]
	v_mfma_f32_16x16x32_bf16 v[124:127], v[164:167], v[196:199], v[124:127]
	v_mfma_f32_16x16x32_bf16 v[116:119], v[172:175], v[196:199], v[116:119]
	v_mfma_f32_16x16x32_bf16 v[116:119], v[168:171], v[192:195], v[116:119]
	v_mfma_f32_16x16x32_bf16 v[100:103], v[168:171], v[200:203], v[100:103]
	v_mfma_f32_16x16x32_bf16 v[100:103], v[172:175], v[204:207], v[100:103]
	v_mfma_f32_16x16x32_bf16 v[108:111], v[164:167], v[204:207], v[108:111]
	v_mfma_f32_16x16x32_bf16 v[108:111], v[160:163], v[200:203], v[108:111]
	v_mfma_f32_16x16x32_bf16 v[92:95], v[160:163], v[208:211], v[92:95]
	v_mfma_f32_16x16x32_bf16 v[92:95], v[164:167], v[212:215], v[92:95]
	v_mfma_f32_16x16x32_bf16 v[84:87], v[172:175], v[212:215], v[84:87]
	v_mfma_f32_16x16x32_bf16 v[84:87], v[168:171], v[208:211], v[84:87]
	v_mfma_f32_16x16x32_bf16 v[68:71], v[168:171], v[216:219], v[68:71]
	v_mfma_f32_16x16x32_bf16 v[68:71], v[172:175], v[220:223], v[68:71]
	v_mfma_f32_16x16x32_bf16 v[76:79], v[164:167], v[220:223], v[76:79]
	v_mfma_f32_16x16x32_bf16 v[76:79], v[160:163], v[216:219], v[76:79]
	s_setprio 0
	s_setprio 1
	v_mfma_f32_16x16x32_bf16 v[120:123], v[176:179], v[192:195], v[120:123]
	v_mfma_f32_16x16x32_bf16 v[120:123], v[180:183], v[196:199], v[120:123]
	v_mfma_f32_16x16x32_bf16 v[112:115], v[188:191], v[196:199], v[112:115]
	v_mfma_f32_16x16x32_bf16 v[112:115], v[184:187], v[192:195], v[112:115]
	v_mfma_f32_16x16x32_bf16 v[96:99], v[184:187], v[200:203], v[96:99]
	v_mfma_f32_16x16x32_bf16 v[96:99], v[188:191], v[204:207], v[96:99]
	v_mfma_f32_16x16x32_bf16 v[104:107], v[180:183], v[204:207], v[104:107]
	v_mfma_f32_16x16x32_bf16 v[104:107], v[176:179], v[200:203], v[104:107]
	v_mfma_f32_16x16x32_bf16 v[88:91], v[176:179], v[208:211], v[88:91]
	v_mfma_f32_16x16x32_bf16 v[88:91], v[180:183], v[212:215], v[88:91]
	v_mfma_f32_16x16x32_bf16 v[80:83], v[188:191], v[212:215], v[80:83]
	v_mfma_f32_16x16x32_bf16 v[80:83], v[184:187], v[208:211], v[80:83]
	v_mfma_f32_16x16x32_bf16 v[64:67], v[184:187], v[216:219], v[64:67]
	v_mfma_f32_16x16x32_bf16 v[64:67], v[188:191], v[220:223], v[64:67]
	v_mfma_f32_16x16x32_bf16 v[72:75], v[180:183], v[220:223], v[72:75]
	v_mfma_f32_16x16x32_bf16 v[72:75], v[176:179], v[216:219], v[72:75]
	s_barrier
	s_setprio 0
	s_add_i32 s46, s71, s49
	v_lshl_add_u64 v[154:155], v[154:155], 0, s[14:15]
	s_mov_b32 m0, s46
	ds_read_b128 v[192:195], v150 offset:49152
	v_xor_b32_e32 v253, 64, v150
	ds_read_b128 v[196:199], v253 offset:49152
	ds_read_b128 v[200:203], v150 offset:51200
	ds_read_b128 v[204:207], v253 offset:51200
	ds_read_b128 v[208:211], v150 offset:53248
	ds_read_b128 v[212:215], v253 offset:53248
	ds_read_b128 v[216:219], v150 offset:55296
	ds_read_b128 v[220:223], v253 offset:55296
	global_load_lds_dwordx4 v[154:155], off
	s_add_i32 m0, s46, 0x2000
	s_add_u32 s44, s44, 0x40080
	v_lshl_add_u64 v[154:155], v[224:225], 0, s[14:15]
	s_addc_u32 s45, s45, 0
	s_add_i32 s46, s72, s49
	global_load_lds_dwordx4 v[154:155], off
	v_lshl_add_u64 v[154:155], s[44:45], 0, v[132:133]
	s_mov_b32 m0, s46
	s_nop 0
	global_load_lds_dwordx4 v[154:155], off
	v_lshl_add_u64 v[154:155], s[44:45], 0, v[128:129]
	s_add_i32 m0, s46, 0x2000
	s_nop 0
	global_load_lds_dwordx4 v[154:155], off
	v_lshl_add_u64 v[154:155], v[226:227], 0, s[14:15]
	s_mov_b32 m0, s57
	s_nop 0
	global_load_lds_dwordx4 v[154:155], off
	v_lshl_add_u64 v[154:155], v[228:229], 0, s[14:15]
	s_mov_b32 m0, s58
	s_nop 0
	global_load_lds_dwordx4 v[154:155], off
	s_waitcnt vmcnt(8)
	s_waitcnt lgkmcnt(0)
	s_setprio 1
	s_barrier
	v_mfma_f32_16x16x32_bf16 v[60:63], v[160:163], v[192:195], v[60:63]
	v_mfma_f32_16x16x32_bf16 v[60:63], v[164:167], v[196:199], v[60:63]
	v_mfma_f32_16x16x32_bf16 v[52:55], v[172:175], v[196:199], v[52:55]
	v_mfma_f32_16x16x32_bf16 v[52:55], v[168:171], v[192:195], v[52:55]
	v_mfma_f32_16x16x32_bf16 v[36:39], v[168:171], v[200:203], v[36:39]
	v_mfma_f32_16x16x32_bf16 v[36:39], v[172:175], v[204:207], v[36:39]
	v_mfma_f32_16x16x32_bf16 v[44:47], v[164:167], v[204:207], v[44:47]
	v_mfma_f32_16x16x32_bf16 v[44:47], v[160:163], v[200:203], v[44:47]
	v_mfma_f32_16x16x32_bf16 v[28:31], v[160:163], v[208:211], v[28:31]
	v_mfma_f32_16x16x32_bf16 v[28:31], v[164:167], v[212:215], v[28:31]
	v_mfma_f32_16x16x32_bf16 v[20:23], v[172:175], v[212:215], v[20:23]
	v_mfma_f32_16x16x32_bf16 v[20:23], v[168:171], v[208:211], v[20:23]
	v_mfma_f32_16x16x32_bf16 v[4:7], v[168:171], v[216:219], v[4:7]
	v_mfma_f32_16x16x32_bf16 v[4:7], v[172:175], v[220:223], v[4:7]
	v_mfma_f32_16x16x32_bf16 v[12:15], v[164:167], v[220:223], v[12:15]
	v_mfma_f32_16x16x32_bf16 v[12:15], v[160:163], v[216:219], v[12:15]
	s_setprio 0
	s_setprio 1
	v_mfma_f32_16x16x32_bf16 v[56:59], v[176:179], v[192:195], v[56:59]
	v_mfma_f32_16x16x32_bf16 v[56:59], v[180:183], v[196:199], v[56:59]
	v_mfma_f32_16x16x32_bf16 v[48:51], v[188:191], v[196:199], v[48:51]
	v_mfma_f32_16x16x32_bf16 v[48:51], v[184:187], v[192:195], v[48:51]
	v_mfma_f32_16x16x32_bf16 v[32:35], v[184:187], v[200:203], v[32:35]
	v_mfma_f32_16x16x32_bf16 v[32:35], v[188:191], v[204:207], v[32:35]
	v_mfma_f32_16x16x32_bf16 v[40:43], v[180:183], v[204:207], v[40:43]
	v_mfma_f32_16x16x32_bf16 v[40:43], v[176:179], v[200:203], v[40:43]
	v_mfma_f32_16x16x32_bf16 v[24:27], v[176:179], v[208:211], v[24:27]
	v_mfma_f32_16x16x32_bf16 v[24:27], v[180:183], v[212:215], v[24:27]
	v_mfma_f32_16x16x32_bf16 v[16:19], v[188:191], v[212:215], v[16:19]
	v_mfma_f32_16x16x32_bf16 v[16:19], v[184:187], v[208:211], v[16:19]
	v_mfma_f32_16x16x32_bf16 v[0:3], v[184:187], v[216:219], v[0:3]
	v_mfma_f32_16x16x32_bf16 v[0:3], v[188:191], v[220:223], v[0:3]
	v_mfma_f32_16x16x32_bf16 v[8:11], v[180:183], v[220:223], v[8:11]
	v_mfma_f32_16x16x32_bf16 v[8:11], v[176:179], v[216:219], v[8:11]
	s_barrier
	s_setprio 0
	s_add_i32 s70, s70, 2
	s_add_u32 s68, s68, 0x100
	s_addc_u32 s69, s69, 0
	s_add_u32 s30, s30, 0x100
	s_addc_u32 s31, s31, 0
	s_branch .LBB0_1098
.Lfa_10:
	v_add_u32_e32 v153, s61, v147
	ds_read_b128 v[160:163], v153
	v_xor_b32_e32 v253, 64, v153
	ds_read_b128 v[164:167], v253
	ds_read_b128 v[168:171], v153 offset:2048
	ds_read_b128 v[172:175], v253 offset:2048
	v_add_u32_e32 v153, s62, v147
	ds_read_b128 v[176:179], v153
	v_xor_b32_e32 v253, 64, v153
	ds_read_b128 v[180:183], v253
	ds_read_b128 v[184:187], v153 offset:2048
	ds_read_b128 v[188:191], v253 offset:2048
	s_add_u32 s46, s30, 0xfffc0080
	s_addc_u32 s47, s31, -1
	s_and_b64 s[44:45], s[44:45], exec
	s_cselect_b32 s47, s25, s47
	s_cselect_b32 s46, s65, s46
	s_cselect_b32 s45, s66, s69
	s_cselect_b32 s44, s67, s68
	v_lshl_add_u64 v[154:155], s[30:31], 0, v[138:139]
	s_add_i32 m0, s52, 0xc000
	ds_read_b128 v[192:195], v150
	v_xor_b32_e32 v253, 64, v150
	ds_read_b128 v[196:199], v253
	ds_read_b128 v[200:203], v150 offset:2048
	ds_read_b128 v[204:207], v253 offset:2048
	ds_read_b128 v[208:211], v150 offset:4096
	ds_read_b128 v[212:215], v253 offset:4096
	ds_read_b128 v[216:219], v150 offset:6144
	ds_read_b128 v[220:223], v253 offset:6144
	global_load_lds_dwordx4 v[154:155], off
	v_lshl_add_u64 v[154:155], s[30:31], 0, v[136:137]
	s_add_i32 m0, s52, 0xe000
	s_nop 0
	global_load_lds_dwordx4 v[154:155], off
	s_waitcnt vmcnt(8)
	s_waitcnt lgkmcnt(0)
	s_setprio 1
	s_barrier
	v_mfma_f32_16x16x32_bf16 v[124:127], v[160:163], v[192:195], 0
	v_mfma_f32_16x16x32_bf16 v[116:119], v[168:171], v[192:195], 0
	v_mfma_f32_16x16x32_bf16 v[108:111], v[160:163], v[200:203], 0
	v_mfma_f32_16x16x32_bf16 v[100:103], v[168:171], v[200:203], 0
	v_mfma_f32_16x16x32_bf16 v[92:95], v[160:163], v[208:211], 0
	v_mfma_f32_16x16x32_bf16 v[84:87], v[168:171], v[208:211], 0
	v_mfma_f32_16x16x32_bf16 v[76:79], v[160:163], v[216:219], 0
	v_mfma_f32_16x16x32_bf16 v[68:71], v[168:171], v[216:219], 0
	v_mfma_f32_16x16x32_bf16 v[124:127], v[164:167], v[196:199], v[124:127]
	v_mfma_f32_16x16x32_bf16 v[116:119], v[172:175], v[196:199], v[116:119]
	v_mfma_f32_16x16x32_bf16 v[108:111], v[164:167], v[204:207], v[108:111]
	v_mfma_f32_16x16x32_bf16 v[100:103], v[172:175], v[204:207], v[100:103]
	v_mfma_f32_16x16x32_bf16 v[92:95], v[164:167], v[212:215], v[92:95]
	v_mfma_f32_16x16x32_bf16 v[84:87], v[172:175], v[212:215], v[84:87]
	v_mfma_f32_16x16x32_bf16 v[76:79], v[164:167], v[220:223], v[76:79]
	v_mfma_f32_16x16x32_bf16 v[68:71], v[172:175], v[220:223], v[68:71]
	s_setprio 0
	s_setprio 1
	v_mfma_f32_16x16x32_bf16 v[120:123], v[176:179], v[192:195], 0
	v_mfma_f32_16x16x32_bf16 v[112:115], v[184:187], v[192:195], 0
	v_mfma_f32_16x16x32_bf16 v[104:107], v[176:179], v[200:203], 0
	v_mfma_f32_16x16x32_bf16 v[96:99], v[184:187], v[200:203], 0
	v_mfma_f32_16x16x32_bf16 v[88:91], v[176:179], v[208:211], 0
	v_mfma_f32_16x16x32_bf16 v[80:83], v[184:187], v[208:211], 0
	v_mfma_f32_16x16x32_bf16 v[72:75], v[176:179], v[216:219], 0
	v_mfma_f32_16x16x32_bf16 v[64:67], v[184:187], v[216:219], 0
	v_mfma_f32_16x16x32_bf16 v[120:123], v[180:183], v[196:199], v[120:123]
	v_mfma_f32_16x16x32_bf16 v[112:115], v[188:191], v[196:199], v[112:115]
	v_mfma_f32_16x16x32_bf16 v[104:107], v[180:183], v[204:207], v[104:107]
	v_mfma_f32_16x16x32_bf16 v[96:99], v[188:191], v[204:207], v[96:99]
	v_mfma_f32_16x16x32_bf16 v[88:91], v[180:183], v[212:215], v[88:91]
	v_mfma_f32_16x16x32_bf16 v[80:83], v[188:191], v[212:215], v[80:83]
	v_mfma_f32_16x16x32_bf16 v[72:75], v[180:183], v[220:223], v[72:75]
	v_mfma_f32_16x16x32_bf16 v[64:67], v[188:191], v[220:223], v[64:67]
	s_barrier
	s_setprio 0
	s_add_i32 s71, s61, s49
	v_lshl_add_u64 v[154:155], s[44:45], 0, v[132:133]
	s_mov_b32 m0, s71
	ds_read_b128 v[192:195], v150 offset:16384
	v_xor_b32_e32 v253, 64, v150
	ds_read_b128 v[196:199], v253 offset:16384
	ds_read_b128 v[200:203], v150 offset:18432
	ds_read_b128 v[204:207], v253 offset:18432
	ds_read_b128 v[208:211], v150 offset:20480
	ds_read_b128 v[212:215], v253 offset:20480
	ds_read_b128 v[216:219], v150 offset:22528
	ds_read_b128 v[220:223], v253 offset:22528
	global_load_lds_dwordx4 v[154:155], off
	s_add_i32 m0, s71, 0x2000
	s_add_u32 s72, s44, 0x40000
	v_lshl_add_u64 v[224:225], s[44:45], 0, v[128:129]
	s_addc_u32 s73, s45, 0
	s_add_i32 s71, s62, s49
	global_load_lds_dwordx4 v[224:225], off
	v_lshl_add_u64 v[226:227], s[72:73], 0, v[132:133]
	s_mov_b32 m0, s71
	v_lshl_add_u64 v[228:229], s[46:47], 0, v[130:131]
	global_load_lds_dwordx4 v[226:227], off
	v_lshl_add_u64 v[226:227], s[72:73], 0, v[128:129]
	s_add_i32 m0, s71, 0x2000
	s_nop 0
	global_load_lds_dwordx4 v[226:227], off
	v_lshl_add_u64 v[226:227], s[46:47], 0, v[134:135]
	s_mov_b32 m0, s52
	s_nop 0
	global_load_lds_dwordx4 v[226:227], off
	s_mov_b32 m0, s53
	s_nop 0
	global_load_lds_dwordx4 v[228:229], off
	s_waitcnt vmcnt(8)
	s_waitcnt lgkmcnt(0)
	s_setprio 1
	s_barrier
	v_mfma_f32_16x16x32_bf16 v[60:63], v[160:163], v[192:195], 0
	v_mfma_f32_16x16x32_bf16 v[52:55], v[168:171], v[192:195], 0
	v_mfma_f32_16x16x32_bf16 v[44:47], v[160:163], v[200:203], 0
	v_mfma_f32_16x16x32_bf16 v[36:39], v[168:171], v[200:203], 0
	v_mfma_f32_16x16x32_bf16 v[28:31], v[160:163], v[208:211], 0
	v_mfma_f32_16x16x32_bf16 v[20:23], v[168:171], v[208:211], 0
	v_mfma_f32_16x16x32_bf16 v[12:15], v[160:163], v[216:219], 0
	v_mfma_f32_16x16x32_bf16 v[4:7], v[168:171], v[216:219], 0
	v_mfma_f32_16x16x32_bf16 v[60:63], v[164:167], v[196:199], v[60:63]
	v_mfma_f32_16x16x32_bf16 v[52:55], v[172:175], v[196:199], v[52:55]
	v_mfma_f32_16x16x32_bf16 v[44:47], v[164:167], v[204:207], v[44:47]
	v_mfma_f32_16x16x32_bf16 v[36:39], v[172:175], v[204:207], v[36:39]
	v_mfma_f32_16x16x32_bf16 v[28:31], v[164:167], v[212:215], v[28:31]
	v_mfma_f32_16x16x32_bf16 v[20:23], v[172:175], v[212:215], v[20:23]
	v_mfma_f32_16x16x32_bf16 v[12:15], v[164:167], v[220:223], v[12:15]
	v_mfma_f32_16x16x32_bf16 v[4:7], v[172:175], v[220:223], v[4:7]
	s_setprio 0
	s_setprio 1
	v_mfma_f32_16x16x32_bf16 v[56:59], v[176:179], v[192:195], 0
	v_mfma_f32_16x16x32_bf16 v[48:51], v[184:187], v[192:195], 0
	v_mfma_f32_16x16x32_bf16 v[40:43], v[176:179], v[200:203], 0
	v_mfma_f32_16x16x32_bf16 v[32:35], v[184:187], v[200:203], 0
	v_mfma_f32_16x16x32_bf16 v[24:27], v[176:179], v[208:211], 0
	v_mfma_f32_16x16x32_bf16 v[16:19], v[184:187], v[208:211], 0
	v_mfma_f32_16x16x32_bf16 v[8:11], v[176:179], v[216:219], 0
	v_mfma_f32_16x16x32_bf16 v[0:3], v[184:187], v[216:219], 0
	v_mfma_f32_16x16x32_bf16 v[56:59], v[180:183], v[196:199], v[56:59]
	v_mfma_f32_16x16x32_bf16 v[48:51], v[188:191], v[196:199], v[48:51]
	v_mfma_f32_16x16x32_bf16 v[40:43], v[180:183], v[204:207], v[40:43]
	v_mfma_f32_16x16x32_bf16 v[32:35], v[188:191], v[204:207], v[32:35]
	v_mfma_f32_16x16x32_bf16 v[24:27], v[180:183], v[212:215], v[24:27]
	v_mfma_f32_16x16x32_bf16 v[16:19], v[188:191], v[212:215], v[16:19]
	v_mfma_f32_16x16x32_bf16 v[8:11], v[180:183], v[220:223], v[8:11]
	v_mfma_f32_16x16x32_bf16 v[0:3], v[188:191], v[220:223], v[0:3]
	s_barrier
	s_setprio 0
	s_add_i32 s71, 0, 0x18000
	v_add_u32_e32 v153, s71, v147
	s_add_i32 s72, 0, 0x1c000
	ds_read_b128 v[160:163], v153
	v_xor_b32_e32 v253, 64, v153
	ds_read_b128 v[164:167], v253
	ds_read_b128 v[168:171], v153 offset:2048
	ds_read_b128 v[172:175], v253 offset:2048
	v_add_u32_e32 v153, s72, v147
	ds_read_b128 v[176:179], v153
	v_xor_b32_e32 v253, 64, v153
	ds_read_b128 v[180:183], v253
	ds_read_b128 v[184:187], v153 offset:2048
	ds_read_b128 v[188:191], v253 offset:2048
	s_add_u32 s46, s46, 0x40000
	s_addc_u32 s47, s47, 0
	s_mov_b32 m0, s54
	v_lshl_add_u64 v[230:231], s[46:47], 0, v[134:135]
	ds_read_b128 v[192:195], v150 offset:32768
	v_xor_b32_e32 v253, 64, v150
	ds_read_b128 v[196:199], v253 offset:32768
	ds_read_b128 v[200:203], v150 offset:34816
	ds_read_b128 v[204:207], v253 offset:34816
	ds_read_b128 v[208:211], v150 offset:36864
	ds_read_b128 v[212:215], v253 offset:36864
	ds_read_b128 v[216:219], v150 offset:38912
	ds_read_b128 v[220:223], v253 offset:38912
	global_load_lds_dwordx4 v[230:231], off
	v_lshl_add_u64 v[230:231], s[46:47], 0, v[130:131]
	s_mov_b32 m0, s55
	s_nop 0
	global_load_lds_dwordx4 v[230:231], off
	s_waitcnt vmcnt(8)
	s_waitcnt lgkmcnt(0)
	s_setprio 1
	s_barrier
	v_mfma_f32_16x16x32_bf16 v[124:127], v[160:163], v[192:195], v[124:127]
	v_mfma_f32_16x16x32_bf16 v[124:127], v[164:167], v[196:199], v[124:127]
	v_mfma_f32_16x16x32_bf16 v[116:119], v[172:175], v[196:199], v[116:119]
	v_mfma_f32_16x16x32_bf16 v[116:119], v[168:171], v[192:195], v[116:119]
	v_mfma_f32_16x16x32_bf16 v[100:103], v[168:171], v[200:203], v[100:103]
	v_mfma_f32_16x16x32_bf16 v[100:103], v[172:175], v[204:207], v[100:103]
	v_mfma_f32_16x16x32_bf16 v[108:111], v[164:167], v[204:207], v[108:111]
	v_mfma_f32_16x16x32_bf16 v[108:111], v[160:163], v[200:203], v[108:111]
	v_mfma_f32_16x16x32_bf16 v[92:95], v[160:163], v[208:211], v[92:95]
	v_mfma_f32_16x16x32_bf16 v[92:95], v[164:167], v[212:215], v[92:95]
	v_mfma_f32_16x16x32_bf16 v[84:87], v[172:175], v[212:215], v[84:87]
	v_mfma_f32_16x16x32_bf16 v[84:87], v[168:171], v[208:211], v[84:87]
	v_mfma_f32_16x16x32_bf16 v[68:71], v[168:171], v[216:219], v[68:71]
	v_mfma_f32_16x16x32_bf16 v[68:71], v[172:175], v[220:223], v[68:71]
	v_mfma_f32_16x16x32_bf16 v[76:79], v[164:167], v[220:223], v[76:79]
	v_mfma_f32_16x16x32_bf16 v[76:79], v[160:163], v[216:219], v[76:79]
	s_setprio 0
	s_setprio 1
	v_mfma_f32_16x16x32_bf16 v[120:123], v[176:179], v[192:195], v[120:123]
	v_mfma_f32_16x16x32_bf16 v[120:123], v[180:183], v[196:199], v[120:123]
	v_mfma_f32_16x16x32_bf16 v[112:115], v[188:191], v[196:199], v[112:115]
	v_mfma_f32_16x16x32_bf16 v[112:115], v[184:187], v[192:195], v[112:115]
	v_mfma_f32_16x16x32_bf16 v[96:99], v[184:187], v[200:203], v[96:99]
	v_mfma_f32_16x16x32_bf16 v[96:99], v[188:191], v[204:207], v[96:99]
	v_mfma_f32_16x16x32_bf16 v[104:107], v[180:183], v[204:207], v[104:107]
	v_mfma_f32_16x16x32_bf16 v[104:107], v[176:179], v[200:203], v[104:107]
	v_mfma_f32_16x16x32_bf16 v[88:91], v[176:179], v[208:211], v[88:91]
	v_mfma_f32_16x16x32_bf16 v[88:91], v[180:183], v[212:215], v[88:91]
	v_mfma_f32_16x16x32_bf16 v[80:83], v[188:191], v[212:215], v[80:83]
	v_mfma_f32_16x16x32_bf16 v[80:83], v[184:187], v[208:211], v[80:83]
	v_mfma_f32_16x16x32_bf16 v[64:67], v[184:187], v[216:219], v[64:67]
	v_mfma_f32_16x16x32_bf16 v[64:67], v[188:191], v[220:223], v[64:67]
	v_mfma_f32_16x16x32_bf16 v[72:75], v[180:183], v[220:223], v[72:75]
	v_mfma_f32_16x16x32_bf16 v[72:75], v[176:179], v[216:219], v[72:75]
	s_barrier
	s_setprio 0
	s_add_i32 s46, s71, s49
	v_lshl_add_u64 v[154:155], v[154:155], 0, s[14:15]
	s_mov_b32 m0, s46
	ds_read_b128 v[192:195], v150 offset:49152
	v_xor_b32_e32 v253, 64, v150
	ds_read_b128 v[196:199], v253 offset:49152
	ds_read_b128 v[200:203], v150 offset:51200
	ds_read_b128 v[204:207], v253 offset:51200
	ds_read_b128 v[208:211], v150 offset:53248
	ds_read_b128 v[212:215], v253 offset:53248
	ds_read_b128 v[216:219], v150 offset:55296
	ds_read_b128 v[220:223], v253 offset:55296
	global_load_lds_dwordx4 v[154:155], off
	s_add_i32 m0, s46, 0x2000
	s_add_u32 s44, s44, 0x40080
	v_lshl_add_u64 v[154:155], v[224:225], 0, s[14:15]
	s_addc_u32 s45, s45, 0
	s_add_i32 s46, s72, s49
	global_load_lds_dwordx4 v[154:155], off
	v_lshl_add_u64 v[154:155], s[44:45], 0, v[132:133]
	s_mov_b32 m0, s46
	s_nop 0
	global_load_lds_dwordx4 v[154:155], off
	v_lshl_add_u64 v[154:155], s[44:45], 0, v[128:129]
	s_add_i32 m0, s46, 0x2000
	s_nop 0
	global_load_lds_dwordx4 v[154:155], off
	v_lshl_add_u64 v[154:155], v[226:227], 0, s[14:15]
	s_mov_b32 m0, s57
	s_nop 0
	global_load_lds_dwordx4 v[154:155], off
	v_lshl_add_u64 v[154:155], v[228:229], 0, s[14:15]
	s_mov_b32 m0, s58
	s_nop 0
	global_load_lds_dwordx4 v[154:155], off
	s_waitcnt vmcnt(8)
	s_waitcnt lgkmcnt(0)
	s_setprio 1
	s_barrier
	v_mfma_f32_16x16x32_bf16 v[60:63], v[160:163], v[192:195], v[60:63]
	v_mfma_f32_16x16x32_bf16 v[60:63], v[164:167], v[196:199], v[60:63]
	v_mfma_f32_16x16x32_bf16 v[52:55], v[172:175], v[196:199], v[52:55]
	v_mfma_f32_16x16x32_bf16 v[52:55], v[168:171], v[192:195], v[52:55]
	v_mfma_f32_16x16x32_bf16 v[36:39], v[168:171], v[200:203], v[36:39]
	v_mfma_f32_16x16x32_bf16 v[36:39], v[172:175], v[204:207], v[36:39]
	v_mfma_f32_16x16x32_bf16 v[44:47], v[164:167], v[204:207], v[44:47]
	v_mfma_f32_16x16x32_bf16 v[44:47], v[160:163], v[200:203], v[44:47]
	v_mfma_f32_16x16x32_bf16 v[28:31], v[160:163], v[208:211], v[28:31]
	v_mfma_f32_16x16x32_bf16 v[28:31], v[164:167], v[212:215], v[28:31]
	v_mfma_f32_16x16x32_bf16 v[20:23], v[172:175], v[212:215], v[20:23]
	v_mfma_f32_16x16x32_bf16 v[20:23], v[168:171], v[208:211], v[20:23]
	v_mfma_f32_16x16x32_bf16 v[4:7], v[168:171], v[216:219], v[4:7]
	v_mfma_f32_16x16x32_bf16 v[4:7], v[172:175], v[220:223], v[4:7]
	v_mfma_f32_16x16x32_bf16 v[12:15], v[164:167], v[220:223], v[12:15]
	v_mfma_f32_16x16x32_bf16 v[12:15], v[160:163], v[216:219], v[12:15]
	s_setprio 0
	s_setprio 1
	v_mfma_f32_16x16x32_bf16 v[56:59], v[176:179], v[192:195], v[56:59]
	v_mfma_f32_16x16x32_bf16 v[56:59], v[180:183], v[196:199], v[56:59]
	v_mfma_f32_16x16x32_bf16 v[48:51], v[188:191], v[196:199], v[48:51]
	v_mfma_f32_16x16x32_bf16 v[48:51], v[184:187], v[192:195], v[48:51]
	v_mfma_f32_16x16x32_bf16 v[32:35], v[184:187], v[200:203], v[32:35]
	v_mfma_f32_16x16x32_bf16 v[32:35], v[188:191], v[204:207], v[32:35]
	v_mfma_f32_16x16x32_bf16 v[40:43], v[180:183], v[204:207], v[40:43]
	v_mfma_f32_16x16x32_bf16 v[40:43], v[176:179], v[200:203], v[40:43]
	v_mfma_f32_16x16x32_bf16 v[24:27], v[176:179], v[208:211], v[24:27]
	v_mfma_f32_16x16x32_bf16 v[24:27], v[180:183], v[212:215], v[24:27]
	v_mfma_f32_16x16x32_bf16 v[16:19], v[188:191], v[212:215], v[16:19]
	v_mfma_f32_16x16x32_bf16 v[16:19], v[184:187], v[208:211], v[16:19]
	v_mfma_f32_16x16x32_bf16 v[0:3], v[184:187], v[216:219], v[0:3]
	v_mfma_f32_16x16x32_bf16 v[0:3], v[188:191], v[220:223], v[0:3]
	v_mfma_f32_16x16x32_bf16 v[8:11], v[180:183], v[220:223], v[8:11]
	v_mfma_f32_16x16x32_bf16 v[8:11], v[176:179], v[216:219], v[8:11]
	s_barrier
	s_setprio 0
	s_add_i32 s70, s70, 2
	s_add_u32 s68, s68, 0x100
	s_addc_u32 s69, s69, 0
	s_add_u32 s30, s30, 0x100
	s_addc_u32 s31, s31, 0
	s_branch .LBB0_1098
.LBB0_1097:
	v_add_u32_e32 v153, s61, v147
	ds_read_b128 v[160:163], v153
	v_xor_b32_e32 v253, 64, v153
	ds_read_b128 v[164:167], v253
	ds_read_b128 v[168:171], v153 offset:2048
	ds_read_b128 v[172:175], v253 offset:2048
	v_add_u32_e32 v153, s62, v147
	ds_read_b128 v[176:179], v153
	v_xor_b32_e32 v253, 64, v153
	ds_read_b128 v[180:183], v253
	ds_read_b128 v[184:187], v153 offset:2048
	ds_read_b128 v[188:191], v253 offset:2048
	s_add_u32 s46, s30, 0xfffc0080
	s_addc_u32 s47, s31, -1
	s_and_b64 s[44:45], s[44:45], exec
	s_cselect_b32 s47, s25, s47
	s_cselect_b32 s46, s65, s46
	s_cselect_b32 s45, s66, s69
	s_cselect_b32 s44, s67, s68
	v_lshl_add_u64 v[154:155], s[30:31], 0, v[138:139]
	s_add_i32 m0, s52, 0xc000
	ds_read_b128 v[192:195], v150
	v_xor_b32_e32 v253, 64, v150
	ds_read_b128 v[196:199], v253
	ds_read_b128 v[200:203], v150 offset:2048
	ds_read_b128 v[204:207], v253 offset:2048
	ds_read_b128 v[208:211], v150 offset:4096
	ds_read_b128 v[212:215], v253 offset:4096
	ds_read_b128 v[216:219], v150 offset:6144
	ds_read_b128 v[220:223], v253 offset:6144
	global_load_lds_dwordx4 v[154:155], off
	v_lshl_add_u64 v[154:155], s[30:31], 0, v[136:137]
	s_add_i32 m0, s52, 0xe000
	s_nop 0
	global_load_lds_dwordx4 v[154:155], off
	s_waitcnt vmcnt(8)
	s_waitcnt lgkmcnt(0)
	s_setprio 1
	s_barrier
	v_mfma_f32_16x16x32_bf16 v[124:127], v[160:163], v[192:195], v[124:127]
	v_mfma_f32_16x16x32_bf16 v[124:127], v[164:167], v[196:199], v[124:127]
	v_mfma_f32_16x16x32_bf16 v[116:119], v[172:175], v[196:199], v[116:119]
	v_mfma_f32_16x16x32_bf16 v[116:119], v[168:171], v[192:195], v[116:119]
	v_mfma_f32_16x16x32_bf16 v[100:103], v[168:171], v[200:203], v[100:103]
	v_mfma_f32_16x16x32_bf16 v[100:103], v[172:175], v[204:207], v[100:103]
	v_mfma_f32_16x16x32_bf16 v[108:111], v[164:167], v[204:207], v[108:111]
	v_mfma_f32_16x16x32_bf16 v[108:111], v[160:163], v[200:203], v[108:111]
	v_mfma_f32_16x16x32_bf16 v[92:95], v[160:163], v[208:211], v[92:95]
	v_mfma_f32_16x16x32_bf16 v[92:95], v[164:167], v[212:215], v[92:95]
	v_mfma_f32_16x16x32_bf16 v[84:87], v[172:175], v[212:215], v[84:87]
	v_mfma_f32_16x16x32_bf16 v[84:87], v[168:171], v[208:211], v[84:87]
	v_mfma_f32_16x16x32_bf16 v[68:71], v[168:171], v[216:219], v[68:71]
	v_mfma_f32_16x16x32_bf16 v[68:71], v[172:175], v[220:223], v[68:71]
	v_mfma_f32_16x16x32_bf16 v[76:79], v[164:167], v[220:223], v[76:79]
	v_mfma_f32_16x16x32_bf16 v[76:79], v[160:163], v[216:219], v[76:79]
	s_setprio 0
	s_setprio 1
	v_mfma_f32_16x16x32_bf16 v[120:123], v[176:179], v[192:195], v[120:123]
	v_mfma_f32_16x16x32_bf16 v[120:123], v[180:183], v[196:199], v[120:123]
	v_mfma_f32_16x16x32_bf16 v[112:115], v[188:191], v[196:199], v[112:115]
	v_mfma_f32_16x16x32_bf16 v[112:115], v[184:187], v[192:195], v[112:115]
	v_mfma_f32_16x16x32_bf16 v[96:99], v[184:187], v[200:203], v[96:99]
	v_mfma_f32_16x16x32_bf16 v[96:99], v[188:191], v[204:207], v[96:99]
	v_mfma_f32_16x16x32_bf16 v[104:107], v[180:183], v[204:207], v[104:107]
	v_mfma_f32_16x16x32_bf16 v[104:107], v[176:179], v[200:203], v[104:107]
	v_mfma_f32_16x16x32_bf16 v[88:91], v[176:179], v[208:211], v[88:91]
	v_mfma_f32_16x16x32_bf16 v[88:91], v[180:183], v[212:215], v[88:91]
	v_mfma_f32_16x16x32_bf16 v[80:83], v[188:191], v[212:215], v[80:83]
	v_mfma_f32_16x16x32_bf16 v[80:83], v[184:187], v[208:211], v[80:83]
	v_mfma_f32_16x16x32_bf16 v[64:67], v[184:187], v[216:219], v[64:67]
	v_mfma_f32_16x16x32_bf16 v[64:67], v[188:191], v[220:223], v[64:67]
	v_mfma_f32_16x16x32_bf16 v[72:75], v[180:183], v[220:223], v[72:75]
	v_mfma_f32_16x16x32_bf16 v[72:75], v[176:179], v[216:219], v[72:75]
	s_barrier
	s_setprio 0
	s_add_i32 s71, s61, s49
	v_lshl_add_u64 v[154:155], s[44:45], 0, v[132:133]
	s_mov_b32 m0, s71
	ds_read_b128 v[192:195], v150 offset:16384
	v_xor_b32_e32 v253, 64, v150
	ds_read_b128 v[196:199], v253 offset:16384
	ds_read_b128 v[200:203], v150 offset:18432
	ds_read_b128 v[204:207], v253 offset:18432
	ds_read_b128 v[208:211], v150 offset:20480
	ds_read_b128 v[212:215], v253 offset:20480
	ds_read_b128 v[216:219], v150 offset:22528
	ds_read_b128 v[220:223], v253 offset:22528
	global_load_lds_dwordx4 v[154:155], off
	s_add_i32 m0, s71, 0x2000
	s_add_u32 s72, s44, 0x40000
	v_lshl_add_u64 v[224:225], s[44:45], 0, v[128:129]
	s_addc_u32 s73, s45, 0
	s_add_i32 s71, s62, s49
	global_load_lds_dwordx4 v[224:225], off
	v_lshl_add_u64 v[226:227], s[72:73], 0, v[132:133]
	s_mov_b32 m0, s71
	v_lshl_add_u64 v[228:229], s[46:47], 0, v[130:131]
	global_load_lds_dwordx4 v[226:227], off
	v_lshl_add_u64 v[226:227], s[72:73], 0, v[128:129]
	s_add_i32 m0, s71, 0x2000
	s_nop 0
	global_load_lds_dwordx4 v[226:227], off
	v_lshl_add_u64 v[226:227], s[46:47], 0, v[134:135]
	s_mov_b32 m0, s52
	s_nop 0
	global_load_lds_dwordx4 v[226:227], off
	s_mov_b32 m0, s53
	s_nop 0
	global_load_lds_dwordx4 v[228:229], off
	s_waitcnt vmcnt(8)
	s_waitcnt lgkmcnt(0)
	s_setprio 1
	s_barrier
	v_mfma_f32_16x16x32_bf16 v[60:63], v[160:163], v[192:195], v[60:63]
	v_mfma_f32_16x16x32_bf16 v[60:63], v[164:167], v[196:199], v[60:63]
	v_mfma_f32_16x16x32_bf16 v[52:55], v[172:175], v[196:199], v[52:55]
	v_mfma_f32_16x16x32_bf16 v[52:55], v[168:171], v[192:195], v[52:55]
	v_mfma_f32_16x16x32_bf16 v[36:39], v[168:171], v[200:203], v[36:39]
	v_mfma_f32_16x16x32_bf16 v[36:39], v[172:175], v[204:207], v[36:39]
	v_mfma_f32_16x16x32_bf16 v[44:47], v[164:167], v[204:207], v[44:47]
	v_mfma_f32_16x16x32_bf16 v[44:47], v[160:163], v[200:203], v[44:47]
	v_mfma_f32_16x16x32_bf16 v[28:31], v[160:163], v[208:211], v[28:31]
	v_mfma_f32_16x16x32_bf16 v[28:31], v[164:167], v[212:215], v[28:31]
	v_mfma_f32_16x16x32_bf16 v[20:23], v[172:175], v[212:215], v[20:23]
	v_mfma_f32_16x16x32_bf16 v[20:23], v[168:171], v[208:211], v[20:23]
	v_mfma_f32_16x16x32_bf16 v[4:7], v[168:171], v[216:219], v[4:7]
	v_mfma_f32_16x16x32_bf16 v[4:7], v[172:175], v[220:223], v[4:7]
	v_mfma_f32_16x16x32_bf16 v[12:15], v[164:167], v[220:223], v[12:15]
	v_mfma_f32_16x16x32_bf16 v[12:15], v[160:163], v[216:219], v[12:15]
	s_setprio 0
	s_setprio 1
	v_mfma_f32_16x16x32_bf16 v[56:59], v[176:179], v[192:195], v[56:59]
	v_mfma_f32_16x16x32_bf16 v[56:59], v[180:183], v[196:199], v[56:59]
	v_mfma_f32_16x16x32_bf16 v[48:51], v[188:191], v[196:199], v[48:51]
	v_mfma_f32_16x16x32_bf16 v[48:51], v[184:187], v[192:195], v[48:51]
	v_mfma_f32_16x16x32_bf16 v[32:35], v[184:187], v[200:203], v[32:35]
	v_mfma_f32_16x16x32_bf16 v[32:35], v[188:191], v[204:207], v[32:35]
	v_mfma_f32_16x16x32_bf16 v[40:43], v[180:183], v[204:207], v[40:43]
	v_mfma_f32_16x16x32_bf16 v[40:43], v[176:179], v[200:203], v[40:43]
	v_mfma_f32_16x16x32_bf16 v[24:27], v[176:179], v[208:211], v[24:27]
	v_mfma_f32_16x16x32_bf16 v[24:27], v[180:183], v[212:215], v[24:27]
	v_mfma_f32_16x16x32_bf16 v[16:19], v[188:191], v[212:215], v[16:19]
	v_mfma_f32_16x16x32_bf16 v[16:19], v[184:187], v[208:211], v[16:19]
	v_mfma_f32_16x16x32_bf16 v[0:3], v[184:187], v[216:219], v[0:3]
	v_mfma_f32_16x16x32_bf16 v[0:3], v[188:191], v[220:223], v[0:3]
	v_mfma_f32_16x16x32_bf16 v[8:11], v[180:183], v[220:223], v[8:11]
	v_mfma_f32_16x16x32_bf16 v[8:11], v[176:179], v[216:219], v[8:11]
	s_barrier
	s_setprio 0
	s_add_i32 s71, 0, 0x18000
	v_add_u32_e32 v153, s71, v147
	s_add_i32 s72, 0, 0x1c000
	ds_read_b128 v[160:163], v153
	v_xor_b32_e32 v253, 64, v153
	ds_read_b128 v[164:167], v253
	ds_read_b128 v[168:171], v153 offset:2048
	ds_read_b128 v[172:175], v253 offset:2048
	v_add_u32_e32 v153, s72, v147
	ds_read_b128 v[176:179], v153
	v_xor_b32_e32 v253, 64, v153
	ds_read_b128 v[180:183], v253
	ds_read_b128 v[184:187], v153 offset:2048
	ds_read_b128 v[188:191], v253 offset:2048
	s_add_u32 s46, s46, 0x40000
	s_addc_u32 s47, s47, 0
	s_mov_b32 m0, s54
	v_lshl_add_u64 v[230:231], s[46:47], 0, v[134:135]
	ds_read_b128 v[192:195], v150 offset:32768
	v_xor_b32_e32 v253, 64, v150
	ds_read_b128 v[196:199], v253 offset:32768
	ds_read_b128 v[200:203], v150 offset:34816
	ds_read_b128 v[204:207], v253 offset:34816
	ds_read_b128 v[208:211], v150 offset:36864
	ds_read_b128 v[212:215], v253 offset:36864
	ds_read_b128 v[216:219], v150 offset:38912
	ds_read_b128 v[220:223], v253 offset:38912
	global_load_lds_dwordx4 v[230:231], off
	v_lshl_add_u64 v[230:231], s[46:47], 0, v[130:131]
	s_mov_b32 m0, s55
	s_nop 0
	global_load_lds_dwordx4 v[230:231], off
	s_waitcnt vmcnt(8)
	s_waitcnt lgkmcnt(0)
	s_setprio 1
	s_barrier
	v_mfma_f32_16x16x32_bf16 v[124:127], v[160:163], v[192:195], v[124:127]
	v_mfma_f32_16x16x32_bf16 v[124:127], v[164:167], v[196:199], v[124:127]
	v_mfma_f32_16x16x32_bf16 v[116:119], v[172:175], v[196:199], v[116:119]
	v_mfma_f32_16x16x32_bf16 v[116:119], v[168:171], v[192:195], v[116:119]
	v_mfma_f32_16x16x32_bf16 v[100:103], v[168:171], v[200:203], v[100:103]
	v_mfma_f32_16x16x32_bf16 v[100:103], v[172:175], v[204:207], v[100:103]
	v_mfma_f32_16x16x32_bf16 v[108:111], v[164:167], v[204:207], v[108:111]
	v_mfma_f32_16x16x32_bf16 v[108:111], v[160:163], v[200:203], v[108:111]
	v_mfma_f32_16x16x32_bf16 v[92:95], v[160:163], v[208:211], v[92:95]
	v_mfma_f32_16x16x32_bf16 v[92:95], v[164:167], v[212:215], v[92:95]
	v_mfma_f32_16x16x32_bf16 v[84:87], v[172:175], v[212:215], v[84:87]
	v_mfma_f32_16x16x32_bf16 v[84:87], v[168:171], v[208:211], v[84:87]
	v_mfma_f32_16x16x32_bf16 v[68:71], v[168:171], v[216:219], v[68:71]
	v_mfma_f32_16x16x32_bf16 v[68:71], v[172:175], v[220:223], v[68:71]
	v_mfma_f32_16x16x32_bf16 v[76:79], v[164:167], v[220:223], v[76:79]
	v_mfma_f32_16x16x32_bf16 v[76:79], v[160:163], v[216:219], v[76:79]
	s_setprio 0
	s_setprio 1
	v_mfma_f32_16x16x32_bf16 v[120:123], v[176:179], v[192:195], v[120:123]
	v_mfma_f32_16x16x32_bf16 v[120:123], v[180:183], v[196:199], v[120:123]
	v_mfma_f32_16x16x32_bf16 v[112:115], v[188:191], v[196:199], v[112:115]
	v_mfma_f32_16x16x32_bf16 v[112:115], v[184:187], v[192:195], v[112:115]
	v_mfma_f32_16x16x32_bf16 v[96:99], v[184:187], v[200:203], v[96:99]
	v_mfma_f32_16x16x32_bf16 v[96:99], v[188:191], v[204:207], v[96:99]
	v_mfma_f32_16x16x32_bf16 v[104:107], v[180:183], v[204:207], v[104:107]
	v_mfma_f32_16x16x32_bf16 v[104:107], v[176:179], v[200:203], v[104:107]
	v_mfma_f32_16x16x32_bf16 v[88:91], v[176:179], v[208:211], v[88:91]
	v_mfma_f32_16x16x32_bf16 v[88:91], v[180:183], v[212:215], v[88:91]
	v_mfma_f32_16x16x32_bf16 v[80:83], v[188:191], v[212:215], v[80:83]
	v_mfma_f32_16x16x32_bf16 v[80:83], v[184:187], v[208:211], v[80:83]
	v_mfma_f32_16x16x32_bf16 v[64:67], v[184:187], v[216:219], v[64:67]
	v_mfma_f32_16x16x32_bf16 v[64:67], v[188:191], v[220:223], v[64:67]
	v_mfma_f32_16x16x32_bf16 v[72:75], v[180:183], v[220:223], v[72:75]
	v_mfma_f32_16x16x32_bf16 v[72:75], v[176:179], v[216:219], v[72:75]
	s_barrier
	s_setprio 0
	s_add_i32 s46, s71, s49
	v_lshl_add_u64 v[154:155], v[154:155], 0, s[14:15]
	s_mov_b32 m0, s46
	ds_read_b128 v[192:195], v150 offset:49152
	v_xor_b32_e32 v253, 64, v150
	ds_read_b128 v[196:199], v253 offset:49152
	ds_read_b128 v[200:203], v150 offset:51200
	ds_read_b128 v[204:207], v253 offset:51200
	ds_read_b128 v[208:211], v150 offset:53248
	ds_read_b128 v[212:215], v253 offset:53248
	ds_read_b128 v[216:219], v150 offset:55296
	ds_read_b128 v[220:223], v253 offset:55296
	global_load_lds_dwordx4 v[154:155], off
	s_add_i32 m0, s46, 0x2000
	s_add_u32 s44, s44, 0x40080
	v_lshl_add_u64 v[154:155], v[224:225], 0, s[14:15]
	s_addc_u32 s45, s45, 0
	s_add_i32 s46, s72, s49
	global_load_lds_dwordx4 v[154:155], off
	v_lshl_add_u64 v[154:155], s[44:45], 0, v[132:133]
	s_mov_b32 m0, s46
	s_nop 0
	global_load_lds_dwordx4 v[154:155], off
	v_lshl_add_u64 v[154:155], s[44:45], 0, v[128:129]
	s_add_i32 m0, s46, 0x2000
	s_nop 0
	global_load_lds_dwordx4 v[154:155], off
	v_lshl_add_u64 v[154:155], v[226:227], 0, s[14:15]
	s_mov_b32 m0, s57
	s_nop 0
	global_load_lds_dwordx4 v[154:155], off
	v_lshl_add_u64 v[154:155], v[228:229], 0, s[14:15]
	s_mov_b32 m0, s58
	s_nop 0
	global_load_lds_dwordx4 v[154:155], off
	s_waitcnt vmcnt(8)
	s_waitcnt lgkmcnt(0)
	s_setprio 1
	s_barrier
	v_mfma_f32_16x16x32_bf16 v[60:63], v[160:163], v[192:195], v[60:63]
	v_mfma_f32_16x16x32_bf16 v[60:63], v[164:167], v[196:199], v[60:63]
	v_mfma_f32_16x16x32_bf16 v[52:55], v[172:175], v[196:199], v[52:55]
	v_mfma_f32_16x16x32_bf16 v[52:55], v[168:171], v[192:195], v[52:55]
	v_mfma_f32_16x16x32_bf16 v[36:39], v[168:171], v[200:203], v[36:39]
	v_mfma_f32_16x16x32_bf16 v[36:39], v[172:175], v[204:207], v[36:39]
	v_mfma_f32_16x16x32_bf16 v[44:47], v[164:167], v[204:207], v[44:47]
	v_mfma_f32_16x16x32_bf16 v[44:47], v[160:163], v[200:203], v[44:47]
	v_mfma_f32_16x16x32_bf16 v[28:31], v[160:163], v[208:211], v[28:31]
	v_mfma_f32_16x16x32_bf16 v[28:31], v[164:167], v[212:215], v[28:31]
	v_mfma_f32_16x16x32_bf16 v[20:23], v[172:175], v[212:215], v[20:23]
	v_mfma_f32_16x16x32_bf16 v[20:23], v[168:171], v[208:211], v[20:23]
	v_mfma_f32_16x16x32_bf16 v[4:7], v[168:171], v[216:219], v[4:7]
	v_mfma_f32_16x16x32_bf16 v[4:7], v[172:175], v[220:223], v[4:7]
	v_mfma_f32_16x16x32_bf16 v[12:15], v[164:167], v[220:223], v[12:15]
	v_mfma_f32_16x16x32_bf16 v[12:15], v[160:163], v[216:219], v[12:15]
	s_setprio 0
	s_setprio 1
	v_mfma_f32_16x16x32_bf16 v[56:59], v[176:179], v[192:195], v[56:59]
	v_mfma_f32_16x16x32_bf16 v[56:59], v[180:183], v[196:199], v[56:59]
	v_mfma_f32_16x16x32_bf16 v[48:51], v[188:191], v[196:199], v[48:51]
	v_mfma_f32_16x16x32_bf16 v[48:51], v[184:187], v[192:195], v[48:51]
	v_mfma_f32_16x16x32_bf16 v[32:35], v[184:187], v[200:203], v[32:35]
	v_mfma_f32_16x16x32_bf16 v[32:35], v[188:191], v[204:207], v[32:35]
	v_mfma_f32_16x16x32_bf16 v[40:43], v[180:183], v[204:207], v[40:43]
	v_mfma_f32_16x16x32_bf16 v[40:43], v[176:179], v[200:203], v[40:43]
	v_mfma_f32_16x16x32_bf16 v[24:27], v[176:179], v[208:211], v[24:27]
	v_mfma_f32_16x16x32_bf16 v[24:27], v[180:183], v[212:215], v[24:27]
	v_mfma_f32_16x16x32_bf16 v[16:19], v[188:191], v[212:215], v[16:19]
	v_mfma_f32_16x16x32_bf16 v[16:19], v[184:187], v[208:211], v[16:19]
	v_mfma_f32_16x16x32_bf16 v[0:3], v[184:187], v[216:219], v[0:3]
	v_mfma_f32_16x16x32_bf16 v[0:3], v[188:191], v[220:223], v[0:3]
	v_mfma_f32_16x16x32_bf16 v[8:11], v[180:183], v[220:223], v[8:11]
	v_mfma_f32_16x16x32_bf16 v[8:11], v[176:179], v[216:219], v[8:11]
	s_barrier
	s_setprio 0
	s_add_i32 s70, s70, 2
	s_add_u32 s68, s68, 0x100
	s_addc_u32 s69, s69, 0
	s_add_u32 s30, s30, 0x100
	s_addc_u32 s31, s31, 0
	s_cmp_gt_u32 s70, 13
	s_cbranch_scc1 .LBB0_1100

.Llast_10:
	v_add_u32_e32 v153, s61, v147
	ds_read_b128 v[160:163], v153
	v_xor_b32_e32 v253, 64, v153
	ds_read_b128 v[164:167], v253
	ds_read_b128 v[168:171], v153 offset:2048
	ds_read_b128 v[172:175], v253 offset:2048
	v_add_u32_e32 v153, s62, v147
	ds_read_b128 v[176:179], v153
	v_xor_b32_e32 v253, 64, v153
	ds_read_b128 v[180:183], v253
	ds_read_b128 v[184:187], v153 offset:2048
	ds_read_b128 v[188:191], v253 offset:2048
	s_add_u32 s46, s30, 0xfffc0080
	s_addc_u32 s47, s31, -1
	s_and_b64 s[44:45], s[44:45], exec
	s_cselect_b32 s47, s25, s47
	s_cselect_b32 s46, s65, s46
	s_cselect_b32 s45, s66, s69
	s_cselect_b32 s44, s67, s68
	v_lshl_add_u64 v[154:155], s[30:31], 0, v[138:139]
	s_add_i32 m0, s52, 0xc000
	ds_read_b128 v[192:195], v150
	v_xor_b32_e32 v253, 64, v150
	ds_read_b128 v[196:199], v253
	ds_read_b128 v[200:203], v150 offset:2048
	ds_read_b128 v[204:207], v253 offset:2048
	ds_read_b128 v[208:211], v150 offset:4096
	ds_read_b128 v[212:215], v253 offset:4096
	ds_read_b128 v[216:219], v150 offset:6144
	ds_read_b128 v[220:223], v253 offset:6144
	global_load_lds_dwordx4 v[154:155], off
	v_lshl_add_u64 v[154:155], s[30:31], 0, v[136:137]
	s_add_i32 m0, s52, 0xe000
	s_nop 0
	global_load_lds_dwordx4 v[154:155], off
	s_waitcnt vmcnt(8)
	s_waitcnt lgkmcnt(0)
	s_setprio 1
	s_barrier
	v_mfma_f32_16x16x32_bf16 v[124:127], v[160:163], v[192:195], v[124:127]
	v_mfma_f32_16x16x32_bf16 v[124:127], v[164:167], v[196:199], v[124:127]
	v_mfma_f32_16x16x32_bf16 v[116:119], v[172:175], v[196:199], v[116:119]
	v_mfma_f32_16x16x32_bf16 v[116:119], v[168:171], v[192:195], v[116:119]
	v_mfma_f32_16x16x32_bf16 v[100:103], v[168:171], v[200:203], v[100:103]
	v_mfma_f32_16x16x32_bf16 v[100:103], v[172:175], v[204:207], v[100:103]
	v_mfma_f32_16x16x32_bf16 v[108:111], v[164:167], v[204:207], v[108:111]
	v_mfma_f32_16x16x32_bf16 v[108:111], v[160:163], v[200:203], v[108:111]
	v_mfma_f32_16x16x32_bf16 v[92:95], v[160:163], v[208:211], v[92:95]
	v_mfma_f32_16x16x32_bf16 v[92:95], v[164:167], v[212:215], v[92:95]
	v_mfma_f32_16x16x32_bf16 v[84:87], v[172:175], v[212:215], v[84:87]
	v_mfma_f32_16x16x32_bf16 v[84:87], v[168:171], v[208:211], v[84:87]
	v_mfma_f32_16x16x32_bf16 v[68:71], v[168:171], v[216:219], v[68:71]
	v_mfma_f32_16x16x32_bf16 v[68:71], v[172:175], v[220:223], v[68:71]
	v_mfma_f32_16x16x32_bf16 v[76:79], v[164:167], v[220:223], v[76:79]
	v_mfma_f32_16x16x32_bf16 v[76:79], v[160:163], v[216:219], v[76:79]
	s_setprio 0
	s_setprio 1
	v_mfma_f32_16x16x32_bf16 v[120:123], v[176:179], v[192:195], v[120:123]
	v_mfma_f32_16x16x32_bf16 v[120:123], v[180:183], v[196:199], v[120:123]
	v_mfma_f32_16x16x32_bf16 v[112:115], v[188:191], v[196:199], v[112:115]
	v_mfma_f32_16x16x32_bf16 v[112:115], v[184:187], v[192:195], v[112:115]
	v_mfma_f32_16x16x32_bf16 v[96:99], v[184:187], v[200:203], v[96:99]
	v_mfma_f32_16x16x32_bf16 v[96:99], v[188:191], v[204:207], v[96:99]
	v_mfma_f32_16x16x32_bf16 v[104:107], v[180:183], v[204:207], v[104:107]
	v_mfma_f32_16x16x32_bf16 v[104:107], v[176:179], v[200:203], v[104:107]
	v_mfma_f32_16x16x32_bf16 v[88:91], v[176:179], v[208:211], v[88:91]
	v_mfma_f32_16x16x32_bf16 v[88:91], v[180:183], v[212:215], v[88:91]
	v_mfma_f32_16x16x32_bf16 v[80:83], v[188:191], v[212:215], v[80:83]
	v_mfma_f32_16x16x32_bf16 v[80:83], v[184:187], v[208:211], v[80:83]
	v_mfma_f32_16x16x32_bf16 v[64:67], v[184:187], v[216:219], v[64:67]
	v_mfma_f32_16x16x32_bf16 v[64:67], v[188:191], v[220:223], v[64:67]
	v_mfma_f32_16x16x32_bf16 v[72:75], v[180:183], v[220:223], v[72:75]
	v_mfma_f32_16x16x32_bf16 v[72:75], v[176:179], v[216:219], v[72:75]
	s_barrier
	s_setprio 0
	s_add_i32 s71, s61, s49
	v_lshl_add_u64 v[154:155], s[44:45], 0, v[132:133]
	s_mov_b32 m0, s71
	ds_read_b128 v[192:195], v150 offset:16384
	v_xor_b32_e32 v253, 64, v150
	ds_read_b128 v[196:199], v253 offset:16384
	ds_read_b128 v[200:203], v150 offset:18432
	ds_read_b128 v[204:207], v253 offset:18432
	ds_read_b128 v[208:211], v150 offset:20480
	ds_read_b128 v[212:215], v253 offset:20480
	ds_read_b128 v[216:219], v150 offset:22528
	ds_read_b128 v[220:223], v253 offset:22528
	global_load_lds_dwordx4 v[154:155], off
	s_add_i32 m0, s71, 0x2000
	s_add_u32 s72, s44, 0x40000
	v_lshl_add_u64 v[224:225], s[44:45], 0, v[128:129]
	s_addc_u32 s73, s45, 0
	s_add_i32 s71, s62, s49
	global_load_lds_dwordx4 v[224:225], off
	v_lshl_add_u64 v[226:227], s[72:73], 0, v[132:133]
	s_mov_b32 m0, s71
	v_lshl_add_u64 v[228:229], s[46:47], 0, v[130:131]
	global_load_lds_dwordx4 v[226:227], off
	v_lshl_add_u64 v[226:227], s[72:73], 0, v[128:129]
	s_add_i32 m0, s71, 0x2000
	s_nop 0
	global_load_lds_dwordx4 v[226:227], off
	v_lshl_add_u64 v[226:227], s[46:47], 0, v[134:135]
	s_mov_b32 m0, s52
	s_nop 0
	global_load_lds_dwordx4 v[226:227], off
	s_mov_b32 m0, s53
	s_nop 0
	global_load_lds_dwordx4 v[228:229], off
	s_waitcnt vmcnt(8)
	s_waitcnt lgkmcnt(0)
	s_setprio 1
	s_barrier
	v_mfma_f32_16x16x32_bf16 v[60:63], v[160:163], v[192:195], v[60:63]
	v_mfma_f32_16x16x32_bf16 v[60:63], v[164:167], v[196:199], v[60:63]
	v_mfma_f32_16x16x32_bf16 v[52:55], v[172:175], v[196:199], v[52:55]
	v_mfma_f32_16x16x32_bf16 v[52:55], v[168:171], v[192:195], v[52:55]
	v_mfma_f32_16x16x32_bf16 v[36:39], v[168:171], v[200:203], v[36:39]
	v_mfma_f32_16x16x32_bf16 v[36:39], v[172:175], v[204:207], v[36:39]
	v_mfma_f32_16x16x32_bf16 v[44:47], v[164:167], v[204:207], v[44:47]
	v_mfma_f32_16x16x32_bf16 v[44:47], v[160:163], v[200:203], v[44:47]
	v_mfma_f32_16x16x32_bf16 v[28:31], v[160:163], v[208:211], v[28:31]
	v_mfma_f32_16x16x32_bf16 v[28:31], v[164:167], v[212:215], v[28:31]
	v_mfma_f32_16x16x32_bf16 v[20:23], v[172:175], v[212:215], v[20:23]
	v_mfma_f32_16x16x32_bf16 v[20:23], v[168:171], v[208:211], v[20:23]
	v_mfma_f32_16x16x32_bf16 v[4:7], v[168:171], v[216:219], v[4:7]
	v_mfma_f32_16x16x32_bf16 v[4:7], v[172:175], v[220:223], v[4:7]
	v_mfma_f32_16x16x32_bf16 v[12:15], v[164:167], v[220:223], v[12:15]
	v_mfma_f32_16x16x32_bf16 v[12:15], v[160:163], v[216:219], v[12:15]
	s_setprio 0
	s_setprio 1
	v_mfma_f32_16x16x32_bf16 v[56:59], v[176:179], v[192:195], v[56:59]
	v_mfma_f32_16x16x32_bf16 v[56:59], v[180:183], v[196:199], v[56:59]
	v_mfma_f32_16x16x32_bf16 v[48:51], v[188:191], v[196:199], v[48:51]
	v_mfma_f32_16x16x32_bf16 v[48:51], v[184:187], v[192:195], v[48:51]
	v_mfma_f32_16x16x32_bf16 v[32:35], v[184:187], v[200:203], v[32:35]
	v_mfma_f32_16x16x32_bf16 v[32:35], v[188:191], v[204:207], v[32:35]
	v_mfma_f32_16x16x32_bf16 v[40:43], v[180:183], v[204:207], v[40:43]
	v_mfma_f32_16x16x32_bf16 v[40:43], v[176:179], v[200:203], v[40:43]
	v_mfma_f32_16x16x32_bf16 v[24:27], v[176:179], v[208:211], v[24:27]
	v_mfma_f32_16x16x32_bf16 v[24:27], v[180:183], v[212:215], v[24:27]
	v_mfma_f32_16x16x32_bf16 v[16:19], v[188:191], v[212:215], v[16:19]
	v_mfma_f32_16x16x32_bf16 v[16:19], v[184:187], v[208:211], v[16:19]
	v_mfma_f32_16x16x32_bf16 v[0:3], v[184:187], v[216:219], v[0:3]
	v_mfma_f32_16x16x32_bf16 v[0:3], v[188:191], v[220:223], v[0:3]
	v_mfma_f32_16x16x32_bf16 v[8:11], v[180:183], v[220:223], v[8:11]
	v_mfma_f32_16x16x32_bf16 v[8:11], v[176:179], v[216:219], v[8:11]
	s_barrier
	s_setprio 0
	s_add_i32 s71, 0, 0x18000
	v_add_u32_e32 v153, s71, v147
	s_add_i32 s72, 0, 0x1c000
	ds_read_b128 v[160:163], v153
	v_xor_b32_e32 v253, 64, v153
	ds_read_b128 v[164:167], v253
	ds_read_b128 v[168:171], v153 offset:2048
	ds_read_b128 v[172:175], v253 offset:2048
	v_add_u32_e32 v153, s72, v147
	ds_read_b128 v[176:179], v153
	v_xor_b32_e32 v253, 64, v153
	ds_read_b128 v[180:183], v253
	ds_read_b128 v[184:187], v153 offset:2048
	ds_read_b128 v[188:191], v253 offset:2048
	s_add_u32 s46, s46, 0x40000
	s_addc_u32 s47, s47, 0
	s_mov_b32 m0, s54
	v_lshl_add_u64 v[230:231], s[46:47], 0, v[134:135]
	ds_read_b128 v[192:195], v150 offset:32768
	v_xor_b32_e32 v253, 64, v150
	ds_read_b128 v[196:199], v253 offset:32768
	ds_read_b128 v[200:203], v150 offset:34816
	ds_read_b128 v[204:207], v253 offset:34816
	ds_read_b128 v[208:211], v150 offset:36864
	ds_read_b128 v[212:215], v253 offset:36864
	ds_read_b128 v[216:219], v150 offset:38912
	ds_read_b128 v[220:223], v253 offset:38912
	global_load_lds_dwordx4 v[230:231], off
	v_lshl_add_u64 v[230:231], s[46:47], 0, v[130:131]
	s_mov_b32 m0, s55
	s_nop 0
	global_load_lds_dwordx4 v[230:231], off
	s_waitcnt vmcnt(8)
	s_waitcnt lgkmcnt(0)
	s_setprio 1
	s_barrier
	v_mfma_f32_16x16x32_bf16 v[124:127], v[160:163], v[192:195], v[124:127]
	v_mfma_f32_16x16x32_bf16 v[124:127], v[164:167], v[196:199], v[124:127]
	v_mfma_f32_16x16x32_bf16 v[116:119], v[172:175], v[196:199], v[116:119]
	v_mfma_f32_16x16x32_bf16 v[116:119], v[168:171], v[192:195], v[116:119]
	v_mfma_f32_16x16x32_bf16 v[100:103], v[168:171], v[200:203], v[100:103]
	v_mfma_f32_16x16x32_bf16 v[100:103], v[172:175], v[204:207], v[100:103]
	v_mfma_f32_16x16x32_bf16 v[108:111], v[164:167], v[204:207], v[108:111]
	v_mfma_f32_16x16x32_bf16 v[108:111], v[160:163], v[200:203], v[108:111]
	v_mfma_f32_16x16x32_bf16 v[92:95], v[160:163], v[208:211], v[92:95]
	v_mfma_f32_16x16x32_bf16 v[92:95], v[164:167], v[212:215], v[92:95]
	v_mfma_f32_16x16x32_bf16 v[84:87], v[172:175], v[212:215], v[84:87]
	v_mfma_f32_16x16x32_bf16 v[84:87], v[168:171], v[208:211], v[84:87]
	v_mfma_f32_16x16x32_bf16 v[68:71], v[168:171], v[216:219], v[68:71]
	v_mfma_f32_16x16x32_bf16 v[68:71], v[172:175], v[220:223], v[68:71]
	v_mfma_f32_16x16x32_bf16 v[76:79], v[164:167], v[220:223], v[76:79]
	v_mfma_f32_16x16x32_bf16 v[76:79], v[160:163], v[216:219], v[76:79]
	s_setprio 0
	s_setprio 1
	v_mfma_f32_16x16x32_bf16 v[120:123], v[176:179], v[192:195], v[120:123]
	v_mfma_f32_16x16x32_bf16 v[120:123], v[180:183], v[196:199], v[120:123]
	v_mfma_f32_16x16x32_bf16 v[112:115], v[188:191], v[196:199], v[112:115]
	v_mfma_f32_16x16x32_bf16 v[112:115], v[184:187], v[192:195], v[112:115]
	v_mfma_f32_16x16x32_bf16 v[96:99], v[184:187], v[200:203], v[96:99]
	v_mfma_f32_16x16x32_bf16 v[96:99], v[188:191], v[204:207], v[96:99]
	v_mfma_f32_16x16x32_bf16 v[104:107], v[180:183], v[204:207], v[104:107]
	v_mfma_f32_16x16x32_bf16 v[104:107], v[176:179], v[200:203], v[104:107]
	v_mfma_f32_16x16x32_bf16 v[88:91], v[176:179], v[208:211], v[88:91]
	v_mfma_f32_16x16x32_bf16 v[88:91], v[180:183], v[212:215], v[88:91]
	v_mfma_f32_16x16x32_bf16 v[80:83], v[188:191], v[212:215], v[80:83]
	v_mfma_f32_16x16x32_bf16 v[80:83], v[184:187], v[208:211], v[80:83]
	v_mfma_f32_16x16x32_bf16 v[64:67], v[184:187], v[216:219], v[64:67]
	v_mfma_f32_16x16x32_bf16 v[64:67], v[188:191], v[220:223], v[64:67]
	v_mfma_f32_16x16x32_bf16 v[72:75], v[180:183], v[220:223], v[72:75]
	v_mfma_f32_16x16x32_bf16 v[72:75], v[176:179], v[216:219], v[72:75]
	s_barrier
	s_setprio 0
	v_add_u32_e32 v234, 0x21000, v151
	ds_read_b128 v[236:239], v234
	ds_read_b128 v[240:243], v234 offset:256
	ds_read_b128 v[244:247], v234 offset:512
	ds_read_b128 v[248:251], v234 offset:768
	v_add_u32_e32 v235, s23, v146
	v_mul_u32_u24_e32 v235, 0x1600, v235
	v_lshl_or_b32 v234, s64, 7, v149
	v_lshl_add_u32 v235, v234, 1, v235
	s_add_i32 s46, s71, s49
	v_lshl_add_u64 v[154:155], v[154:155], 0, s[14:15]
	s_mov_b32 m0, s46
	ds_read_b128 v[192:195], v150 offset:49152
	v_xor_b32_e32 v253, 64, v150
	ds_read_b128 v[196:199], v253 offset:49152
	ds_read_b128 v[200:203], v150 offset:51200
	ds_read_b128 v[204:207], v253 offset:51200
	ds_read_b128 v[208:211], v150 offset:53248
	ds_read_b128 v[212:215], v253 offset:53248
	ds_read_b128 v[216:219], v150 offset:55296
	ds_read_b128 v[220:223], v253 offset:55296
	global_load_lds_dwordx4 v[154:155], off
	s_add_i32 m0, s46, 0x2000
	s_add_u32 s44, s44, 0x40080
	v_lshl_add_u64 v[154:155], v[224:225], 0, s[14:15]
	s_addc_u32 s45, s45, 0
	s_add_i32 s46, s72, s49
	global_load_lds_dwordx4 v[154:155], off
	v_lshl_add_u64 v[154:155], s[44:45], 0, v[132:133]
	s_mov_b32 m0, s46
	s_nop 0
	global_load_lds_dwordx4 v[154:155], off
	v_lshl_add_u64 v[154:155], s[44:45], 0, v[128:129]
	s_add_i32 m0, s46, 0x2000
	s_nop 0
	global_load_lds_dwordx4 v[154:155], off
	v_lshl_add_u64 v[154:155], v[226:227], 0, s[14:15]
	s_mov_b32 m0, s57
	s_nop 0
	global_load_lds_dwordx4 v[154:155], off
	v_lshl_add_u64 v[154:155], v[228:229], 0, s[14:15]
	s_mov_b32 m0, s58
	s_nop 0
	global_load_lds_dwordx4 v[154:155], off
	s_waitcnt lgkmcnt(8)
	v_add_f32_e32 v236, v236, v237
	v_add_f32_e32 v238, v238, v239
	v_add_f32_e32 v240, v240, v241
	v_add_f32_e32 v242, v242, v243
	v_add_f32_e32 v244, v244, v245
	v_add_f32_e32 v246, v246, v247
	v_add_f32_e32 v248, v248, v249
	v_add_f32_e32 v250, v250, v251
	v_add_f32_e32 v236, v236, v238
	v_add_f32_e32 v240, v240, v242
	v_add_f32_e32 v244, v244, v246
	v_add_f32_e32 v248, v248, v250
	v_fmamk_f32 v236, v236, 0x3a800000, v152
	v_fmamk_f32 v240, v240, 0x3a800000, v152
	v_fmamk_f32 v244, v244, 0x3a800000, v152
	v_fmamk_f32 v248, v248, 0x3a800000, v152
	v_rsq_f32_e32 v236, v236
	v_rsq_f32_e32 v240, v240
	v_rsq_f32_e32 v244, v244
	v_rsq_f32_e32 v248, v248
	v_mul_f32_e32 v252, 0xbfb8aa3b, v236
	v_mul_f32_e32 v254, v236, v236
	v_rcp_f32_e32 v254, v254
	v_pk_mul_f32 v[120:121], v[124:125], v[120:121]
	v_pk_mul_f32 v[122:123], v[126:127], v[122:123]
	v_pk_mul_f32 v[112:113], v[116:117], v[112:113]
	v_pk_mul_f32 v[114:115], v[118:119], v[114:115]
	v_pk_mul_f32 v[124:125], v[124:125], v[252:253] op_sel_hi:[1,0]
	v_pk_mul_f32 v[126:127], v[126:127], v[252:253] op_sel_hi:[1,0]
	v_pk_mul_f32 v[116:117], v[116:117], v[252:253] op_sel_hi:[1,0]
	v_pk_mul_f32 v[118:119], v[118:119], v[252:253] op_sel_hi:[1,0]
	v_exp_f32_e32 v124, v124
	v_exp_f32_e32 v125, v125
	v_exp_f32_e32 v126, v126
	v_exp_f32_e32 v127, v127
	v_exp_f32_e32 v116, v116
	v_exp_f32_e32 v117, v117
	v_exp_f32_e32 v118, v118
	v_exp_f32_e32 v119, v119
	v_pk_fma_f32 v[124:125], v[124:125], v[254:255], v[254:255] op_sel_hi:[1,0,0]
	v_pk_fma_f32 v[126:127], v[126:127], v[254:255], v[254:255] op_sel_hi:[1,0,0]
	v_pk_fma_f32 v[116:117], v[116:117], v[254:255], v[254:255] op_sel_hi:[1,0,0]
	v_pk_fma_f32 v[118:119], v[118:119], v[254:255], v[254:255] op_sel_hi:[1,0,0]
	v_rcp_f32_e32 v124, v124
	v_rcp_f32_e32 v125, v125
	v_rcp_f32_e32 v126, v126
	v_rcp_f32_e32 v127, v127
	v_rcp_f32_e32 v116, v116
	v_rcp_f32_e32 v117, v117
	v_rcp_f32_e32 v118, v118
	v_rcp_f32_e32 v119, v119
	v_pk_mul_f32 v[120:121], v[120:121], v[124:125]
	v_pk_mul_f32 v[122:123], v[122:123], v[126:127]
	v_pk_mul_f32 v[112:113], v[112:113], v[116:117]
	v_pk_mul_f32 v[114:115], v[114:115], v[118:119]
	v_cvt_pk_bf16_f32 v120, v120, v121
	v_cvt_pk_bf16_f32 v121, v122, v123
	v_cvt_pk_bf16_f32 v122, v112, v113
	v_cvt_pk_bf16_f32 v123, v114, v115
	global_store_dwordx4 v235, v[120:123], s[10:11]
	v_add_u32_e32 v234, 0x16000, v235
	v_mul_f32_e32 v252, 0xbfb8aa3b, v240
	v_mul_f32_e32 v254, v240, v240
	v_rcp_f32_e32 v254, v254
	v_pk_mul_f32 v[104:105], v[108:109], v[104:105]
	v_pk_mul_f32 v[106:107], v[110:111], v[106:107]
	v_pk_mul_f32 v[96:97], v[100:101], v[96:97]
	v_pk_mul_f32 v[98:99], v[102:103], v[98:99]
	v_pk_mul_f32 v[108:109], v[108:109], v[252:253] op_sel_hi:[1,0]
	v_pk_mul_f32 v[110:111], v[110:111], v[252:253] op_sel_hi:[1,0]
	v_pk_mul_f32 v[100:101], v[100:101], v[252:253] op_sel_hi:[1,0]
	v_pk_mul_f32 v[102:103], v[102:103], v[252:253] op_sel_hi:[1,0]
	v_exp_f32_e32 v108, v108
	v_exp_f32_e32 v109, v109
	v_exp_f32_e32 v110, v110
	v_exp_f32_e32 v111, v111
	v_exp_f32_e32 v100, v100
	v_exp_f32_e32 v101, v101
	v_exp_f32_e32 v102, v102
	v_exp_f32_e32 v103, v103
	v_pk_fma_f32 v[108:109], v[108:109], v[254:255], v[254:255] op_sel_hi:[1,0,0]
	v_pk_fma_f32 v[110:111], v[110:111], v[254:255], v[254:255] op_sel_hi:[1,0,0]
	v_pk_fma_f32 v[100:101], v[100:101], v[254:255], v[254:255] op_sel_hi:[1,0,0]
	v_pk_fma_f32 v[102:103], v[102:103], v[254:255], v[254:255] op_sel_hi:[1,0,0]
	v_rcp_f32_e32 v108, v108
	v_rcp_f32_e32 v109, v109
	v_rcp_f32_e32 v110, v110
	v_rcp_f32_e32 v111, v111
	v_rcp_f32_e32 v100, v100
	v_rcp_f32_e32 v101, v101
	v_rcp_f32_e32 v102, v102
	v_rcp_f32_e32 v103, v103
	v_pk_mul_f32 v[104:105], v[104:105], v[108:109]
	v_pk_mul_f32 v[106:107], v[106:107], v[110:111]
	v_pk_mul_f32 v[96:97], v[96:97], v[100:101]
	v_pk_mul_f32 v[98:99], v[98:99], v[102:103]
	v_cvt_pk_bf16_f32 v104, v104, v105
	v_cvt_pk_bf16_f32 v105, v106, v107
	v_cvt_pk_bf16_f32 v106, v96, v97
	v_cvt_pk_bf16_f32 v107, v98, v99
	global_store_dwordx4 v234, v[104:107], s[10:11]
	v_add_u32_e32 v235, 0x16000, v234
	v_mul_f32_e32 v252, 0xbfb8aa3b, v244
	v_mul_f32_e32 v254, v244, v244
	v_rcp_f32_e32 v254, v254
	v_pk_mul_f32 v[88:89], v[92:93], v[88:89]
	v_pk_mul_f32 v[90:91], v[94:95], v[90:91]
	v_pk_mul_f32 v[80:81], v[84:85], v[80:81]
	v_pk_mul_f32 v[82:83], v[86:87], v[82:83]
	v_pk_mul_f32 v[92:93], v[92:93], v[252:253] op_sel_hi:[1,0]
	v_pk_mul_f32 v[94:95], v[94:95], v[252:253] op_sel_hi:[1,0]
	v_pk_mul_f32 v[84:85], v[84:85], v[252:253] op_sel_hi:[1,0]
	v_pk_mul_f32 v[86:87], v[86:87], v[252:253] op_sel_hi:[1,0]
	v_exp_f32_e32 v92, v92
	v_exp_f32_e32 v93, v93
	v_exp_f32_e32 v94, v94
	v_exp_f32_e32 v95, v95
	v_exp_f32_e32 v84, v84
	v_exp_f32_e32 v85, v85
	v_exp_f32_e32 v86, v86
	v_exp_f32_e32 v87, v87
	v_pk_fma_f32 v[92:93], v[92:93], v[254:255], v[254:255] op_sel_hi:[1,0,0]
	v_pk_fma_f32 v[94:95], v[94:95], v[254:255], v[254:255] op_sel_hi:[1,0,0]
	v_pk_fma_f32 v[84:85], v[84:85], v[254:255], v[254:255] op_sel_hi:[1,0,0]
	v_pk_fma_f32 v[86:87], v[86:87], v[254:255], v[254:255] op_sel_hi:[1,0,0]
	v_rcp_f32_e32 v92, v92
	v_rcp_f32_e32 v93, v93
	v_rcp_f32_e32 v94, v94
	v_rcp_f32_e32 v95, v95
	v_rcp_f32_e32 v84, v84
	v_rcp_f32_e32 v85, v85
	v_rcp_f32_e32 v86, v86
	v_rcp_f32_e32 v87, v87
	v_pk_mul_f32 v[88:89], v[88:89], v[92:93]
	v_pk_mul_f32 v[90:91], v[90:91], v[94:95]
	v_pk_mul_f32 v[80:81], v[80:81], v[84:85]
	v_pk_mul_f32 v[82:83], v[82:83], v[86:87]
	v_cvt_pk_bf16_f32 v88, v88, v89
	v_cvt_pk_bf16_f32 v89, v90, v91
	v_cvt_pk_bf16_f32 v90, v80, v81
	v_cvt_pk_bf16_f32 v91, v82, v83
	global_store_dwordx4 v235, v[88:91], s[10:11]
	v_add_u32_e32 v234, 0x16000, v235
	v_mul_f32_e32 v252, 0xbfb8aa3b, v248
	v_mul_f32_e32 v254, v248, v248
	v_rcp_f32_e32 v254, v254
	v_pk_mul_f32 v[72:73], v[76:77], v[72:73]
	v_pk_mul_f32 v[74:75], v[78:79], v[74:75]
	v_pk_mul_f32 v[64:65], v[68:69], v[64:65]
	v_pk_mul_f32 v[66:67], v[70:71], v[66:67]
	v_pk_mul_f32 v[76:77], v[76:77], v[252:253] op_sel_hi:[1,0]
	v_pk_mul_f32 v[78:79], v[78:79], v[252:253] op_sel_hi:[1,0]
	v_pk_mul_f32 v[68:69], v[68:69], v[252:253] op_sel_hi:[1,0]
	v_pk_mul_f32 v[70:71], v[70:71], v[252:253] op_sel_hi:[1,0]
	v_exp_f32_e32 v76, v76
	v_exp_f32_e32 v77, v77
	v_exp_f32_e32 v78, v78
	v_exp_f32_e32 v79, v79
	v_exp_f32_e32 v68, v68
	v_exp_f32_e32 v69, v69
	v_exp_f32_e32 v70, v70
	v_exp_f32_e32 v71, v71
	v_pk_fma_f32 v[76:77], v[76:77], v[254:255], v[254:255] op_sel_hi:[1,0,0]
	v_pk_fma_f32 v[78:79], v[78:79], v[254:255], v[254:255] op_sel_hi:[1,0,0]
	v_pk_fma_f32 v[68:69], v[68:69], v[254:255], v[254:255] op_sel_hi:[1,0,0]
	v_pk_fma_f32 v[70:71], v[70:71], v[254:255], v[254:255] op_sel_hi:[1,0,0]
	v_rcp_f32_e32 v76, v76
	v_rcp_f32_e32 v77, v77
	v_rcp_f32_e32 v78, v78
	v_rcp_f32_e32 v79, v79
	v_rcp_f32_e32 v68, v68
	v_rcp_f32_e32 v69, v69
	v_rcp_f32_e32 v70, v70
	v_rcp_f32_e32 v71, v71
	v_pk_mul_f32 v[72:73], v[72:73], v[76:77]
	v_pk_mul_f32 v[74:75], v[74:75], v[78:79]
	v_pk_mul_f32 v[64:65], v[64:65], v[68:69]
	v_pk_mul_f32 v[66:67], v[66:67], v[70:71]
	v_cvt_pk_bf16_f32 v72, v72, v73
	v_cvt_pk_bf16_f32 v73, v74, v75
	v_cvt_pk_bf16_f32 v74, v64, v65
	v_cvt_pk_bf16_f32 v75, v66, v67
	global_store_dwordx4 v234, v[72:75], s[10:11]
	s_waitcnt vmcnt(12)
	s_waitcnt lgkmcnt(0)
	s_setprio 1
	s_barrier
	v_mfma_f32_16x16x32_bf16 v[60:63], v[160:163], v[192:195], v[60:63]
	v_mfma_f32_16x16x32_bf16 v[60:63], v[164:167], v[196:199], v[60:63]
	v_mfma_f32_16x16x32_bf16 v[52:55], v[172:175], v[196:199], v[52:55]
	v_mfma_f32_16x16x32_bf16 v[52:55], v[168:171], v[192:195], v[52:55]
	v_mfma_f32_16x16x32_bf16 v[36:39], v[168:171], v[200:203], v[36:39]
	v_mfma_f32_16x16x32_bf16 v[36:39], v[172:175], v[204:207], v[36:39]
	v_mfma_f32_16x16x32_bf16 v[44:47], v[164:167], v[204:207], v[44:47]
	v_mfma_f32_16x16x32_bf16 v[44:47], v[160:163], v[200:203], v[44:47]
	v_mfma_f32_16x16x32_bf16 v[28:31], v[160:163], v[208:211], v[28:31]
	v_mfma_f32_16x16x32_bf16 v[28:31], v[164:167], v[212:215], v[28:31]
	v_mfma_f32_16x16x32_bf16 v[20:23], v[172:175], v[212:215], v[20:23]
	v_mfma_f32_16x16x32_bf16 v[20:23], v[168:171], v[208:211], v[20:23]
	v_mfma_f32_16x16x32_bf16 v[4:7], v[168:171], v[216:219], v[4:7]
	v_mfma_f32_16x16x32_bf16 v[4:7], v[172:175], v[220:223], v[4:7]
	v_mfma_f32_16x16x32_bf16 v[12:15], v[164:167], v[220:223], v[12:15]
	v_mfma_f32_16x16x32_bf16 v[12:15], v[160:163], v[216:219], v[12:15]
	s_setprio 0
	s_setprio 1
	v_mfma_f32_16x16x32_bf16 v[56:59], v[176:179], v[192:195], v[56:59]
	v_mfma_f32_16x16x32_bf16 v[56:59], v[180:183], v[196:199], v[56:59]
	v_mfma_f32_16x16x32_bf16 v[48:51], v[188:191], v[196:199], v[48:51]
	v_mfma_f32_16x16x32_bf16 v[48:51], v[184:187], v[192:195], v[48:51]
	v_mfma_f32_16x16x32_bf16 v[32:35], v[184:187], v[200:203], v[32:35]
	v_mfma_f32_16x16x32_bf16 v[32:35], v[188:191], v[204:207], v[32:35]
	v_mfma_f32_16x16x32_bf16 v[40:43], v[180:183], v[204:207], v[40:43]
	v_mfma_f32_16x16x32_bf16 v[40:43], v[176:179], v[200:203], v[40:43]
	v_mfma_f32_16x16x32_bf16 v[24:27], v[176:179], v[208:211], v[24:27]
	v_mfma_f32_16x16x32_bf16 v[24:27], v[180:183], v[212:215], v[24:27]
	v_mfma_f32_16x16x32_bf16 v[16:19], v[188:191], v[212:215], v[16:19]
	v_mfma_f32_16x16x32_bf16 v[16:19], v[184:187], v[208:211], v[16:19]
	v_mfma_f32_16x16x32_bf16 v[0:3], v[184:187], v[216:219], v[0:3]
	v_mfma_f32_16x16x32_bf16 v[0:3], v[188:191], v[220:223], v[0:3]
	v_mfma_f32_16x16x32_bf16 v[8:11], v[180:183], v[220:223], v[8:11]
	v_mfma_f32_16x16x32_bf16 v[8:11], v[176:179], v[216:219], v[8:11]
	s_barrier
	s_setprio 0
	s_add_i32 s70, s70, 2
	s_add_u32 s68, s68, 0x100
	s_addc_u32 s69, s69, 0
	s_add_u32 s30, s30, 0x100
	s_addc_u32 s31, s31, 0

.LBB0_1180:
	s_add_u32 s72, s50, 0x100
	s_addc_u32 s73, s51, 0
	s_mov_b32 s74, -2
	s_waitcnt lgkmcnt(0)
	s_cmp_eq_u32 s63, 1
	s_cbranch_scc1 .Lfa_11
	ds_read_b128 v[128:131], v188
	v_xor_b32_e32 v253, 64, v188
	ds_read_b128 v[132:135], v253
	ds_read_b128 v[136:139], v188 offset:2048
	ds_read_b128 v[140:143], v253 offset:2048
	ds_read_b128 v[144:147], v189
	v_xor_b32_e32 v253, 64, v189
	ds_read_b128 v[148:151], v253
	ds_read_b128 v[172:175], v189 offset:2048
	ds_read_b128 v[176:179], v253 offset:2048
	s_add_u32 s50, s48, 0x100
	s_addc_u32 s51, s49, 0
	s_cmp_eq_u32 s74, 40
	s_cselect_b32 s55, s11, s51
	s_cselect_b32 s54, s10, s50
	s_cselect_b32 s53, s47, s73
	s_cselect_b32 s52, s46, s72
	v_lshl_add_u64 v[220:221], s[48:49], 0, v[166:167]
	s_add_i32 m0, s59, 0xc000
	ds_read_b128 v[180:183], v190
	v_xor_b32_e32 v253, 64, v190
	ds_read_b128 v[192:195], v253
	ds_read_b128 v[196:199], v190 offset:2048
	ds_read_b128 v[200:203], v253 offset:2048
	ds_read_b128 v[204:207], v190 offset:4096
	ds_read_b128 v[208:211], v253 offset:4096
	ds_read_b128 v[212:215], v190 offset:6144
	ds_read_b128 v[216:219], v253 offset:6144
	global_load_lds_dwordx4 v[220:221], off
	v_lshl_add_u64 v[220:221], s[48:49], 0, v[164:165]
	s_add_i32 m0, s59, 0xe000
	s_nop 0
	global_load_lds_dwordx4 v[220:221], off
	s_waitcnt vmcnt(24)
	s_waitcnt lgkmcnt(0)
	s_setprio 1
	s_barrier
	v_mfma_f32_16x16x32_bf16 v[124:127], v[128:131], v[180:183], 0
	v_mfma_f32_16x16x32_bf16 v[120:123], v[136:139], v[180:183], 0
	v_mfma_f32_16x16x32_bf16 v[108:111], v[128:131], v[196:199], 0
	v_mfma_f32_16x16x32_bf16 v[104:107], v[136:139], v[196:199], 0
	v_mfma_f32_16x16x32_bf16 v[92:95], v[128:131], v[204:207], 0
	v_mfma_f32_16x16x32_bf16 v[88:91], v[136:139], v[204:207], 0
	v_mfma_f32_16x16x32_bf16 v[76:79], v[128:131], v[212:215], 0
	v_mfma_f32_16x16x32_bf16 v[72:75], v[136:139], v[212:215], 0
	v_mfma_f32_16x16x32_bf16 v[124:127], v[132:135], v[192:195], v[124:127]
	v_mfma_f32_16x16x32_bf16 v[120:123], v[140:143], v[192:195], v[120:123]
	v_mfma_f32_16x16x32_bf16 v[108:111], v[132:135], v[200:203], v[108:111]
	v_mfma_f32_16x16x32_bf16 v[104:107], v[140:143], v[200:203], v[104:107]
	v_mfma_f32_16x16x32_bf16 v[92:95], v[132:135], v[208:211], v[92:95]
	v_mfma_f32_16x16x32_bf16 v[88:91], v[140:143], v[208:211], v[88:91]
	v_mfma_f32_16x16x32_bf16 v[76:79], v[132:135], v[216:219], v[76:79]
	v_mfma_f32_16x16x32_bf16 v[72:75], v[140:143], v[216:219], v[72:75]
	s_setprio 0
	s_setprio 1
	v_mfma_f32_16x16x32_bf16 v[116:119], v[144:147], v[180:183], 0
	v_mfma_f32_16x16x32_bf16 v[112:115], v[172:175], v[180:183], 0
	v_mfma_f32_16x16x32_bf16 v[100:103], v[144:147], v[196:199], 0
	v_mfma_f32_16x16x32_bf16 v[96:99], v[172:175], v[196:199], 0
	v_mfma_f32_16x16x32_bf16 v[84:87], v[144:147], v[204:207], 0
	v_mfma_f32_16x16x32_bf16 v[80:83], v[172:175], v[204:207], 0
	v_mfma_f32_16x16x32_bf16 v[68:71], v[144:147], v[212:215], 0
	v_mfma_f32_16x16x32_bf16 v[64:67], v[172:175], v[212:215], 0
	v_mfma_f32_16x16x32_bf16 v[116:119], v[148:151], v[192:195], v[116:119]
	v_mfma_f32_16x16x32_bf16 v[112:115], v[176:179], v[192:195], v[112:115]
	v_mfma_f32_16x16x32_bf16 v[100:103], v[148:151], v[200:203], v[100:103]
	v_mfma_f32_16x16x32_bf16 v[96:99], v[176:179], v[200:203], v[96:99]
	v_mfma_f32_16x16x32_bf16 v[84:87], v[148:151], v[208:211], v[84:87]
	v_mfma_f32_16x16x32_bf16 v[80:83], v[176:179], v[208:211], v[80:83]
	v_mfma_f32_16x16x32_bf16 v[68:71], v[148:151], v[216:219], v[68:71]
	v_mfma_f32_16x16x32_bf16 v[64:67], v[176:179], v[216:219], v[64:67]
	s_barrier
	s_setprio 0
	s_add_i32 s48, s68, s58
	v_lshl_add_u64 v[220:221], s[52:53], 0, v[154:155]
	s_mov_b32 m0, s48
	ds_read_b128 v[180:183], v190 offset:16384
	v_xor_b32_e32 v253, 64, v190
	ds_read_b128 v[192:195], v253 offset:16384
	ds_read_b128 v[196:199], v190 offset:18432
	ds_read_b128 v[200:203], v253 offset:18432
	ds_read_b128 v[204:207], v190 offset:20480
	ds_read_b128 v[208:211], v253 offset:20480
	ds_read_b128 v[212:215], v190 offset:22528
	ds_read_b128 v[216:219], v253 offset:22528
	global_load_lds_dwordx4 v[220:221], off
	s_add_i32 m0, s48, 0x2000
	s_add_u32 s48, s52, 0xb0000
	v_lshl_add_u64 v[222:223], s[52:53], 0, v[162:163]
	s_addc_u32 s49, s53, 0
	s_add_i32 s75, s69, s58
	global_load_lds_dwordx4 v[222:223], off
	v_lshl_add_u64 v[224:225], s[48:49], 0, v[154:155]
	s_mov_b32 m0, s75
	v_lshl_add_u64 v[226:227], s[54:55], 0, v[160:161]
	global_load_lds_dwordx4 v[224:225], off
	v_lshl_add_u64 v[224:225], s[48:49], 0, v[162:163]
	s_add_i32 m0, s75, 0x2000
	s_nop 0
	global_load_lds_dwordx4 v[224:225], off
	v_lshl_add_u64 v[224:225], s[54:55], 0, v[152:153]
	s_mov_b32 m0, s59
	s_nop 0
	global_load_lds_dwordx4 v[224:225], off
	s_mov_b32 m0, s60
	s_nop 0
	global_load_lds_dwordx4 v[226:227], off
	s_waitcnt vmcnt(24)
	s_waitcnt lgkmcnt(0)
	s_setprio 1
	s_barrier
	v_mfma_f32_16x16x32_bf16 v[60:63], v[128:131], v[180:183], 0
	v_mfma_f32_16x16x32_bf16 v[56:59], v[136:139], v[180:183], 0
	v_mfma_f32_16x16x32_bf16 v[44:47], v[128:131], v[196:199], 0
	v_mfma_f32_16x16x32_bf16 v[40:43], v[136:139], v[196:199], 0
	v_mfma_f32_16x16x32_bf16 v[28:31], v[128:131], v[204:207], 0
	v_mfma_f32_16x16x32_bf16 v[24:27], v[136:139], v[204:207], 0
	v_mfma_f32_16x16x32_bf16 v[12:15], v[128:131], v[212:215], 0
	v_mfma_f32_16x16x32_bf16 v[8:11], v[136:139], v[212:215], 0
	v_mfma_f32_16x16x32_bf16 v[60:63], v[132:135], v[192:195], v[60:63]
	v_mfma_f32_16x16x32_bf16 v[56:59], v[140:143], v[192:195], v[56:59]
	v_mfma_f32_16x16x32_bf16 v[44:47], v[132:135], v[200:203], v[44:47]
	v_mfma_f32_16x16x32_bf16 v[40:43], v[140:143], v[200:203], v[40:43]
	v_mfma_f32_16x16x32_bf16 v[28:31], v[132:135], v[208:211], v[28:31]
	v_mfma_f32_16x16x32_bf16 v[24:27], v[140:143], v[208:211], v[24:27]
	v_mfma_f32_16x16x32_bf16 v[12:15], v[132:135], v[216:219], v[12:15]
	v_mfma_f32_16x16x32_bf16 v[8:11], v[140:143], v[216:219], v[8:11]
	s_setprio 0
	s_setprio 1
	v_mfma_f32_16x16x32_bf16 v[52:55], v[144:147], v[180:183], 0
	v_mfma_f32_16x16x32_bf16 v[48:51], v[172:175], v[180:183], 0
	v_mfma_f32_16x16x32_bf16 v[36:39], v[144:147], v[196:199], 0
	v_mfma_f32_16x16x32_bf16 v[32:35], v[172:175], v[196:199], 0
	v_mfma_f32_16x16x32_bf16 v[20:23], v[144:147], v[204:207], 0
	v_mfma_f32_16x16x32_bf16 v[16:19], v[172:175], v[204:207], 0
	v_mfma_f32_16x16x32_bf16 v[4:7], v[144:147], v[212:215], 0
	v_mfma_f32_16x16x32_bf16 v[0:3], v[172:175], v[212:215], 0
	v_mfma_f32_16x16x32_bf16 v[52:55], v[148:151], v[192:195], v[52:55]
	v_mfma_f32_16x16x32_bf16 v[48:51], v[176:179], v[192:195], v[48:51]
	v_mfma_f32_16x16x32_bf16 v[36:39], v[148:151], v[200:203], v[36:39]
	v_mfma_f32_16x16x32_bf16 v[32:35], v[176:179], v[200:203], v[32:35]
	v_mfma_f32_16x16x32_bf16 v[20:23], v[148:151], v[208:211], v[20:23]
	v_mfma_f32_16x16x32_bf16 v[16:19], v[176:179], v[208:211], v[16:19]
	v_mfma_f32_16x16x32_bf16 v[4:7], v[148:151], v[216:219], v[4:7]
	v_mfma_f32_16x16x32_bf16 v[0:3], v[176:179], v[216:219], v[0:3]
	s_barrier
	s_setprio 0
	s_add_i32 s75, 0, 0x18000
	s_add_i32 s76, 0, 0x1c000
	v_add_u32_e32 v140, s75, v185
	v_add_u32_e32 v176, s76, v185
	ds_read_b128 v[128:131], v140
	v_xor_b32_e32 v253, 64, v140
	ds_read_b128 v[132:135], v253
	ds_read_b128 v[136:139], v140 offset:2048
	ds_read_b128 v[140:143], v253 offset:2048
	ds_read_b128 v[144:147], v176
	v_xor_b32_e32 v253, 64, v176
	ds_read_b128 v[148:151], v253
	ds_read_b128 v[172:175], v176 offset:2048
	ds_read_b128 v[176:179], v253 offset:2048
	s_add_u32 s48, s54, 0xb0000
	s_addc_u32 s49, s55, 0
	s_mov_b32 m0, s61
	v_lshl_add_u64 v[228:229], s[48:49], 0, v[152:153]
	ds_read_b128 v[180:183], v190 offset:32768
	v_xor_b32_e32 v253, 64, v190
	ds_read_b128 v[192:195], v253 offset:32768
	ds_read_b128 v[196:199], v190 offset:34816
	ds_read_b128 v[200:203], v253 offset:34816
	ds_read_b128 v[204:207], v190 offset:36864
	ds_read_b128 v[208:211], v253 offset:36864
	ds_read_b128 v[212:215], v190 offset:38912
	ds_read_b128 v[216:219], v253 offset:38912
	global_load_lds_dwordx4 v[228:229], off
	v_lshl_add_u64 v[228:229], s[48:49], 0, v[160:161]
	s_mov_b32 m0, s62
	s_nop 0
	global_load_lds_dwordx4 v[228:229], off
	s_waitcnt vmcnt(8)
	s_waitcnt lgkmcnt(0)
	s_setprio 1
	s_barrier
	v_mfma_f32_16x16x32_bf16 v[124:127], v[128:131], v[180:183], v[124:127]
	v_mfma_f32_16x16x32_bf16 v[124:127], v[132:135], v[192:195], v[124:127]
	v_mfma_f32_16x16x32_bf16 v[120:123], v[140:143], v[192:195], v[120:123]
	v_mfma_f32_16x16x32_bf16 v[120:123], v[136:139], v[180:183], v[120:123]
	v_mfma_f32_16x16x32_bf16 v[104:107], v[136:139], v[196:199], v[104:107]
	v_mfma_f32_16x16x32_bf16 v[104:107], v[140:143], v[200:203], v[104:107]
	v_mfma_f32_16x16x32_bf16 v[108:111], v[132:135], v[200:203], v[108:111]
	v_mfma_f32_16x16x32_bf16 v[108:111], v[128:131], v[196:199], v[108:111]
	v_mfma_f32_16x16x32_bf16 v[92:95], v[128:131], v[204:207], v[92:95]
	v_mfma_f32_16x16x32_bf16 v[92:95], v[132:135], v[208:211], v[92:95]
	v_mfma_f32_16x16x32_bf16 v[88:91], v[140:143], v[208:211], v[88:91]
	v_mfma_f32_16x16x32_bf16 v[88:91], v[136:139], v[204:207], v[88:91]
	v_mfma_f32_16x16x32_bf16 v[72:75], v[136:139], v[212:215], v[72:75]
	v_mfma_f32_16x16x32_bf16 v[72:75], v[140:143], v[216:219], v[72:75]
	v_mfma_f32_16x16x32_bf16 v[76:79], v[132:135], v[216:219], v[76:79]
	v_mfma_f32_16x16x32_bf16 v[76:79], v[128:131], v[212:215], v[76:79]
	s_setprio 0
	s_setprio 1
	v_mfma_f32_16x16x32_bf16 v[116:119], v[144:147], v[180:183], v[116:119]
	v_mfma_f32_16x16x32_bf16 v[116:119], v[148:151], v[192:195], v[116:119]
	v_mfma_f32_16x16x32_bf16 v[112:115], v[176:179], v[192:195], v[112:115]
	v_mfma_f32_16x16x32_bf16 v[112:115], v[172:175], v[180:183], v[112:115]
	v_mfma_f32_16x16x32_bf16 v[96:99], v[172:175], v[196:199], v[96:99]
	v_mfma_f32_16x16x32_bf16 v[96:99], v[176:179], v[200:203], v[96:99]
	v_mfma_f32_16x16x32_bf16 v[100:103], v[148:151], v[200:203], v[100:103]
	v_mfma_f32_16x16x32_bf16 v[100:103], v[144:147], v[196:199], v[100:103]
	v_mfma_f32_16x16x32_bf16 v[84:87], v[144:147], v[204:207], v[84:87]
	v_mfma_f32_16x16x32_bf16 v[84:87], v[148:151], v[208:211], v[84:87]
	v_mfma_f32_16x16x32_bf16 v[80:83], v[176:179], v[208:211], v[80:83]
	v_mfma_f32_16x16x32_bf16 v[80:83], v[172:175], v[204:207], v[80:83]
	v_mfma_f32_16x16x32_bf16 v[64:67], v[172:175], v[212:215], v[64:67]
	v_mfma_f32_16x16x32_bf16 v[64:67], v[176:179], v[216:219], v[64:67]
	v_mfma_f32_16x16x32_bf16 v[68:71], v[148:151], v[216:219], v[68:71]
	v_mfma_f32_16x16x32_bf16 v[68:71], v[144:147], v[212:215], v[68:71]
	s_barrier
	s_setprio 0
	s_add_i32 s48, s75, s58
	v_lshl_add_u64 v[220:221], v[220:221], 0, s[22:23]
	s_mov_b32 m0, s48
	ds_read_b128 v[180:183], v190 offset:49152
	v_xor_b32_e32 v253, 64, v190
	ds_read_b128 v[192:195], v253 offset:49152
	ds_read_b128 v[196:199], v190 offset:51200
	ds_read_b128 v[200:203], v253 offset:51200
	ds_read_b128 v[204:207], v190 offset:53248
	ds_read_b128 v[208:211], v253 offset:53248
	ds_read_b128 v[212:215], v190 offset:55296
	ds_read_b128 v[216:219], v253 offset:55296
	global_load_lds_dwordx4 v[220:221], off
	s_add_i32 m0, s48, 0x2000
	s_add_u32 s48, s52, 0xb0080
	v_lshl_add_u64 v[220:221], v[222:223], 0, s[22:23]
	s_addc_u32 s49, s53, 0
	s_add_i32 s52, s76, s58
	global_load_lds_dwordx4 v[220:221], off
	v_lshl_add_u64 v[220:221], s[48:49], 0, v[154:155]
	s_mov_b32 m0, s52
	s_nop 0
	global_load_lds_dwordx4 v[220:221], off
	v_lshl_add_u64 v[220:221], s[48:49], 0, v[162:163]
	s_add_i32 m0, s52, 0x2000
	s_nop 0
	global_load_lds_dwordx4 v[220:221], off
	v_lshl_add_u64 v[220:221], v[224:225], 0, s[22:23]
	s_mov_b32 m0, s3
	s_nop 0
	global_load_lds_dwordx4 v[220:221], off
	v_lshl_add_u64 v[220:221], v[226:227], 0, s[22:23]
	s_mov_b32 m0, s64
	s_nop 0
	global_load_lds_dwordx4 v[220:221], off
	s_waitcnt vmcnt(8)
	s_waitcnt lgkmcnt(0)
	s_setprio 1
	s_barrier
	v_mfma_f32_16x16x32_bf16 v[60:63], v[128:131], v[180:183], v[60:63]
	v_mfma_f32_16x16x32_bf16 v[60:63], v[132:135], v[192:195], v[60:63]
	v_mfma_f32_16x16x32_bf16 v[56:59], v[140:143], v[192:195], v[56:59]
	v_mfma_f32_16x16x32_bf16 v[56:59], v[136:139], v[180:183], v[56:59]
	v_mfma_f32_16x16x32_bf16 v[40:43], v[136:139], v[196:199], v[40:43]
	v_mfma_f32_16x16x32_bf16 v[40:43], v[140:143], v[200:203], v[40:43]
	v_mfma_f32_16x16x32_bf16 v[44:47], v[132:135], v[200:203], v[44:47]
	v_mfma_f32_16x16x32_bf16 v[44:47], v[128:131], v[196:199], v[44:47]
	v_mfma_f32_16x16x32_bf16 v[28:31], v[128:131], v[204:207], v[28:31]
	v_mfma_f32_16x16x32_bf16 v[28:31], v[132:135], v[208:211], v[28:31]
	v_mfma_f32_16x16x32_bf16 v[24:27], v[140:143], v[208:211], v[24:27]
	v_mfma_f32_16x16x32_bf16 v[24:27], v[136:139], v[204:207], v[24:27]
	v_mfma_f32_16x16x32_bf16 v[8:11], v[136:139], v[212:215], v[8:11]
	v_mfma_f32_16x16x32_bf16 v[8:11], v[140:143], v[216:219], v[8:11]
	v_mfma_f32_16x16x32_bf16 v[12:15], v[132:135], v[216:219], v[12:15]
	v_mfma_f32_16x16x32_bf16 v[12:15], v[128:131], v[212:215], v[12:15]
	s_setprio 0
	s_setprio 1
	v_mfma_f32_16x16x32_bf16 v[52:55], v[144:147], v[180:183], v[52:55]
	v_mfma_f32_16x16x32_bf16 v[52:55], v[148:151], v[192:195], v[52:55]
	v_mfma_f32_16x16x32_bf16 v[48:51], v[176:179], v[192:195], v[48:51]
	v_mfma_f32_16x16x32_bf16 v[48:51], v[172:175], v[180:183], v[48:51]
	v_mfma_f32_16x16x32_bf16 v[32:35], v[172:175], v[196:199], v[32:35]
	v_mfma_f32_16x16x32_bf16 v[32:35], v[176:179], v[200:203], v[32:35]
	v_mfma_f32_16x16x32_bf16 v[36:39], v[148:151], v[200:203], v[36:39]
	v_mfma_f32_16x16x32_bf16 v[36:39], v[144:147], v[196:199], v[36:39]
	v_mfma_f32_16x16x32_bf16 v[20:23], v[144:147], v[204:207], v[20:23]
	v_mfma_f32_16x16x32_bf16 v[20:23], v[148:151], v[208:211], v[20:23]
	v_mfma_f32_16x16x32_bf16 v[16:19], v[176:179], v[208:211], v[16:19]
	v_mfma_f32_16x16x32_bf16 v[16:19], v[172:175], v[204:207], v[16:19]
	v_mfma_f32_16x16x32_bf16 v[0:3], v[172:175], v[212:215], v[0:3]
	v_mfma_f32_16x16x32_bf16 v[0:3], v[176:179], v[216:219], v[0:3]
	v_mfma_f32_16x16x32_bf16 v[4:7], v[148:151], v[216:219], v[4:7]
	v_mfma_f32_16x16x32_bf16 v[4:7], v[144:147], v[212:215], v[4:7]
	s_barrier
	s_setprio 0
	s_add_i32 s74, s74, 2
	s_add_u32 s72, s72, 0x100
	s_addc_u32 s73, s73, 0
	s_cmp_gt_u32 s74, 41
	s_mov_b64 s[48:49], s[50:51]
	s_branch .LBB0_1181
.Lfa_11:
	ds_read_b128 v[128:131], v188
	v_xor_b32_e32 v253, 64, v188
	ds_read_b128 v[132:135], v253
	ds_read_b128 v[136:139], v188 offset:2048
	ds_read_b128 v[140:143], v253 offset:2048
	ds_read_b128 v[144:147], v189
	v_xor_b32_e32 v253, 64, v189
	ds_read_b128 v[148:151], v253
	ds_read_b128 v[172:175], v189 offset:2048
	ds_read_b128 v[176:179], v253 offset:2048
	s_add_u32 s50, s48, 0x100
	s_addc_u32 s51, s49, 0
	s_cmp_eq_u32 s74, 40
	s_cselect_b32 s55, s11, s51
	s_cselect_b32 s54, s10, s50
	s_cselect_b32 s53, s47, s73
	s_cselect_b32 s52, s46, s72
	v_lshl_add_u64 v[220:221], s[48:49], 0, v[166:167]
	s_add_i32 m0, s59, 0xc000
	ds_read_b128 v[180:183], v190
	v_xor_b32_e32 v253, 64, v190
	ds_read_b128 v[192:195], v253
	ds_read_b128 v[196:199], v190 offset:2048
	ds_read_b128 v[200:203], v253 offset:2048
	ds_read_b128 v[204:207], v190 offset:4096
	ds_read_b128 v[208:211], v253 offset:4096
	ds_read_b128 v[212:215], v190 offset:6144
	ds_read_b128 v[216:219], v253 offset:6144
	global_load_lds_dwordx4 v[220:221], off
	v_lshl_add_u64 v[220:221], s[48:49], 0, v[164:165]
	s_add_i32 m0, s59, 0xe000
	s_nop 0
	global_load_lds_dwordx4 v[220:221], off
	s_waitcnt vmcnt(8)
	s_waitcnt lgkmcnt(0)
	s_setprio 1
	s_barrier
	v_mfma_f32_16x16x32_bf16 v[124:127], v[128:131], v[180:183], 0
	v_mfma_f32_16x16x32_bf16 v[120:123], v[136:139], v[180:183], 0
	v_mfma_f32_16x16x32_bf16 v[108:111], v[128:131], v[196:199], 0
	v_mfma_f32_16x16x32_bf16 v[104:107], v[136:139], v[196:199], 0
	v_mfma_f32_16x16x32_bf16 v[92:95], v[128:131], v[204:207], 0
	v_mfma_f32_16x16x32_bf16 v[88:91], v[136:139], v[204:207], 0
	v_mfma_f32_16x16x32_bf16 v[76:79], v[128:131], v[212:215], 0
	v_mfma_f32_16x16x32_bf16 v[72:75], v[136:139], v[212:215], 0
	v_mfma_f32_16x16x32_bf16 v[124:127], v[132:135], v[192:195], v[124:127]
	v_mfma_f32_16x16x32_bf16 v[120:123], v[140:143], v[192:195], v[120:123]
	v_mfma_f32_16x16x32_bf16 v[108:111], v[132:135], v[200:203], v[108:111]
	v_mfma_f32_16x16x32_bf16 v[104:107], v[140:143], v[200:203], v[104:107]
	v_mfma_f32_16x16x32_bf16 v[92:95], v[132:135], v[208:211], v[92:95]
	v_mfma_f32_16x16x32_bf16 v[88:91], v[140:143], v[208:211], v[88:91]
	v_mfma_f32_16x16x32_bf16 v[76:79], v[132:135], v[216:219], v[76:79]
	v_mfma_f32_16x16x32_bf16 v[72:75], v[140:143], v[216:219], v[72:75]
	s_setprio 0
	s_setprio 1
	v_mfma_f32_16x16x32_bf16 v[116:119], v[144:147], v[180:183], 0
	v_mfma_f32_16x16x32_bf16 v[112:115], v[172:175], v[180:183], 0
	v_mfma_f32_16x16x32_bf16 v[100:103], v[144:147], v[196:199], 0
	v_mfma_f32_16x16x32_bf16 v[96:99], v[172:175], v[196:199], 0
	v_mfma_f32_16x16x32_bf16 v[84:87], v[144:147], v[204:207], 0
	v_mfma_f32_16x16x32_bf16 v[80:83], v[172:175], v[204:207], 0
	v_mfma_f32_16x16x32_bf16 v[68:71], v[144:147], v[212:215], 0
	v_mfma_f32_16x16x32_bf16 v[64:67], v[172:175], v[212:215], 0
	v_mfma_f32_16x16x32_bf16 v[116:119], v[148:151], v[192:195], v[116:119]
	v_mfma_f32_16x16x32_bf16 v[112:115], v[176:179], v[192:195], v[112:115]
	v_mfma_f32_16x16x32_bf16 v[100:103], v[148:151], v[200:203], v[100:103]
	v_mfma_f32_16x16x32_bf16 v[96:99], v[176:179], v[200:203], v[96:99]
	v_mfma_f32_16x16x32_bf16 v[84:87], v[148:151], v[208:211], v[84:87]
	v_mfma_f32_16x16x32_bf16 v[80:83], v[176:179], v[208:211], v[80:83]
	v_mfma_f32_16x16x32_bf16 v[68:71], v[148:151], v[216:219], v[68:71]
	v_mfma_f32_16x16x32_bf16 v[64:67], v[176:179], v[216:219], v[64:67]
	s_barrier
	s_setprio 0
	s_add_i32 s48, s68, s58
	v_lshl_add_u64 v[220:221], s[52:53], 0, v[154:155]
	s_mov_b32 m0, s48
	ds_read_b128 v[180:183], v190 offset:16384
	v_xor_b32_e32 v253, 64, v190
	ds_read_b128 v[192:195], v253 offset:16384
	ds_read_b128 v[196:199], v190 offset:18432
	ds_read_b128 v[200:203], v253 offset:18432
	ds_read_b128 v[204:207], v190 offset:20480
	ds_read_b128 v[208:211], v253 offset:20480
	ds_read_b128 v[212:215], v190 offset:22528
	ds_read_b128 v[216:219], v253 offset:22528
	global_load_lds_dwordx4 v[220:221], off
	s_add_i32 m0, s48, 0x2000
	s_add_u32 s48, s52, 0xb0000
	v_lshl_add_u64 v[222:223], s[52:53], 0, v[162:163]
	s_addc_u32 s49, s53, 0
	s_add_i32 s75, s69, s58
	global_load_lds_dwordx4 v[222:223], off
	v_lshl_add_u64 v[224:225], s[48:49], 0, v[154:155]
	s_mov_b32 m0, s75
	v_lshl_add_u64 v[226:227], s[54:55], 0, v[160:161]
	global_load_lds_dwordx4 v[224:225], off
	v_lshl_add_u64 v[224:225], s[48:49], 0, v[162:163]
	s_add_i32 m0, s75, 0x2000
	s_nop 0
	global_load_lds_dwordx4 v[224:225], off
	v_lshl_add_u64 v[224:225], s[54:55], 0, v[152:153]
	s_mov_b32 m0, s59
	s_nop 0
	global_load_lds_dwordx4 v[224:225], off
	s_mov_b32 m0, s60
	s_nop 0
	global_load_lds_dwordx4 v[226:227], off
	s_waitcnt vmcnt(8)
	s_waitcnt lgkmcnt(0)
	s_setprio 1
	s_barrier
	v_mfma_f32_16x16x32_bf16 v[60:63], v[128:131], v[180:183], 0
	v_mfma_f32_16x16x32_bf16 v[56:59], v[136:139], v[180:183], 0
	v_mfma_f32_16x16x32_bf16 v[44:47], v[128:131], v[196:199], 0
	v_mfma_f32_16x16x32_bf16 v[40:43], v[136:139], v[196:199], 0
	v_mfma_f32_16x16x32_bf16 v[28:31], v[128:131], v[204:207], 0
	v_mfma_f32_16x16x32_bf16 v[24:27], v[136:139], v[204:207], 0
	v_mfma_f32_16x16x32_bf16 v[12:15], v[128:131], v[212:215], 0
	v_mfma_f32_16x16x32_bf16 v[8:11], v[136:139], v[212:215], 0
	v_mfma_f32_16x16x32_bf16 v[60:63], v[132:135], v[192:195], v[60:63]
	v_mfma_f32_16x16x32_bf16 v[56:59], v[140:143], v[192:195], v[56:59]
	v_mfma_f32_16x16x32_bf16 v[44:47], v[132:135], v[200:203], v[44:47]
	v_mfma_f32_16x16x32_bf16 v[40:43], v[140:143], v[200:203], v[40:43]
	v_mfma_f32_16x16x32_bf16 v[28:31], v[132:135], v[208:211], v[28:31]
	v_mfma_f32_16x16x32_bf16 v[24:27], v[140:143], v[208:211], v[24:27]
	v_mfma_f32_16x16x32_bf16 v[12:15], v[132:135], v[216:219], v[12:15]
	v_mfma_f32_16x16x32_bf16 v[8:11], v[140:143], v[216:219], v[8:11]
	s_setprio 0
	s_setprio 1
	v_mfma_f32_16x16x32_bf16 v[52:55], v[144:147], v[180:183], 0
	v_mfma_f32_16x16x32_bf16 v[48:51], v[172:175], v[180:183], 0
	v_mfma_f32_16x16x32_bf16 v[36:39], v[144:147], v[196:199], 0
	v_mfma_f32_16x16x32_bf16 v[32:35], v[172:175], v[196:199], 0
	v_mfma_f32_16x16x32_bf16 v[20:23], v[144:147], v[204:207], 0
	v_mfma_f32_16x16x32_bf16 v[16:19], v[172:175], v[204:207], 0
	v_mfma_f32_16x16x32_bf16 v[4:7], v[144:147], v[212:215], 0
	v_mfma_f32_16x16x32_bf16 v[0:3], v[172:175], v[212:215], 0
	v_mfma_f32_16x16x32_bf16 v[52:55], v[148:151], v[192:195], v[52:55]
	v_mfma_f32_16x16x32_bf16 v[48:51], v[176:179], v[192:195], v[48:51]
	v_mfma_f32_16x16x32_bf16 v[36:39], v[148:151], v[200:203], v[36:39]
	v_mfma_f32_16x16x32_bf16 v[32:35], v[176:179], v[200:203], v[32:35]
	v_mfma_f32_16x16x32_bf16 v[20:23], v[148:151], v[208:211], v[20:23]
	v_mfma_f32_16x16x32_bf16 v[16:19], v[176:179], v[208:211], v[16:19]
	v_mfma_f32_16x16x32_bf16 v[4:7], v[148:151], v[216:219], v[4:7]
	v_mfma_f32_16x16x32_bf16 v[0:3], v[176:179], v[216:219], v[0:3]
	s_barrier
	s_setprio 0
	s_add_i32 s75, 0, 0x18000
	s_add_i32 s76, 0, 0x1c000
	v_add_u32_e32 v140, s75, v185
	v_add_u32_e32 v176, s76, v185
	ds_read_b128 v[128:131], v140
	v_xor_b32_e32 v253, 64, v140
	ds_read_b128 v[132:135], v253
	ds_read_b128 v[136:139], v140 offset:2048
	ds_read_b128 v[140:143], v253 offset:2048
	ds_read_b128 v[144:147], v176
	v_xor_b32_e32 v253, 64, v176
	ds_read_b128 v[148:151], v253
	ds_read_b128 v[172:175], v176 offset:2048
	ds_read_b128 v[176:179], v253 offset:2048
	s_add_u32 s48, s54, 0xb0000
	s_addc_u32 s49, s55, 0
	s_mov_b32 m0, s61
	v_lshl_add_u64 v[228:229], s[48:49], 0, v[152:153]
	ds_read_b128 v[180:183], v190 offset:32768
	v_xor_b32_e32 v253, 64, v190
	ds_read_b128 v[192:195], v253 offset:32768
	ds_read_b128 v[196:199], v190 offset:34816
	ds_read_b128 v[200:203], v253 offset:34816
	ds_read_b128 v[204:207], v190 offset:36864
	ds_read_b128 v[208:211], v253 offset:36864
	ds_read_b128 v[212:215], v190 offset:38912
	ds_read_b128 v[216:219], v253 offset:38912
	global_load_lds_dwordx4 v[228:229], off
	v_lshl_add_u64 v[228:229], s[48:49], 0, v[160:161]
	s_mov_b32 m0, s62
	s_nop 0
	global_load_lds_dwordx4 v[228:229], off
	s_waitcnt vmcnt(8)
	s_waitcnt lgkmcnt(0)
	s_setprio 1
	s_barrier
	v_mfma_f32_16x16x32_bf16 v[124:127], v[128:131], v[180:183], v[124:127]
	v_mfma_f32_16x16x32_bf16 v[124:127], v[132:135], v[192:195], v[124:127]
	v_mfma_f32_16x16x32_bf16 v[120:123], v[140:143], v[192:195], v[120:123]
	v_mfma_f32_16x16x32_bf16 v[120:123], v[136:139], v[180:183], v[120:123]
	v_mfma_f32_16x16x32_bf16 v[104:107], v[136:139], v[196:199], v[104:107]
	v_mfma_f32_16x16x32_bf16 v[104:107], v[140:143], v[200:203], v[104:107]
	v_mfma_f32_16x16x32_bf16 v[108:111], v[132:135], v[200:203], v[108:111]
	v_mfma_f32_16x16x32_bf16 v[108:111], v[128:131], v[196:199], v[108:111]
	v_mfma_f32_16x16x32_bf16 v[92:95], v[128:131], v[204:207], v[92:95]
	v_mfma_f32_16x16x32_bf16 v[92:95], v[132:135], v[208:211], v[92:95]
	v_mfma_f32_16x16x32_bf16 v[88:91], v[140:143], v[208:211], v[88:91]
	v_mfma_f32_16x16x32_bf16 v[88:91], v[136:139], v[204:207], v[88:91]
	v_mfma_f32_16x16x32_bf16 v[72:75], v[136:139], v[212:215], v[72:75]
	v_mfma_f32_16x16x32_bf16 v[72:75], v[140:143], v[216:219], v[72:75]
	v_mfma_f32_16x16x32_bf16 v[76:79], v[132:135], v[216:219], v[76:79]
	v_mfma_f32_16x16x32_bf16 v[76:79], v[128:131], v[212:215], v[76:79]
	s_setprio 0
	s_setprio 1
	v_mfma_f32_16x16x32_bf16 v[116:119], v[144:147], v[180:183], v[116:119]
	v_mfma_f32_16x16x32_bf16 v[116:119], v[148:151], v[192:195], v[116:119]
	v_mfma_f32_16x16x32_bf16 v[112:115], v[176:179], v[192:195], v[112:115]
	v_mfma_f32_16x16x32_bf16 v[112:115], v[172:175], v[180:183], v[112:115]
	v_mfma_f32_16x16x32_bf16 v[96:99], v[172:175], v[196:199], v[96:99]
	v_mfma_f32_16x16x32_bf16 v[96:99], v[176:179], v[200:203], v[96:99]
	v_mfma_f32_16x16x32_bf16 v[100:103], v[148:151], v[200:203], v[100:103]
	v_mfma_f32_16x16x32_bf16 v[100:103], v[144:147], v[196:199], v[100:103]
	v_mfma_f32_16x16x32_bf16 v[84:87], v[144:147], v[204:207], v[84:87]
	v_mfma_f32_16x16x32_bf16 v[84:87], v[148:151], v[208:211], v[84:87]
	v_mfma_f32_16x16x32_bf16 v[80:83], v[176:179], v[208:211], v[80:83]
	v_mfma_f32_16x16x32_bf16 v[80:83], v[172:175], v[204:207], v[80:83]
	v_mfma_f32_16x16x32_bf16 v[64:67], v[172:175], v[212:215], v[64:67]
	v_mfma_f32_16x16x32_bf16 v[64:67], v[176:179], v[216:219], v[64:67]
	v_mfma_f32_16x16x32_bf16 v[68:71], v[148:151], v[216:219], v[68:71]
	v_mfma_f32_16x16x32_bf16 v[68:71], v[144:147], v[212:215], v[68:71]
	s_barrier
	s_setprio 0
	s_add_i32 s48, s75, s58
	v_lshl_add_u64 v[220:221], v[220:221], 0, s[22:23]
	s_mov_b32 m0, s48
	ds_read_b128 v[180:183], v190 offset:49152
	v_xor_b32_e32 v253, 64, v190
	ds_read_b128 v[192:195], v253 offset:49152
	ds_read_b128 v[196:199], v190 offset:51200
	ds_read_b128 v[200:203], v253 offset:51200
	ds_read_b128 v[204:207], v190 offset:53248
	ds_read_b128 v[208:211], v253 offset:53248
	ds_read_b128 v[212:215], v190 offset:55296
	ds_read_b128 v[216:219], v253 offset:55296
	global_load_lds_dwordx4 v[220:221], off
	s_add_i32 m0, s48, 0x2000
	s_add_u32 s48, s52, 0xb0080
	v_lshl_add_u64 v[220:221], v[222:223], 0, s[22:23]
	s_addc_u32 s49, s53, 0
	s_add_i32 s52, s76, s58
	global_load_lds_dwordx4 v[220:221], off
	v_lshl_add_u64 v[220:221], s[48:49], 0, v[154:155]
	s_mov_b32 m0, s52
	s_nop 0
	global_load_lds_dwordx4 v[220:221], off
	v_lshl_add_u64 v[220:221], s[48:49], 0, v[162:163]
	s_add_i32 m0, s52, 0x2000
	s_nop 0
	global_load_lds_dwordx4 v[220:221], off
	v_lshl_add_u64 v[220:221], v[224:225], 0, s[22:23]
	s_mov_b32 m0, s3
	s_nop 0
	global_load_lds_dwordx4 v[220:221], off
	v_lshl_add_u64 v[220:221], v[226:227], 0, s[22:23]
	s_mov_b32 m0, s64
	s_nop 0
	global_load_lds_dwordx4 v[220:221], off
	s_waitcnt vmcnt(8)
	s_waitcnt lgkmcnt(0)
	s_setprio 1
	s_barrier
	v_mfma_f32_16x16x32_bf16 v[60:63], v[128:131], v[180:183], v[60:63]
	v_mfma_f32_16x16x32_bf16 v[60:63], v[132:135], v[192:195], v[60:63]
	v_mfma_f32_16x16x32_bf16 v[56:59], v[140:143], v[192:195], v[56:59]
	v_mfma_f32_16x16x32_bf16 v[56:59], v[136:139], v[180:183], v[56:59]
	v_mfma_f32_16x16x32_bf16 v[40:43], v[136:139], v[196:199], v[40:43]
	v_mfma_f32_16x16x32_bf16 v[40:43], v[140:143], v[200:203], v[40:43]
	v_mfma_f32_16x16x32_bf16 v[44:47], v[132:135], v[200:203], v[44:47]
	v_mfma_f32_16x16x32_bf16 v[44:47], v[128:131], v[196:199], v[44:47]
	v_mfma_f32_16x16x32_bf16 v[28:31], v[128:131], v[204:207], v[28:31]
	v_mfma_f32_16x16x32_bf16 v[28:31], v[132:135], v[208:211], v[28:31]
	v_mfma_f32_16x16x32_bf16 v[24:27], v[140:143], v[208:211], v[24:27]
	v_mfma_f32_16x16x32_bf16 v[24:27], v[136:139], v[204:207], v[24:27]
	v_mfma_f32_16x16x32_bf16 v[8:11], v[136:139], v[212:215], v[8:11]
	v_mfma_f32_16x16x32_bf16 v[8:11], v[140:143], v[216:219], v[8:11]
	v_mfma_f32_16x16x32_bf16 v[12:15], v[132:135], v[216:219], v[12:15]
	v_mfma_f32_16x16x32_bf16 v[12:15], v[128:131], v[212:215], v[12:15]
	s_setprio 0
	s_setprio 1
	v_mfma_f32_16x16x32_bf16 v[52:55], v[144:147], v[180:183], v[52:55]
	v_mfma_f32_16x16x32_bf16 v[52:55], v[148:151], v[192:195], v[52:55]
	v_mfma_f32_16x16x32_bf16 v[48:51], v[176:179], v[192:195], v[48:51]
	v_mfma_f32_16x16x32_bf16 v[48:51], v[172:175], v[180:183], v[48:51]
	v_mfma_f32_16x16x32_bf16 v[32:35], v[172:175], v[196:199], v[32:35]
	v_mfma_f32_16x16x32_bf16 v[32:35], v[176:179], v[200:203], v[32:35]
	v_mfma_f32_16x16x32_bf16 v[36:39], v[148:151], v[200:203], v[36:39]
	v_mfma_f32_16x16x32_bf16 v[36:39], v[144:147], v[196:199], v[36:39]
	v_mfma_f32_16x16x32_bf16 v[20:23], v[144:147], v[204:207], v[20:23]
	v_mfma_f32_16x16x32_bf16 v[20:23], v[148:151], v[208:211], v[20:23]
	v_mfma_f32_16x16x32_bf16 v[16:19], v[176:179], v[208:211], v[16:19]
	v_mfma_f32_16x16x32_bf16 v[16:19], v[172:175], v[204:207], v[16:19]
	v_mfma_f32_16x16x32_bf16 v[0:3], v[172:175], v[212:215], v[0:3]
	v_mfma_f32_16x16x32_bf16 v[0:3], v[176:179], v[216:219], v[0:3]
	v_mfma_f32_16x16x32_bf16 v[4:7], v[148:151], v[216:219], v[4:7]
	v_mfma_f32_16x16x32_bf16 v[4:7], v[144:147], v[212:215], v[4:7]
	s_barrier
	s_setprio 0
	s_add_i32 s74, s74, 2
	s_add_u32 s72, s72, 0x100
	s_addc_u32 s73, s73, 0
	s_cmp_gt_u32 s74, 41
	s_mov_b64 s[48:49], s[50:51]
.LBB0_1181:
	ds_read_b128 v[128:131], v188
	v_xor_b32_e32 v253, 64, v188
	ds_read_b128 v[132:135], v253
	ds_read_b128 v[136:139], v188 offset:2048
	ds_read_b128 v[140:143], v253 offset:2048
	ds_read_b128 v[144:147], v189
	v_xor_b32_e32 v253, 64, v189
	ds_read_b128 v[148:151], v253
	ds_read_b128 v[172:175], v189 offset:2048
	ds_read_b128 v[176:179], v253 offset:2048
	s_add_u32 s50, s48, 0x100
	s_addc_u32 s51, s49, 0
	s_cmp_eq_u32 s74, 40
	s_cselect_b32 s55, s11, s51
	s_cselect_b32 s54, s10, s50
	s_cselect_b32 s53, s47, s73
	s_cselect_b32 s52, s46, s72
	v_lshl_add_u64 v[220:221], s[48:49], 0, v[166:167]
	s_add_i32 m0, s59, 0xc000
	ds_read_b128 v[180:183], v190
	v_xor_b32_e32 v253, 64, v190
	ds_read_b128 v[192:195], v253
	ds_read_b128 v[196:199], v190 offset:2048
	ds_read_b128 v[200:203], v253 offset:2048
	ds_read_b128 v[204:207], v190 offset:4096
	ds_read_b128 v[208:211], v253 offset:4096
	ds_read_b128 v[212:215], v190 offset:6144
	ds_read_b128 v[216:219], v253 offset:6144
	global_load_lds_dwordx4 v[220:221], off
	v_lshl_add_u64 v[220:221], s[48:49], 0, v[164:165]
	s_add_i32 m0, s59, 0xe000
	s_nop 0
	global_load_lds_dwordx4 v[220:221], off
	s_waitcnt vmcnt(8)
	s_waitcnt lgkmcnt(0)
	s_setprio 1
	s_barrier
	v_mfma_f32_16x16x32_bf16 v[124:127], v[128:131], v[180:183], v[124:127]
	v_mfma_f32_16x16x32_bf16 v[124:127], v[132:135], v[192:195], v[124:127]
	v_mfma_f32_16x16x32_bf16 v[120:123], v[140:143], v[192:195], v[120:123]
	v_mfma_f32_16x16x32_bf16 v[120:123], v[136:139], v[180:183], v[120:123]
	v_mfma_f32_16x16x32_bf16 v[104:107], v[136:139], v[196:199], v[104:107]
	v_mfma_f32_16x16x32_bf16 v[104:107], v[140:143], v[200:203], v[104:107]
	v_mfma_f32_16x16x32_bf16 v[108:111], v[132:135], v[200:203], v[108:111]
	v_mfma_f32_16x16x32_bf16 v[108:111], v[128:131], v[196:199], v[108:111]
	v_mfma_f32_16x16x32_bf16 v[92:95], v[128:131], v[204:207], v[92:95]
	v_mfma_f32_16x16x32_bf16 v[92:95], v[132:135], v[208:211], v[92:95]
	v_mfma_f32_16x16x32_bf16 v[88:91], v[140:143], v[208:211], v[88:91]
	v_mfma_f32_16x16x32_bf16 v[88:91], v[136:139], v[204:207], v[88:91]
	v_mfma_f32_16x16x32_bf16 v[72:75], v[136:139], v[212:215], v[72:75]
	v_mfma_f32_16x16x32_bf16 v[72:75], v[140:143], v[216:219], v[72:75]
	v_mfma_f32_16x16x32_bf16 v[76:79], v[132:135], v[216:219], v[76:79]
	v_mfma_f32_16x16x32_bf16 v[76:79], v[128:131], v[212:215], v[76:79]
	s_setprio 0
	s_setprio 1
	v_mfma_f32_16x16x32_bf16 v[116:119], v[144:147], v[180:183], v[116:119]
	v_mfma_f32_16x16x32_bf16 v[116:119], v[148:151], v[192:195], v[116:119]
	v_mfma_f32_16x16x32_bf16 v[112:115], v[176:179], v[192:195], v[112:115]
	v_mfma_f32_16x16x32_bf16 v[112:115], v[172:175], v[180:183], v[112:115]
	v_mfma_f32_16x16x32_bf16 v[96:99], v[172:175], v[196:199], v[96:99]
	v_mfma_f32_16x16x32_bf16 v[96:99], v[176:179], v[200:203], v[96:99]
	v_mfma_f32_16x16x32_bf16 v[100:103], v[148:151], v[200:203], v[100:103]
	v_mfma_f32_16x16x32_bf16 v[100:103], v[144:147], v[196:199], v[100:103]
	v_mfma_f32_16x16x32_bf16 v[84:87], v[144:147], v[204:207], v[84:87]
	v_mfma_f32_16x16x32_bf16 v[84:87], v[148:151], v[208:211], v[84:87]
	v_mfma_f32_16x16x32_bf16 v[80:83], v[176:179], v[208:211], v[80:83]
	v_mfma_f32_16x16x32_bf16 v[80:83], v[172:175], v[204:207], v[80:83]
	v_mfma_f32_16x16x32_bf16 v[64:67], v[172:175], v[212:215], v[64:67]
	v_mfma_f32_16x16x32_bf16 v[64:67], v[176:179], v[216:219], v[64:67]
	v_mfma_f32_16x16x32_bf16 v[68:71], v[148:151], v[216:219], v[68:71]
	v_mfma_f32_16x16x32_bf16 v[68:71], v[144:147], v[212:215], v[68:71]
	s_barrier
	s_setprio 0
	s_add_i32 s48, s68, s58
	v_lshl_add_u64 v[220:221], s[52:53], 0, v[154:155]
	s_mov_b32 m0, s48
	ds_read_b128 v[180:183], v190 offset:16384
	v_xor_b32_e32 v253, 64, v190
	ds_read_b128 v[192:195], v253 offset:16384
	ds_read_b128 v[196:199], v190 offset:18432
	ds_read_b128 v[200:203], v253 offset:18432
	ds_read_b128 v[204:207], v190 offset:20480
	ds_read_b128 v[208:211], v253 offset:20480
	ds_read_b128 v[212:215], v190 offset:22528
	ds_read_b128 v[216:219], v253 offset:22528
	global_load_lds_dwordx4 v[220:221], off
	s_add_i32 m0, s48, 0x2000
	s_add_u32 s48, s52, 0xb0000
	v_lshl_add_u64 v[222:223], s[52:53], 0, v[162:163]
	s_addc_u32 s49, s53, 0
	s_add_i32 s75, s69, s58
	global_load_lds_dwordx4 v[222:223], off
	v_lshl_add_u64 v[224:225], s[48:49], 0, v[154:155]
	s_mov_b32 m0, s75
	v_lshl_add_u64 v[226:227], s[54:55], 0, v[160:161]
	global_load_lds_dwordx4 v[224:225], off
	v_lshl_add_u64 v[224:225], s[48:49], 0, v[162:163]
	s_add_i32 m0, s75, 0x2000
	s_nop 0
	global_load_lds_dwordx4 v[224:225], off
	v_lshl_add_u64 v[224:225], s[54:55], 0, v[152:153]
	s_mov_b32 m0, s59
	s_nop 0
	global_load_lds_dwordx4 v[224:225], off
	s_mov_b32 m0, s60
	s_nop 0
	global_load_lds_dwordx4 v[226:227], off
	s_waitcnt vmcnt(8)
	s_waitcnt lgkmcnt(0)
	s_setprio 1
	s_barrier
	v_mfma_f32_16x16x32_bf16 v[60:63], v[128:131], v[180:183], v[60:63]
	v_mfma_f32_16x16x32_bf16 v[60:63], v[132:135], v[192:195], v[60:63]
	v_mfma_f32_16x16x32_bf16 v[56:59], v[140:143], v[192:195], v[56:59]
	v_mfma_f32_16x16x32_bf16 v[56:59], v[136:139], v[180:183], v[56:59]
	v_mfma_f32_16x16x32_bf16 v[40:43], v[136:139], v[196:199], v[40:43]
	v_mfma_f32_16x16x32_bf16 v[40:43], v[140:143], v[200:203], v[40:43]
	v_mfma_f32_16x16x32_bf16 v[44:47], v[132:135], v[200:203], v[44:47]
	v_mfma_f32_16x16x32_bf16 v[44:47], v[128:131], v[196:199], v[44:47]
	v_mfma_f32_16x16x32_bf16 v[28:31], v[128:131], v[204:207], v[28:31]
	v_mfma_f32_16x16x32_bf16 v[28:31], v[132:135], v[208:211], v[28:31]
	v_mfma_f32_16x16x32_bf16 v[24:27], v[140:143], v[208:211], v[24:27]
	v_mfma_f32_16x16x32_bf16 v[24:27], v[136:139], v[204:207], v[24:27]
	v_mfma_f32_16x16x32_bf16 v[8:11], v[136:139], v[212:215], v[8:11]
	v_mfma_f32_16x16x32_bf16 v[8:11], v[140:143], v[216:219], v[8:11]
	v_mfma_f32_16x16x32_bf16 v[12:15], v[132:135], v[216:219], v[12:15]
	v_mfma_f32_16x16x32_bf16 v[12:15], v[128:131], v[212:215], v[12:15]
	s_setprio 0
	s_setprio 1
	v_mfma_f32_16x16x32_bf16 v[52:55], v[144:147], v[180:183], v[52:55]
	v_mfma_f32_16x16x32_bf16 v[52:55], v[148:151], v[192:195], v[52:55]
	v_mfma_f32_16x16x32_bf16 v[48:51], v[176:179], v[192:195], v[48:51]
	v_mfma_f32_16x16x32_bf16 v[48:51], v[172:175], v[180:183], v[48:51]
	v_mfma_f32_16x16x32_bf16 v[32:35], v[172:175], v[196:199], v[32:35]
	v_mfma_f32_16x16x32_bf16 v[32:35], v[176:179], v[200:203], v[32:35]
	v_mfma_f32_16x16x32_bf16 v[36:39], v[148:151], v[200:203], v[36:39]
	v_mfma_f32_16x16x32_bf16 v[36:39], v[144:147], v[196:199], v[36:39]
	v_mfma_f32_16x16x32_bf16 v[20:23], v[144:147], v[204:207], v[20:23]
	v_mfma_f32_16x16x32_bf16 v[20:23], v[148:151], v[208:211], v[20:23]
	v_mfma_f32_16x16x32_bf16 v[16:19], v[176:179], v[208:211], v[16:19]
	v_mfma_f32_16x16x32_bf16 v[16:19], v[172:175], v[204:207], v[16:19]
	v_mfma_f32_16x16x32_bf16 v[0:3], v[172:175], v[212:215], v[0:3]
	v_mfma_f32_16x16x32_bf16 v[0:3], v[176:179], v[216:219], v[0:3]
	v_mfma_f32_16x16x32_bf16 v[4:7], v[148:151], v[216:219], v[4:7]
	v_mfma_f32_16x16x32_bf16 v[4:7], v[144:147], v[212:215], v[4:7]
	s_barrier
	s_setprio 0
	s_add_i32 s75, 0, 0x18000
	s_add_i32 s76, 0, 0x1c000
	v_add_u32_e32 v140, s75, v185
	v_add_u32_e32 v176, s76, v185
	ds_read_b128 v[128:131], v140
	v_xor_b32_e32 v253, 64, v140
	ds_read_b128 v[132:135], v253
	ds_read_b128 v[136:139], v140 offset:2048
	ds_read_b128 v[140:143], v253 offset:2048
	ds_read_b128 v[144:147], v176
	v_xor_b32_e32 v253, 64, v176
	ds_read_b128 v[148:151], v253
	ds_read_b128 v[172:175], v176 offset:2048
	ds_read_b128 v[176:179], v253 offset:2048
	s_add_u32 s48, s54, 0xb0000
	s_addc_u32 s49, s55, 0
	s_mov_b32 m0, s61
	v_lshl_add_u64 v[228:229], s[48:49], 0, v[152:153]
	ds_read_b128 v[180:183], v190 offset:32768
	v_xor_b32_e32 v253, 64, v190
	ds_read_b128 v[192:195], v253 offset:32768
	ds_read_b128 v[196:199], v190 offset:34816
	ds_read_b128 v[200:203], v253 offset:34816
	ds_read_b128 v[204:207], v190 offset:36864
	ds_read_b128 v[208:211], v253 offset:36864
	ds_read_b128 v[212:215], v190 offset:38912
	ds_read_b128 v[216:219], v253 offset:38912
	global_load_lds_dwordx4 v[228:229], off
	v_lshl_add_u64 v[228:229], s[48:49], 0, v[160:161]
	s_mov_b32 m0, s62
	s_nop 0
	global_load_lds_dwordx4 v[228:229], off
	s_waitcnt vmcnt(8)
	s_waitcnt lgkmcnt(0)
	s_setprio 1
	s_barrier
	v_mfma_f32_16x16x32_bf16 v[124:127], v[128:131], v[180:183], v[124:127]
	v_mfma_f32_16x16x32_bf16 v[124:127], v[132:135], v[192:195], v[124:127]
	v_mfma_f32_16x16x32_bf16 v[120:123], v[140:143], v[192:195], v[120:123]
	v_mfma_f32_16x16x32_bf16 v[120:123], v[136:139], v[180:183], v[120:123]
	v_mfma_f32_16x16x32_bf16 v[104:107], v[136:139], v[196:199], v[104:107]
	v_mfma_f32_16x16x32_bf16 v[104:107], v[140:143], v[200:203], v[104:107]
	v_mfma_f32_16x16x32_bf16 v[108:111], v[132:135], v[200:203], v[108:111]
	v_mfma_f32_16x16x32_bf16 v[108:111], v[128:131], v[196:199], v[108:111]
	v_mfma_f32_16x16x32_bf16 v[92:95], v[128:131], v[204:207], v[92:95]
	v_mfma_f32_16x16x32_bf16 v[92:95], v[132:135], v[208:211], v[92:95]
	v_mfma_f32_16x16x32_bf16 v[88:91], v[140:143], v[208:211], v[88:91]
	v_mfma_f32_16x16x32_bf16 v[88:91], v[136:139], v[204:207], v[88:91]
	v_mfma_f32_16x16x32_bf16 v[72:75], v[136:139], v[212:215], v[72:75]
	v_mfma_f32_16x16x32_bf16 v[72:75], v[140:143], v[216:219], v[72:75]
	v_mfma_f32_16x16x32_bf16 v[76:79], v[132:135], v[216:219], v[76:79]
	v_mfma_f32_16x16x32_bf16 v[76:79], v[128:131], v[212:215], v[76:79]
	s_setprio 0
	s_setprio 1
	v_mfma_f32_16x16x32_bf16 v[116:119], v[144:147], v[180:183], v[116:119]
	v_mfma_f32_16x16x32_bf16 v[116:119], v[148:151], v[192:195], v[116:119]
	v_mfma_f32_16x16x32_bf16 v[112:115], v[176:179], v[192:195], v[112:115]
	v_mfma_f32_16x16x32_bf16 v[112:115], v[172:175], v[180:183], v[112:115]
	v_mfma_f32_16x16x32_bf16 v[96:99], v[172:175], v[196:199], v[96:99]
	v_mfma_f32_16x16x32_bf16 v[96:99], v[176:179], v[200:203], v[96:99]
	v_mfma_f32_16x16x32_bf16 v[100:103], v[148:151], v[200:203], v[100:103]
	v_mfma_f32_16x16x32_bf16 v[100:103], v[144:147], v[196:199], v[100:103]
	v_mfma_f32_16x16x32_bf16 v[84:87], v[144:147], v[204:207], v[84:87]
	v_mfma_f32_16x16x32_bf16 v[84:87], v[148:151], v[208:211], v[84:87]
	v_mfma_f32_16x16x32_bf16 v[80:83], v[176:179], v[208:211], v[80:83]
	v_mfma_f32_16x16x32_bf16 v[80:83], v[172:175], v[204:207], v[80:83]
	v_mfma_f32_16x16x32_bf16 v[64:67], v[172:175], v[212:215], v[64:67]
	v_mfma_f32_16x16x32_bf16 v[64:67], v[176:179], v[216:219], v[64:67]
	v_mfma_f32_16x16x32_bf16 v[68:71], v[148:151], v[216:219], v[68:71]
	v_mfma_f32_16x16x32_bf16 v[68:71], v[144:147], v[212:215], v[68:71]
	s_barrier
	s_setprio 0
	s_add_i32 s48, s75, s58
	v_lshl_add_u64 v[220:221], v[220:221], 0, s[22:23]
	s_mov_b32 m0, s48
	ds_read_b128 v[180:183], v190 offset:49152
	v_xor_b32_e32 v253, 64, v190
	ds_read_b128 v[192:195], v253 offset:49152
	ds_read_b128 v[196:199], v190 offset:51200
	ds_read_b128 v[200:203], v253 offset:51200
	ds_read_b128 v[204:207], v190 offset:53248
	ds_read_b128 v[208:211], v253 offset:53248
	ds_read_b128 v[212:215], v190 offset:55296
	ds_read_b128 v[216:219], v253 offset:55296
	global_load_lds_dwordx4 v[220:221], off
	s_add_i32 m0, s48, 0x2000
	s_add_u32 s48, s52, 0xb0080
	v_lshl_add_u64 v[220:221], v[222:223], 0, s[22:23]
	s_addc_u32 s49, s53, 0
	s_add_i32 s52, s76, s58
	global_load_lds_dwordx4 v[220:221], off
	v_lshl_add_u64 v[220:221], s[48:49], 0, v[154:155]
	s_mov_b32 m0, s52
	s_nop 0
	global_load_lds_dwordx4 v[220:221], off
	v_lshl_add_u64 v[220:221], s[48:49], 0, v[162:163]
	s_add_i32 m0, s52, 0x2000
	s_nop 0
	global_load_lds_dwordx4 v[220:221], off
	v_lshl_add_u64 v[220:221], v[224:225], 0, s[22:23]
	s_mov_b32 m0, s3
	s_nop 0
	global_load_lds_dwordx4 v[220:221], off
	v_lshl_add_u64 v[220:221], v[226:227], 0, s[22:23]
	s_mov_b32 m0, s64
	s_nop 0
	global_load_lds_dwordx4 v[220:221], off
	s_waitcnt vmcnt(8)
	s_waitcnt lgkmcnt(0)
	s_setprio 1
	s_barrier
	v_mfma_f32_16x16x32_bf16 v[60:63], v[128:131], v[180:183], v[60:63]
	v_mfma_f32_16x16x32_bf16 v[60:63], v[132:135], v[192:195], v[60:63]
	v_mfma_f32_16x16x32_bf16 v[56:59], v[140:143], v[192:195], v[56:59]
	v_mfma_f32_16x16x32_bf16 v[56:59], v[136:139], v[180:183], v[56:59]
	v_mfma_f32_16x16x32_bf16 v[40:43], v[136:139], v[196:199], v[40:43]
	v_mfma_f32_16x16x32_bf16 v[40:43], v[140:143], v[200:203], v[40:43]
	v_mfma_f32_16x16x32_bf16 v[44:47], v[132:135], v[200:203], v[44:47]
	v_mfma_f32_16x16x32_bf16 v[44:47], v[128:131], v[196:199], v[44:47]
	v_mfma_f32_16x16x32_bf16 v[28:31], v[128:131], v[204:207], v[28:31]
	v_mfma_f32_16x16x32_bf16 v[28:31], v[132:135], v[208:211], v[28:31]
	v_mfma_f32_16x16x32_bf16 v[24:27], v[140:143], v[208:211], v[24:27]
	v_mfma_f32_16x16x32_bf16 v[24:27], v[136:139], v[204:207], v[24:27]
	v_mfma_f32_16x16x32_bf16 v[8:11], v[136:139], v[212:215], v[8:11]
	v_mfma_f32_16x16x32_bf16 v[8:11], v[140:143], v[216:219], v[8:11]
	v_mfma_f32_16x16x32_bf16 v[12:15], v[132:135], v[216:219], v[12:15]
	v_mfma_f32_16x16x32_bf16 v[12:15], v[128:131], v[212:215], v[12:15]
	s_setprio 0
	s_setprio 1
	v_mfma_f32_16x16x32_bf16 v[52:55], v[144:147], v[180:183], v[52:55]
	v_mfma_f32_16x16x32_bf16 v[52:55], v[148:151], v[192:195], v[52:55]
	v_mfma_f32_16x16x32_bf16 v[48:51], v[176:179], v[192:195], v[48:51]
	v_mfma_f32_16x16x32_bf16 v[48:51], v[172:175], v[180:183], v[48:51]
	v_mfma_f32_16x16x32_bf16 v[32:35], v[172:175], v[196:199], v[32:35]
	v_mfma_f32_16x16x32_bf16 v[32:35], v[176:179], v[200:203], v[32:35]
	v_mfma_f32_16x16x32_bf16 v[36:39], v[148:151], v[200:203], v[36:39]
	v_mfma_f32_16x16x32_bf16 v[36:39], v[144:147], v[196:199], v[36:39]
	v_mfma_f32_16x16x32_bf16 v[20:23], v[144:147], v[204:207], v[20:23]
	v_mfma_f32_16x16x32_bf16 v[20:23], v[148:151], v[208:211], v[20:23]
	v_mfma_f32_16x16x32_bf16 v[16:19], v[176:179], v[208:211], v[16:19]
	v_mfma_f32_16x16x32_bf16 v[16:19], v[172:175], v[204:207], v[16:19]
	v_mfma_f32_16x16x32_bf16 v[0:3], v[172:175], v[212:215], v[0:3]
	v_mfma_f32_16x16x32_bf16 v[0:3], v[176:179], v[216:219], v[0:3]
	v_mfma_f32_16x16x32_bf16 v[4:7], v[148:151], v[216:219], v[4:7]
	v_mfma_f32_16x16x32_bf16 v[4:7], v[144:147], v[212:215], v[4:7]
	s_barrier
	s_setprio 0
	s_add_i32 s74, s74, 2
	s_add_u32 s72, s72, 0x100
	s_addc_u32 s73, s73, 0
	s_cmp_gt_u32 s74, 41
	s_mov_b64 s[48:49], s[50:51]
	s_cbranch_scc0 .LBB0_1181
	s_and_b64 vcc, exec, s[24:25]
	s_cbranch_vccz .LBB0_1184
	s_barrier
